# EpiWin rstd batching: 8 ssq loads + 16 bpermutes per tile issued together at epilogue head, variants use precomputed rstd, stores flat->global
# speedup vs baseline: 1.0091x; 1.0033x over previous
; __device__ __forceinline__ float row_rstd(const float* ssq, int row, int fq) {
;     const f32x4 v = *(const f32x4*)(ssq + (size_t)row * 16 + fq * 4);
;     float s = (v[0] + v[1]) + (v[2] + v[3]);
;     s += __shfl_xor(s, 16); s += __shfl_xor(s, 32);
;     return __builtin_amdgcn_rsqf(s * (1.f / DM) + EPS);
; }
;     __device__ __forceinline__ void operator()(const f32x4 (&acc)[2][2][4][2], const pg8::Unit& u, int wr, int wc, int fr, int fq) const {
;     ...
;         const int grp = pn >> 1, cb = (pn & 1) * 256 + cw;
.LBB0_394:
	v_mov_b32_e32 v128, v166
	v_ashrrev_i32_e32 v129, 31, v128
	v_lshlrev_b64 v[128:129], 6, v[128:129]
	v_lshl_add_u64 v[128:129], v[160:161], 0, v[128:129]
	global_load_dwordx4 v[128:131], v[128:129], off
	v_add_u32_e32 v132, 16, v166
	v_ashrrev_i32_e32 v133, 31, v132
	v_lshlrev_b64 v[132:133], 6, v[132:133]
	v_lshl_add_u64 v[132:133], v[160:161], 0, v[132:133]
	global_load_dwordx4 v[132:135], v[132:133], off
	v_add_u32_e32 v136, 32, v166
	v_ashrrev_i32_e32 v137, 31, v136
	v_lshlrev_b64 v[136:137], 6, v[136:137]
	v_lshl_add_u64 v[136:137], v[160:161], 0, v[136:137]
	global_load_dwordx4 v[136:139], v[136:137], off
	v_add_u32_e32 v140, 48, v166
	v_ashrrev_i32_e32 v141, 31, v140
	v_lshlrev_b64 v[140:141], 6, v[140:141]
	v_lshl_add_u64 v[140:141], v[160:161], 0, v[140:141]
	global_load_dwordx4 v[140:143], v[140:141], off
	v_add_u32_e32 v144, 0x80, v166
	v_ashrrev_i32_e32 v145, 31, v144
	v_lshlrev_b64 v[144:145], 6, v[144:145]
	v_lshl_add_u64 v[144:145], v[160:161], 0, v[144:145]
	global_load_dwordx4 v[144:147], v[144:145], off
	v_add_u32_e32 v148, 0x90, v166
	v_ashrrev_i32_e32 v149, 31, v148
	v_lshlrev_b64 v[148:149], 6, v[148:149]
	v_lshl_add_u64 v[148:149], v[160:161], 0, v[148:149]
	global_load_dwordx4 v[148:151], v[148:149], off
	v_add_u32_e32 v236, 0xa0, v166
	v_ashrrev_i32_e32 v237, 31, v236
	v_lshlrev_b64 v[236:237], 6, v[236:237]
	v_lshl_add_u64 v[236:237], v[160:161], 0, v[236:237]
	global_load_dwordx4 v[236:239], v[236:237], off
	v_add_u32_e32 v246, 0xb0, v166
	v_ashrrev_i32_e32 v247, 31, v246
	v_lshlrev_b64 v[246:247], 6, v[246:247]
	v_lshl_add_u64 v[246:247], v[160:161], 0, v[246:247]
	global_load_dwordx4 v[246:249], v[246:247], off
	s_waitcnt vmcnt(0)
	v_add_f32_e32 v128, v128, v129
	v_add_f32_e32 v130, v130, v131
	v_add_f32_e32 v132, v132, v133
	v_add_f32_e32 v134, v134, v135
	v_add_f32_e32 v136, v136, v137
	v_add_f32_e32 v138, v138, v139
	v_add_f32_e32 v140, v140, v141
	v_add_f32_e32 v142, v142, v143
	v_add_f32_e32 v144, v144, v145
	v_add_f32_e32 v146, v146, v147
	v_add_f32_e32 v148, v148, v149
	v_add_f32_e32 v150, v150, v151
	v_add_f32_e32 v236, v236, v237
	v_add_f32_e32 v238, v238, v239
	v_add_f32_e32 v246, v246, v247
	v_add_f32_e32 v248, v248, v249
	v_add_f32_e32 v128, v128, v130
	v_add_f32_e32 v132, v132, v134
	v_add_f32_e32 v136, v136, v138
	v_add_f32_e32 v140, v140, v142
	v_add_f32_e32 v144, v144, v146
	v_add_f32_e32 v148, v148, v150
	v_add_f32_e32 v236, v236, v238
	v_add_f32_e32 v246, v246, v248
	v_xor_b32_e32 v130, 16, v215
	v_xor_b32_e32 v131, 32, v215
	v_lshlrev_b32_e32 v130, 2, v130
	v_lshlrev_b32_e32 v131, 2, v131
	ds_bpermute_b32 v129, v130, v128
	ds_bpermute_b32 v133, v130, v132
	ds_bpermute_b32 v137, v130, v136
	ds_bpermute_b32 v141, v130, v140
	ds_bpermute_b32 v145, v130, v144
	ds_bpermute_b32 v149, v130, v148
	ds_bpermute_b32 v237, v130, v236
	ds_bpermute_b32 v247, v130, v246
	s_waitcnt lgkmcnt(0)
	v_add_f32_e32 v128, v128, v129
	v_add_f32_e32 v132, v132, v133
	v_add_f32_e32 v136, v136, v137
	v_add_f32_e32 v140, v140, v141
	v_add_f32_e32 v144, v144, v145
	v_add_f32_e32 v148, v148, v149
	v_add_f32_e32 v236, v236, v237
	v_add_f32_e32 v246, v246, v247
	ds_bpermute_b32 v129, v131, v128
	ds_bpermute_b32 v133, v131, v132
	ds_bpermute_b32 v137, v131, v136
	ds_bpermute_b32 v141, v131, v140
	ds_bpermute_b32 v145, v131, v144
	ds_bpermute_b32 v149, v131, v148
	ds_bpermute_b32 v237, v131, v236
	ds_bpermute_b32 v247, v131, v246
	s_waitcnt lgkmcnt(0)
	v_add_f32_e32 v128, v128, v129
	v_add_f32_e32 v132, v132, v133
	v_add_f32_e32 v136, v136, v137
	v_add_f32_e32 v140, v140, v141
	v_add_f32_e32 v144, v144, v145
	v_add_f32_e32 v148, v148, v149
	v_add_f32_e32 v236, v236, v237
	v_add_f32_e32 v246, v246, v247
	v_fmamk_f32 v128, v128, 0x3a800000, v212
	v_fmamk_f32 v132, v132, 0x3a800000, v212
	v_fmamk_f32 v136, v136, 0x3a800000, v212
	v_fmamk_f32 v140, v140, 0x3a800000, v212
	v_fmamk_f32 v144, v144, 0x3a800000, v212
	v_fmamk_f32 v148, v148, 0x3a800000, v212
	v_fmamk_f32 v236, v236, 0x3a800000, v212
	v_fmamk_f32 v246, v246, 0x3a800000, v212
	v_rsq_f32_e32 v250, v128
	v_rsq_f32_e32 v251, v132
	v_rsq_f32_e32 v252, v136
	v_rsq_f32_e32 v253, v140
	v_rsq_f32_e32 v254, v144
	v_rsq_f32_e32 v240, v148
	v_rsq_f32_e32 v241, v236
	v_rsq_f32_e32 v245, v246
	s_nop 0
	s_lshl_b32 s8, s2, 8
	s_and_b32 s8, s8, 0x100
	v_or_b32_e32 v176, s8, v174
	s_cmp_gt_u32 s2, 1
	s_mov_b64 s[8:9], -1
	s_cbranch_scc0 .LBB0_417
	s_ashr_i32 s14, s2, 1
	s_mov_b64 s[12:13], -1
	s_mov_b64 s[8:9], 0
	s_cmp_lt_i32 s14, 3
	s_mov_b64 s[10:11], 0
	s_cbranch_scc1 .LBB0_407
	s_cmp_gt_i32 s14, 3
	s_cbranch_scc0 .LBB0_404
	s_cmp_gt_i32 s14, 4
	s_cbranch_scc0 .LBB0_401
	s_cmp_eq_u32 s14, 5
	s_mov_b64 s[10:11], -1
	s_cbranch_scc0 .LBB0_400
; __device__ __forceinline__ float silu_f(float x) { return x * __builtin_amdgcn_rcpf(1.f + __expf(-x)); }
; __device__ __forceinline__ v4u pack8(const f32x4 a, const f32x4 b) { v4u w; w.x = cvt_pk_bf16(a[0], a[1]); w.y = cvt_pk_bf16(a[2], a[3]); w.z = cvt_pk_bf16(b[0], b[1]); w.w = cvt_pk_bf16(b[2], b[3]); return w; }
;     __device__ __forceinline__ void operator()(const f32x4 (&acc)[2][2][4][2], const pg8::Unit& u, int wr, int wc, int fr, int fq) const {
;     ...
;         if (grp == 0) { WIN_LOOP( _Pragma("unroll") for (int i = 0; i < 4; ++i) { a[i] = silu_f(a[i]); b[i] = silu_f(b[i]); } *(v4u*)(QO + (size_t)row * DM + c) = pack8(a, b); ) }
;         else if (grp == 3) { WIN_LOOP( _Pragma("unroll") for (int i = 0; i < 4; ++i) { a[i] = silu_f(a[i]); b[i] = silu_f(b[i]); } *(v4u*)(GH + (size_t)row * 512 + c) = pack8(a, b); ) }
;         else if (grp == 1) {
;             f32x4 l0[2], l1[2];
; #pragma unroll
;             for (int bj = 0; bj < 2; ++bj) { l0[bj] = *(const f32x4*)(lb + cb + bj * 128); l1[bj] = *(const f32x4*)(lb + cb + bj * 128 + 4); }
;             WIN_LOOP( _Pragma("unroll") for (int i = 0; i < 4; ++i) { const float s0 = fminf(a[i], 0.f) - __logf(1.f + __expf(-fabsf(a[i]))), s1 = fminf(b[i], 0.f) - __logf(1.f + __expf(-fabsf(b[i]))); const float la = l0[bj][i], lbv = l1[bj][i];
;                     a[i] = la > 0.f ? __logf(la + (1.f - la) * __expf(s0)) : s0; b[i] = lbv > 0.f ? __logf(lbv + (1.f - lbv) * __expf(s1)) : s1; }
;                 *(f32x4*)(LF + (size_t)row * 512 + c) = a; *(f32x4*)(LF + (size_t)row * 512 + c + 4) = b; __builtin_amdgcn_sched_barrier(0); ) }
;         else if (grp == 2) { WIN_LOOP( *(v4u*)(VH + (size_t)row * 512 + c) = pack8(a, b); ) }
;         else if (grp == 4) { WIN_LOOP( *(v4u*)(QO + (size_t)row * DM + 512 + c) = pack8(a * C2Q, b * C2Q); ) }
;         else if (grp == 5) { WIN_LOOP( *(v4u*)(FK + (size_t)row * 512 + c) = pack8(a, b); ) }
	v_and_b32_e32 v129, 64, v215
	v_xor_b32_e32 v128, 16, v215
	v_add_u32_e32 v129, 64, v129
	v_cmp_lt_i32_e32 vcc, v128, v129
	v_ashrrev_i32_e32 v167, 31, v166
	v_readlane_b32 s10, v255, 41
	v_cndmask_b32_e32 v128, v215, v128, vcc
	v_lshlrev_b32_e32 v130, 2, v128
	v_xor_b32_e32 v128, 32, v215
	v_cmp_lt_i32_e32 vcc, v128, v129
	v_readlane_b32 s11, v255, 42
	v_lshlrev_b32_e32 v192, 1, v176
	v_cndmask_b32_e32 v128, v215, v128, vcc
	v_lshlrev_b32_e32 v131, 2, v128
	v_lshlrev_b64 v[128:129], 6, v[166:167]
	v_lshl_add_u64 v[128:129], v[160:161], 0, v[128:129]
	s_nop 0
	s_waitcnt lgkmcnt(0)
	s_nop 0
	s_nop 0
	s_nop 0
	s_nop 0
	v_lshlrev_b64 v[132:133], 10, v[166:167]
	s_nop 0
	s_nop 0
	v_lshl_add_u64 v[136:137], s[10:11], 0, v[132:133]
	v_lshl_add_u64 v[136:137], v[136:137], 0, v[192:193]
	s_waitcnt lgkmcnt(0)
	s_nop 0
	s_nop 0
	s_waitcnt lgkmcnt(0)
	s_nop 0
	s_nop 0
	v_mov_b32_e32 v128, v250
	s_nop 0
	v_pk_mul_f32 v[134:135], v[62:63], v[128:129] op_sel_hi:[1,0]
	v_pk_mul_f32 v[132:133], v[60:61], v[128:129] op_sel_hi:[1,0]
	v_pk_mul_f32 v[138:139], v[58:59], v[128:129] op_sel_hi:[1,0]
	v_pk_mul_f32 v[140:141], v[56:57], v[128:129] op_sel_hi:[1,0]
	v_cvt_pk_bf16_f32 v132, v132, v133
	v_cvt_pk_bf16_f32 v133, v134, v135
	v_cvt_pk_bf16_f32 v134, v140, v141
	v_cvt_pk_bf16_f32 v135, v138, v139
	global_store_dwordx4 v[136:137], v[132:135], off
	v_pk_mul_f32 v[138:139], v[122:123], v[128:129] op_sel_hi:[1,0]
	s_nop 0
	v_pk_mul_f32 v[134:135], v[126:127], v[128:129] op_sel_hi:[1,0]
	v_pk_mul_f32 v[132:133], v[124:125], v[128:129] op_sel_hi:[1,0]
	v_pk_mul_f32 v[128:129], v[120:121], v[128:129] op_sel_hi:[1,0]
	v_cvt_pk_bf16_f32 v132, v132, v133
	v_cvt_pk_bf16_f32 v133, v134, v135
	v_cvt_pk_bf16_f32 v134, v128, v129
	v_or_b32_e32 v128, 16, v166
	v_cvt_pk_bf16_f32 v135, v138, v139
	v_ashrrev_i32_e32 v129, 31, v128
	global_store_dwordx4 v[136:137], v[132:135], off offset:256
	s_nop 1
	v_lshlrev_b64 v[132:133], 6, v[128:129]
	v_lshl_add_u64 v[132:133], v[160:161], 0, v[132:133]
	s_nop 0
	v_lshlrev_b64 v[128:129], 10, v[128:129]
	v_lshl_add_u64 v[128:129], s[10:11], 0, v[128:129]
	v_lshl_add_u64 v[128:129], v[128:129], 0, v[192:193]
	s_waitcnt lgkmcnt(0)
	s_nop 0
	s_nop 0
	s_nop 0
	s_nop 0
	s_nop 0
	s_nop 0
	s_nop 0
	s_waitcnt lgkmcnt(0)
	s_nop 0
	s_nop 0
	s_waitcnt lgkmcnt(0)
	s_nop 0
	s_nop 0
	v_mov_b32_e32 v136, v251
	s_nop 0
	v_pk_mul_f32 v[134:135], v[54:55], v[136:137] op_sel_hi:[1,0]
	v_pk_mul_f32 v[132:133], v[52:53], v[136:137] op_sel_hi:[1,0]
	v_pk_mul_f32 v[138:139], v[50:51], v[136:137] op_sel_hi:[1,0]
	v_pk_mul_f32 v[140:141], v[48:49], v[136:137] op_sel_hi:[1,0]
	v_cvt_pk_bf16_f32 v132, v132, v133
	v_cvt_pk_bf16_f32 v133, v134, v135
	v_cvt_pk_bf16_f32 v134, v140, v141
	v_cvt_pk_bf16_f32 v135, v138, v139
	global_store_dwordx4 v[128:129], v[132:135], off
	v_pk_mul_f32 v[138:139], v[114:115], v[136:137] op_sel_hi:[1,0]
	s_nop 0
	v_pk_mul_f32 v[134:135], v[118:119], v[136:137] op_sel_hi:[1,0]
	v_pk_mul_f32 v[132:133], v[116:117], v[136:137] op_sel_hi:[1,0]
	v_pk_mul_f32 v[136:137], v[112:113], v[136:137] op_sel_hi:[1,0]
	v_cvt_pk_bf16_f32 v132, v132, v133
	v_cvt_pk_bf16_f32 v133, v134, v135
	v_cvt_pk_bf16_f32 v134, v136, v137
	v_cvt_pk_bf16_f32 v135, v138, v139
	global_store_dwordx4 v[128:129], v[132:135], off offset:256
	v_or_b32_e32 v128, 32, v166
	v_ashrrev_i32_e32 v129, 31, v128
	v_lshlrev_b64 v[132:133], 6, v[128:129]
	v_lshl_add_u64 v[132:133], v[160:161], 0, v[132:133]
	s_nop 0
	v_lshlrev_b64 v[128:129], 10, v[128:129]
	v_lshl_add_u64 v[128:129], s[10:11], 0, v[128:129]
	v_lshl_add_u64 v[128:129], v[128:129], 0, v[192:193]
	s_waitcnt lgkmcnt(0)
	s_nop 0
	s_nop 0
	s_nop 0
	s_nop 0
	s_nop 0
	s_nop 0
	s_nop 0
	s_waitcnt lgkmcnt(0)
	s_nop 0
	s_nop 0
	s_waitcnt lgkmcnt(0)
	s_nop 0
	s_nop 0
	v_mov_b32_e32 v136, v252
	s_nop 0
	v_pk_mul_f32 v[134:135], v[46:47], v[136:137] op_sel_hi:[1,0]
	v_pk_mul_f32 v[132:133], v[44:45], v[136:137] op_sel_hi:[1,0]
	v_pk_mul_f32 v[138:139], v[42:43], v[136:137] op_sel_hi:[1,0]
	v_pk_mul_f32 v[140:141], v[40:41], v[136:137] op_sel_hi:[1,0]
	v_cvt_pk_bf16_f32 v132, v132, v133
	v_cvt_pk_bf16_f32 v133, v134, v135
	v_cvt_pk_bf16_f32 v134, v140, v141
	v_cvt_pk_bf16_f32 v135, v138, v139
	global_store_dwordx4 v[128:129], v[132:135], off
	v_pk_mul_f32 v[138:139], v[106:107], v[136:137] op_sel_hi:[1,0]
	s_nop 0
	v_pk_mul_f32 v[134:135], v[110:111], v[136:137] op_sel_hi:[1,0]
	v_pk_mul_f32 v[132:133], v[108:109], v[136:137] op_sel_hi:[1,0]
	v_pk_mul_f32 v[136:137], v[104:105], v[136:137] op_sel_hi:[1,0]
	v_cvt_pk_bf16_f32 v132, v132, v133
	v_cvt_pk_bf16_f32 v133, v134, v135
	v_cvt_pk_bf16_f32 v134, v136, v137
	v_cvt_pk_bf16_f32 v135, v138, v139
	global_store_dwordx4 v[128:129], v[132:135], off offset:256
	v_or_b32_e32 v128, 48, v166
	v_ashrrev_i32_e32 v129, 31, v128
	v_lshlrev_b64 v[132:133], 6, v[128:129]
	v_lshl_add_u64 v[132:133], v[160:161], 0, v[132:133]
	s_nop 0
	v_lshlrev_b64 v[128:129], 10, v[128:129]
	v_lshl_add_u64 v[128:129], s[10:11], 0, v[128:129]
	v_lshl_add_u64 v[128:129], v[128:129], 0, v[192:193]
	s_waitcnt lgkmcnt(0)
	s_nop 0
	s_nop 0
	s_nop 0
	s_nop 0
	s_nop 0
	s_nop 0
	s_nop 0
	s_waitcnt lgkmcnt(0)
	s_nop 0
	s_nop 0
	s_waitcnt lgkmcnt(0)
; __device__ __forceinline__ float silu_f(float x) { return x * __builtin_amdgcn_rcpf(1.f + __expf(-x)); }
; __device__ __forceinline__ v4u pack8(const f32x4 a, const f32x4 b) { v4u w; w.x = cvt_pk_bf16(a[0], a[1]); w.y = cvt_pk_bf16(a[2], a[3]); w.z = cvt_pk_bf16(b[0], b[1]); w.w = cvt_pk_bf16(b[2], b[3]); return w; }
;     __device__ __forceinline__ void operator()(const f32x4 (&acc)[2][2][4][2], const pg8::Unit& u, int wr, int wc, int fr, int fq) const {
;     ...
;         if (grp == 0) { WIN_LOOP( _Pragma("unroll") for (int i = 0; i < 4; ++i) { a[i] = silu_f(a[i]); b[i] = silu_f(b[i]); } *(v4u*)(QO + (size_t)row * DM + c) = pack8(a, b); ) }
;         else if (grp == 3) { WIN_LOOP( _Pragma("unroll") for (int i = 0; i < 4; ++i) { a[i] = silu_f(a[i]); b[i] = silu_f(b[i]); } *(v4u*)(GH + (size_t)row * 512 + c) = pack8(a, b); ) }
;         else if (grp == 1) {
;             f32x4 l0[2], l1[2];
; #pragma unroll
;             for (int bj = 0; bj < 2; ++bj) { l0[bj] = *(const f32x4*)(lb + cb + bj * 128); l1[bj] = *(const f32x4*)(lb + cb + bj * 128 + 4); }
;             WIN_LOOP( _Pragma("unroll") for (int i = 0; i < 4; ++i) { const float s0 = fminf(a[i], 0.f) - __logf(1.f + __expf(-fabsf(a[i]))), s1 = fminf(b[i], 0.f) - __logf(1.f + __expf(-fabsf(b[i]))); const float la = l0[bj][i], lbv = l1[bj][i];
;                     a[i] = la > 0.f ? __logf(la + (1.f - la) * __expf(s0)) : s0; b[i] = lbv > 0.f ? __logf(lbv + (1.f - lbv) * __expf(s1)) : s1; }
;                 *(f32x4*)(LF + (size_t)row * 512 + c) = a; *(f32x4*)(LF + (size_t)row * 512 + c + 4) = b; __builtin_amdgcn_sched_barrier(0); ) }
;         else if (grp == 2) { WIN_LOOP( *(v4u*)(VH + (size_t)row * 512 + c) = pack8(a, b); ) }
;         else if (grp == 4) { WIN_LOOP( *(v4u*)(QO + (size_t)row * DM + 512 + c) = pack8(a * C2Q, b * C2Q); ) }
;         else if (grp == 5) { WIN_LOOP( *(v4u*)(FK + (size_t)row * 512 + c) = pack8(a, b); ) }
	s_nop 0
	s_nop 0
	v_mov_b32_e32 v136, v253
	s_nop 0
	v_pk_mul_f32 v[134:135], v[38:39], v[136:137] op_sel_hi:[1,0]
	v_pk_mul_f32 v[132:133], v[36:37], v[136:137] op_sel_hi:[1,0]
	v_pk_mul_f32 v[138:139], v[34:35], v[136:137] op_sel_hi:[1,0]
	v_pk_mul_f32 v[140:141], v[32:33], v[136:137] op_sel_hi:[1,0]
	v_cvt_pk_bf16_f32 v132, v132, v133
	v_cvt_pk_bf16_f32 v133, v134, v135
	v_cvt_pk_bf16_f32 v134, v140, v141
	v_cvt_pk_bf16_f32 v135, v138, v139
	global_store_dwordx4 v[128:129], v[132:135], off
	v_pk_mul_f32 v[138:139], v[98:99], v[136:137] op_sel_hi:[1,0]
	s_nop 0
	v_pk_mul_f32 v[134:135], v[102:103], v[136:137] op_sel_hi:[1,0]
	v_pk_mul_f32 v[132:133], v[100:101], v[136:137] op_sel_hi:[1,0]
	v_pk_mul_f32 v[136:137], v[96:97], v[136:137] op_sel_hi:[1,0]
	v_cvt_pk_bf16_f32 v132, v132, v133
	v_cvt_pk_bf16_f32 v133, v134, v135
	v_cvt_pk_bf16_f32 v134, v136, v137
	v_cvt_pk_bf16_f32 v135, v138, v139
	global_store_dwordx4 v[128:129], v[132:135], off offset:256
	v_add_u32_e32 v128, 0x80, v166
	v_ashrrev_i32_e32 v129, 31, v128
	v_lshlrev_b64 v[132:133], 6, v[128:129]
	v_lshl_add_u64 v[132:133], v[160:161], 0, v[132:133]
	s_nop 0
	v_lshlrev_b64 v[128:129], 10, v[128:129]
	v_lshl_add_u64 v[128:129], s[10:11], 0, v[128:129]
	v_lshl_add_u64 v[128:129], v[128:129], 0, v[192:193]
	s_waitcnt lgkmcnt(0)
	s_nop 0
	s_nop 0
	s_nop 0
	s_nop 0
	s_nop 0
	s_nop 0
	s_nop 0
	s_waitcnt lgkmcnt(0)
	s_nop 0
	s_nop 0
	s_waitcnt lgkmcnt(0)
	s_nop 0
	s_nop 0
	v_mov_b32_e32 v136, v254
	s_nop 0
	v_pk_mul_f32 v[134:135], v[30:31], v[136:137] op_sel_hi:[1,0]
	v_pk_mul_f32 v[132:133], v[28:29], v[136:137] op_sel_hi:[1,0]
	v_pk_mul_f32 v[138:139], v[26:27], v[136:137] op_sel_hi:[1,0]
	v_pk_mul_f32 v[140:141], v[24:25], v[136:137] op_sel_hi:[1,0]
	v_cvt_pk_bf16_f32 v132, v132, v133
	v_cvt_pk_bf16_f32 v133, v134, v135
	v_cvt_pk_bf16_f32 v134, v140, v141
	v_cvt_pk_bf16_f32 v135, v138, v139
	global_store_dwordx4 v[128:129], v[132:135], off
	v_pk_mul_f32 v[138:139], v[90:91], v[136:137] op_sel_hi:[1,0]
	s_nop 0
	v_pk_mul_f32 v[134:135], v[94:95], v[136:137] op_sel_hi:[1,0]
	v_pk_mul_f32 v[132:133], v[92:93], v[136:137] op_sel_hi:[1,0]
	v_pk_mul_f32 v[136:137], v[88:89], v[136:137] op_sel_hi:[1,0]
	v_cvt_pk_bf16_f32 v132, v132, v133
	v_cvt_pk_bf16_f32 v133, v134, v135
	v_cvt_pk_bf16_f32 v134, v136, v137
	v_cvt_pk_bf16_f32 v135, v138, v139
	global_store_dwordx4 v[128:129], v[132:135], off offset:256
	v_add_u32_e32 v128, 0x90, v166
	v_ashrrev_i32_e32 v129, 31, v128
	v_lshlrev_b64 v[132:133], 6, v[128:129]
	v_lshl_add_u64 v[132:133], v[160:161], 0, v[132:133]
	s_nop 0
	v_lshlrev_b64 v[128:129], 10, v[128:129]
	v_lshl_add_u64 v[128:129], s[10:11], 0, v[128:129]
	v_lshl_add_u64 v[128:129], v[128:129], 0, v[192:193]
	s_waitcnt lgkmcnt(0)
	s_nop 0
	s_nop 0
	s_nop 0
	s_nop 0
	s_nop 0
	s_nop 0
	s_nop 0
	s_waitcnt lgkmcnt(0)
	s_nop 0
	s_nop 0
	s_waitcnt lgkmcnt(0)
	s_nop 0
	s_nop 0
	v_mov_b32_e32 v136, v240
	s_nop 0
	v_pk_mul_f32 v[134:135], v[22:23], v[136:137] op_sel_hi:[1,0]
	v_pk_mul_f32 v[132:133], v[20:21], v[136:137] op_sel_hi:[1,0]
	v_pk_mul_f32 v[138:139], v[18:19], v[136:137] op_sel_hi:[1,0]
	v_pk_mul_f32 v[140:141], v[16:17], v[136:137] op_sel_hi:[1,0]
	v_cvt_pk_bf16_f32 v132, v132, v133
	v_cvt_pk_bf16_f32 v133, v134, v135
	v_cvt_pk_bf16_f32 v134, v140, v141
	v_cvt_pk_bf16_f32 v135, v138, v139
	global_store_dwordx4 v[128:129], v[132:135], off
	v_pk_mul_f32 v[138:139], v[82:83], v[136:137] op_sel_hi:[1,0]
	s_nop 0
	v_pk_mul_f32 v[134:135], v[86:87], v[136:137] op_sel_hi:[1,0]
	v_pk_mul_f32 v[132:133], v[84:85], v[136:137] op_sel_hi:[1,0]
	v_pk_mul_f32 v[136:137], v[80:81], v[136:137] op_sel_hi:[1,0]
	v_cvt_pk_bf16_f32 v132, v132, v133
	v_cvt_pk_bf16_f32 v133, v134, v135
	v_cvt_pk_bf16_f32 v134, v136, v137
	v_cvt_pk_bf16_f32 v135, v138, v139
	global_store_dwordx4 v[128:129], v[132:135], off offset:256
	v_add_u32_e32 v128, 0xa0, v166
	v_ashrrev_i32_e32 v129, 31, v128
	v_lshlrev_b64 v[132:133], 6, v[128:129]
	v_lshl_add_u64 v[132:133], v[160:161], 0, v[132:133]
	s_nop 0
	v_lshlrev_b64 v[128:129], 10, v[128:129]
	v_lshl_add_u64 v[128:129], s[10:11], 0, v[128:129]
	v_lshl_add_u64 v[128:129], v[128:129], 0, v[192:193]
	s_waitcnt lgkmcnt(0)
	s_nop 0
	s_nop 0
	s_nop 0
	s_nop 0
	s_nop 0
	s_nop 0
	s_nop 0
	s_waitcnt lgkmcnt(0)
	s_nop 0
	s_nop 0
	s_waitcnt lgkmcnt(0)
	s_nop 0
	s_nop 0
	v_mov_b32_e32 v136, v241
	s_nop 0
	v_pk_mul_f32 v[134:135], v[14:15], v[136:137] op_sel_hi:[1,0]
	v_pk_mul_f32 v[132:133], v[12:13], v[136:137] op_sel_hi:[1,0]
	v_pk_mul_f32 v[138:139], v[10:11], v[136:137] op_sel_hi:[1,0]
	v_pk_mul_f32 v[140:141], v[8:9], v[136:137] op_sel_hi:[1,0]
	v_cvt_pk_bf16_f32 v132, v132, v133
	v_cvt_pk_bf16_f32 v133, v134, v135
	v_cvt_pk_bf16_f32 v134, v140, v141
	v_cvt_pk_bf16_f32 v135, v138, v139
	global_store_dwordx4 v[128:129], v[132:135], off
	v_pk_mul_f32 v[138:139], v[74:75], v[136:137] op_sel_hi:[1,0]
	s_nop 0
	v_pk_mul_f32 v[134:135], v[78:79], v[136:137] op_sel_hi:[1,0]
	v_pk_mul_f32 v[132:133], v[76:77], v[136:137] op_sel_hi:[1,0]
	v_pk_mul_f32 v[136:137], v[72:73], v[136:137] op_sel_hi:[1,0]
	v_cvt_pk_bf16_f32 v132, v132, v133
	v_cvt_pk_bf16_f32 v133, v134, v135
	v_cvt_pk_bf16_f32 v134, v136, v137
	v_cvt_pk_bf16_f32 v135, v138, v139
	global_store_dwordx4 v[128:129], v[132:135], off offset:256
	v_add_u32_e32 v128, 0xb0, v166
	v_ashrrev_i32_e32 v129, 31, v128
	v_lshlrev_b64 v[132:133], 6, v[128:129]
	v_lshl_add_u64 v[132:133], v[160:161], 0, v[132:133]
	s_nop 0
	v_lshlrev_b64 v[128:129], 10, v[128:129]
	s_waitcnt lgkmcnt(0)
	s_nop 0
	s_nop 0
	s_nop 0
	s_nop 0
	v_lshl_add_u64 v[134:135], s[10:11], 0, v[128:129]
	s_nop 0
	s_nop 0
	v_lshl_add_u64 v[134:135], v[134:135], 0, v[192:193]
	s_mov_b64 s[10:11], 0
	s_waitcnt lgkmcnt(0)
	s_nop 0
	s_nop 0
	s_waitcnt lgkmcnt(0)
	s_nop 0
	s_nop 0
	v_mov_b32_e32 v132, v245
	s_nop 0
	v_pk_mul_f32 v[130:131], v[6:7], v[132:133] op_sel_hi:[1,0]
	v_pk_mul_f32 v[128:129], v[4:5], v[132:133] op_sel_hi:[1,0]
	v_pk_mul_f32 v[136:137], v[2:3], v[132:133] op_sel_hi:[1,0]
	v_pk_mul_f32 v[138:139], v[0:1], v[132:133] op_sel_hi:[1,0]
	v_cvt_pk_bf16_f32 v128, v128, v129
	v_cvt_pk_bf16_f32 v129, v130, v131
	v_cvt_pk_bf16_f32 v130, v138, v139
	v_cvt_pk_bf16_f32 v131, v136, v137
	global_store_dwordx4 v[134:135], v[128:131], off
	v_pk_mul_f32 v[136:137], v[66:67], v[132:133] op_sel_hi:[1,0]
	s_nop 0
	v_pk_mul_f32 v[130:131], v[70:71], v[132:133] op_sel_hi:[1,0]
	v_pk_mul_f32 v[128:129], v[68:69], v[132:133] op_sel_hi:[1,0]
	v_pk_mul_f32 v[132:133], v[64:65], v[132:133] op_sel_hi:[1,0]
	v_cvt_pk_bf16_f32 v128, v128, v129
	v_cvt_pk_bf16_f32 v129, v130, v131
	v_cvt_pk_bf16_f32 v130, v132, v133
	v_cvt_pk_bf16_f32 v131, v136, v137
	global_store_dwordx4 v[134:135], v[128:131], off offset:256

; __device__ __forceinline__ float silu_f(float x) { return x * __builtin_amdgcn_rcpf(1.f + __expf(-x)); }
; __device__ __forceinline__ v4u pack8(const f32x4 a, const f32x4 b) { v4u w; w.x = cvt_pk_bf16(a[0], a[1]); w.y = cvt_pk_bf16(a[2], a[3]); w.z = cvt_pk_bf16(b[0], b[1]); w.w = cvt_pk_bf16(b[2], b[3]); return w; }
;     __device__ __forceinline__ void operator()(const f32x4 (&acc)[2][2][4][2], const pg8::Unit& u, int wr, int wc, int fr, int fq) const {
;     ...
;         if (grp == 0) { WIN_LOOP( _Pragma("unroll") for (int i = 0; i < 4; ++i) { a[i] = silu_f(a[i]); b[i] = silu_f(b[i]); } *(v4u*)(QO + (size_t)row * DM + c) = pack8(a, b); ) }
;         else if (grp == 3) { WIN_LOOP( _Pragma("unroll") for (int i = 0; i < 4; ++i) { a[i] = silu_f(a[i]); b[i] = silu_f(b[i]); } *(v4u*)(GH + (size_t)row * 512 + c) = pack8(a, b); ) }
;         else if (grp == 1) {
;             f32x4 l0[2], l1[2];
; #pragma unroll
;             for (int bj = 0; bj < 2; ++bj) { l0[bj] = *(const f32x4*)(lb + cb + bj * 128); l1[bj] = *(const f32x4*)(lb + cb + bj * 128 + 4); }
;             WIN_LOOP( _Pragma("unroll") for (int i = 0; i < 4; ++i) { const float s0 = fminf(a[i], 0.f) - __logf(1.f + __expf(-fabsf(a[i]))), s1 = fminf(b[i], 0.f) - __logf(1.f + __expf(-fabsf(b[i]))); const float la = l0[bj][i], lbv = l1[bj][i];
;                     a[i] = la > 0.f ? __logf(la + (1.f - la) * __expf(s0)) : s0; b[i] = lbv > 0.f ? __logf(lbv + (1.f - lbv) * __expf(s1)) : s1; }
;                 *(f32x4*)(LF + (size_t)row * 512 + c) = a; *(f32x4*)(LF + (size_t)row * 512 + c + 4) = b; __builtin_amdgcn_sched_barrier(0); ) }
;         else if (grp == 2) { WIN_LOOP( *(v4u*)(VH + (size_t)row * 512 + c) = pack8(a, b); ) }
;         else if (grp == 4) { WIN_LOOP( *(v4u*)(QO + (size_t)row * DM + 512 + c) = pack8(a * C2Q, b * C2Q); ) }
.LBB0_401:
	s_and_b64 vcc, exec, s[12:13]
	s_cbranch_vccz .LBB0_403
	v_and_b32_e32 v129, 64, v215
	v_xor_b32_e32 v128, 16, v215
	v_add_u32_e32 v129, 64, v129
	v_cmp_lt_i32_e32 vcc, v128, v129
	v_ashrrev_i32_e32 v167, 31, v166
	s_mov_b32 s2, 0x3e38aa3b
	v_cndmask_b32_e32 v128, v215, v128, vcc
	v_lshlrev_b32_e32 v132, 2, v128
	v_xor_b32_e32 v128, 32, v215
	v_cmp_lt_i32_e32 vcc, v128, v129
	v_lshlrev_b32_e32 v192, 1, v176
	s_nop 0
	v_cndmask_b32_e32 v128, v215, v128, vcc
	v_lshlrev_b32_e32 v133, 2, v128
	v_lshlrev_b64 v[128:129], 6, v[166:167]
	v_lshl_add_u64 v[128:129], v[160:161], 0, v[128:129]
	s_nop 0
	s_waitcnt lgkmcnt(0)
	s_nop 0
	s_nop 0
	s_nop 0
	s_nop 0
	s_nop 0
	s_nop 0
	s_nop 0
	s_waitcnt lgkmcnt(0)
	s_nop 0
	s_nop 0
	s_waitcnt lgkmcnt(0)
	s_nop 0
	s_nop 0
	v_mov_b32_e32 v134, v250
	v_lshlrev_b64 v[128:129], 11, v[166:167]
	v_lshl_add_u64 v[136:137], s[44:45], 0, v[128:129]
	v_lshl_add_u64 v[136:137], v[136:137], 0, v[192:193]
	v_pk_mul_f32 v[128:129], v[60:61], v[134:135] op_sel_hi:[1,0]
	v_pk_mul_f32 v[130:131], v[62:63], v[134:135] op_sel_hi:[1,0]
	v_pk_mul_f32 v[138:139], v[56:57], v[134:135] op_sel_hi:[1,0]
	v_pk_mul_f32 v[140:141], v[58:59], v[134:135] op_sel_hi:[1,0]
	v_pk_mul_f32 v[130:131], v[130:131], s[2:3] op_sel_hi:[1,0]
	v_pk_mul_f32 v[128:129], v[128:129], s[2:3] op_sel_hi:[1,0]
	v_pk_mul_f32 v[140:141], v[140:141], s[2:3] op_sel_hi:[1,0]
	v_pk_mul_f32 v[138:139], v[138:139], s[2:3] op_sel_hi:[1,0]
	v_cvt_pk_bf16_f32 v128, v128, v129
	v_cvt_pk_bf16_f32 v129, v130, v131
	v_cvt_pk_bf16_f32 v130, v138, v139
	v_cvt_pk_bf16_f32 v131, v140, v141
	global_store_dwordx4 v[136:137], v[128:131], off offset:1024
	v_pk_mul_f32 v[138:139], v[120:121], v[134:135] op_sel_hi:[1,0]
	s_nop 0
	v_pk_mul_f32 v[128:129], v[124:125], v[134:135] op_sel_hi:[1,0]
	v_pk_mul_f32 v[130:131], v[126:127], v[134:135] op_sel_hi:[1,0]
	v_pk_mul_f32 v[134:135], v[122:123], v[134:135] op_sel_hi:[1,0]
	v_pk_mul_f32 v[130:131], v[130:131], s[2:3] op_sel_hi:[1,0]
	v_pk_mul_f32 v[128:129], v[128:129], s[2:3] op_sel_hi:[1,0]
	v_pk_mul_f32 v[134:135], v[134:135], s[2:3] op_sel_hi:[1,0]
	v_pk_mul_f32 v[138:139], v[138:139], s[2:3] op_sel_hi:[1,0]
	v_cvt_pk_bf16_f32 v128, v128, v129
	v_cvt_pk_bf16_f32 v129, v130, v131
	v_cvt_pk_bf16_f32 v131, v134, v135
	v_or_b32_e32 v134, 16, v166
	v_cvt_pk_bf16_f32 v130, v138, v139
	v_ashrrev_i32_e32 v135, 31, v134
	global_store_dwordx4 v[136:137], v[128:131], off offset:1280
	s_nop 1
	v_lshlrev_b64 v[128:129], 6, v[134:135]
	v_lshl_add_u64 v[128:129], v[160:161], 0, v[128:129]
	s_nop 0
	s_waitcnt lgkmcnt(0)
	s_nop 0
	s_nop 0
	s_nop 0
	s_nop 0
	s_nop 0
	s_nop 0
	s_nop 0
	s_waitcnt lgkmcnt(0)
	s_nop 0
	s_nop 0
	s_waitcnt lgkmcnt(0)
	s_nop 0
	s_nop 0
	v_mov_b32_e32 v136, v251
	v_lshlrev_b64 v[128:129], 11, v[134:135]
	v_lshl_add_u64 v[134:135], s[44:45], 0, v[128:129]
	v_lshl_add_u64 v[134:135], v[134:135], 0, v[192:193]
	v_pk_mul_f32 v[128:129], v[52:53], v[136:137] op_sel_hi:[1,0]
	v_pk_mul_f32 v[130:131], v[54:55], v[136:137] op_sel_hi:[1,0]
	v_pk_mul_f32 v[138:139], v[48:49], v[136:137] op_sel_hi:[1,0]
	v_pk_mul_f32 v[140:141], v[50:51], v[136:137] op_sel_hi:[1,0]
	v_pk_mul_f32 v[130:131], v[130:131], s[2:3] op_sel_hi:[1,0]
	v_pk_mul_f32 v[128:129], v[128:129], s[2:3] op_sel_hi:[1,0]
	v_pk_mul_f32 v[140:141], v[140:141], s[2:3] op_sel_hi:[1,0]
	v_pk_mul_f32 v[138:139], v[138:139], s[2:3] op_sel_hi:[1,0]
	v_cvt_pk_bf16_f32 v128, v128, v129
	v_cvt_pk_bf16_f32 v129, v130, v131
	v_cvt_pk_bf16_f32 v130, v138, v139
	v_cvt_pk_bf16_f32 v131, v140, v141
	global_store_dwordx4 v[134:135], v[128:131], off offset:1024
	v_pk_mul_f32 v[138:139], v[112:113], v[136:137] op_sel_hi:[1,0]
	s_nop 0
	v_pk_mul_f32 v[128:129], v[116:117], v[136:137] op_sel_hi:[1,0]
	v_pk_mul_f32 v[130:131], v[118:119], v[136:137] op_sel_hi:[1,0]
	v_pk_mul_f32 v[136:137], v[114:115], v[136:137] op_sel_hi:[1,0]
	v_pk_mul_f32 v[130:131], v[130:131], s[2:3] op_sel_hi:[1,0]
	v_pk_mul_f32 v[128:129], v[128:129], s[2:3] op_sel_hi:[1,0]
	v_pk_mul_f32 v[136:137], v[136:137], s[2:3] op_sel_hi:[1,0]
	v_pk_mul_f32 v[138:139], v[138:139], s[2:3] op_sel_hi:[1,0]
	v_cvt_pk_bf16_f32 v128, v128, v129
	v_cvt_pk_bf16_f32 v129, v130, v131
	v_cvt_pk_bf16_f32 v130, v138, v139
	v_cvt_pk_bf16_f32 v131, v136, v137
	global_store_dwordx4 v[134:135], v[128:131], off offset:1280
	v_or_b32_e32 v134, 32, v166
	v_ashrrev_i32_e32 v135, 31, v134
	v_lshlrev_b64 v[128:129], 6, v[134:135]
	v_lshl_add_u64 v[128:129], v[160:161], 0, v[128:129]
	s_nop 0
	s_waitcnt lgkmcnt(0)
	s_nop 0
	s_nop 0
	s_nop 0
	s_nop 0
	s_nop 0
	s_nop 0
	s_nop 0
	s_waitcnt lgkmcnt(0)
	s_nop 0
	s_nop 0
	s_waitcnt lgkmcnt(0)
	s_nop 0
	s_nop 0
	v_mov_b32_e32 v136, v252
	v_lshlrev_b64 v[128:129], 11, v[134:135]
	v_lshl_add_u64 v[134:135], s[44:45], 0, v[128:129]
	v_lshl_add_u64 v[134:135], v[134:135], 0, v[192:193]
	v_pk_mul_f32 v[128:129], v[44:45], v[136:137] op_sel_hi:[1,0]
	v_pk_mul_f32 v[130:131], v[46:47], v[136:137] op_sel_hi:[1,0]
	v_pk_mul_f32 v[138:139], v[40:41], v[136:137] op_sel_hi:[1,0]
	v_pk_mul_f32 v[140:141], v[42:43], v[136:137] op_sel_hi:[1,0]
	v_pk_mul_f32 v[130:131], v[130:131], s[2:3] op_sel_hi:[1,0]
	v_pk_mul_f32 v[128:129], v[128:129], s[2:3] op_sel_hi:[1,0]
	v_pk_mul_f32 v[140:141], v[140:141], s[2:3] op_sel_hi:[1,0]
	v_pk_mul_f32 v[138:139], v[138:139], s[2:3] op_sel_hi:[1,0]
	v_cvt_pk_bf16_f32 v128, v128, v129
	v_cvt_pk_bf16_f32 v129, v130, v131
	v_cvt_pk_bf16_f32 v130, v138, v139
	v_cvt_pk_bf16_f32 v131, v140, v141
	global_store_dwordx4 v[134:135], v[128:131], off offset:1024
	v_pk_mul_f32 v[138:139], v[104:105], v[136:137] op_sel_hi:[1,0]
	s_nop 0
	v_pk_mul_f32 v[128:129], v[108:109], v[136:137] op_sel_hi:[1,0]
	v_pk_mul_f32 v[130:131], v[110:111], v[136:137] op_sel_hi:[1,0]
	v_pk_mul_f32 v[136:137], v[106:107], v[136:137] op_sel_hi:[1,0]
	v_pk_mul_f32 v[130:131], v[130:131], s[2:3] op_sel_hi:[1,0]
	v_pk_mul_f32 v[128:129], v[128:129], s[2:3] op_sel_hi:[1,0]
	v_pk_mul_f32 v[136:137], v[136:137], s[2:3] op_sel_hi:[1,0]
	v_pk_mul_f32 v[138:139], v[138:139], s[2:3] op_sel_hi:[1,0]
	v_cvt_pk_bf16_f32 v128, v128, v129
	v_cvt_pk_bf16_f32 v129, v130, v131
	v_cvt_pk_bf16_f32 v130, v138, v139
	v_cvt_pk_bf16_f32 v131, v136, v137
	global_store_dwordx4 v[134:135], v[128:131], off offset:1280
	v_or_b32_e32 v134, 48, v166
	v_ashrrev_i32_e32 v135, 31, v134
	v_lshlrev_b64 v[128:129], 6, v[134:135]
	v_lshl_add_u64 v[128:129], v[160:161], 0, v[128:129]
	s_nop 0
	s_waitcnt lgkmcnt(0)
; __device__ __forceinline__ float silu_f(float x) { return x * __builtin_amdgcn_rcpf(1.f + __expf(-x)); }
; __device__ __forceinline__ v4u pack8(const f32x4 a, const f32x4 b) { v4u w; w.x = cvt_pk_bf16(a[0], a[1]); w.y = cvt_pk_bf16(a[2], a[3]); w.z = cvt_pk_bf16(b[0], b[1]); w.w = cvt_pk_bf16(b[2], b[3]); return w; }
;     __device__ __forceinline__ void operator()(const f32x4 (&acc)[2][2][4][2], const pg8::Unit& u, int wr, int wc, int fr, int fq) const {
;     ...
;         if (grp == 0) { WIN_LOOP( _Pragma("unroll") for (int i = 0; i < 4; ++i) { a[i] = silu_f(a[i]); b[i] = silu_f(b[i]); } *(v4u*)(QO + (size_t)row * DM + c) = pack8(a, b); ) }
;         else if (grp == 3) { WIN_LOOP( _Pragma("unroll") for (int i = 0; i < 4; ++i) { a[i] = silu_f(a[i]); b[i] = silu_f(b[i]); } *(v4u*)(GH + (size_t)row * 512 + c) = pack8(a, b); ) }
;         else if (grp == 1) {
;             f32x4 l0[2], l1[2];
; #pragma unroll
;             for (int bj = 0; bj < 2; ++bj) { l0[bj] = *(const f32x4*)(lb + cb + bj * 128); l1[bj] = *(const f32x4*)(lb + cb + bj * 128 + 4); }
;             WIN_LOOP( _Pragma("unroll") for (int i = 0; i < 4; ++i) { const float s0 = fminf(a[i], 0.f) - __logf(1.f + __expf(-fabsf(a[i]))), s1 = fminf(b[i], 0.f) - __logf(1.f + __expf(-fabsf(b[i]))); const float la = l0[bj][i], lbv = l1[bj][i];
;                     a[i] = la > 0.f ? __logf(la + (1.f - la) * __expf(s0)) : s0; b[i] = lbv > 0.f ? __logf(lbv + (1.f - lbv) * __expf(s1)) : s1; }
;                 *(f32x4*)(LF + (size_t)row * 512 + c) = a; *(f32x4*)(LF + (size_t)row * 512 + c + 4) = b; __builtin_amdgcn_sched_barrier(0); ) }
;         else if (grp == 2) { WIN_LOOP( *(v4u*)(VH + (size_t)row * 512 + c) = pack8(a, b); ) }
;         else if (grp == 4) { WIN_LOOP( *(v4u*)(QO + (size_t)row * DM + 512 + c) = pack8(a * C2Q, b * C2Q); ) }
	s_nop 0
	s_nop 0
	s_nop 0
	s_nop 0
	s_nop 0
	s_nop 0
	s_nop 0
	s_waitcnt lgkmcnt(0)
	s_nop 0
	s_nop 0
	s_waitcnt lgkmcnt(0)
	s_nop 0
	s_nop 0
	v_mov_b32_e32 v136, v253
	v_lshlrev_b64 v[128:129], 11, v[134:135]
	v_lshl_add_u64 v[134:135], s[44:45], 0, v[128:129]
	v_lshl_add_u64 v[134:135], v[134:135], 0, v[192:193]
	v_pk_mul_f32 v[128:129], v[36:37], v[136:137] op_sel_hi:[1,0]
	v_pk_mul_f32 v[130:131], v[38:39], v[136:137] op_sel_hi:[1,0]
	v_pk_mul_f32 v[138:139], v[32:33], v[136:137] op_sel_hi:[1,0]
	v_pk_mul_f32 v[140:141], v[34:35], v[136:137] op_sel_hi:[1,0]
	v_pk_mul_f32 v[130:131], v[130:131], s[2:3] op_sel_hi:[1,0]
	v_pk_mul_f32 v[128:129], v[128:129], s[2:3] op_sel_hi:[1,0]
	v_pk_mul_f32 v[140:141], v[140:141], s[2:3] op_sel_hi:[1,0]
	v_pk_mul_f32 v[138:139], v[138:139], s[2:3] op_sel_hi:[1,0]
	v_cvt_pk_bf16_f32 v128, v128, v129
	v_cvt_pk_bf16_f32 v129, v130, v131
	v_cvt_pk_bf16_f32 v130, v138, v139
	v_cvt_pk_bf16_f32 v131, v140, v141
	global_store_dwordx4 v[134:135], v[128:131], off offset:1024
	v_pk_mul_f32 v[138:139], v[96:97], v[136:137] op_sel_hi:[1,0]
	s_nop 0
	v_pk_mul_f32 v[128:129], v[100:101], v[136:137] op_sel_hi:[1,0]
	v_pk_mul_f32 v[130:131], v[102:103], v[136:137] op_sel_hi:[1,0]
	v_pk_mul_f32 v[136:137], v[98:99], v[136:137] op_sel_hi:[1,0]
	v_pk_mul_f32 v[130:131], v[130:131], s[2:3] op_sel_hi:[1,0]
	v_pk_mul_f32 v[128:129], v[128:129], s[2:3] op_sel_hi:[1,0]
	v_pk_mul_f32 v[136:137], v[136:137], s[2:3] op_sel_hi:[1,0]
	v_pk_mul_f32 v[138:139], v[138:139], s[2:3] op_sel_hi:[1,0]
	v_cvt_pk_bf16_f32 v128, v128, v129
	v_cvt_pk_bf16_f32 v129, v130, v131
	v_cvt_pk_bf16_f32 v130, v138, v139
	v_cvt_pk_bf16_f32 v131, v136, v137
	global_store_dwordx4 v[134:135], v[128:131], off offset:1280
	s_nop 1
	v_add_u32_e32 v128, 0x80, v166
	v_ashrrev_i32_e32 v129, 31, v128
	v_lshlrev_b64 v[130:131], 6, v[128:129]
	v_lshl_add_u64 v[130:131], v[160:161], 0, v[130:131]
	s_nop 0
	v_lshlrev_b64 v[128:129], 11, v[128:129]
	s_waitcnt lgkmcnt(0)
	s_nop 0
	s_nop 0
	s_nop 0
	s_nop 0
	v_lshl_add_u64 v[136:137], s[44:45], 0, v[128:129]
	s_nop 0
	s_nop 0
	v_lshl_add_u64 v[136:137], v[136:137], 0, v[192:193]
	s_waitcnt lgkmcnt(0)
	s_nop 0
	s_nop 0
	s_waitcnt lgkmcnt(0)
	s_nop 0
	s_nop 0
	v_mov_b32_e32 v134, v254
	s_nop 0
	v_pk_mul_f32 v[128:129], v[28:29], v[134:135] op_sel_hi:[1,0]
	v_pk_mul_f32 v[130:131], v[30:31], v[134:135] op_sel_hi:[1,0]
	v_pk_mul_f32 v[138:139], v[24:25], v[134:135] op_sel_hi:[1,0]
	v_pk_mul_f32 v[140:141], v[26:27], v[134:135] op_sel_hi:[1,0]
	v_pk_mul_f32 v[130:131], v[130:131], s[2:3] op_sel_hi:[1,0]
	v_pk_mul_f32 v[128:129], v[128:129], s[2:3] op_sel_hi:[1,0]
	v_pk_mul_f32 v[140:141], v[140:141], s[2:3] op_sel_hi:[1,0]
	v_pk_mul_f32 v[138:139], v[138:139], s[2:3] op_sel_hi:[1,0]
	v_cvt_pk_bf16_f32 v128, v128, v129
	v_cvt_pk_bf16_f32 v129, v130, v131
	v_cvt_pk_bf16_f32 v130, v138, v139
	v_cvt_pk_bf16_f32 v131, v140, v141
	global_store_dwordx4 v[136:137], v[128:131], off offset:1024
	v_pk_mul_f32 v[138:139], v[88:89], v[134:135] op_sel_hi:[1,0]
	s_nop 0
	v_pk_mul_f32 v[128:129], v[92:93], v[134:135] op_sel_hi:[1,0]
	v_pk_mul_f32 v[130:131], v[94:95], v[134:135] op_sel_hi:[1,0]
	v_pk_mul_f32 v[134:135], v[90:91], v[134:135] op_sel_hi:[1,0]
	v_pk_mul_f32 v[130:131], v[130:131], s[2:3] op_sel_hi:[1,0]
	v_pk_mul_f32 v[128:129], v[128:129], s[2:3] op_sel_hi:[1,0]
	v_pk_mul_f32 v[134:135], v[134:135], s[2:3] op_sel_hi:[1,0]
	v_pk_mul_f32 v[138:139], v[138:139], s[2:3] op_sel_hi:[1,0]
	v_cvt_pk_bf16_f32 v128, v128, v129
	v_cvt_pk_bf16_f32 v129, v130, v131
	v_cvt_pk_bf16_f32 v131, v134, v135
	v_add_u32_e32 v134, 0x90, v166
	v_cvt_pk_bf16_f32 v130, v138, v139
	v_ashrrev_i32_e32 v135, 31, v134
	global_store_dwordx4 v[136:137], v[128:131], off offset:1280
	s_nop 1
	v_lshlrev_b64 v[128:129], 6, v[134:135]
	v_lshl_add_u64 v[128:129], v[160:161], 0, v[128:129]
	s_nop 0
	s_waitcnt lgkmcnt(0)
	s_nop 0
	s_nop 0
	s_nop 0
	s_nop 0
	s_nop 0
	s_nop 0
	s_nop 0
	s_waitcnt lgkmcnt(0)
	s_nop 0
	s_nop 0
	s_waitcnt lgkmcnt(0)
; __device__ __forceinline__ float silu_f(float x) { return x * __builtin_amdgcn_rcpf(1.f + __expf(-x)); }
; __device__ __forceinline__ v4u pack8(const f32x4 a, const f32x4 b) { v4u w; w.x = cvt_pk_bf16(a[0], a[1]); w.y = cvt_pk_bf16(a[2], a[3]); w.z = cvt_pk_bf16(b[0], b[1]); w.w = cvt_pk_bf16(b[2], b[3]); return w; }
;     __device__ __forceinline__ void operator()(const f32x4 (&acc)[2][2][4][2], const pg8::Unit& u, int wr, int wc, int fr, int fq) const {
;     ...
;         if (grp == 0) { WIN_LOOP( _Pragma("unroll") for (int i = 0; i < 4; ++i) { a[i] = silu_f(a[i]); b[i] = silu_f(b[i]); } *(v4u*)(QO + (size_t)row * DM + c) = pack8(a, b); ) }
;         else if (grp == 3) { WIN_LOOP( _Pragma("unroll") for (int i = 0; i < 4; ++i) { a[i] = silu_f(a[i]); b[i] = silu_f(b[i]); } *(v4u*)(GH + (size_t)row * 512 + c) = pack8(a, b); ) }
;         else if (grp == 1) {
;             f32x4 l0[2], l1[2];
; #pragma unroll
;             for (int bj = 0; bj < 2; ++bj) { l0[bj] = *(const f32x4*)(lb + cb + bj * 128); l1[bj] = *(const f32x4*)(lb + cb + bj * 128 + 4); }
;             WIN_LOOP( _Pragma("unroll") for (int i = 0; i < 4; ++i) { const float s0 = fminf(a[i], 0.f) - __logf(1.f + __expf(-fabsf(a[i]))), s1 = fminf(b[i], 0.f) - __logf(1.f + __expf(-fabsf(b[i]))); const float la = l0[bj][i], lbv = l1[bj][i];
;                     a[i] = la > 0.f ? __logf(la + (1.f - la) * __expf(s0)) : s0; b[i] = lbv > 0.f ? __logf(lbv + (1.f - lbv) * __expf(s1)) : s1; }
;                 *(f32x4*)(LF + (size_t)row * 512 + c) = a; *(f32x4*)(LF + (size_t)row * 512 + c + 4) = b; __builtin_amdgcn_sched_barrier(0); ) }
;         else if (grp == 2) { WIN_LOOP( *(v4u*)(VH + (size_t)row * 512 + c) = pack8(a, b); ) }
;         else if (grp == 4) { WIN_LOOP( *(v4u*)(QO + (size_t)row * DM + 512 + c) = pack8(a * C2Q, b * C2Q); ) }
	s_nop 0
	s_nop 0
	v_mov_b32_e32 v136, v240
	v_lshlrev_b64 v[128:129], 11, v[134:135]
	v_lshl_add_u64 v[134:135], s[44:45], 0, v[128:129]
	v_lshl_add_u64 v[134:135], v[134:135], 0, v[192:193]
	v_pk_mul_f32 v[128:129], v[20:21], v[136:137] op_sel_hi:[1,0]
	v_pk_mul_f32 v[130:131], v[22:23], v[136:137] op_sel_hi:[1,0]
	v_pk_mul_f32 v[138:139], v[16:17], v[136:137] op_sel_hi:[1,0]
	v_pk_mul_f32 v[140:141], v[18:19], v[136:137] op_sel_hi:[1,0]
	v_pk_mul_f32 v[130:131], v[130:131], s[2:3] op_sel_hi:[1,0]
	v_pk_mul_f32 v[128:129], v[128:129], s[2:3] op_sel_hi:[1,0]
	v_pk_mul_f32 v[140:141], v[140:141], s[2:3] op_sel_hi:[1,0]
	v_pk_mul_f32 v[138:139], v[138:139], s[2:3] op_sel_hi:[1,0]
	v_cvt_pk_bf16_f32 v128, v128, v129
	v_cvt_pk_bf16_f32 v129, v130, v131
	v_cvt_pk_bf16_f32 v130, v138, v139
	v_cvt_pk_bf16_f32 v131, v140, v141
	global_store_dwordx4 v[134:135], v[128:131], off offset:1024
	v_pk_mul_f32 v[138:139], v[80:81], v[136:137] op_sel_hi:[1,0]
	s_nop 0
	v_pk_mul_f32 v[128:129], v[84:85], v[136:137] op_sel_hi:[1,0]
	v_pk_mul_f32 v[130:131], v[86:87], v[136:137] op_sel_hi:[1,0]
	v_pk_mul_f32 v[136:137], v[82:83], v[136:137] op_sel_hi:[1,0]
	v_pk_mul_f32 v[130:131], v[130:131], s[2:3] op_sel_hi:[1,0]
	v_pk_mul_f32 v[128:129], v[128:129], s[2:3] op_sel_hi:[1,0]
	v_pk_mul_f32 v[136:137], v[136:137], s[2:3] op_sel_hi:[1,0]
	v_pk_mul_f32 v[138:139], v[138:139], s[2:3] op_sel_hi:[1,0]
	v_cvt_pk_bf16_f32 v128, v128, v129
	v_cvt_pk_bf16_f32 v129, v130, v131
	v_cvt_pk_bf16_f32 v130, v138, v139
	v_cvt_pk_bf16_f32 v131, v136, v137
	global_store_dwordx4 v[134:135], v[128:131], off offset:1280
	v_add_u32_e32 v134, 0xa0, v166
	v_ashrrev_i32_e32 v135, 31, v134
	v_lshlrev_b64 v[128:129], 6, v[134:135]
	v_lshl_add_u64 v[128:129], v[160:161], 0, v[128:129]
	s_nop 0
	s_waitcnt lgkmcnt(0)
	s_nop 0
	s_nop 0
	s_nop 0
	s_nop 0
	s_nop 0
	s_nop 0
	s_nop 0
	s_waitcnt lgkmcnt(0)
	s_nop 0
	s_nop 0
	s_waitcnt lgkmcnt(0)
	s_nop 0
	s_nop 0
	v_mov_b32_e32 v136, v241
	v_lshlrev_b64 v[128:129], 11, v[134:135]
	v_lshl_add_u64 v[134:135], s[44:45], 0, v[128:129]
	v_lshl_add_u64 v[134:135], v[134:135], 0, v[192:193]
	v_pk_mul_f32 v[128:129], v[12:13], v[136:137] op_sel_hi:[1,0]
	v_pk_mul_f32 v[130:131], v[14:15], v[136:137] op_sel_hi:[1,0]
	v_pk_mul_f32 v[138:139], v[8:9], v[136:137] op_sel_hi:[1,0]
	v_pk_mul_f32 v[140:141], v[10:11], v[136:137] op_sel_hi:[1,0]
	v_pk_mul_f32 v[130:131], v[130:131], s[2:3] op_sel_hi:[1,0]
	v_pk_mul_f32 v[128:129], v[128:129], s[2:3] op_sel_hi:[1,0]
	v_pk_mul_f32 v[140:141], v[140:141], s[2:3] op_sel_hi:[1,0]
	v_pk_mul_f32 v[138:139], v[138:139], s[2:3] op_sel_hi:[1,0]
	v_cvt_pk_bf16_f32 v128, v128, v129
	v_cvt_pk_bf16_f32 v129, v130, v131
	v_cvt_pk_bf16_f32 v130, v138, v139
	v_cvt_pk_bf16_f32 v131, v140, v141
	global_store_dwordx4 v[134:135], v[128:131], off offset:1024
	v_pk_mul_f32 v[138:139], v[72:73], v[136:137] op_sel_hi:[1,0]
	s_nop 0
	v_pk_mul_f32 v[128:129], v[76:77], v[136:137] op_sel_hi:[1,0]
	v_pk_mul_f32 v[130:131], v[78:79], v[136:137] op_sel_hi:[1,0]
	v_pk_mul_f32 v[136:137], v[74:75], v[136:137] op_sel_hi:[1,0]
	v_pk_mul_f32 v[130:131], v[130:131], s[2:3] op_sel_hi:[1,0]
	v_pk_mul_f32 v[128:129], v[128:129], s[2:3] op_sel_hi:[1,0]
	v_pk_mul_f32 v[136:137], v[136:137], s[2:3] op_sel_hi:[1,0]
	v_pk_mul_f32 v[138:139], v[138:139], s[2:3] op_sel_hi:[1,0]
	v_cvt_pk_bf16_f32 v128, v128, v129
	v_cvt_pk_bf16_f32 v129, v130, v131
	v_cvt_pk_bf16_f32 v130, v138, v139
	v_cvt_pk_bf16_f32 v131, v136, v137
	global_store_dwordx4 v[134:135], v[128:131], off offset:1280
	v_add_u32_e32 v134, 0xb0, v166
	v_ashrrev_i32_e32 v135, 31, v134
	v_lshlrev_b64 v[128:129], 6, v[134:135]
	v_lshl_add_u64 v[128:129], v[160:161], 0, v[128:129]
	s_nop 0
	s_waitcnt lgkmcnt(0)
	s_nop 0
	s_nop 0
	s_nop 0
	s_nop 0
	s_nop 0
	s_nop 0
	s_nop 0
	s_waitcnt lgkmcnt(0)
	s_nop 0
	s_nop 0
	s_waitcnt lgkmcnt(0)
	s_nop 0
	s_nop 0
	v_mov_b32_e32 v132, v245
	v_lshlrev_b64 v[128:129], 11, v[134:135]
	v_lshl_add_u64 v[134:135], s[44:45], 0, v[128:129]
	v_lshl_add_u64 v[134:135], v[134:135], 0, v[192:193]
	v_pk_mul_f32 v[128:129], v[4:5], v[132:133] op_sel_hi:[1,0]
	v_pk_mul_f32 v[130:131], v[6:7], v[132:133] op_sel_hi:[1,0]
	v_pk_mul_f32 v[136:137], v[0:1], v[132:133] op_sel_hi:[1,0]
	v_pk_mul_f32 v[138:139], v[2:3], v[132:133] op_sel_hi:[1,0]
	v_pk_mul_f32 v[130:131], v[130:131], s[2:3] op_sel_hi:[1,0]
	v_pk_mul_f32 v[128:129], v[128:129], s[2:3] op_sel_hi:[1,0]
	v_pk_mul_f32 v[138:139], v[138:139], s[2:3] op_sel_hi:[1,0]
	v_pk_mul_f32 v[136:137], v[136:137], s[2:3] op_sel_hi:[1,0]
	v_cvt_pk_bf16_f32 v128, v128, v129
	v_cvt_pk_bf16_f32 v129, v130, v131
	v_cvt_pk_bf16_f32 v130, v136, v137
	v_cvt_pk_bf16_f32 v131, v138, v139
	global_store_dwordx4 v[134:135], v[128:131], off offset:1024
	v_pk_mul_f32 v[136:137], v[64:65], v[132:133] op_sel_hi:[1,0]
	s_nop 0
	v_pk_mul_f32 v[128:129], v[68:69], v[132:133] op_sel_hi:[1,0]
	v_pk_mul_f32 v[130:131], v[70:71], v[132:133] op_sel_hi:[1,0]
	v_pk_mul_f32 v[132:133], v[66:67], v[132:133] op_sel_hi:[1,0]
	v_pk_mul_f32 v[130:131], v[130:131], s[2:3] op_sel_hi:[1,0]
	v_pk_mul_f32 v[128:129], v[128:129], s[2:3] op_sel_hi:[1,0]
	v_pk_mul_f32 v[132:133], v[132:133], s[2:3] op_sel_hi:[1,0]
	v_pk_mul_f32 v[136:137], v[136:137], s[2:3] op_sel_hi:[1,0]
	v_cvt_pk_bf16_f32 v128, v128, v129
	v_cvt_pk_bf16_f32 v129, v130, v131
	v_cvt_pk_bf16_f32 v130, v136, v137
	v_cvt_pk_bf16_f32 v131, v132, v133
	global_store_dwordx4 v[134:135], v[128:131], off offset:1280

; __device__ __forceinline__ float silu_f(float x) { return x * __builtin_amdgcn_rcpf(1.f + __expf(-x)); }
; __device__ __forceinline__ v4u pack8(const f32x4 a, const f32x4 b) { v4u w; w.x = cvt_pk_bf16(a[0], a[1]); w.y = cvt_pk_bf16(a[2], a[3]); w.z = cvt_pk_bf16(b[0], b[1]); w.w = cvt_pk_bf16(b[2], b[3]); return w; }
;     __device__ __forceinline__ void operator()(const f32x4 (&acc)[2][2][4][2], const pg8::Unit& u, int wr, int wc, int fr, int fq) const {
;     ...
;         if (grp == 0) { WIN_LOOP( _Pragma("unroll") for (int i = 0; i < 4; ++i) { a[i] = silu_f(a[i]); b[i] = silu_f(b[i]); } *(v4u*)(QO + (size_t)row * DM + c) = pack8(a, b); ) }
;         else if (grp == 3) { WIN_LOOP( _Pragma("unroll") for (int i = 0; i < 4; ++i) { a[i] = silu_f(a[i]); b[i] = silu_f(b[i]); } *(v4u*)(GH + (size_t)row * 512 + c) = pack8(a, b); ) }
.LBB0_404:
	s_and_b64 vcc, exec, s[12:13]
	s_cbranch_vccz .LBB0_406
	v_and_b32_e32 v129, 64, v215
	v_xor_b32_e32 v128, 16, v215
	v_add_u32_e32 v129, 64, v129
	v_cmp_lt_i32_e32 vcc, v128, v129
	v_ashrrev_i32_e32 v167, 31, v166
	v_readlane_b32 s12, v255, 39
	v_cndmask_b32_e32 v128, v215, v128, vcc
	v_lshlrev_b32_e32 v140, 2, v128
	v_xor_b32_e32 v128, 32, v215
	v_cmp_lt_i32_e32 vcc, v128, v129
	v_readlane_b32 s13, v255, 40
	v_lshlrev_b32_e32 v192, 1, v176
	v_cndmask_b32_e32 v128, v215, v128, vcc
	v_lshlrev_b32_e32 v141, 2, v128
	v_lshlrev_b64 v[128:129], 6, v[166:167]
	v_lshl_add_u64 v[128:129], v[160:161], 0, v[128:129]
	s_nop 0
	s_waitcnt lgkmcnt(0)
	s_nop 0
	s_nop 0
	s_nop 0
	s_nop 0
	s_nop 0
	s_nop 0
	s_nop 0
	s_waitcnt lgkmcnt(0)
	s_nop 0
	s_nop 0
	s_waitcnt lgkmcnt(0)
	s_nop 0
	s_nop 0
	v_mov_b32_e32 v132, v250
	v_lshlrev_b64 v[128:129], 10, v[166:167]
	v_lshl_add_u64 v[134:135], s[12:13], 0, v[128:129]
	v_lshl_add_u64 v[134:135], v[134:135], 0, v[192:193]
	v_pk_mul_f32 v[130:131], v[60:61], v[132:133] op_sel_hi:[1,0]
	v_pk_mul_f32 v[128:129], v[62:63], v[132:133] op_sel_hi:[1,0]
	v_pk_mul_f32 v[136:137], v[58:59], v[132:133] op_sel_hi:[1,0]
	v_pk_mul_f32 v[138:139], v[56:57], v[132:133] op_sel_hi:[1,0]
	v_mul_f32_e32 v133, 0xbfb8aa3b, v130
	v_exp_f32_e32 v133, v133
	s_nop 0
	v_add_f32_e32 v133, 1.0, v133
	v_rcp_f32_e32 v142, v133
	v_mul_f32_e32 v133, 0xbfb8aa3b, v138
	v_exp_f32_e32 v133, v133
	s_nop 0
	v_add_f32_e32 v133, 1.0, v133
	v_rcp_f32_e32 v144, v133
	v_mul_f32_e32 v133, 0xbfb8aa3b, v131
	v_exp_f32_e32 v133, v133
	s_nop 0
	v_add_f32_e32 v133, 1.0, v133
	v_rcp_f32_e32 v143, v133
	v_mul_f32_e32 v133, 0xbfb8aa3b, v139
	v_exp_f32_e32 v133, v133
	v_pk_mul_f32 v[130:131], v[130:131], v[142:143]
	v_add_f32_e32 v133, 1.0, v133
	v_rcp_f32_e32 v145, v133
	v_mul_f32_e32 v133, 0xbfb8aa3b, v128
	v_exp_f32_e32 v133, v133
	v_pk_mul_f32 v[138:139], v[138:139], v[144:145]
	v_add_f32_e32 v133, 1.0, v133
	v_rcp_f32_e32 v142, v133
	v_mul_f32_e32 v133, 0xbfb8aa3b, v136
	v_exp_f32_e32 v133, v133
	s_nop 0
	v_add_f32_e32 v133, 1.0, v133
	v_rcp_f32_e32 v144, v133
	v_mul_f32_e32 v133, 0xbfb8aa3b, v129
	v_exp_f32_e32 v133, v133
	s_nop 0
	v_add_f32_e32 v133, 1.0, v133
	v_rcp_f32_e32 v143, v133
	s_nop 0
	v_pk_mul_f32 v[142:143], v[128:129], v[142:143]
	v_mul_f32_e32 v128, 0xbfb8aa3b, v137
	v_exp_f32_e32 v128, v128
	v_cvt_pk_bf16_f32 v129, v142, v143
	v_add_f32_e32 v128, 1.0, v128
	v_rcp_f32_e32 v145, v128
	v_cvt_pk_bf16_f32 v128, v130, v131
	v_cvt_pk_bf16_f32 v130, v138, v139
	v_pk_mul_f32 v[136:137], v[136:137], v[144:145]
	s_nop 0
	v_cvt_pk_bf16_f32 v131, v136, v137
	global_store_dwordx4 v[134:135], v[128:131], off
	v_pk_mul_f32 v[136:137], v[122:123], v[132:133] op_sel_hi:[1,0]
	s_nop 0
	v_pk_mul_f32 v[128:129], v[126:127], v[132:133] op_sel_hi:[1,0]
	v_pk_mul_f32 v[130:131], v[124:125], v[132:133] op_sel_hi:[1,0]
	v_pk_mul_f32 v[132:133], v[120:121], v[132:133] op_sel_hi:[1,0]
	v_mul_f32_e32 v138, 0xbfb8aa3b, v130
	v_mul_f32_e32 v139, 0xbfb8aa3b, v132
	v_exp_f32_e32 v139, v139
	v_exp_f32_e32 v138, v138
	v_add_f32_e32 v139, 1.0, v139
	v_rcp_f32_e32 v142, v139
	v_mul_f32_e32 v139, 0xbfb8aa3b, v131
	v_exp_f32_e32 v139, v139
	v_add_f32_e32 v138, 1.0, v138
	v_rcp_f32_e32 v138, v138
	v_add_f32_e32 v139, 1.0, v139
	v_rcp_f32_e32 v139, v139
	s_nop 0
	v_pk_mul_f32 v[130:131], v[130:131], v[138:139]
	v_mul_f32_e32 v138, 0xbfb8aa3b, v133
	v_exp_f32_e32 v138, v138
	v_mul_f32_e32 v139, 0xbfb8aa3b, v136
	v_exp_f32_e32 v139, v139
	v_add_f32_e32 v138, 1.0, v138
	v_rcp_f32_e32 v143, v138
	v_add_f32_e32 v139, 1.0, v139
	v_mul_f32_e32 v138, 0xbfb8aa3b, v128
	v_exp_f32_e32 v138, v138
	v_pk_mul_f32 v[132:133], v[132:133], v[142:143]
	v_rcp_f32_e32 v142, v139
	v_mul_f32_e32 v139, 0xbfb8aa3b, v129
	v_exp_f32_e32 v139, v139
	v_add_f32_e32 v138, 1.0, v138
	v_rcp_f32_e32 v138, v138
	v_add_f32_e32 v139, 1.0, v139
	v_rcp_f32_e32 v139, v139
	s_nop 0
	v_pk_mul_f32 v[138:139], v[128:129], v[138:139]
	v_mul_f32_e32 v128, 0xbfb8aa3b, v137
	v_exp_f32_e32 v128, v128
	v_cvt_pk_bf16_f32 v129, v138, v139
	v_add_f32_e32 v128, 1.0, v128
	v_rcp_f32_e32 v143, v128
	v_cvt_pk_bf16_f32 v128, v130, v131
	v_cvt_pk_bf16_f32 v130, v132, v133
	v_pk_mul_f32 v[136:137], v[136:137], v[142:143]
	s_nop 0
	v_cvt_pk_bf16_f32 v131, v136, v137
	global_store_dwordx4 v[134:135], v[128:131], off offset:256
	v_or_b32_e32 v134, 16, v166
	v_ashrrev_i32_e32 v135, 31, v134
	v_lshlrev_b64 v[128:129], 6, v[134:135]
	v_lshl_add_u64 v[128:129], v[160:161], 0, v[128:129]
	s_nop 0
	s_waitcnt lgkmcnt(0)
	s_nop 0
	s_nop 0
	s_nop 0
	s_nop 0
	s_nop 0
	s_nop 0
	s_nop 0
	s_waitcnt lgkmcnt(0)
	s_nop 0
	s_nop 0
	s_waitcnt lgkmcnt(0)
; __device__ __forceinline__ float silu_f(float x) { return x * __builtin_amdgcn_rcpf(1.f + __expf(-x)); }
; __device__ __forceinline__ v4u pack8(const f32x4 a, const f32x4 b) { v4u w; w.x = cvt_pk_bf16(a[0], a[1]); w.y = cvt_pk_bf16(a[2], a[3]); w.z = cvt_pk_bf16(b[0], b[1]); w.w = cvt_pk_bf16(b[2], b[3]); return w; }
;     __device__ __forceinline__ void operator()(const f32x4 (&acc)[2][2][4][2], const pg8::Unit& u, int wr, int wc, int fr, int fq) const {
;     ...
;         if (grp == 0) { WIN_LOOP( _Pragma("unroll") for (int i = 0; i < 4; ++i) { a[i] = silu_f(a[i]); b[i] = silu_f(b[i]); } *(v4u*)(QO + (size_t)row * DM + c) = pack8(a, b); ) }
;         else if (grp == 3) { WIN_LOOP( _Pragma("unroll") for (int i = 0; i < 4; ++i) { a[i] = silu_f(a[i]); b[i] = silu_f(b[i]); } *(v4u*)(GH + (size_t)row * 512 + c) = pack8(a, b); ) }
	s_nop 0
	s_nop 0
	v_mov_b32_e32 v132, v251
	v_lshlrev_b64 v[128:129], 10, v[134:135]
	v_lshl_add_u64 v[128:129], s[12:13], 0, v[128:129]
	v_lshl_add_u64 v[128:129], v[128:129], 0, v[192:193]
	v_pk_mul_f32 v[134:135], v[52:53], v[132:133] op_sel_hi:[1,0]
	v_pk_mul_f32 v[130:131], v[54:55], v[132:133] op_sel_hi:[1,0]
	v_pk_mul_f32 v[136:137], v[50:51], v[132:133] op_sel_hi:[1,0]
	v_pk_mul_f32 v[138:139], v[48:49], v[132:133] op_sel_hi:[1,0]
	v_mul_f32_e32 v133, 0xbfb8aa3b, v134
	v_exp_f32_e32 v133, v133
	s_nop 0
	v_add_f32_e32 v133, 1.0, v133
	v_rcp_f32_e32 v142, v133
	v_mul_f32_e32 v133, 0xbfb8aa3b, v138
	v_exp_f32_e32 v133, v133
	s_nop 0
	v_add_f32_e32 v133, 1.0, v133
	v_rcp_f32_e32 v144, v133
	v_mul_f32_e32 v133, 0xbfb8aa3b, v135
	v_exp_f32_e32 v133, v133
	s_nop 0
	v_add_f32_e32 v133, 1.0, v133
	v_rcp_f32_e32 v143, v133
	v_mul_f32_e32 v133, 0xbfb8aa3b, v139
	v_exp_f32_e32 v133, v133
	v_pk_mul_f32 v[134:135], v[134:135], v[142:143]
	s_nop 0
	v_cvt_pk_bf16_f32 v134, v134, v135
	v_add_f32_e32 v133, 1.0, v133
	v_rcp_f32_e32 v145, v133
	v_mul_f32_e32 v133, 0xbfb8aa3b, v130
	v_exp_f32_e32 v133, v133
	v_pk_mul_f32 v[138:139], v[138:139], v[144:145]
	v_add_f32_e32 v133, 1.0, v133
	v_rcp_f32_e32 v142, v133
	v_mul_f32_e32 v133, 0xbfb8aa3b, v136
	v_exp_f32_e32 v133, v133
	s_nop 0
	v_add_f32_e32 v133, 1.0, v133
	v_rcp_f32_e32 v144, v133
	v_mul_f32_e32 v133, 0xbfb8aa3b, v131
	v_exp_f32_e32 v133, v133
	s_nop 0
	v_add_f32_e32 v133, 1.0, v133
	v_rcp_f32_e32 v143, v133
	v_mul_f32_e32 v133, 0xbfb8aa3b, v137
	v_exp_f32_e32 v133, v133
	v_pk_mul_f32 v[130:131], v[130:131], v[142:143]
	s_nop 0
	v_cvt_pk_bf16_f32 v135, v130, v131
	v_add_f32_e32 v133, 1.0, v133
	v_rcp_f32_e32 v145, v133
	v_pk_mul_f32 v[130:131], v[114:115], v[132:133] op_sel_hi:[1,0]
	v_pk_mul_f32 v[142:143], v[136:137], v[144:145]
	v_cvt_pk_bf16_f32 v136, v138, v139
	v_cvt_pk_bf16_f32 v137, v142, v143
	global_store_dwordx4 v[128:129], v[134:137], off
	v_pk_mul_f32 v[138:139], v[118:119], v[132:133] op_sel_hi:[1,0]
	s_nop 0
	v_pk_mul_f32 v[136:137], v[112:113], v[132:133] op_sel_hi:[1,0]
	v_pk_mul_f32 v[134:135], v[116:117], v[132:133] op_sel_hi:[1,0]
	v_mul_f32_e32 v133, 0xbfb8aa3b, v136
	v_exp_f32_e32 v133, v133
	v_mul_f32_e32 v132, 0xbfb8aa3b, v134
	v_exp_f32_e32 v132, v132
	v_add_f32_e32 v133, 1.0, v133
	v_rcp_f32_e32 v142, v133
	v_mul_f32_e32 v133, 0xbfb8aa3b, v135
	v_exp_f32_e32 v133, v133
	v_add_f32_e32 v132, 1.0, v132
	v_rcp_f32_e32 v132, v132
	v_add_f32_e32 v133, 1.0, v133
	v_rcp_f32_e32 v133, v133
	s_nop 0
	v_pk_mul_f32 v[132:133], v[134:135], v[132:133]
	v_mul_f32_e32 v134, 0xbfb8aa3b, v137
	v_exp_f32_e32 v134, v134
	s_nop 0
	v_add_f32_e32 v134, 1.0, v134
	v_rcp_f32_e32 v143, v134
	s_nop 0
	v_pk_mul_f32 v[134:135], v[136:137], v[142:143]
	v_mul_f32_e32 v136, 0xbfb8aa3b, v138
	v_mul_f32_e32 v137, 0xbfb8aa3b, v139
	v_exp_f32_e32 v136, v136
	v_exp_f32_e32 v137, v137
	v_add_f32_e32 v136, 1.0, v136
	v_add_f32_e32 v137, 1.0, v137
	v_rcp_f32_e32 v142, v136
	v_mul_f32_e32 v136, 0xbfb8aa3b, v130
	v_rcp_f32_e32 v143, v137
	v_mul_f32_e32 v137, 0xbfb8aa3b, v131
	v_exp_f32_e32 v136, v136
	v_exp_f32_e32 v137, v137
	v_pk_mul_f32 v[138:139], v[138:139], v[142:143]
	v_add_f32_e32 v136, 1.0, v136
	v_add_f32_e32 v137, 1.0, v137
	v_rcp_f32_e32 v136, v136
	v_rcp_f32_e32 v137, v137
	s_nop 0
	v_pk_mul_f32 v[136:137], v[130:131], v[136:137]
	v_cvt_pk_bf16_f32 v130, v132, v133
	v_cvt_pk_bf16_f32 v131, v138, v139
	v_cvt_pk_bf16_f32 v132, v134, v135
	v_cvt_pk_bf16_f32 v133, v136, v137
	global_store_dwordx4 v[128:129], v[130:133], off offset:256
	s_nop 1
	v_or_b32_e32 v132, 32, v166
	v_ashrrev_i32_e32 v133, 31, v132
	v_lshlrev_b64 v[128:129], 6, v[132:133]
	v_lshl_add_u64 v[128:129], v[160:161], 0, v[128:129]
	s_nop 0
	s_waitcnt lgkmcnt(0)
	s_nop 0
	s_nop 0
	s_nop 0
	s_nop 0
	s_nop 0
	s_nop 0
	s_nop 0
	s_waitcnt lgkmcnt(0)
	s_nop 0
	s_nop 0
	s_waitcnt lgkmcnt(0)
	s_nop 0
	s_nop 0
	v_mov_b32_e32 v134, v252
	v_lshlrev_b64 v[128:129], 10, v[132:133]
	v_lshl_add_u64 v[128:129], s[12:13], 0, v[128:129]
	v_lshl_add_u64 v[128:129], v[128:129], 0, v[192:193]
	v_pk_mul_f32 v[132:133], v[44:45], v[134:135] op_sel_hi:[1,0]
	v_pk_mul_f32 v[130:131], v[46:47], v[134:135] op_sel_hi:[1,0]
	v_pk_mul_f32 v[136:137], v[42:43], v[134:135] op_sel_hi:[1,0]
	v_pk_mul_f32 v[138:139], v[40:41], v[134:135] op_sel_hi:[1,0]
	v_mul_f32_e32 v135, 0xbfb8aa3b, v132
	v_exp_f32_e32 v135, v135
	s_nop 0
	v_add_f32_e32 v135, 1.0, v135
	v_rcp_f32_e32 v142, v135
	v_mul_f32_e32 v135, 0xbfb8aa3b, v138
	v_exp_f32_e32 v135, v135
	s_nop 0
	v_add_f32_e32 v135, 1.0, v135
	v_rcp_f32_e32 v144, v135
	v_mul_f32_e32 v135, 0xbfb8aa3b, v133
	v_exp_f32_e32 v135, v135
	s_nop 0
	v_add_f32_e32 v135, 1.0, v135
	v_rcp_f32_e32 v143, v135
	v_mul_f32_e32 v135, 0xbfb8aa3b, v139
	v_exp_f32_e32 v135, v135
	v_pk_mul_f32 v[132:133], v[132:133], v[142:143]
	v_add_f32_e32 v135, 1.0, v135
	v_rcp_f32_e32 v145, v135
	v_mul_f32_e32 v135, 0xbfb8aa3b, v130
	v_exp_f32_e32 v135, v135
	v_pk_mul_f32 v[138:139], v[138:139], v[144:145]
	v_add_f32_e32 v135, 1.0, v135
	v_rcp_f32_e32 v142, v135
	v_mul_f32_e32 v135, 0xbfb8aa3b, v136
	v_exp_f32_e32 v135, v135
	s_nop 0
	v_add_f32_e32 v135, 1.0, v135
	v_rcp_f32_e32 v144, v135
	v_mul_f32_e32 v135, 0xbfb8aa3b, v131
	v_exp_f32_e32 v135, v135
	s_nop 0
	v_add_f32_e32 v135, 1.0, v135
	v_rcp_f32_e32 v143, v135
	s_nop 0
	v_pk_mul_f32 v[142:143], v[130:131], v[142:143]
	v_mul_f32_e32 v130, 0xbfb8aa3b, v137
	v_exp_f32_e32 v130, v130
	v_cvt_pk_bf16_f32 v131, v142, v143
	v_add_f32_e32 v130, 1.0, v130
	v_rcp_f32_e32 v145, v130
	v_cvt_pk_bf16_f32 v130, v132, v133
	v_cvt_pk_bf16_f32 v132, v138, v139
	v_pk_mul_f32 v[138:139], v[104:105], v[134:135] op_sel_hi:[1,0]
; __device__ __forceinline__ float silu_f(float x) { return x * __builtin_amdgcn_rcpf(1.f + __expf(-x)); }
; __device__ __forceinline__ v4u pack8(const f32x4 a, const f32x4 b) { v4u w; w.x = cvt_pk_bf16(a[0], a[1]); w.y = cvt_pk_bf16(a[2], a[3]); w.z = cvt_pk_bf16(b[0], b[1]); w.w = cvt_pk_bf16(b[2], b[3]); return w; }
;     __device__ __forceinline__ void operator()(const f32x4 (&acc)[2][2][4][2], const pg8::Unit& u, int wr, int wc, int fr, int fq) const {
;     ...
;         if (grp == 0) { WIN_LOOP( _Pragma("unroll") for (int i = 0; i < 4; ++i) { a[i] = silu_f(a[i]); b[i] = silu_f(b[i]); } *(v4u*)(QO + (size_t)row * DM + c) = pack8(a, b); ) }
;         else if (grp == 3) { WIN_LOOP( _Pragma("unroll") for (int i = 0; i < 4; ++i) { a[i] = silu_f(a[i]); b[i] = silu_f(b[i]); } *(v4u*)(GH + (size_t)row * 512 + c) = pack8(a, b); ) }
	v_pk_mul_f32 v[136:137], v[136:137], v[144:145]
	s_nop 0
	v_cvt_pk_bf16_f32 v133, v136, v137
	global_store_dwordx4 v[128:129], v[130:133], off
	v_pk_mul_f32 v[136:137], v[108:109], v[134:135] op_sel_hi:[1,0]
	s_nop 0
	v_pk_mul_f32 v[132:133], v[110:111], v[134:135] op_sel_hi:[1,0]
	v_pk_mul_f32 v[130:131], v[106:107], v[134:135] op_sel_hi:[1,0]
	v_mul_f32_e32 v135, 0xbfb8aa3b, v138
	v_exp_f32_e32 v135, v135
	v_mul_f32_e32 v134, 0xbfb8aa3b, v136
	v_exp_f32_e32 v134, v134
	v_add_f32_e32 v135, 1.0, v135
	v_rcp_f32_e32 v142, v135
	v_mul_f32_e32 v135, 0xbfb8aa3b, v137
	v_exp_f32_e32 v135, v135
	v_add_f32_e32 v134, 1.0, v134
	v_rcp_f32_e32 v134, v134
	v_add_f32_e32 v135, 1.0, v135
	v_rcp_f32_e32 v135, v135
	s_nop 0
	v_pk_mul_f32 v[134:135], v[136:137], v[134:135]
	v_mul_f32_e32 v136, 0xbfb8aa3b, v139
	v_exp_f32_e32 v136, v136
	s_nop 0
	v_add_f32_e32 v136, 1.0, v136
	v_rcp_f32_e32 v143, v136
	s_nop 0
	v_pk_mul_f32 v[136:137], v[138:139], v[142:143]
	v_mul_f32_e32 v138, 0xbfb8aa3b, v132
	v_mul_f32_e32 v139, 0xbfb8aa3b, v133
	v_exp_f32_e32 v138, v138
	v_exp_f32_e32 v139, v139
	v_add_f32_e32 v138, 1.0, v138
	v_add_f32_e32 v139, 1.0, v139
	v_rcp_f32_e32 v142, v138
	v_mul_f32_e32 v138, 0xbfb8aa3b, v130
	v_rcp_f32_e32 v143, v139
	v_mul_f32_e32 v139, 0xbfb8aa3b, v131
	v_exp_f32_e32 v138, v138
	v_exp_f32_e32 v139, v139
	v_pk_mul_f32 v[132:133], v[132:133], v[142:143]
	v_add_f32_e32 v138, 1.0, v138
	v_add_f32_e32 v139, 1.0, v139
	v_rcp_f32_e32 v138, v138
	v_rcp_f32_e32 v139, v139
	s_nop 0
	v_pk_mul_f32 v[138:139], v[130:131], v[138:139]
	v_cvt_pk_bf16_f32 v130, v134, v135
	v_cvt_pk_bf16_f32 v131, v132, v133
	v_cvt_pk_bf16_f32 v132, v136, v137
	v_cvt_pk_bf16_f32 v133, v138, v139
	global_store_dwordx4 v[128:129], v[130:133], off offset:256
	s_nop 1
	v_or_b32_e32 v132, 48, v166
	v_ashrrev_i32_e32 v133, 31, v132
	v_lshlrev_b64 v[128:129], 6, v[132:133]
	v_lshl_add_u64 v[128:129], v[160:161], 0, v[128:129]
	s_nop 0
	s_waitcnt lgkmcnt(0)
	s_nop 0
	s_nop 0
	s_nop 0
	s_nop 0
	s_nop 0
	s_nop 0
	s_nop 0
	s_waitcnt lgkmcnt(0)
	s_nop 0
	s_nop 0
	s_waitcnt lgkmcnt(0)
	s_nop 0
	s_nop 0
	v_mov_b32_e32 v134, v253
	v_lshlrev_b64 v[128:129], 10, v[132:133]
	v_lshl_add_u64 v[132:133], s[12:13], 0, v[128:129]
	v_lshl_add_u64 v[132:133], v[132:133], 0, v[192:193]
	v_pk_mul_f32 v[130:131], v[36:37], v[134:135] op_sel_hi:[1,0]
	v_pk_mul_f32 v[128:129], v[38:39], v[134:135] op_sel_hi:[1,0]
	v_pk_mul_f32 v[136:137], v[34:35], v[134:135] op_sel_hi:[1,0]
	v_pk_mul_f32 v[138:139], v[32:33], v[134:135] op_sel_hi:[1,0]
	v_mul_f32_e32 v135, 0xbfb8aa3b, v130
	v_exp_f32_e32 v135, v135
	s_nop 0
	v_add_f32_e32 v135, 1.0, v135
	v_rcp_f32_e32 v142, v135
	v_mul_f32_e32 v135, 0xbfb8aa3b, v138
	v_exp_f32_e32 v135, v135
	s_nop 0
	v_add_f32_e32 v135, 1.0, v135
	v_rcp_f32_e32 v144, v135
	v_mul_f32_e32 v135, 0xbfb8aa3b, v131
	v_exp_f32_e32 v135, v135
	s_nop 0
	v_add_f32_e32 v135, 1.0, v135
	v_rcp_f32_e32 v143, v135
	v_mul_f32_e32 v135, 0xbfb8aa3b, v139
	v_exp_f32_e32 v135, v135
	v_pk_mul_f32 v[130:131], v[130:131], v[142:143]
	v_add_f32_e32 v135, 1.0, v135
	v_rcp_f32_e32 v145, v135
	v_mul_f32_e32 v135, 0xbfb8aa3b, v128
	v_exp_f32_e32 v135, v135
	v_pk_mul_f32 v[138:139], v[138:139], v[144:145]
	v_add_f32_e32 v135, 1.0, v135
	v_rcp_f32_e32 v142, v135
	v_mul_f32_e32 v135, 0xbfb8aa3b, v136
	v_exp_f32_e32 v135, v135
	s_nop 0
	v_add_f32_e32 v135, 1.0, v135
	v_rcp_f32_e32 v144, v135
	v_mul_f32_e32 v135, 0xbfb8aa3b, v129
	v_exp_f32_e32 v135, v135
	s_nop 0
	v_add_f32_e32 v135, 1.0, v135
	v_rcp_f32_e32 v143, v135
	s_nop 0
	v_pk_mul_f32 v[142:143], v[128:129], v[142:143]
	v_mul_f32_e32 v128, 0xbfb8aa3b, v137
	v_exp_f32_e32 v128, v128
	v_cvt_pk_bf16_f32 v129, v142, v143
	v_add_f32_e32 v128, 1.0, v128
	v_rcp_f32_e32 v145, v128
	v_cvt_pk_bf16_f32 v128, v130, v131
	v_cvt_pk_bf16_f32 v130, v138, v139
	v_pk_mul_f32 v[136:137], v[136:137], v[144:145]
	s_nop 0
	v_cvt_pk_bf16_f32 v131, v136, v137
	global_store_dwordx4 v[132:133], v[128:131], off
	v_pk_mul_f32 v[136:137], v[98:99], v[134:135] op_sel_hi:[1,0]
	s_nop 0
	v_pk_mul_f32 v[128:129], v[102:103], v[134:135] op_sel_hi:[1,0]
	v_pk_mul_f32 v[130:131], v[100:101], v[134:135] op_sel_hi:[1,0]
	v_pk_mul_f32 v[134:135], v[96:97], v[134:135] op_sel_hi:[1,0]
	v_mul_f32_e32 v138, 0xbfb8aa3b, v130
	v_mul_f32_e32 v139, 0xbfb8aa3b, v134
	v_exp_f32_e32 v139, v139
	v_exp_f32_e32 v138, v138
	v_add_f32_e32 v139, 1.0, v139
	v_rcp_f32_e32 v142, v139
	v_mul_f32_e32 v139, 0xbfb8aa3b, v131
	v_exp_f32_e32 v139, v139
	v_add_f32_e32 v138, 1.0, v138
	v_rcp_f32_e32 v138, v138
	v_add_f32_e32 v139, 1.0, v139
	v_rcp_f32_e32 v139, v139
	s_nop 0
	v_pk_mul_f32 v[130:131], v[130:131], v[138:139]
	v_mul_f32_e32 v138, 0xbfb8aa3b, v135
	v_exp_f32_e32 v138, v138
	v_mul_f32_e32 v139, 0xbfb8aa3b, v136
	v_exp_f32_e32 v139, v139
	v_add_f32_e32 v138, 1.0, v138
	v_rcp_f32_e32 v143, v138
	v_add_f32_e32 v139, 1.0, v139
	v_mul_f32_e32 v138, 0xbfb8aa3b, v128
	v_exp_f32_e32 v138, v138
	v_pk_mul_f32 v[134:135], v[134:135], v[142:143]
	v_rcp_f32_e32 v142, v139
	v_mul_f32_e32 v139, 0xbfb8aa3b, v129
	v_exp_f32_e32 v139, v139
	v_add_f32_e32 v138, 1.0, v138
	v_rcp_f32_e32 v138, v138
	v_add_f32_e32 v139, 1.0, v139
	v_rcp_f32_e32 v139, v139
	s_nop 0
	v_pk_mul_f32 v[138:139], v[128:129], v[138:139]
	v_mul_f32_e32 v128, 0xbfb8aa3b, v137
	v_exp_f32_e32 v128, v128
	v_cvt_pk_bf16_f32 v129, v138, v139
	v_add_f32_e32 v128, 1.0, v128
	v_rcp_f32_e32 v143, v128
	v_cvt_pk_bf16_f32 v128, v130, v131
	v_cvt_pk_bf16_f32 v130, v134, v135
	v_pk_mul_f32 v[136:137], v[136:137], v[142:143]
	s_nop 0
	v_cvt_pk_bf16_f32 v131, v136, v137
	global_store_dwordx4 v[132:133], v[128:131], off offset:256
	v_add_u32_e32 v132, 0x80, v166
	v_ashrrev_i32_e32 v133, 31, v132
	v_lshlrev_b64 v[128:129], 6, v[132:133]
	v_lshl_add_u64 v[128:129], v[160:161], 0, v[128:129]
	s_nop 0
	s_waitcnt lgkmcnt(0)
; __device__ __forceinline__ float silu_f(float x) { return x * __builtin_amdgcn_rcpf(1.f + __expf(-x)); }
; __device__ __forceinline__ v4u pack8(const f32x4 a, const f32x4 b) { v4u w; w.x = cvt_pk_bf16(a[0], a[1]); w.y = cvt_pk_bf16(a[2], a[3]); w.z = cvt_pk_bf16(b[0], b[1]); w.w = cvt_pk_bf16(b[2], b[3]); return w; }
;     __device__ __forceinline__ void operator()(const f32x4 (&acc)[2][2][4][2], const pg8::Unit& u, int wr, int wc, int fr, int fq) const {
;     ...
;         if (grp == 0) { WIN_LOOP( _Pragma("unroll") for (int i = 0; i < 4; ++i) { a[i] = silu_f(a[i]); b[i] = silu_f(b[i]); } *(v4u*)(QO + (size_t)row * DM + c) = pack8(a, b); ) }
;         else if (grp == 3) { WIN_LOOP( _Pragma("unroll") for (int i = 0; i < 4; ++i) { a[i] = silu_f(a[i]); b[i] = silu_f(b[i]); } *(v4u*)(GH + (size_t)row * 512 + c) = pack8(a, b); ) }
	s_nop 0
	s_nop 0
	s_nop 0
	s_nop 0
	s_nop 0
	s_nop 0
	s_nop 0
	s_waitcnt lgkmcnt(0)
	s_nop 0
	s_nop 0
	s_waitcnt lgkmcnt(0)
	s_nop 0
	s_nop 0
	v_mov_b32_e32 v134, v254
	v_lshlrev_b64 v[128:129], 10, v[132:133]
	v_lshl_add_u64 v[132:133], s[12:13], 0, v[128:129]
	v_lshl_add_u64 v[132:133], v[132:133], 0, v[192:193]
	v_pk_mul_f32 v[130:131], v[28:29], v[134:135] op_sel_hi:[1,0]
	v_pk_mul_f32 v[128:129], v[30:31], v[134:135] op_sel_hi:[1,0]
	v_pk_mul_f32 v[136:137], v[26:27], v[134:135] op_sel_hi:[1,0]
	v_pk_mul_f32 v[138:139], v[24:25], v[134:135] op_sel_hi:[1,0]
	v_mul_f32_e32 v135, 0xbfb8aa3b, v130
	v_exp_f32_e32 v135, v135
	s_nop 0
	v_add_f32_e32 v135, 1.0, v135
	v_rcp_f32_e32 v142, v135
	v_mul_f32_e32 v135, 0xbfb8aa3b, v138
	v_exp_f32_e32 v135, v135
	s_nop 0
	v_add_f32_e32 v135, 1.0, v135
	v_rcp_f32_e32 v144, v135
	v_mul_f32_e32 v135, 0xbfb8aa3b, v131
	v_exp_f32_e32 v135, v135
	s_nop 0
	v_add_f32_e32 v135, 1.0, v135
	v_rcp_f32_e32 v143, v135
	v_mul_f32_e32 v135, 0xbfb8aa3b, v139
	v_exp_f32_e32 v135, v135
	v_pk_mul_f32 v[130:131], v[130:131], v[142:143]
	v_add_f32_e32 v135, 1.0, v135
	v_rcp_f32_e32 v145, v135
	v_mul_f32_e32 v135, 0xbfb8aa3b, v128
	v_exp_f32_e32 v135, v135
	v_pk_mul_f32 v[138:139], v[138:139], v[144:145]
	v_add_f32_e32 v135, 1.0, v135
	v_rcp_f32_e32 v142, v135
	v_mul_f32_e32 v135, 0xbfb8aa3b, v136
	v_exp_f32_e32 v135, v135
	s_nop 0
	v_add_f32_e32 v135, 1.0, v135
	v_rcp_f32_e32 v144, v135
	v_mul_f32_e32 v135, 0xbfb8aa3b, v129
	v_exp_f32_e32 v135, v135
	s_nop 0
	v_add_f32_e32 v135, 1.0, v135
	v_rcp_f32_e32 v143, v135
	s_nop 0
	v_pk_mul_f32 v[142:143], v[128:129], v[142:143]
	v_mul_f32_e32 v128, 0xbfb8aa3b, v137
	v_exp_f32_e32 v128, v128
	v_cvt_pk_bf16_f32 v129, v142, v143
	v_add_f32_e32 v128, 1.0, v128
	v_rcp_f32_e32 v145, v128
	v_cvt_pk_bf16_f32 v128, v130, v131
	v_cvt_pk_bf16_f32 v130, v138, v139
	v_pk_mul_f32 v[136:137], v[136:137], v[144:145]
	s_nop 0
	v_cvt_pk_bf16_f32 v131, v136, v137
	global_store_dwordx4 v[132:133], v[128:131], off
	v_pk_mul_f32 v[136:137], v[90:91], v[134:135] op_sel_hi:[1,0]
	s_nop 0
	v_pk_mul_f32 v[128:129], v[94:95], v[134:135] op_sel_hi:[1,0]
	v_pk_mul_f32 v[130:131], v[92:93], v[134:135] op_sel_hi:[1,0]
	v_pk_mul_f32 v[134:135], v[88:89], v[134:135] op_sel_hi:[1,0]
	v_mul_f32_e32 v138, 0xbfb8aa3b, v130
	v_mul_f32_e32 v139, 0xbfb8aa3b, v134
	v_exp_f32_e32 v139, v139
	v_exp_f32_e32 v138, v138
	v_add_f32_e32 v139, 1.0, v139
	v_rcp_f32_e32 v142, v139
	v_mul_f32_e32 v139, 0xbfb8aa3b, v131
	v_exp_f32_e32 v139, v139
	v_add_f32_e32 v138, 1.0, v138
	v_rcp_f32_e32 v138, v138
	v_add_f32_e32 v139, 1.0, v139
	v_rcp_f32_e32 v139, v139
	s_nop 0
	v_pk_mul_f32 v[130:131], v[130:131], v[138:139]
	v_mul_f32_e32 v138, 0xbfb8aa3b, v135
	v_exp_f32_e32 v138, v138
	v_mul_f32_e32 v139, 0xbfb8aa3b, v136
	v_exp_f32_e32 v139, v139
	v_add_f32_e32 v138, 1.0, v138
	v_rcp_f32_e32 v143, v138
	v_add_f32_e32 v139, 1.0, v139
	v_mul_f32_e32 v138, 0xbfb8aa3b, v128
	v_exp_f32_e32 v138, v138
	v_pk_mul_f32 v[134:135], v[134:135], v[142:143]
	v_rcp_f32_e32 v142, v139
	v_mul_f32_e32 v139, 0xbfb8aa3b, v129
	v_exp_f32_e32 v139, v139
	v_add_f32_e32 v138, 1.0, v138
	v_rcp_f32_e32 v138, v138
	v_add_f32_e32 v139, 1.0, v139
	v_rcp_f32_e32 v139, v139
	s_nop 0
	v_pk_mul_f32 v[138:139], v[128:129], v[138:139]
	v_mul_f32_e32 v128, 0xbfb8aa3b, v137
	v_exp_f32_e32 v128, v128
	v_cvt_pk_bf16_f32 v129, v138, v139
	v_add_f32_e32 v128, 1.0, v128
	v_rcp_f32_e32 v143, v128
	v_cvt_pk_bf16_f32 v128, v130, v131
	v_cvt_pk_bf16_f32 v130, v134, v135
	v_pk_mul_f32 v[136:137], v[136:137], v[142:143]
	s_nop 0
	v_cvt_pk_bf16_f32 v131, v136, v137
	global_store_dwordx4 v[132:133], v[128:131], off offset:256
	v_add_u32_e32 v132, 0x90, v166
	v_ashrrev_i32_e32 v133, 31, v132
	v_lshlrev_b64 v[128:129], 6, v[132:133]
	v_lshl_add_u64 v[128:129], v[160:161], 0, v[128:129]
	s_nop 0
	s_waitcnt lgkmcnt(0)
	s_nop 0
	s_nop 0
	s_nop 0
	s_nop 0
	s_nop 0
	s_nop 0
	s_nop 0
	s_waitcnt lgkmcnt(0)
	s_nop 0
	s_nop 0
	s_waitcnt lgkmcnt(0)
	s_nop 0
	s_nop 0
	v_mov_b32_e32 v134, v240
	v_lshlrev_b64 v[128:129], 10, v[132:133]
	v_lshl_add_u64 v[132:133], s[12:13], 0, v[128:129]
	v_lshl_add_u64 v[132:133], v[132:133], 0, v[192:193]
	v_pk_mul_f32 v[130:131], v[20:21], v[134:135] op_sel_hi:[1,0]
	v_pk_mul_f32 v[128:129], v[22:23], v[134:135] op_sel_hi:[1,0]
	v_pk_mul_f32 v[136:137], v[18:19], v[134:135] op_sel_hi:[1,0]
	v_pk_mul_f32 v[138:139], v[16:17], v[134:135] op_sel_hi:[1,0]
	v_mul_f32_e32 v135, 0xbfb8aa3b, v130
	v_exp_f32_e32 v135, v135
	s_nop 0
	v_add_f32_e32 v135, 1.0, v135
	v_rcp_f32_e32 v142, v135
	v_mul_f32_e32 v135, 0xbfb8aa3b, v138
	v_exp_f32_e32 v135, v135
	s_nop 0
	v_add_f32_e32 v135, 1.0, v135
	v_rcp_f32_e32 v144, v135
	v_mul_f32_e32 v135, 0xbfb8aa3b, v131
	v_exp_f32_e32 v135, v135
	s_nop 0
	v_add_f32_e32 v135, 1.0, v135
	v_rcp_f32_e32 v143, v135
	v_mul_f32_e32 v135, 0xbfb8aa3b, v139
	v_exp_f32_e32 v135, v135
	v_pk_mul_f32 v[130:131], v[130:131], v[142:143]
	v_add_f32_e32 v135, 1.0, v135
	v_rcp_f32_e32 v145, v135
	v_mul_f32_e32 v135, 0xbfb8aa3b, v128
	v_exp_f32_e32 v135, v135
	v_pk_mul_f32 v[138:139], v[138:139], v[144:145]
	v_add_f32_e32 v135, 1.0, v135
	v_rcp_f32_e32 v142, v135
	v_mul_f32_e32 v135, 0xbfb8aa3b, v136
	v_exp_f32_e32 v135, v135
	s_nop 0
	v_add_f32_e32 v135, 1.0, v135
	v_rcp_f32_e32 v144, v135
	v_mul_f32_e32 v135, 0xbfb8aa3b, v129
	v_exp_f32_e32 v135, v135
	s_nop 0
	v_add_f32_e32 v135, 1.0, v135
	v_rcp_f32_e32 v143, v135
	s_nop 0
	v_pk_mul_f32 v[142:143], v[128:129], v[142:143]
	v_mul_f32_e32 v128, 0xbfb8aa3b, v137
	v_exp_f32_e32 v128, v128
	v_cvt_pk_bf16_f32 v129, v142, v143
	v_add_f32_e32 v128, 1.0, v128
	v_rcp_f32_e32 v145, v128
	v_cvt_pk_bf16_f32 v128, v130, v131
; __device__ __forceinline__ float silu_f(float x) { return x * __builtin_amdgcn_rcpf(1.f + __expf(-x)); }
; __device__ __forceinline__ v4u pack8(const f32x4 a, const f32x4 b) { v4u w; w.x = cvt_pk_bf16(a[0], a[1]); w.y = cvt_pk_bf16(a[2], a[3]); w.z = cvt_pk_bf16(b[0], b[1]); w.w = cvt_pk_bf16(b[2], b[3]); return w; }
;     __device__ __forceinline__ void operator()(const f32x4 (&acc)[2][2][4][2], const pg8::Unit& u, int wr, int wc, int fr, int fq) const {
;     ...
;         if (grp == 0) { WIN_LOOP( _Pragma("unroll") for (int i = 0; i < 4; ++i) { a[i] = silu_f(a[i]); b[i] = silu_f(b[i]); } *(v4u*)(QO + (size_t)row * DM + c) = pack8(a, b); ) }
;         else if (grp == 3) { WIN_LOOP( _Pragma("unroll") for (int i = 0; i < 4; ++i) { a[i] = silu_f(a[i]); b[i] = silu_f(b[i]); } *(v4u*)(GH + (size_t)row * 512 + c) = pack8(a, b); ) }
	v_cvt_pk_bf16_f32 v130, v138, v139
	v_pk_mul_f32 v[136:137], v[136:137], v[144:145]
	s_nop 0
	v_cvt_pk_bf16_f32 v131, v136, v137
	global_store_dwordx4 v[132:133], v[128:131], off
	v_pk_mul_f32 v[136:137], v[82:83], v[134:135] op_sel_hi:[1,0]
	s_nop 0
	v_pk_mul_f32 v[128:129], v[86:87], v[134:135] op_sel_hi:[1,0]
	v_pk_mul_f32 v[130:131], v[84:85], v[134:135] op_sel_hi:[1,0]
	v_pk_mul_f32 v[134:135], v[80:81], v[134:135] op_sel_hi:[1,0]
	v_mul_f32_e32 v138, 0xbfb8aa3b, v130
	v_mul_f32_e32 v139, 0xbfb8aa3b, v134
	v_exp_f32_e32 v139, v139
	v_exp_f32_e32 v138, v138
	v_add_f32_e32 v139, 1.0, v139
	v_rcp_f32_e32 v142, v139
	v_mul_f32_e32 v139, 0xbfb8aa3b, v131
	v_exp_f32_e32 v139, v139
	v_add_f32_e32 v138, 1.0, v138
	v_rcp_f32_e32 v138, v138
	v_add_f32_e32 v139, 1.0, v139
	v_rcp_f32_e32 v139, v139
	s_nop 0
	v_pk_mul_f32 v[130:131], v[130:131], v[138:139]
	v_mul_f32_e32 v138, 0xbfb8aa3b, v135
	v_exp_f32_e32 v138, v138
	v_mul_f32_e32 v139, 0xbfb8aa3b, v136
	v_exp_f32_e32 v139, v139
	v_add_f32_e32 v138, 1.0, v138
	v_rcp_f32_e32 v143, v138
	v_add_f32_e32 v139, 1.0, v139
	v_mul_f32_e32 v138, 0xbfb8aa3b, v128
	v_exp_f32_e32 v138, v138
	v_pk_mul_f32 v[134:135], v[134:135], v[142:143]
	v_rcp_f32_e32 v142, v139
	v_mul_f32_e32 v139, 0xbfb8aa3b, v129
	v_exp_f32_e32 v139, v139
	v_add_f32_e32 v138, 1.0, v138
	v_rcp_f32_e32 v138, v138
	v_add_f32_e32 v139, 1.0, v139
	v_rcp_f32_e32 v139, v139
	s_nop 0
	v_pk_mul_f32 v[138:139], v[128:129], v[138:139]
	v_mul_f32_e32 v128, 0xbfb8aa3b, v137
	v_exp_f32_e32 v128, v128
	v_cvt_pk_bf16_f32 v129, v138, v139
	v_add_f32_e32 v128, 1.0, v128
	v_rcp_f32_e32 v143, v128
	v_cvt_pk_bf16_f32 v128, v130, v131
	v_cvt_pk_bf16_f32 v130, v134, v135
	v_pk_mul_f32 v[136:137], v[136:137], v[142:143]
	s_nop 0
	v_cvt_pk_bf16_f32 v131, v136, v137
	global_store_dwordx4 v[132:133], v[128:131], off offset:256
	v_add_u32_e32 v132, 0xa0, v166
	v_ashrrev_i32_e32 v133, 31, v132
	v_lshlrev_b64 v[128:129], 6, v[132:133]
	v_lshl_add_u64 v[128:129], v[160:161], 0, v[128:129]
	s_nop 0
	s_waitcnt lgkmcnt(0)
	s_nop 0
	s_nop 0
	s_nop 0
	s_nop 0
	s_nop 0
	s_nop 0
	s_nop 0
	s_waitcnt lgkmcnt(0)
	s_nop 0
	s_nop 0
	s_waitcnt lgkmcnt(0)
	s_nop 0
	s_nop 0
	v_mov_b32_e32 v134, v241
	v_lshlrev_b64 v[128:129], 10, v[132:133]
	v_lshl_add_u64 v[132:133], s[12:13], 0, v[128:129]
	v_lshl_add_u64 v[132:133], v[132:133], 0, v[192:193]
	v_pk_mul_f32 v[130:131], v[12:13], v[134:135] op_sel_hi:[1,0]
	v_pk_mul_f32 v[128:129], v[14:15], v[134:135] op_sel_hi:[1,0]
	v_pk_mul_f32 v[136:137], v[10:11], v[134:135] op_sel_hi:[1,0]
	v_pk_mul_f32 v[138:139], v[8:9], v[134:135] op_sel_hi:[1,0]
	v_mul_f32_e32 v135, 0xbfb8aa3b, v130
	v_exp_f32_e32 v135, v135
	s_nop 0
	v_add_f32_e32 v135, 1.0, v135
	v_rcp_f32_e32 v142, v135
	v_mul_f32_e32 v135, 0xbfb8aa3b, v138
	v_exp_f32_e32 v135, v135
	s_nop 0
	v_add_f32_e32 v135, 1.0, v135
	v_rcp_f32_e32 v144, v135
	v_mul_f32_e32 v135, 0xbfb8aa3b, v131
	v_exp_f32_e32 v135, v135
	s_nop 0
	v_add_f32_e32 v135, 1.0, v135
	v_rcp_f32_e32 v143, v135
	v_mul_f32_e32 v135, 0xbfb8aa3b, v139
	v_exp_f32_e32 v135, v135
	v_pk_mul_f32 v[130:131], v[130:131], v[142:143]
	v_add_f32_e32 v135, 1.0, v135
	v_rcp_f32_e32 v145, v135
	v_mul_f32_e32 v135, 0xbfb8aa3b, v128
	v_exp_f32_e32 v135, v135
	v_pk_mul_f32 v[138:139], v[138:139], v[144:145]
	v_add_f32_e32 v135, 1.0, v135
	v_rcp_f32_e32 v142, v135
	v_mul_f32_e32 v135, 0xbfb8aa3b, v136
	v_exp_f32_e32 v135, v135
	s_nop 0
	v_add_f32_e32 v135, 1.0, v135
	v_rcp_f32_e32 v144, v135
	v_mul_f32_e32 v135, 0xbfb8aa3b, v129
	v_exp_f32_e32 v135, v135
	s_nop 0
	v_add_f32_e32 v135, 1.0, v135
	v_rcp_f32_e32 v143, v135
	s_nop 0
	v_pk_mul_f32 v[142:143], v[128:129], v[142:143]
	v_mul_f32_e32 v128, 0xbfb8aa3b, v137
	v_exp_f32_e32 v128, v128
	v_cvt_pk_bf16_f32 v129, v142, v143
	v_add_f32_e32 v128, 1.0, v128
	v_rcp_f32_e32 v145, v128
	v_cvt_pk_bf16_f32 v128, v130, v131
	v_cvt_pk_bf16_f32 v130, v138, v139
	v_pk_mul_f32 v[136:137], v[136:137], v[144:145]
	s_nop 0
	v_cvt_pk_bf16_f32 v131, v136, v137
	global_store_dwordx4 v[132:133], v[128:131], off
	v_pk_mul_f32 v[136:137], v[74:75], v[134:135] op_sel_hi:[1,0]
	s_nop 0
	v_pk_mul_f32 v[128:129], v[78:79], v[134:135] op_sel_hi:[1,0]
	v_pk_mul_f32 v[130:131], v[76:77], v[134:135] op_sel_hi:[1,0]
	v_pk_mul_f32 v[134:135], v[72:73], v[134:135] op_sel_hi:[1,0]
	v_mul_f32_e32 v138, 0xbfb8aa3b, v130
	v_mul_f32_e32 v139, 0xbfb8aa3b, v134
	v_exp_f32_e32 v139, v139
	v_exp_f32_e32 v138, v138
	v_add_f32_e32 v139, 1.0, v139
	v_rcp_f32_e32 v142, v139
	v_mul_f32_e32 v139, 0xbfb8aa3b, v131
	v_exp_f32_e32 v139, v139
	v_add_f32_e32 v138, 1.0, v138
	v_rcp_f32_e32 v138, v138
	v_add_f32_e32 v139, 1.0, v139
	v_rcp_f32_e32 v139, v139
	s_nop 0
	v_pk_mul_f32 v[130:131], v[130:131], v[138:139]
	v_mul_f32_e32 v138, 0xbfb8aa3b, v135
	v_exp_f32_e32 v138, v138
	v_mul_f32_e32 v139, 0xbfb8aa3b, v136
	v_exp_f32_e32 v139, v139
	v_add_f32_e32 v138, 1.0, v138
	v_rcp_f32_e32 v143, v138
	v_add_f32_e32 v139, 1.0, v139
	v_mul_f32_e32 v138, 0xbfb8aa3b, v128
	v_exp_f32_e32 v138, v138
	v_pk_mul_f32 v[134:135], v[134:135], v[142:143]
	v_rcp_f32_e32 v142, v139
	v_mul_f32_e32 v139, 0xbfb8aa3b, v129
	v_exp_f32_e32 v139, v139
	v_add_f32_e32 v138, 1.0, v138
	v_rcp_f32_e32 v138, v138
	v_add_f32_e32 v139, 1.0, v139
	v_rcp_f32_e32 v139, v139
	s_nop 0
	v_pk_mul_f32 v[138:139], v[128:129], v[138:139]
	v_mul_f32_e32 v128, 0xbfb8aa3b, v137
	v_exp_f32_e32 v128, v128
	v_cvt_pk_bf16_f32 v129, v138, v139
	v_add_f32_e32 v128, 1.0, v128
	v_rcp_f32_e32 v143, v128
	v_cvt_pk_bf16_f32 v128, v130, v131
	v_cvt_pk_bf16_f32 v130, v134, v135
	v_pk_mul_f32 v[136:137], v[136:137], v[142:143]
	s_nop 0
	v_cvt_pk_bf16_f32 v131, v136, v137
	global_store_dwordx4 v[132:133], v[128:131], off offset:256
	v_add_u32_e32 v132, 0xb0, v166
	v_ashrrev_i32_e32 v133, 31, v132
	v_lshlrev_b64 v[128:129], 6, v[132:133]
	v_lshl_add_u64 v[128:129], v[160:161], 0, v[128:129]
	s_nop 0
	s_waitcnt lgkmcnt(0)
; __device__ __forceinline__ float silu_f(float x) { return x * __builtin_amdgcn_rcpf(1.f + __expf(-x)); }
; __device__ __forceinline__ v4u pack8(const f32x4 a, const f32x4 b) { v4u w; w.x = cvt_pk_bf16(a[0], a[1]); w.y = cvt_pk_bf16(a[2], a[3]); w.z = cvt_pk_bf16(b[0], b[1]); w.w = cvt_pk_bf16(b[2], b[3]); return w; }
;     __device__ __forceinline__ void operator()(const f32x4 (&acc)[2][2][4][2], const pg8::Unit& u, int wr, int wc, int fr, int fq) const {
;     ...
;         if (grp == 0) { WIN_LOOP( _Pragma("unroll") for (int i = 0; i < 4; ++i) { a[i] = silu_f(a[i]); b[i] = silu_f(b[i]); } *(v4u*)(QO + (size_t)row * DM + c) = pack8(a, b); ) }
;         else if (grp == 3) { WIN_LOOP( _Pragma("unroll") for (int i = 0; i < 4; ++i) { a[i] = silu_f(a[i]); b[i] = silu_f(b[i]); } *(v4u*)(GH + (size_t)row * 512 + c) = pack8(a, b); ) }
	s_nop 0
	s_nop 0
	s_nop 0
	s_nop 0
	s_nop 0
	s_nop 0
	s_nop 0
	s_waitcnt lgkmcnt(0)
	s_nop 0
	s_nop 0
	s_waitcnt lgkmcnt(0)
	s_nop 0
	s_nop 0
	v_mov_b32_e32 v134, v245
	v_lshlrev_b64 v[128:129], 10, v[132:133]
	v_lshl_add_u64 v[132:133], s[12:13], 0, v[128:129]
	v_lshl_add_u64 v[132:133], v[132:133], 0, v[192:193]
	v_pk_mul_f32 v[130:131], v[4:5], v[134:135] op_sel_hi:[1,0]
	v_pk_mul_f32 v[128:129], v[6:7], v[134:135] op_sel_hi:[1,0]
	v_pk_mul_f32 v[136:137], v[2:3], v[134:135] op_sel_hi:[1,0]
	v_pk_mul_f32 v[138:139], v[0:1], v[134:135] op_sel_hi:[1,0]
	v_mul_f32_e32 v135, 0xbfb8aa3b, v130
	v_exp_f32_e32 v135, v135
	s_nop 0
	v_add_f32_e32 v135, 1.0, v135
	v_rcp_f32_e32 v140, v135
	v_mul_f32_e32 v135, 0xbfb8aa3b, v138
	v_exp_f32_e32 v135, v135
	s_nop 0
	v_add_f32_e32 v135, 1.0, v135
	v_rcp_f32_e32 v142, v135
	v_mul_f32_e32 v135, 0xbfb8aa3b, v131
	v_exp_f32_e32 v135, v135
	s_nop 0
	v_add_f32_e32 v135, 1.0, v135
	v_rcp_f32_e32 v141, v135
	v_mul_f32_e32 v135, 0xbfb8aa3b, v139
	v_exp_f32_e32 v135, v135
	v_pk_mul_f32 v[130:131], v[130:131], v[140:141]
	v_add_f32_e32 v135, 1.0, v135
	v_rcp_f32_e32 v143, v135
	v_mul_f32_e32 v135, 0xbfb8aa3b, v128
	v_exp_f32_e32 v135, v135
	v_pk_mul_f32 v[138:139], v[138:139], v[142:143]
	v_add_f32_e32 v135, 1.0, v135
	v_rcp_f32_e32 v140, v135
	v_mul_f32_e32 v135, 0xbfb8aa3b, v136
	v_exp_f32_e32 v135, v135
	s_nop 0
	v_add_f32_e32 v135, 1.0, v135
	v_rcp_f32_e32 v142, v135
	v_mul_f32_e32 v135, 0xbfb8aa3b, v129
	v_exp_f32_e32 v135, v135
	s_nop 0
	v_add_f32_e32 v135, 1.0, v135
	v_rcp_f32_e32 v141, v135
	s_nop 0
	v_pk_mul_f32 v[140:141], v[128:129], v[140:141]
	v_mul_f32_e32 v128, 0xbfb8aa3b, v137
	v_exp_f32_e32 v128, v128
	v_cvt_pk_bf16_f32 v129, v140, v141
	v_add_f32_e32 v128, 1.0, v128
	v_rcp_f32_e32 v143, v128
	v_cvt_pk_bf16_f32 v128, v130, v131
	v_cvt_pk_bf16_f32 v130, v138, v139
	v_pk_mul_f32 v[136:137], v[136:137], v[142:143]
	s_nop 0
	v_cvt_pk_bf16_f32 v131, v136, v137
	global_store_dwordx4 v[132:133], v[128:131], off
	v_pk_mul_f32 v[136:137], v[66:67], v[134:135] op_sel_hi:[1,0]
	s_nop 0
	v_pk_mul_f32 v[128:129], v[70:71], v[134:135] op_sel_hi:[1,0]
	v_pk_mul_f32 v[130:131], v[68:69], v[134:135] op_sel_hi:[1,0]
	v_pk_mul_f32 v[134:135], v[64:65], v[134:135] op_sel_hi:[1,0]
	v_mul_f32_e32 v138, 0xbfb8aa3b, v130
	v_mul_f32_e32 v139, 0xbfb8aa3b, v134
	v_exp_f32_e32 v139, v139
	v_exp_f32_e32 v138, v138
	v_add_f32_e32 v139, 1.0, v139
	v_rcp_f32_e32 v140, v139
	v_mul_f32_e32 v139, 0xbfb8aa3b, v131
	v_exp_f32_e32 v139, v139
	v_add_f32_e32 v138, 1.0, v138
	v_rcp_f32_e32 v138, v138
	v_add_f32_e32 v139, 1.0, v139
	v_rcp_f32_e32 v139, v139
	s_nop 0
	v_pk_mul_f32 v[130:131], v[130:131], v[138:139]
	v_mul_f32_e32 v138, 0xbfb8aa3b, v135
	v_exp_f32_e32 v138, v138
	v_mul_f32_e32 v139, 0xbfb8aa3b, v136
	v_exp_f32_e32 v139, v139
	v_add_f32_e32 v138, 1.0, v138
	v_rcp_f32_e32 v141, v138
	v_add_f32_e32 v139, 1.0, v139
	v_mul_f32_e32 v138, 0xbfb8aa3b, v128
	v_exp_f32_e32 v138, v138
	v_pk_mul_f32 v[134:135], v[134:135], v[140:141]
	v_rcp_f32_e32 v140, v139
	v_mul_f32_e32 v139, 0xbfb8aa3b, v129
	v_exp_f32_e32 v139, v139
	v_add_f32_e32 v138, 1.0, v138
	v_rcp_f32_e32 v138, v138
	v_add_f32_e32 v139, 1.0, v139
	v_rcp_f32_e32 v139, v139
	s_nop 0
	v_pk_mul_f32 v[138:139], v[128:129], v[138:139]
	v_mul_f32_e32 v128, 0xbfb8aa3b, v137
	v_exp_f32_e32 v128, v128
	v_cvt_pk_bf16_f32 v129, v138, v139
	v_add_f32_e32 v128, 1.0, v128
	v_rcp_f32_e32 v141, v128
	v_cvt_pk_bf16_f32 v128, v130, v131
	v_cvt_pk_bf16_f32 v130, v134, v135
	v_pk_mul_f32 v[136:137], v[136:137], v[140:141]
	s_nop 0
	v_cvt_pk_bf16_f32 v131, v136, v137
	global_store_dwordx4 v[132:133], v[128:131], off offset:256

; __device__ __forceinline__ float silu_f(float x) { return x * __builtin_amdgcn_rcpf(1.f + __expf(-x)); }
; __device__ __forceinline__ v4u pack8(const f32x4 a, const f32x4 b) { v4u w; w.x = cvt_pk_bf16(a[0], a[1]); w.y = cvt_pk_bf16(a[2], a[3]); w.z = cvt_pk_bf16(b[0], b[1]); w.w = cvt_pk_bf16(b[2], b[3]); return w; }
;     __device__ __forceinline__ void operator()(const f32x4 (&acc)[2][2][4][2], const pg8::Unit& u, int wr, int wc, int fr, int fq) const {
;     ...
;         if (grp == 0) { WIN_LOOP( _Pragma("unroll") for (int i = 0; i < 4; ++i) { a[i] = silu_f(a[i]); b[i] = silu_f(b[i]); } *(v4u*)(QO + (size_t)row * DM + c) = pack8(a, b); ) }
;         else if (grp == 3) { WIN_LOOP( _Pragma("unroll") for (int i = 0; i < 4; ++i) { a[i] = silu_f(a[i]); b[i] = silu_f(b[i]); } *(v4u*)(GH + (size_t)row * 512 + c) = pack8(a, b); ) }
;         else if (grp == 1) {
;             f32x4 l0[2], l1[2];
; #pragma unroll
;             for (int bj = 0; bj < 2; ++bj) { l0[bj] = *(const f32x4*)(lb + cb + bj * 128); l1[bj] = *(const f32x4*)(lb + cb + bj * 128 + 4); }
;             WIN_LOOP( _Pragma("unroll") for (int i = 0; i < 4; ++i) { const float s0 = fminf(a[i], 0.f) - __logf(1.f + __expf(-fabsf(a[i]))), s1 = fminf(b[i], 0.f) - __logf(1.f + __expf(-fabsf(b[i]))); const float la = l0[bj][i], lbv = l1[bj][i];
;                     a[i] = la > 0.f ? __logf(la + (1.f - la) * __expf(s0)) : s0; b[i] = lbv > 0.f ? __logf(lbv + (1.f - lbv) * __expf(s1)) : s1; }
;                 *(f32x4*)(LF + (size_t)row * 512 + c) = a; *(f32x4*)(LF + (size_t)row * 512 + c + 4) = b; __builtin_amdgcn_sched_barrier(0); ) }
;         else if (grp == 2) { WIN_LOOP( *(v4u*)(VH + (size_t)row * 512 + c) = pack8(a, b); ) }
.LBB0_407:
	s_and_b64 vcc, exec, s[12:13]
	s_cbranch_vccz .LBB0_412
	s_cmp_gt_i32 s14, 1
	s_mov_b64 s[8:9], -1
	s_cbranch_scc0 .LBB0_410
	v_and_b32_e32 v129, 64, v215
	v_xor_b32_e32 v128, 16, v215
	v_add_u32_e32 v129, 64, v129
	v_cmp_lt_i32_e32 vcc, v128, v129
	v_ashrrev_i32_e32 v167, 31, v166
	v_readlane_b32 s8, v255, 37
	v_cndmask_b32_e32 v128, v215, v128, vcc
	v_lshlrev_b32_e32 v130, 2, v128
	v_xor_b32_e32 v128, 32, v215
	v_cmp_lt_i32_e32 vcc, v128, v129
	v_readlane_b32 s9, v255, 38
	v_lshlrev_b32_e32 v192, 1, v176
	v_cndmask_b32_e32 v128, v215, v128, vcc
	v_lshlrev_b32_e32 v131, 2, v128
	v_lshlrev_b64 v[128:129], 6, v[166:167]
	v_lshl_add_u64 v[128:129], v[160:161], 0, v[128:129]
	s_nop 0
	s_waitcnt lgkmcnt(0)
	s_nop 0
	s_nop 0
	s_nop 0
	s_nop 0
	v_lshlrev_b64 v[132:133], 10, v[166:167]
	s_nop 0
	s_nop 0
	v_lshl_add_u64 v[136:137], s[8:9], 0, v[132:133]
	v_lshl_add_u64 v[136:137], v[136:137], 0, v[192:193]
	s_waitcnt lgkmcnt(0)
	s_nop 0
	s_nop 0
	s_waitcnt lgkmcnt(0)
	s_nop 0
	s_nop 0
	v_mov_b32_e32 v128, v250
	s_nop 0
	v_pk_mul_f32 v[134:135], v[62:63], v[128:129] op_sel_hi:[1,0]
	v_pk_mul_f32 v[132:133], v[60:61], v[128:129] op_sel_hi:[1,0]
	v_pk_mul_f32 v[138:139], v[58:59], v[128:129] op_sel_hi:[1,0]
	v_pk_mul_f32 v[140:141], v[56:57], v[128:129] op_sel_hi:[1,0]
	v_cvt_pk_bf16_f32 v132, v132, v133
	v_cvt_pk_bf16_f32 v133, v134, v135
	v_cvt_pk_bf16_f32 v134, v140, v141
	v_cvt_pk_bf16_f32 v135, v138, v139
	global_store_dwordx4 v[136:137], v[132:135], off
	v_pk_mul_f32 v[138:139], v[122:123], v[128:129] op_sel_hi:[1,0]
	s_nop 0
	v_pk_mul_f32 v[134:135], v[126:127], v[128:129] op_sel_hi:[1,0]
	v_pk_mul_f32 v[132:133], v[124:125], v[128:129] op_sel_hi:[1,0]
	v_pk_mul_f32 v[128:129], v[120:121], v[128:129] op_sel_hi:[1,0]
	v_cvt_pk_bf16_f32 v132, v132, v133
	v_cvt_pk_bf16_f32 v133, v134, v135
	v_cvt_pk_bf16_f32 v134, v128, v129
	v_or_b32_e32 v128, 16, v166
	v_cvt_pk_bf16_f32 v135, v138, v139
	v_ashrrev_i32_e32 v129, 31, v128
	global_store_dwordx4 v[136:137], v[132:135], off offset:256
	s_nop 1
	v_lshlrev_b64 v[132:133], 6, v[128:129]
	v_lshl_add_u64 v[132:133], v[160:161], 0, v[132:133]
	s_nop 0
	v_lshlrev_b64 v[128:129], 10, v[128:129]
	v_lshl_add_u64 v[128:129], s[8:9], 0, v[128:129]
	v_lshl_add_u64 v[128:129], v[128:129], 0, v[192:193]
	s_waitcnt lgkmcnt(0)
	s_nop 0
	s_nop 0
	s_nop 0
	s_nop 0
	s_nop 0
	s_nop 0
	s_nop 0
	s_waitcnt lgkmcnt(0)
	s_nop 0
	s_nop 0
	s_waitcnt lgkmcnt(0)
	s_nop 0
	s_nop 0
	v_mov_b32_e32 v136, v251
	s_nop 0
	v_pk_mul_f32 v[134:135], v[54:55], v[136:137] op_sel_hi:[1,0]
	v_pk_mul_f32 v[132:133], v[52:53], v[136:137] op_sel_hi:[1,0]
	v_pk_mul_f32 v[138:139], v[50:51], v[136:137] op_sel_hi:[1,0]
	v_pk_mul_f32 v[140:141], v[48:49], v[136:137] op_sel_hi:[1,0]
	v_cvt_pk_bf16_f32 v132, v132, v133
	v_cvt_pk_bf16_f32 v133, v134, v135
	v_cvt_pk_bf16_f32 v134, v140, v141
	v_cvt_pk_bf16_f32 v135, v138, v139
	global_store_dwordx4 v[128:129], v[132:135], off
	v_pk_mul_f32 v[138:139], v[114:115], v[136:137] op_sel_hi:[1,0]
	s_nop 0
	v_pk_mul_f32 v[134:135], v[118:119], v[136:137] op_sel_hi:[1,0]
	v_pk_mul_f32 v[132:133], v[116:117], v[136:137] op_sel_hi:[1,0]
	v_pk_mul_f32 v[136:137], v[112:113], v[136:137] op_sel_hi:[1,0]
	v_cvt_pk_bf16_f32 v132, v132, v133
	v_cvt_pk_bf16_f32 v133, v134, v135
	v_cvt_pk_bf16_f32 v134, v136, v137
	v_cvt_pk_bf16_f32 v135, v138, v139
	global_store_dwordx4 v[128:129], v[132:135], off offset:256
	v_or_b32_e32 v128, 32, v166
	v_ashrrev_i32_e32 v129, 31, v128
	v_lshlrev_b64 v[132:133], 6, v[128:129]
	v_lshl_add_u64 v[132:133], v[160:161], 0, v[132:133]
	s_nop 0
	v_lshlrev_b64 v[128:129], 10, v[128:129]
	v_lshl_add_u64 v[128:129], s[8:9], 0, v[128:129]
	v_lshl_add_u64 v[128:129], v[128:129], 0, v[192:193]
	s_waitcnt lgkmcnt(0)
	s_nop 0
	s_nop 0
	s_nop 0
	s_nop 0
	s_nop 0
	s_nop 0
	s_nop 0
	s_waitcnt lgkmcnt(0)
	s_nop 0
	s_nop 0
	s_waitcnt lgkmcnt(0)
	s_nop 0
	s_nop 0
	v_mov_b32_e32 v136, v252
	s_nop 0
	v_pk_mul_f32 v[134:135], v[46:47], v[136:137] op_sel_hi:[1,0]
	v_pk_mul_f32 v[132:133], v[44:45], v[136:137] op_sel_hi:[1,0]
	v_pk_mul_f32 v[138:139], v[42:43], v[136:137] op_sel_hi:[1,0]
	v_pk_mul_f32 v[140:141], v[40:41], v[136:137] op_sel_hi:[1,0]
	v_cvt_pk_bf16_f32 v132, v132, v133
	v_cvt_pk_bf16_f32 v133, v134, v135
	v_cvt_pk_bf16_f32 v134, v140, v141
	v_cvt_pk_bf16_f32 v135, v138, v139
	global_store_dwordx4 v[128:129], v[132:135], off
	v_pk_mul_f32 v[138:139], v[106:107], v[136:137] op_sel_hi:[1,0]
	s_nop 0
	v_pk_mul_f32 v[134:135], v[110:111], v[136:137] op_sel_hi:[1,0]
	v_pk_mul_f32 v[132:133], v[108:109], v[136:137] op_sel_hi:[1,0]
	v_pk_mul_f32 v[136:137], v[104:105], v[136:137] op_sel_hi:[1,0]
	v_cvt_pk_bf16_f32 v132, v132, v133
	v_cvt_pk_bf16_f32 v133, v134, v135
	v_cvt_pk_bf16_f32 v134, v136, v137
	v_cvt_pk_bf16_f32 v135, v138, v139
	global_store_dwordx4 v[128:129], v[132:135], off offset:256
	v_or_b32_e32 v128, 48, v166
	v_ashrrev_i32_e32 v129, 31, v128
	v_lshlrev_b64 v[132:133], 6, v[128:129]
	v_lshl_add_u64 v[132:133], v[160:161], 0, v[132:133]
	s_nop 0
	v_lshlrev_b64 v[128:129], 10, v[128:129]
	v_lshl_add_u64 v[128:129], s[8:9], 0, v[128:129]
	v_lshl_add_u64 v[128:129], v[128:129], 0, v[192:193]
	s_waitcnt lgkmcnt(0)
	s_nop 0
	s_nop 0
	s_nop 0
	s_nop 0
	s_nop 0
	s_nop 0
	s_nop 0
	s_waitcnt lgkmcnt(0)
	s_nop 0
	s_nop 0
	s_waitcnt lgkmcnt(0)
; __device__ __forceinline__ v4u pack8(const f32x4 a, const f32x4 b) { v4u w; w.x = cvt_pk_bf16(a[0], a[1]); w.y = cvt_pk_bf16(a[2], a[3]); w.z = cvt_pk_bf16(b[0], b[1]); w.w = cvt_pk_bf16(b[2], b[3]); return w; }
;     __device__ __forceinline__ void operator()(const f32x4 (&acc)[2][2][4][2], const pg8::Unit& u, int wr, int wc, int fr, int fq) const {
;     ...
;         else if (grp == 2) { WIN_LOOP( *(v4u*)(VH + (size_t)row * 512 + c) = pack8(a, b); ) }
;         else if (grp == 4) { WIN_LOOP( *(v4u*)(QO + (size_t)row * DM + 512 + c) = pack8(a * C2Q, b * C2Q); ) }
;         else if (grp == 5) { WIN_LOOP( *(v4u*)(FK + (size_t)row * 512 + c) = pack8(a, b); ) }
;         else { WIN_LOOP( *(v4u*)(FV + (size_t)row * 512 + c) = pack8(a, b); ) }
	s_nop 0
	s_nop 0
	v_mov_b32_e32 v136, v253
	s_nop 0
	v_pk_mul_f32 v[134:135], v[38:39], v[136:137] op_sel_hi:[1,0]
	v_pk_mul_f32 v[132:133], v[36:37], v[136:137] op_sel_hi:[1,0]
	v_pk_mul_f32 v[138:139], v[34:35], v[136:137] op_sel_hi:[1,0]
	v_pk_mul_f32 v[140:141], v[32:33], v[136:137] op_sel_hi:[1,0]
	v_cvt_pk_bf16_f32 v132, v132, v133
	v_cvt_pk_bf16_f32 v133, v134, v135
	v_cvt_pk_bf16_f32 v134, v140, v141
	v_cvt_pk_bf16_f32 v135, v138, v139
	global_store_dwordx4 v[128:129], v[132:135], off
	v_pk_mul_f32 v[138:139], v[98:99], v[136:137] op_sel_hi:[1,0]
	s_nop 0
	v_pk_mul_f32 v[134:135], v[102:103], v[136:137] op_sel_hi:[1,0]
	v_pk_mul_f32 v[132:133], v[100:101], v[136:137] op_sel_hi:[1,0]
	v_pk_mul_f32 v[136:137], v[96:97], v[136:137] op_sel_hi:[1,0]
	v_cvt_pk_bf16_f32 v132, v132, v133
	v_cvt_pk_bf16_f32 v133, v134, v135
	v_cvt_pk_bf16_f32 v134, v136, v137
	v_cvt_pk_bf16_f32 v135, v138, v139
	global_store_dwordx4 v[128:129], v[132:135], off offset:256
	v_add_u32_e32 v128, 0x80, v166
	v_ashrrev_i32_e32 v129, 31, v128
	v_lshlrev_b64 v[132:133], 6, v[128:129]
	v_lshl_add_u64 v[132:133], v[160:161], 0, v[132:133]
	s_nop 0
	v_lshlrev_b64 v[128:129], 10, v[128:129]
	v_lshl_add_u64 v[128:129], s[8:9], 0, v[128:129]
	v_lshl_add_u64 v[128:129], v[128:129], 0, v[192:193]
	s_waitcnt lgkmcnt(0)
	s_nop 0
	s_nop 0
	s_nop 0
	s_nop 0
	s_nop 0
	s_nop 0
	s_nop 0
	s_waitcnt lgkmcnt(0)
	s_nop 0
	s_nop 0
	s_waitcnt lgkmcnt(0)
	s_nop 0
	s_nop 0
	v_mov_b32_e32 v136, v254
	s_nop 0
	v_pk_mul_f32 v[134:135], v[30:31], v[136:137] op_sel_hi:[1,0]
	v_pk_mul_f32 v[132:133], v[28:29], v[136:137] op_sel_hi:[1,0]
	v_pk_mul_f32 v[138:139], v[26:27], v[136:137] op_sel_hi:[1,0]
	v_pk_mul_f32 v[140:141], v[24:25], v[136:137] op_sel_hi:[1,0]
	v_cvt_pk_bf16_f32 v132, v132, v133
	v_cvt_pk_bf16_f32 v133, v134, v135
	v_cvt_pk_bf16_f32 v134, v140, v141
	v_cvt_pk_bf16_f32 v135, v138, v139
	global_store_dwordx4 v[128:129], v[132:135], off
	v_pk_mul_f32 v[138:139], v[90:91], v[136:137] op_sel_hi:[1,0]
	s_nop 0
	v_pk_mul_f32 v[134:135], v[94:95], v[136:137] op_sel_hi:[1,0]
	v_pk_mul_f32 v[132:133], v[92:93], v[136:137] op_sel_hi:[1,0]
	v_pk_mul_f32 v[136:137], v[88:89], v[136:137] op_sel_hi:[1,0]
	v_cvt_pk_bf16_f32 v132, v132, v133
	v_cvt_pk_bf16_f32 v133, v134, v135
	v_cvt_pk_bf16_f32 v134, v136, v137
	v_cvt_pk_bf16_f32 v135, v138, v139
	global_store_dwordx4 v[128:129], v[132:135], off offset:256
	v_add_u32_e32 v128, 0x90, v166
	v_ashrrev_i32_e32 v129, 31, v128
	v_lshlrev_b64 v[132:133], 6, v[128:129]
	v_lshl_add_u64 v[132:133], v[160:161], 0, v[132:133]
	s_nop 0
	v_lshlrev_b64 v[128:129], 10, v[128:129]
	v_lshl_add_u64 v[128:129], s[8:9], 0, v[128:129]
	v_lshl_add_u64 v[128:129], v[128:129], 0, v[192:193]
	s_waitcnt lgkmcnt(0)
	s_nop 0
	s_nop 0
	s_nop 0
	s_nop 0
	s_nop 0
	s_nop 0
	s_nop 0
	s_waitcnt lgkmcnt(0)
	s_nop 0
	s_nop 0
	s_waitcnt lgkmcnt(0)
	s_nop 0
	s_nop 0
	v_mov_b32_e32 v136, v240
	s_nop 0
	v_pk_mul_f32 v[134:135], v[22:23], v[136:137] op_sel_hi:[1,0]
	v_pk_mul_f32 v[132:133], v[20:21], v[136:137] op_sel_hi:[1,0]
	v_pk_mul_f32 v[138:139], v[18:19], v[136:137] op_sel_hi:[1,0]
	v_pk_mul_f32 v[140:141], v[16:17], v[136:137] op_sel_hi:[1,0]
	v_cvt_pk_bf16_f32 v132, v132, v133
	v_cvt_pk_bf16_f32 v133, v134, v135
	v_cvt_pk_bf16_f32 v134, v140, v141
	v_cvt_pk_bf16_f32 v135, v138, v139
	global_store_dwordx4 v[128:129], v[132:135], off
	v_pk_mul_f32 v[138:139], v[82:83], v[136:137] op_sel_hi:[1,0]
	s_nop 0
	v_pk_mul_f32 v[134:135], v[86:87], v[136:137] op_sel_hi:[1,0]
	v_pk_mul_f32 v[132:133], v[84:85], v[136:137] op_sel_hi:[1,0]
	v_pk_mul_f32 v[136:137], v[80:81], v[136:137] op_sel_hi:[1,0]
	v_cvt_pk_bf16_f32 v132, v132, v133
	v_cvt_pk_bf16_f32 v133, v134, v135
	v_cvt_pk_bf16_f32 v134, v136, v137
	v_cvt_pk_bf16_f32 v135, v138, v139
	global_store_dwordx4 v[128:129], v[132:135], off offset:256
	v_add_u32_e32 v128, 0xa0, v166
	v_ashrrev_i32_e32 v129, 31, v128
	v_lshlrev_b64 v[132:133], 6, v[128:129]
	v_lshl_add_u64 v[132:133], v[160:161], 0, v[132:133]
	s_nop 0
	v_lshlrev_b64 v[128:129], 10, v[128:129]
	v_lshl_add_u64 v[128:129], s[8:9], 0, v[128:129]
	v_lshl_add_u64 v[128:129], v[128:129], 0, v[192:193]
	s_waitcnt lgkmcnt(0)
	s_nop 0
	s_nop 0
	s_nop 0
	s_nop 0
	s_nop 0
	s_nop 0
	s_nop 0
	s_waitcnt lgkmcnt(0)
	s_nop 0
	s_nop 0
	s_waitcnt lgkmcnt(0)
	s_nop 0
	s_nop 0
	v_mov_b32_e32 v136, v241
	s_nop 0
	v_pk_mul_f32 v[134:135], v[14:15], v[136:137] op_sel_hi:[1,0]
	v_pk_mul_f32 v[132:133], v[12:13], v[136:137] op_sel_hi:[1,0]
	v_pk_mul_f32 v[138:139], v[10:11], v[136:137] op_sel_hi:[1,0]
	v_pk_mul_f32 v[140:141], v[8:9], v[136:137] op_sel_hi:[1,0]
	v_cvt_pk_bf16_f32 v132, v132, v133
	v_cvt_pk_bf16_f32 v133, v134, v135
	v_cvt_pk_bf16_f32 v134, v140, v141
	v_cvt_pk_bf16_f32 v135, v138, v139
	global_store_dwordx4 v[128:129], v[132:135], off
	v_pk_mul_f32 v[138:139], v[74:75], v[136:137] op_sel_hi:[1,0]
	s_nop 0
	v_pk_mul_f32 v[134:135], v[78:79], v[136:137] op_sel_hi:[1,0]
	v_pk_mul_f32 v[132:133], v[76:77], v[136:137] op_sel_hi:[1,0]
	v_pk_mul_f32 v[136:137], v[72:73], v[136:137] op_sel_hi:[1,0]
	v_cvt_pk_bf16_f32 v132, v132, v133
	v_cvt_pk_bf16_f32 v133, v134, v135
	v_cvt_pk_bf16_f32 v134, v136, v137
	v_cvt_pk_bf16_f32 v135, v138, v139
	global_store_dwordx4 v[128:129], v[132:135], off offset:256
	v_add_u32_e32 v128, 0xb0, v166
	v_ashrrev_i32_e32 v129, 31, v128
	v_lshlrev_b64 v[132:133], 6, v[128:129]
	v_lshl_add_u64 v[132:133], v[160:161], 0, v[132:133]
	s_nop 0
	v_lshlrev_b64 v[128:129], 10, v[128:129]
	s_waitcnt lgkmcnt(0)
	s_nop 0
	s_nop 0
	s_nop 0
	s_nop 0
	v_lshl_add_u64 v[134:135], s[8:9], 0, v[128:129]
	s_nop 0
	s_nop 0
	v_lshl_add_u64 v[134:135], v[134:135], 0, v[192:193]
	s_mov_b64 s[8:9], 0
	s_waitcnt lgkmcnt(0)
	s_nop 0
	s_nop 0
	s_waitcnt lgkmcnt(0)
	s_nop 0
	s_nop 0
	v_mov_b32_e32 v132, v245
	s_nop 0
	v_pk_mul_f32 v[130:131], v[6:7], v[132:133] op_sel_hi:[1,0]
	v_pk_mul_f32 v[128:129], v[4:5], v[132:133] op_sel_hi:[1,0]
	v_pk_mul_f32 v[136:137], v[2:3], v[132:133] op_sel_hi:[1,0]
	v_pk_mul_f32 v[138:139], v[0:1], v[132:133] op_sel_hi:[1,0]
	v_cvt_pk_bf16_f32 v128, v128, v129
	v_cvt_pk_bf16_f32 v129, v130, v131
	v_cvt_pk_bf16_f32 v130, v138, v139
	v_cvt_pk_bf16_f32 v131, v136, v137
	global_store_dwordx4 v[134:135], v[128:131], off
	v_pk_mul_f32 v[136:137], v[66:67], v[132:133] op_sel_hi:[1,0]
	s_nop 0
	v_pk_mul_f32 v[130:131], v[70:71], v[132:133] op_sel_hi:[1,0]
	v_pk_mul_f32 v[128:129], v[68:69], v[132:133] op_sel_hi:[1,0]
	v_pk_mul_f32 v[132:133], v[64:65], v[132:133] op_sel_hi:[1,0]
	v_cvt_pk_bf16_f32 v128, v128, v129
	v_cvt_pk_bf16_f32 v129, v130, v131
	v_cvt_pk_bf16_f32 v130, v132, v133
	v_cvt_pk_bf16_f32 v131, v136, v137
	global_store_dwordx4 v[134:135], v[128:131], off offset:256

; __device__ __forceinline__ v4u pack8(const f32x4 a, const f32x4 b) { v4u w; w.x = cvt_pk_bf16(a[0], a[1]); w.y = cvt_pk_bf16(a[2], a[3]); w.z = cvt_pk_bf16(b[0], b[1]); w.w = cvt_pk_bf16(b[2], b[3]); return w; }
;     __device__ __forceinline__ void operator()(const f32x4 (&acc)[2][2][4][2], const pg8::Unit& u, int wr, int wc, int fr, int fq) const {
;     ...
;         else if (grp == 2) { WIN_LOOP( *(v4u*)(VH + (size_t)row * 512 + c) = pack8(a, b); ) }
;         else if (grp == 4) { WIN_LOOP( *(v4u*)(QO + (size_t)row * DM + 512 + c) = pack8(a * C2Q, b * C2Q); ) }
;         else if (grp == 5) { WIN_LOOP( *(v4u*)(FK + (size_t)row * 512 + c) = pack8(a, b); ) }
;         else { WIN_LOOP( *(v4u*)(FV + (size_t)row * 512 + c) = pack8(a, b); ) }
.LBB0_412:
	s_and_b64 vcc, exec, s[10:11]
	s_cbranch_vccz .LBB0_414
	v_and_b32_e32 v129, 64, v215
	v_xor_b32_e32 v128, 16, v215
	v_add_u32_e32 v129, 64, v129
	v_cmp_lt_i32_e32 vcc, v128, v129
	v_ashrrev_i32_e32 v167, 31, v166
	v_readlane_b32 s8, v255, 43
	v_cndmask_b32_e32 v128, v215, v128, vcc
	v_lshlrev_b32_e32 v130, 2, v128
	v_xor_b32_e32 v128, 32, v215
	v_cmp_lt_i32_e32 vcc, v128, v129
	v_readlane_b32 s9, v255, 44
	v_lshlrev_b32_e32 v192, 1, v176
	v_cndmask_b32_e32 v128, v215, v128, vcc
	v_lshlrev_b32_e32 v131, 2, v128
	v_lshlrev_b64 v[128:129], 6, v[166:167]
	v_lshl_add_u64 v[128:129], v[160:161], 0, v[128:129]
	s_nop 0
	s_waitcnt lgkmcnt(0)
	s_nop 0
	s_nop 0
	s_nop 0
	s_nop 0
	v_lshlrev_b64 v[132:133], 10, v[166:167]
	s_nop 0
	s_nop 0
	v_lshl_add_u64 v[136:137], s[8:9], 0, v[132:133]
	v_lshl_add_u64 v[136:137], v[136:137], 0, v[192:193]
	s_waitcnt lgkmcnt(0)
	s_nop 0
	s_nop 0
	s_waitcnt lgkmcnt(0)
	s_nop 0
	s_nop 0
	v_mov_b32_e32 v128, v250
	s_nop 0
	v_pk_mul_f32 v[134:135], v[62:63], v[128:129] op_sel_hi:[1,0]
	v_pk_mul_f32 v[132:133], v[60:61], v[128:129] op_sel_hi:[1,0]
	v_pk_mul_f32 v[138:139], v[58:59], v[128:129] op_sel_hi:[1,0]
	v_pk_mul_f32 v[140:141], v[56:57], v[128:129] op_sel_hi:[1,0]
	v_cvt_pk_bf16_f32 v132, v132, v133
	v_cvt_pk_bf16_f32 v133, v134, v135
	v_cvt_pk_bf16_f32 v134, v140, v141
	v_cvt_pk_bf16_f32 v135, v138, v139
	global_store_dwordx4 v[136:137], v[132:135], off
	v_pk_mul_f32 v[138:139], v[122:123], v[128:129] op_sel_hi:[1,0]
	s_nop 0
	v_pk_mul_f32 v[134:135], v[126:127], v[128:129] op_sel_hi:[1,0]
	v_pk_mul_f32 v[132:133], v[124:125], v[128:129] op_sel_hi:[1,0]
	v_pk_mul_f32 v[128:129], v[120:121], v[128:129] op_sel_hi:[1,0]
	v_cvt_pk_bf16_f32 v132, v132, v133
	v_cvt_pk_bf16_f32 v133, v134, v135
	v_cvt_pk_bf16_f32 v134, v128, v129
	v_or_b32_e32 v128, 16, v166
	v_cvt_pk_bf16_f32 v135, v138, v139
	v_ashrrev_i32_e32 v129, 31, v128
	global_store_dwordx4 v[136:137], v[132:135], off offset:256
	s_nop 1
	v_lshlrev_b64 v[132:133], 6, v[128:129]
	v_lshl_add_u64 v[132:133], v[160:161], 0, v[132:133]
	s_nop 0
	v_lshlrev_b64 v[128:129], 10, v[128:129]
	v_lshl_add_u64 v[128:129], s[8:9], 0, v[128:129]
	v_lshl_add_u64 v[128:129], v[128:129], 0, v[192:193]
	s_waitcnt lgkmcnt(0)
	s_nop 0
	s_nop 0
	s_nop 0
	s_nop 0
	s_nop 0
	s_nop 0
	s_nop 0
	s_waitcnt lgkmcnt(0)
	s_nop 0
	s_nop 0
	s_waitcnt lgkmcnt(0)
	s_nop 0
	s_nop 0
	v_mov_b32_e32 v136, v251
	s_nop 0
	v_pk_mul_f32 v[134:135], v[54:55], v[136:137] op_sel_hi:[1,0]
	v_pk_mul_f32 v[132:133], v[52:53], v[136:137] op_sel_hi:[1,0]
	v_pk_mul_f32 v[138:139], v[50:51], v[136:137] op_sel_hi:[1,0]
	v_pk_mul_f32 v[140:141], v[48:49], v[136:137] op_sel_hi:[1,0]
	v_cvt_pk_bf16_f32 v132, v132, v133
	v_cvt_pk_bf16_f32 v133, v134, v135
	v_cvt_pk_bf16_f32 v134, v140, v141
	v_cvt_pk_bf16_f32 v135, v138, v139
	global_store_dwordx4 v[128:129], v[132:135], off
	v_pk_mul_f32 v[138:139], v[114:115], v[136:137] op_sel_hi:[1,0]
	s_nop 0
	v_pk_mul_f32 v[134:135], v[118:119], v[136:137] op_sel_hi:[1,0]
	v_pk_mul_f32 v[132:133], v[116:117], v[136:137] op_sel_hi:[1,0]
	v_pk_mul_f32 v[136:137], v[112:113], v[136:137] op_sel_hi:[1,0]
	v_cvt_pk_bf16_f32 v132, v132, v133
	v_cvt_pk_bf16_f32 v133, v134, v135
	v_cvt_pk_bf16_f32 v134, v136, v137
	v_cvt_pk_bf16_f32 v135, v138, v139
	global_store_dwordx4 v[128:129], v[132:135], off offset:256
	v_or_b32_e32 v128, 32, v166
	v_ashrrev_i32_e32 v129, 31, v128
	v_lshlrev_b64 v[132:133], 6, v[128:129]
	v_lshl_add_u64 v[132:133], v[160:161], 0, v[132:133]
	s_nop 0
	v_lshlrev_b64 v[128:129], 10, v[128:129]
	v_lshl_add_u64 v[128:129], s[8:9], 0, v[128:129]
	v_lshl_add_u64 v[128:129], v[128:129], 0, v[192:193]
	s_waitcnt lgkmcnt(0)
	s_nop 0
	s_nop 0
	s_nop 0
	s_nop 0
	s_nop 0
	s_nop 0
	s_nop 0
	s_waitcnt lgkmcnt(0)
	s_nop 0
	s_nop 0
	s_waitcnt lgkmcnt(0)
	s_nop 0
	s_nop 0
	v_mov_b32_e32 v136, v252
	s_nop 0
	v_pk_mul_f32 v[134:135], v[46:47], v[136:137] op_sel_hi:[1,0]
	v_pk_mul_f32 v[132:133], v[44:45], v[136:137] op_sel_hi:[1,0]
	v_pk_mul_f32 v[138:139], v[42:43], v[136:137] op_sel_hi:[1,0]
	v_pk_mul_f32 v[140:141], v[40:41], v[136:137] op_sel_hi:[1,0]
	v_cvt_pk_bf16_f32 v132, v132, v133
	v_cvt_pk_bf16_f32 v133, v134, v135
	v_cvt_pk_bf16_f32 v134, v140, v141
	v_cvt_pk_bf16_f32 v135, v138, v139
	global_store_dwordx4 v[128:129], v[132:135], off
	v_pk_mul_f32 v[138:139], v[106:107], v[136:137] op_sel_hi:[1,0]
	s_nop 0
	v_pk_mul_f32 v[134:135], v[110:111], v[136:137] op_sel_hi:[1,0]
	v_pk_mul_f32 v[132:133], v[108:109], v[136:137] op_sel_hi:[1,0]
	v_pk_mul_f32 v[136:137], v[104:105], v[136:137] op_sel_hi:[1,0]
	v_cvt_pk_bf16_f32 v132, v132, v133
	v_cvt_pk_bf16_f32 v133, v134, v135
	v_cvt_pk_bf16_f32 v134, v136, v137
	v_cvt_pk_bf16_f32 v135, v138, v139
	global_store_dwordx4 v[128:129], v[132:135], off offset:256
	v_or_b32_e32 v128, 48, v166
	v_ashrrev_i32_e32 v129, 31, v128
	v_lshlrev_b64 v[132:133], 6, v[128:129]
	v_lshl_add_u64 v[132:133], v[160:161], 0, v[132:133]
	s_nop 0
	v_lshlrev_b64 v[128:129], 10, v[128:129]
	v_lshl_add_u64 v[128:129], s[8:9], 0, v[128:129]
	v_lshl_add_u64 v[128:129], v[128:129], 0, v[192:193]
	s_waitcnt lgkmcnt(0)
	s_nop 0
	s_nop 0
	s_nop 0
	s_nop 0
	s_nop 0
	s_nop 0
	s_nop 0
	s_waitcnt lgkmcnt(0)
	s_nop 0
	s_nop 0
	s_waitcnt lgkmcnt(0)
; __device__ __forceinline__ v4u pack8(const f32x4 a, const f32x4 b) { v4u w; w.x = cvt_pk_bf16(a[0], a[1]); w.y = cvt_pk_bf16(a[2], a[3]); w.z = cvt_pk_bf16(b[0], b[1]); w.w = cvt_pk_bf16(b[2], b[3]); return w; }
;     __device__ __forceinline__ void operator()(const f32x4 (&acc)[2][2][4][2], const pg8::Unit& u, int wr, int wc, int fr, int fq) const {
;     ...
;         else if (grp == 2) { WIN_LOOP( *(v4u*)(VH + (size_t)row * 512 + c) = pack8(a, b); ) }
;         else if (grp == 4) { WIN_LOOP( *(v4u*)(QO + (size_t)row * DM + 512 + c) = pack8(a * C2Q, b * C2Q); ) }
;         else if (grp == 5) { WIN_LOOP( *(v4u*)(FK + (size_t)row * 512 + c) = pack8(a, b); ) }
;         else { WIN_LOOP( *(v4u*)(FV + (size_t)row * 512 + c) = pack8(a, b); ) }
	s_nop 0
	s_nop 0
	v_mov_b32_e32 v136, v253
	s_nop 0
	v_pk_mul_f32 v[134:135], v[38:39], v[136:137] op_sel_hi:[1,0]
	v_pk_mul_f32 v[132:133], v[36:37], v[136:137] op_sel_hi:[1,0]
	v_pk_mul_f32 v[138:139], v[34:35], v[136:137] op_sel_hi:[1,0]
	v_pk_mul_f32 v[140:141], v[32:33], v[136:137] op_sel_hi:[1,0]
	v_cvt_pk_bf16_f32 v132, v132, v133
	v_cvt_pk_bf16_f32 v133, v134, v135
	v_cvt_pk_bf16_f32 v134, v140, v141
	v_cvt_pk_bf16_f32 v135, v138, v139
	global_store_dwordx4 v[128:129], v[132:135], off
	v_pk_mul_f32 v[138:139], v[98:99], v[136:137] op_sel_hi:[1,0]
	s_nop 0
	v_pk_mul_f32 v[134:135], v[102:103], v[136:137] op_sel_hi:[1,0]
	v_pk_mul_f32 v[132:133], v[100:101], v[136:137] op_sel_hi:[1,0]
	v_pk_mul_f32 v[136:137], v[96:97], v[136:137] op_sel_hi:[1,0]
	v_cvt_pk_bf16_f32 v132, v132, v133
	v_cvt_pk_bf16_f32 v133, v134, v135
	v_cvt_pk_bf16_f32 v134, v136, v137
	v_cvt_pk_bf16_f32 v135, v138, v139
	global_store_dwordx4 v[128:129], v[132:135], off offset:256
	v_add_u32_e32 v128, 0x80, v166
	v_ashrrev_i32_e32 v129, 31, v128
	v_lshlrev_b64 v[132:133], 6, v[128:129]
	v_lshl_add_u64 v[132:133], v[160:161], 0, v[132:133]
	s_nop 0
	v_lshlrev_b64 v[128:129], 10, v[128:129]
	v_lshl_add_u64 v[128:129], s[8:9], 0, v[128:129]
	v_lshl_add_u64 v[128:129], v[128:129], 0, v[192:193]
	s_waitcnt lgkmcnt(0)
	s_nop 0
	s_nop 0
	s_nop 0
	s_nop 0
	s_nop 0
	s_nop 0
	s_nop 0
	s_waitcnt lgkmcnt(0)
	s_nop 0
	s_nop 0
	s_waitcnt lgkmcnt(0)
	s_nop 0
	s_nop 0
	v_mov_b32_e32 v136, v254
	s_nop 0
	v_pk_mul_f32 v[134:135], v[30:31], v[136:137] op_sel_hi:[1,0]
	v_pk_mul_f32 v[132:133], v[28:29], v[136:137] op_sel_hi:[1,0]
	v_pk_mul_f32 v[138:139], v[26:27], v[136:137] op_sel_hi:[1,0]
	v_pk_mul_f32 v[140:141], v[24:25], v[136:137] op_sel_hi:[1,0]
	v_cvt_pk_bf16_f32 v132, v132, v133
	v_cvt_pk_bf16_f32 v133, v134, v135
	v_cvt_pk_bf16_f32 v134, v140, v141
	v_cvt_pk_bf16_f32 v135, v138, v139
	global_store_dwordx4 v[128:129], v[132:135], off
	v_pk_mul_f32 v[138:139], v[90:91], v[136:137] op_sel_hi:[1,0]
	s_nop 0
	v_pk_mul_f32 v[134:135], v[94:95], v[136:137] op_sel_hi:[1,0]
	v_pk_mul_f32 v[132:133], v[92:93], v[136:137] op_sel_hi:[1,0]
	v_pk_mul_f32 v[136:137], v[88:89], v[136:137] op_sel_hi:[1,0]
	v_cvt_pk_bf16_f32 v132, v132, v133
	v_cvt_pk_bf16_f32 v133, v134, v135
	v_cvt_pk_bf16_f32 v134, v136, v137
	v_cvt_pk_bf16_f32 v135, v138, v139
	global_store_dwordx4 v[128:129], v[132:135], off offset:256
	v_add_u32_e32 v128, 0x90, v166
	v_ashrrev_i32_e32 v129, 31, v128
	v_lshlrev_b64 v[132:133], 6, v[128:129]
	v_lshl_add_u64 v[132:133], v[160:161], 0, v[132:133]
	s_nop 0
	v_lshlrev_b64 v[128:129], 10, v[128:129]
	v_lshl_add_u64 v[128:129], s[8:9], 0, v[128:129]
	v_lshl_add_u64 v[128:129], v[128:129], 0, v[192:193]
	s_waitcnt lgkmcnt(0)
	s_nop 0
	s_nop 0
	s_nop 0
	s_nop 0
	s_nop 0
	s_nop 0
	s_nop 0
	s_waitcnt lgkmcnt(0)
	s_nop 0
	s_nop 0
	s_waitcnt lgkmcnt(0)
	s_nop 0
	s_nop 0
	v_mov_b32_e32 v136, v240
	s_nop 0
	v_pk_mul_f32 v[134:135], v[22:23], v[136:137] op_sel_hi:[1,0]
	v_pk_mul_f32 v[132:133], v[20:21], v[136:137] op_sel_hi:[1,0]
	v_pk_mul_f32 v[138:139], v[18:19], v[136:137] op_sel_hi:[1,0]
	v_pk_mul_f32 v[140:141], v[16:17], v[136:137] op_sel_hi:[1,0]
	v_cvt_pk_bf16_f32 v132, v132, v133
	v_cvt_pk_bf16_f32 v133, v134, v135
	v_cvt_pk_bf16_f32 v134, v140, v141
	v_cvt_pk_bf16_f32 v135, v138, v139
	global_store_dwordx4 v[128:129], v[132:135], off
	v_pk_mul_f32 v[138:139], v[82:83], v[136:137] op_sel_hi:[1,0]
	s_nop 0
	v_pk_mul_f32 v[134:135], v[86:87], v[136:137] op_sel_hi:[1,0]
	v_pk_mul_f32 v[132:133], v[84:85], v[136:137] op_sel_hi:[1,0]
	v_pk_mul_f32 v[136:137], v[80:81], v[136:137] op_sel_hi:[1,0]
	v_cvt_pk_bf16_f32 v132, v132, v133
	v_cvt_pk_bf16_f32 v133, v134, v135
	v_cvt_pk_bf16_f32 v134, v136, v137
	v_cvt_pk_bf16_f32 v135, v138, v139
	global_store_dwordx4 v[128:129], v[132:135], off offset:256
	v_add_u32_e32 v128, 0xa0, v166
	v_ashrrev_i32_e32 v129, 31, v128
	v_lshlrev_b64 v[132:133], 6, v[128:129]
	v_lshl_add_u64 v[132:133], v[160:161], 0, v[132:133]
	s_nop 0
	v_lshlrev_b64 v[128:129], 10, v[128:129]
	v_lshl_add_u64 v[128:129], s[8:9], 0, v[128:129]
	v_lshl_add_u64 v[128:129], v[128:129], 0, v[192:193]
	s_waitcnt lgkmcnt(0)
	s_nop 0
	s_nop 0
	s_nop 0
	s_nop 0
	s_nop 0
	s_nop 0
	s_nop 0
	s_waitcnt lgkmcnt(0)
	s_nop 0
	s_nop 0
	s_waitcnt lgkmcnt(0)
	s_nop 0
	s_nop 0
	v_mov_b32_e32 v136, v241
	s_nop 0
	v_pk_mul_f32 v[134:135], v[14:15], v[136:137] op_sel_hi:[1,0]
	v_pk_mul_f32 v[132:133], v[12:13], v[136:137] op_sel_hi:[1,0]
	v_pk_mul_f32 v[138:139], v[10:11], v[136:137] op_sel_hi:[1,0]
	v_pk_mul_f32 v[140:141], v[8:9], v[136:137] op_sel_hi:[1,0]
	v_cvt_pk_bf16_f32 v132, v132, v133
	v_cvt_pk_bf16_f32 v133, v134, v135
	v_cvt_pk_bf16_f32 v134, v140, v141
	v_cvt_pk_bf16_f32 v135, v138, v139
	global_store_dwordx4 v[128:129], v[132:135], off
	v_pk_mul_f32 v[138:139], v[74:75], v[136:137] op_sel_hi:[1,0]
	s_nop 0
	v_pk_mul_f32 v[134:135], v[78:79], v[136:137] op_sel_hi:[1,0]
	v_pk_mul_f32 v[132:133], v[76:77], v[136:137] op_sel_hi:[1,0]
	v_pk_mul_f32 v[136:137], v[72:73], v[136:137] op_sel_hi:[1,0]
	v_cvt_pk_bf16_f32 v132, v132, v133
	v_cvt_pk_bf16_f32 v133, v134, v135
	v_cvt_pk_bf16_f32 v134, v136, v137
	v_cvt_pk_bf16_f32 v135, v138, v139
	global_store_dwordx4 v[128:129], v[132:135], off offset:256
	v_add_u32_e32 v128, 0xb0, v166
	v_ashrrev_i32_e32 v129, 31, v128
	v_lshlrev_b64 v[132:133], 6, v[128:129]
	v_lshl_add_u64 v[132:133], v[160:161], 0, v[132:133]
	s_nop 0
	v_lshlrev_b64 v[128:129], 10, v[128:129]
	s_waitcnt lgkmcnt(0)
	s_nop 0
	s_nop 0
	s_nop 0
	s_nop 0
	v_lshl_add_u64 v[134:135], s[8:9], 0, v[128:129]
	s_nop 0
	s_nop 0
	v_lshl_add_u64 v[134:135], v[134:135], 0, v[192:193]
	s_mov_b64 s[8:9], 0
	s_waitcnt lgkmcnt(0)
	s_nop 0
	s_nop 0
	s_waitcnt lgkmcnt(0)
	s_nop 0
	s_nop 0
	v_mov_b32_e32 v132, v245
	s_nop 0
	v_pk_mul_f32 v[130:131], v[6:7], v[132:133] op_sel_hi:[1,0]
	v_pk_mul_f32 v[128:129], v[4:5], v[132:133] op_sel_hi:[1,0]
	v_pk_mul_f32 v[136:137], v[2:3], v[132:133] op_sel_hi:[1,0]
	v_pk_mul_f32 v[138:139], v[0:1], v[132:133] op_sel_hi:[1,0]
	v_cvt_pk_bf16_f32 v128, v128, v129
	v_cvt_pk_bf16_f32 v129, v130, v131
	v_cvt_pk_bf16_f32 v130, v138, v139
	v_cvt_pk_bf16_f32 v131, v136, v137
	global_store_dwordx4 v[134:135], v[128:131], off
	v_pk_mul_f32 v[136:137], v[66:67], v[132:133] op_sel_hi:[1,0]
	s_nop 0
	v_pk_mul_f32 v[130:131], v[70:71], v[132:133] op_sel_hi:[1,0]
	v_pk_mul_f32 v[128:129], v[68:69], v[132:133] op_sel_hi:[1,0]
	v_pk_mul_f32 v[132:133], v[64:65], v[132:133] op_sel_hi:[1,0]
	v_cvt_pk_bf16_f32 v128, v128, v129
	v_cvt_pk_bf16_f32 v129, v130, v131
	v_cvt_pk_bf16_f32 v130, v132, v133
	v_cvt_pk_bf16_f32 v131, v136, v137
	global_store_dwordx4 v[134:135], v[128:131], off offset:256
;     __device__ __forceinline__ void operator()(const f32x4 (&acc)[2][2][4][2], const pg8::Unit& u, int wr, int wc, int fr, int fq) const {
;     ...
;         else if (grp == 1) {
;             f32x4 l0[2], l1[2];
; #pragma unroll
;             for (int bj = 0; bj < 2; ++bj) { l0[bj] = *(const f32x4*)(lb + cb + bj * 128); l1[bj] = *(const f32x4*)(lb + cb + bj * 128 + 4); }
;             WIN_LOOP( _Pragma("unroll") for (int i = 0; i < 4; ++i) { const float s0 = fminf(a[i], 0.f) - __logf(1.f + __expf(-fabsf(a[i]))), s1 = fminf(b[i], 0.f) - __logf(1.f + __expf(-fabsf(b[i]))); const float la = l0[bj][i], lbv = l1[bj][i];
;                     a[i] = la > 0.f ? __logf(la + (1.f - la) * __expf(s0)) : s0; b[i] = lbv > 0.f ? __logf(lbv + (1.f - lbv) * __expf(s1)) : s1; }
;                 *(f32x4*)(LF + (size_t)row * 512 + c) = a; *(f32x4*)(LF + (size_t)row * 512 + c + 4) = b; __builtin_amdgcn_sched_barrier(0); ) }
.LBB0_414:
	s_andn2_b64 vcc, exec, s[8:9]
	s_cbranch_vccnz .LBB0_416
	v_ashrrev_i32_e32 v167, 31, v166
	v_lshlrev_b64 v[128:129], 6, v[166:167]
	v_lshl_add_u64 v[128:129], v[160:161], 0, v[128:129]
	s_nop 0
	v_readlane_b32 s8, v255, 35
	v_lshlrev_b32_e32 v192, 2, v176
	v_readlane_b32 s9, v255, 36
	v_and_b32_e32 v133, 64, v215
	v_xor_b32_e32 v132, 16, v215
	v_lshl_add_u64 v[144:145], s[8:9], 0, v[192:193]
	flat_load_dwordx4 v[140:143], v[144:145]
	flat_load_dwordx4 v[136:139], v[144:145] offset:16
	v_add_u32_e32 v134, 64, v133
	v_cmp_lt_i32_e32 vcc, v132, v134
	v_lshlrev_b64 v[146:147], 11, v[166:167]
	v_readlane_b32 s50, v255, 45
	v_cndmask_b32_e32 v132, v215, v132, vcc
	v_lshlrev_b32_e32 v169, 2, v132
	v_readlane_b32 s51, v255, 46
	s_mov_b32 s95, s28
	s_mov_b32 s91, s29
	v_lshl_add_u64 v[170:171], s[50:51], 0, v[146:147]
	v_lshl_add_u64 v[170:171], v[170:171], 0, v[192:193]
	s_waitcnt vmcnt(0) lgkmcnt(0)
	s_nop 0
	s_nop 0
	s_nop 0
	s_nop 0
	v_xor_b32_e32 v130, 32, v215
	s_nop 0
	s_nop 0
	v_cmp_lt_i32_e32 vcc, v130, v134
	v_sub_f32_e32 v190, 1.0, v140
	v_sub_f32_e32 v191, 1.0, v136
	v_cndmask_b32_e32 v130, v215, v130, vcc
	v_lshlrev_b32_e32 v202, 2, v130
	s_waitcnt lgkmcnt(0)
	s_nop 0
	s_nop 0
	flat_load_dwordx4 v[132:135], v[144:145] offset:512
	flat_load_dwordx4 v[128:131], v[144:145] offset:528
	v_sub_f32_e32 v188, 1.0, v141
	v_cmp_lt_f32_e64 s[38:39], 0, v140
	v_cmp_lt_f32_e64 s[36:37], 0, v136
	s_waitcnt lgkmcnt(0)
	s_nop 0
	s_nop 0
	v_mov_b32_e32 v168, v250
	v_sub_f32_e32 v189, 1.0, v137
	v_cmp_lt_f32_e64 s[34:35], 0, v141
	v_cmp_lt_f32_e64 s[30:31], 0, v137
	v_pk_mul_f32 v[144:145], v[60:61], v[168:169] op_sel_hi:[1,0]
	v_pk_mul_f32 v[148:149], v[56:57], v[168:169] op_sel_hi:[1,0]
	v_min_f32_e32 v167, 0, v144
	v_mul_f32_e64 v144, |v144|, s57
	v_min_f32_e32 v177, 0, v148
	v_mul_f32_e64 v148, |v148|, s57
	v_exp_f32_e32 v144, v144
	v_exp_f32_e32 v148, v148
	v_min_f32_e32 v179, 0, v149
	v_mul_f32_e64 v149, |v149|, s57
	v_add_f32_e32 v144, 1.0, v144
	v_exp_f32_e32 v149, v149
	v_add_f32_e32 v148, 1.0, v148
	v_cmp_gt_f32_e64 s[8:9], s97, v144
	v_cmp_gt_f32_e64 s[10:11], s97, v148
	v_min_f32_e32 v178, 0, v145
	v_cndmask_b32_e64 v180, 0, 32, s[8:9]
	v_mul_f32_e64 v145, |v145|, s57
	v_cndmask_b32_e64 v181, 0, 32, s[10:11]
	v_ldexp_f32 v144, v144, v180
	v_exp_f32_e32 v145, v145
	v_ldexp_f32 v148, v148, v181
	v_log_f32_e32 v144, v144
	v_add_f32_e32 v149, 1.0, v149
	v_log_f32_e32 v148, v148
	v_cmp_gt_f32_e32 vcc, s97, v149
	v_add_f32_e32 v145, 1.0, v145
	v_cmp_gt_f32_e64 s[12:13], s97, v145
	v_cndmask_b32_e64 v183, 0, 32, vcc
	v_ldexp_f32 v149, v149, v183
	v_mul_f32_e32 v183, 0x3f317217, v144
	v_mul_f32_e32 v184, 0x3f317217, v148
	v_fma_f32 v183, v144, s52, -v183
	v_cndmask_b32_e64 v182, 0, 32, s[12:13]
	v_fma_f32 v184, v148, s52, -v184
	v_fmac_f32_e32 v183, 0x3377d1cf, v144
	v_cndmask_b32_e64 v180, 0, v216, s[8:9]
	v_ldexp_f32 v145, v145, v182
	v_fmac_f32_e32 v184, 0x3377d1cf, v148
	v_fmac_f32_e32 v183, 0x3f317217, v144
	v_cmp_lt_f32_e64 s[8:9], |v144|, s53
	v_log_f32_e32 v145, v145
	v_fmac_f32_e32 v184, 0x3f317217, v148
	v_cndmask_b32_e64 v144, v144, v183, s[8:9]
	v_cmp_lt_f32_e64 s[8:9], |v148|, s53
	v_cndmask_b32_e64 v181, 0, v216, s[10:11]
	v_log_f32_e32 v149, v149
	v_cndmask_b32_e64 v148, v148, v184, s[8:9]
	v_sub_f32_e32 v144, v144, v180
	v_sub_f32_e32 v148, v148, v181
	v_sub_f32_e32 v144, v167, v144
	v_sub_f32_e32 v167, v177, v148
	v_mul_f32_e32 v148, 0x3fb8aa3b, v144
	v_mul_f32_e32 v185, 0x3f317217, v145
	v_mul_f32_e32 v177, 0x3fb8aa3b, v167
	v_exp_f32_e32 v148, v148
	v_mul_f32_e32 v186, 0x3f317217, v149
	v_fma_f32 v185, v145, s52, -v185
	v_exp_f32_e32 v177, v177
	v_fma_f32 v186, v149, s52, -v186
	v_fmac_f32_e32 v185, 0x3377d1cf, v145
	v_fmac_f32_e32 v186, 0x3377d1cf, v149
	v_fmac_f32_e32 v185, 0x3f317217, v145
	v_cmp_lt_f32_e64 s[8:9], |v145|, s53
	v_fmac_f32_e32 v186, 0x3f317217, v149
	v_fma_f32 v148, v190, v148, v140
	v_cndmask_b32_e64 v145, v145, v185, s[8:9]
	v_cmp_lt_f32_e64 s[8:9], |v149|, s53
	v_fma_f32 v177, v191, v177, v136
	v_cmp_gt_f32_e64 s[10:11], s97, v177
	v_cndmask_b32_e64 v149, v149, v186, s[8:9]
	v_cmp_gt_f32_e64 s[8:9], s97, v148
	v_cndmask_b32_e64 v181, 0, 32, s[10:11]
	v_ldexp_f32 v177, v177, v181
	v_cndmask_b32_e64 v180, 0, 32, s[8:9]
	v_ldexp_f32 v148, v148, v180
	v_log_f32_e32 v148, v148
	v_cndmask_b32_e64 v182, 0, v216, s[12:13]
	v_log_f32_e32 v177, v177
	v_sub_f32_e32 v145, v145, v182
	v_sub_f32_e32 v145, v178, v145
	v_mul_f32_e32 v178, 0x3fb8aa3b, v145
	v_mul_f32_e32 v182, 0x3f317217, v148
	v_exp_f32_e32 v178, v178
	v_mul_f32_e32 v183, 0x3f317217, v177
	v_fma_f32 v182, v148, s52, -v182
	v_fma_f32 v183, v177, s52, -v183
	v_fmac_f32_e32 v182, 0x3377d1cf, v148
	v_cndmask_b32_e64 v180, 0, v216, s[8:9]
	v_fmac_f32_e32 v183, 0x3377d1cf, v177
	v_fmac_f32_e32 v182, 0x3f317217, v148
	v_cmp_lt_f32_e64 s[8:9], |v148|, s53
	v_fmac_f32_e32 v183, 0x3f317217, v177
	v_fma_f32 v178, v188, v178, v141
	v_cndmask_b32_e64 v148, v148, v182, s[8:9]
	v_cmp_lt_f32_e64 s[8:9], |v177|, s53
	v_cndmask_b32_e64 v181, 0, v216, s[10:11]
	v_sub_f32_e32 v148, v148, v180
	v_cndmask_b32_e64 v177, v177, v183, s[8:9]
	v_sub_f32_e32 v177, v177, v181
	v_cmp_gt_f32_e64 s[8:9], s97, v178
	v_cndmask_b32_e64 v148, v144, v148, s[38:39]
	v_cndmask_b32_e64 v144, v167, v177, s[36:37]
	v_cndmask_b32_e64 v167, 0, 32, s[8:9]
	v_ldexp_f32 v167, v178, v167
	v_cndmask_b32_e32 v177, 0, v216, vcc
	v_log_f32_e32 v167, v167
	v_sub_f32_e32 v149, v149, v177
	v_sub_f32_e32 v177, v179, v149
	v_mul_f32_e32 v178, 0x3fb8aa3b, v177
	v_exp_f32_e32 v178, v178
	v_mul_f32_e32 v149, 0x3f317217, v167
	v_fma_f32 v149, v167, s52, -v149
	v_fmac_f32_e32 v149, 0x3377d1cf, v167
;     __device__ __forceinline__ void operator()(const f32x4 (&acc)[2][2][4][2], const pg8::Unit& u, int wr, int wc, int fr, int fq) const {
;     ...
;             WIN_LOOP( _Pragma("unroll") for (int i = 0; i < 4; ++i) { const float s0 = fminf(a[i], 0.f) - __logf(1.f + __expf(-fabsf(a[i]))), s1 = fminf(b[i], 0.f) - __logf(1.f + __expf(-fabsf(b[i]))); const float la = l0[bj][i], lbv = l1[bj][i];
;                     a[i] = la > 0.f ? __logf(la + (1.f - la) * __expf(s0)) : s0; b[i] = lbv > 0.f ? __logf(lbv + (1.f - lbv) * __expf(s1)) : s1; }
;                 *(f32x4*)(LF + (size_t)row * 512 + c) = a; *(f32x4*)(LF + (size_t)row * 512 + c + 4) = b; __builtin_amdgcn_sched_barrier(0); ) }
	v_fmac_f32_e32 v149, 0x3f317217, v167
	v_cmp_lt_f32_e64 vcc, |v167|, s53
	v_fma_f32 v178, v189, v178, v137
	v_pk_mul_f32 v[150:151], v[62:63], v[168:169] op_sel_hi:[1,0]
	v_cndmask_b32_e32 v149, v167, v149, vcc
	v_cmp_gt_f32_e32 vcc, s97, v178
	v_cndmask_b32_e64 v167, 0, v216, s[8:9]
	v_sub_f32_e32 v149, v149, v167
	v_cndmask_b32_e64 v179, 0, 32, vcc
	v_ldexp_f32 v178, v178, v179
	v_log_f32_e32 v178, v178
	v_mul_f32_e64 v167, |v150|, s57
	v_exp_f32_e32 v167, v167
	v_cndmask_b32_e64 v149, v145, v149, s[34:35]
	v_mul_f32_e32 v145, 0x3f317217, v178
	v_fma_f32 v145, v178, s52, -v145
	v_fmac_f32_e32 v145, 0x3377d1cf, v178
	v_fmac_f32_e32 v145, 0x3f317217, v178
	v_cmp_lt_f32_e64 s[8:9], |v178|, s53
	v_add_f32_e32 v167, 1.0, v167
	v_pk_mul_f32 v[146:147], v[58:59], v[168:169] op_sel_hi:[1,0]
	v_cndmask_b32_e64 v145, v178, v145, s[8:9]
	v_cndmask_b32_e32 v178, 0, v216, vcc
	v_cmp_gt_f32_e32 vcc, s97, v167
	v_sub_f32_e32 v145, v145, v178
	v_cndmask_b32_e64 v145, v177, v145, s[30:31]
	v_cndmask_b32_e64 v178, 0, 32, vcc
	v_ldexp_f32 v167, v167, v178
	v_log_f32_e32 v167, v167
	v_mul_f32_e64 v178, |v146|, s57
	v_exp_f32_e32 v178, v178
	v_min_f32_e32 v150, 0, v150
	v_mul_f32_e32 v177, 0x3f317217, v167
	v_fma_f32 v177, v167, s52, -v177
	v_fmac_f32_e32 v177, 0x3377d1cf, v167
	v_fmac_f32_e32 v177, 0x3f317217, v167
	v_cmp_lt_f32_e64 s[8:9], |v167|, s53
	v_add_f32_e32 v178, 1.0, v178
	v_sub_f32_e32 v187, 1.0, v142
	v_cndmask_b32_e64 v167, v167, v177, s[8:9]
	v_cndmask_b32_e32 v177, 0, v216, vcc
	v_cmp_gt_f32_e32 vcc, s97, v178
	v_sub_f32_e32 v167, v167, v177
	v_sub_f32_e32 v150, v150, v167
	v_cndmask_b32_e64 v179, 0, 32, vcc
	v_ldexp_f32 v178, v178, v179
	v_log_f32_e32 v178, v178
	v_mul_f32_e32 v177, 0x3fb8aa3b, v150
	v_exp_f32_e32 v177, v177
	v_min_f32_e32 v146, 0, v146
	v_mul_f32_e32 v167, 0x3f317217, v178
	v_fma_f32 v167, v178, s52, -v167
	v_fmac_f32_e32 v167, 0x3377d1cf, v178
	v_fmac_f32_e32 v167, 0x3f317217, v178
	v_cmp_lt_f32_e64 s[8:9], |v178|, s53
	v_fma_f32 v177, v187, v177, v142
	v_sub_f32_e32 v186, 1.0, v138
	v_cndmask_b32_e64 v167, v178, v167, s[8:9]
	v_cmp_gt_f32_e64 s[8:9], s97, v177
	v_cmp_lt_f32_e64 s[28:29], 0, v142
	v_cmp_lt_f32_e64 s[26:27], 0, v138
	v_cndmask_b32_e64 v178, 0, 32, s[8:9]
	v_ldexp_f32 v177, v177, v178
	v_cndmask_b32_e32 v178, 0, v216, vcc
	v_log_f32_e32 v177, v177
	v_sub_f32_e32 v167, v167, v178
	v_sub_f32_e32 v146, v146, v167
	v_mul_f32_e32 v178, 0x3fb8aa3b, v146
	v_exp_f32_e32 v178, v178
	v_mul_f32_e32 v167, 0x3f317217, v177
	v_fma_f32 v167, v177, s52, -v167
	v_fmac_f32_e32 v167, 0x3377d1cf, v177
	v_fmac_f32_e32 v167, 0x3f317217, v177
	v_cmp_lt_f32_e64 vcc, |v177|, s53
	v_fma_f32 v178, v186, v178, v138
	v_sub_f32_e32 v185, 1.0, v143
	v_cndmask_b32_e32 v167, v177, v167, vcc
	v_cmp_gt_f32_e32 vcc, s97, v178
	v_cndmask_b32_e64 v177, 0, v216, s[8:9]
	v_sub_f32_e32 v167, v167, v177
	v_cndmask_b32_e64 v179, 0, 32, vcc
	v_ldexp_f32 v178, v178, v179
	v_log_f32_e32 v178, v178
	v_mul_f32_e64 v177, |v151|, s57
	v_exp_f32_e32 v177, v177
	v_cndmask_b32_e64 v150, v150, v167, s[28:29]
	v_mul_f32_e32 v167, 0x3f317217, v178
	v_fma_f32 v167, v178, s52, -v167
	v_fmac_f32_e32 v167, 0x3377d1cf, v178
	v_fmac_f32_e32 v167, 0x3f317217, v178
	v_cmp_lt_f32_e64 s[8:9], |v178|, s53
	v_add_f32_e32 v177, 1.0, v177
	v_min_f32_e32 v151, 0, v151
	v_cndmask_b32_e64 v167, v178, v167, s[8:9]
	v_cndmask_b32_e32 v178, 0, v216, vcc
	v_cmp_gt_f32_e32 vcc, s97, v177
	v_sub_f32_e32 v167, v167, v178
	v_cndmask_b32_e64 v146, v146, v167, s[26:27]
	v_cndmask_b32_e64 v178, 0, 32, vcc
	v_ldexp_f32 v177, v177, v178
	v_log_f32_e32 v177, v177
	v_mul_f32_e64 v178, |v147|, s57
	v_exp_f32_e32 v178, v178
	v_min_f32_e32 v147, 0, v147
	v_mul_f32_e32 v167, 0x3f317217, v177
	v_fma_f32 v167, v177, s52, -v167
	v_fmac_f32_e32 v167, 0x3377d1cf, v177
	v_fmac_f32_e32 v167, 0x3f317217, v177
	v_cmp_lt_f32_e64 s[8:9], |v177|, s53
	v_add_f32_e32 v178, 1.0, v178
	v_sub_f32_e32 v184, 1.0, v139
	v_cndmask_b32_e64 v167, v177, v167, s[8:9]
	v_cndmask_b32_e32 v177, 0, v216, vcc
	v_cmp_gt_f32_e32 vcc, s97, v178
	v_sub_f32_e32 v167, v167, v177
	v_sub_f32_e32 v151, v151, v167
	v_cndmask_b32_e64 v179, 0, 32, vcc
	v_ldexp_f32 v178, v178, v179
	v_log_f32_e32 v178, v178
	v_mul_f32_e32 v177, 0x3fb8aa3b, v151
	v_exp_f32_e32 v177, v177
	v_cmp_lt_f32_e64 s[24:25], 0, v143
	v_mul_f32_e32 v167, 0x3f317217, v178
	v_fma_f32 v167, v178, s52, -v167
	v_fmac_f32_e32 v167, 0x3377d1cf, v178
	v_fmac_f32_e32 v167, 0x3f317217, v178
	v_cmp_lt_f32_e64 s[8:9], |v178|, s53
	v_fma_f32 v177, v185, v177, v143
	v_cmp_lt_f32_e64 s[22:23], 0, v139
	v_cndmask_b32_e64 v167, v178, v167, s[8:9]
	v_cmp_gt_f32_e64 s[8:9], s97, v177
	s_nop 1
	v_cndmask_b32_e64 v178, 0, 32, s[8:9]
	v_ldexp_f32 v177, v177, v178
	v_cndmask_b32_e32 v178, 0, v216, vcc
	v_log_f32_e32 v177, v177
	v_sub_f32_e32 v167, v167, v178
	v_sub_f32_e32 v147, v147, v167
	v_mul_f32_e32 v178, 0x3fb8aa3b, v147
	v_exp_f32_e32 v178, v178
	v_mul_f32_e32 v167, 0x3f317217, v177
	v_fma_f32 v167, v177, s52, -v167
	v_fmac_f32_e32 v167, 0x3377d1cf, v177
	v_fmac_f32_e32 v167, 0x3f317217, v177
	v_cmp_lt_f32_e64 vcc, |v177|, s53
	v_fma_f32 v178, v184, v178, v139
	s_nop 0
	v_cndmask_b32_e32 v167, v177, v167, vcc
	v_cmp_gt_f32_e32 vcc, s97, v178
	v_cndmask_b32_e64 v177, 0, v216, s[8:9]
	v_sub_f32_e32 v167, v167, v177
	v_cndmask_b32_e64 v179, 0, 32, vcc
	v_ldexp_f32 v178, v178, v179
	v_log_f32_e32 v178, v178
	v_cndmask_b32_e64 v151, v151, v167, s[24:25]
	v_cndmask_b32_e32 v177, 0, v216, vcc
	v_mul_f32_e32 v167, 0x3f317217, v178
	v_fma_f32 v167, v178, s52, -v167
	v_fmac_f32_e32 v167, 0x3377d1cf, v178
	v_fmac_f32_e32 v167, 0x3f317217, v178
	v_cmp_lt_f32_e64 s[8:9], |v178|, s53
	s_nop 1
	v_cndmask_b32_e64 v167, v178, v167, s[8:9]
	v_sub_f32_e32 v167, v167, v177
	v_cndmask_b32_e64 v147, v147, v167, s[22:23]
	global_store_dwordx4 v[170:171], v[148:151], off
	global_store_dwordx4 v[170:171], v[144:147], off offset:16
	s_nop 1
	v_pk_mul_f32 v[144:145], v[124:125], v[168:169] op_sel_hi:[1,0]
	v_pk_mul_f32 v[150:151], v[126:127], v[168:169] op_sel_hi:[1,0]
	v_mul_f32_e64 v146, |v144|, s57
	v_exp_f32_e32 v148, v146
	v_pk_mul_f32 v[146:147], v[122:123], v[168:169] op_sel_hi:[1,0]
	v_min_f32_e32 v144, 0, v144
	s_waitcnt vmcnt(0)
;     __device__ __forceinline__ void operator()(const f32x4 (&acc)[2][2][4][2], const pg8::Unit& u, int wr, int wc, int fr, int fq) const {
;     ...
;             WIN_LOOP( _Pragma("unroll") for (int i = 0; i < 4; ++i) { const float s0 = fminf(a[i], 0.f) - __logf(1.f + __expf(-fabsf(a[i]))), s1 = fminf(b[i], 0.f) - __logf(1.f + __expf(-fabsf(b[i]))); const float la = l0[bj][i], lbv = l1[bj][i];
;                     a[i] = la > 0.f ? __logf(la + (1.f - la) * __expf(s0)) : s0; b[i] = lbv > 0.f ? __logf(lbv + (1.f - lbv) * __expf(s1)) : s1; }
;                 *(f32x4*)(LF + (size_t)row * 512 + c) = a; *(f32x4*)(LF + (size_t)row * 512 + c + 4) = b; __builtin_amdgcn_sched_barrier(0); ) }
	v_sub_f32_e32 v183, 1.0, v132
	v_add_f32_e32 v148, 1.0, v148
	v_cmp_gt_f32_e32 vcc, s97, v148
	v_sub_f32_e32 v182, 1.0, v128
	v_cmp_lt_f32_e64 s[20:21], 0, v132
	v_cndmask_b32_e64 v149, 0, 32, vcc
	v_ldexp_f32 v148, v148, v149
	v_log_f32_e32 v167, v148
	v_pk_mul_f32 v[148:149], v[120:121], v[168:169] op_sel_hi:[1,0]
	v_cmp_lt_f32_e64 s[18:19], 0, v128
	v_mul_f32_e64 v168, |v148|, s57
	v_exp_f32_e32 v168, v168
	v_mul_f32_e32 v177, 0x3f317217, v167
	v_fma_f32 v177, v167, s52, -v177
	v_fmac_f32_e32 v177, 0x3377d1cf, v167
	v_fmac_f32_e32 v177, 0x3f317217, v167
	v_cmp_lt_f32_e64 s[8:9], |v167|, s53
	v_add_f32_e32 v168, 1.0, v168
	v_min_f32_e32 v148, 0, v148
	v_cndmask_b32_e64 v167, v167, v177, s[8:9]
	v_cndmask_b32_e32 v177, 0, v216, vcc
	v_cmp_gt_f32_e32 vcc, s97, v168
	v_sub_f32_e32 v167, v167, v177
	v_sub_f32_e32 v144, v144, v167
	v_cndmask_b32_e64 v178, 0, 32, vcc
	v_ldexp_f32 v168, v168, v178
	v_log_f32_e32 v168, v168
	v_mul_f32_e32 v177, 0x3fb8aa3b, v144
	v_exp_f32_e32 v177, v177
	v_sub_f32_e32 v181, 1.0, v133
	v_mul_f32_e32 v167, 0x3f317217, v168
	v_fma_f32 v167, v168, s52, -v167
	v_fmac_f32_e32 v167, 0x3377d1cf, v168
	v_fmac_f32_e32 v167, 0x3f317217, v168
	v_cmp_lt_f32_e64 s[8:9], |v168|, s53
	v_sub_f32_e32 v180, 1.0, v129
	v_cmp_lt_f32_e64 s[16:17], 0, v133
	v_cndmask_b32_e64 v167, v168, v167, s[8:9]
	v_fma_f32 v168, v183, v177, v132
	v_cmp_gt_f32_e64 s[8:9], s97, v168
	v_cmp_lt_f32_e64 s[14:15], 0, v129
	v_sub_f32_e32 v179, 1.0, v134
	v_cndmask_b32_e64 v177, 0, 32, s[8:9]
	v_ldexp_f32 v168, v168, v177
	v_cndmask_b32_e32 v177, 0, v216, vcc
	v_log_f32_e32 v168, v168
	v_sub_f32_e32 v167, v167, v177
	v_sub_f32_e32 v148, v148, v167
	v_mul_f32_e32 v177, 0x3fb8aa3b, v148
	v_exp_f32_e32 v177, v177
	v_mul_f32_e32 v167, 0x3f317217, v168
	v_fma_f32 v167, v168, s52, -v167
	v_fmac_f32_e32 v167, 0x3377d1cf, v168
	v_fmac_f32_e32 v167, 0x3f317217, v168
	v_cmp_lt_f32_e64 vcc, |v168|, s53
	v_fma_f32 v177, v182, v177, v128
	v_cmp_lt_f32_e64 s[12:13], 0, v134
	v_cndmask_b32_e32 v167, v168, v167, vcc
	v_cmp_gt_f32_e32 vcc, s97, v177
	v_cndmask_b32_e64 v168, 0, v216, s[8:9]
	v_sub_f32_e32 v167, v167, v168
	v_cndmask_b32_e64 v178, 0, 32, vcc
	v_ldexp_f32 v177, v177, v178
	v_log_f32_e32 v177, v177
	v_mul_f32_e64 v168, |v145|, s57
	v_exp_f32_e32 v168, v168
	v_cndmask_b32_e64 v144, v144, v167, s[20:21]
	v_mul_f32_e32 v167, 0x3f317217, v177
	v_fma_f32 v167, v177, s52, -v167
	v_fmac_f32_e32 v167, 0x3377d1cf, v177
	v_fmac_f32_e32 v167, 0x3f317217, v177
	v_cmp_lt_f32_e64 s[8:9], |v177|, s53
	v_add_f32_e32 v168, 1.0, v168
	v_min_f32_e32 v145, 0, v145
	v_cndmask_b32_e64 v167, v177, v167, s[8:9]
	v_cndmask_b32_e32 v177, 0, v216, vcc
	v_cmp_gt_f32_e32 vcc, s97, v168
	v_sub_f32_e32 v167, v167, v177
	v_cndmask_b32_e64 v148, v148, v167, s[18:19]
	v_cndmask_b32_e64 v177, 0, 32, vcc
	v_ldexp_f32 v168, v168, v177
	v_log_f32_e32 v168, v168
	v_mul_f32_e64 v177, |v149|, s57
	v_exp_f32_e32 v177, v177
	v_min_f32_e32 v149, 0, v149
	v_mul_f32_e32 v167, 0x3f317217, v168
	v_fma_f32 v167, v168, s52, -v167
	v_fmac_f32_e32 v167, 0x3377d1cf, v168
	v_fmac_f32_e32 v167, 0x3f317217, v168
	v_cmp_lt_f32_e64 s[8:9], |v168|, s53
	v_add_f32_e32 v177, 1.0, v177
	v_cmp_lt_f32_e64 s[10:11], 0, v130
	v_cndmask_b32_e64 v167, v168, v167, s[8:9]
	v_cndmask_b32_e32 v168, 0, v216, vcc
	v_cmp_gt_f32_e32 vcc, s97, v177
	v_sub_f32_e32 v167, v167, v168
	v_sub_f32_e32 v145, v145, v167
	v_cndmask_b32_e64 v178, 0, 32, vcc
	v_ldexp_f32 v177, v177, v178
	v_log_f32_e32 v177, v177
	v_mul_f32_e32 v168, 0x3fb8aa3b, v145
	v_exp_f32_e32 v168, v168
	s_mov_b32 s2, s40
	v_mul_f32_e32 v167, 0x3f317217, v177
	v_fma_f32 v167, v177, s52, -v167
	v_fmac_f32_e32 v167, 0x3377d1cf, v177
	v_fmac_f32_e32 v167, 0x3f317217, v177
	v_cmp_lt_f32_e64 s[8:9], |v177|, s53
	v_fma_f32 v168, v181, v168, v133
	s_nop 0
	v_cndmask_b32_e64 v167, v177, v167, s[8:9]
	v_cmp_gt_f32_e64 s[8:9], s97, v168
	s_nop 1
	v_cndmask_b32_e64 v177, 0, 32, s[8:9]
	v_ldexp_f32 v168, v168, v177
	v_cndmask_b32_e32 v177, 0, v216, vcc
	v_log_f32_e32 v168, v168
	v_sub_f32_e32 v167, v167, v177
	v_sub_f32_e32 v149, v149, v167
	v_mul_f32_e32 v177, 0x3fb8aa3b, v149
	v_exp_f32_e32 v177, v177
	v_mul_f32_e32 v167, 0x3f317217, v168
	v_fma_f32 v167, v168, s52, -v167
	v_fmac_f32_e32 v167, 0x3377d1cf, v168
	v_fmac_f32_e32 v167, 0x3f317217, v168
	v_cmp_lt_f32_e64 vcc, |v168|, s53
	v_fma_f32 v177, v180, v177, v129
	s_nop 0
	v_cndmask_b32_e32 v167, v168, v167, vcc
	v_cmp_gt_f32_e32 vcc, s97, v177
	v_cndmask_b32_e64 v168, 0, v216, s[8:9]
	v_sub_f32_e32 v167, v167, v168
	v_cndmask_b32_e64 v178, 0, 32, vcc
	v_ldexp_f32 v177, v177, v178
	v_log_f32_e32 v177, v177
	v_mul_f32_e64 v168, |v150|, s57
	v_exp_f32_e32 v168, v168
	v_cndmask_b32_e64 v145, v145, v167, s[16:17]
	v_mul_f32_e32 v167, 0x3f317217, v177
	v_fma_f32 v167, v177, s52, -v167
	v_fmac_f32_e32 v167, 0x3377d1cf, v177
	v_fmac_f32_e32 v167, 0x3f317217, v177
	v_cmp_lt_f32_e64 s[8:9], |v177|, s53
	v_add_f32_e32 v168, 1.0, v168
	v_min_f32_e32 v150, 0, v150
	v_cndmask_b32_e64 v167, v177, v167, s[8:9]
	v_cndmask_b32_e32 v177, 0, v216, vcc
	v_cmp_gt_f32_e32 vcc, s97, v168
	v_sub_f32_e32 v167, v167, v177
	v_cndmask_b32_e64 v149, v149, v167, s[14:15]
	v_cndmask_b32_e64 v177, 0, 32, vcc
	v_ldexp_f32 v168, v168, v177
	v_log_f32_e32 v168, v168
	v_mul_f32_e64 v177, |v146|, s57
	v_exp_f32_e32 v177, v177
	v_min_f32_e32 v146, 0, v146
	v_mul_f32_e32 v167, 0x3f317217, v168
	v_fma_f32 v167, v168, s52, -v167
	v_fmac_f32_e32 v167, 0x3377d1cf, v168
	v_fmac_f32_e32 v167, 0x3f317217, v168
	v_cmp_lt_f32_e64 s[8:9], |v168|, s53
	v_add_f32_e32 v177, 1.0, v177
	s_nop 0
	v_cndmask_b32_e64 v167, v168, v167, s[8:9]
	v_cndmask_b32_e32 v168, 0, v216, vcc
;     __device__ __forceinline__ void operator()(const f32x4 (&acc)[2][2][4][2], const pg8::Unit& u, int wr, int wc, int fr, int fq) const {
;     ...
;             WIN_LOOP( _Pragma("unroll") for (int i = 0; i < 4; ++i) { const float s0 = fminf(a[i], 0.f) - __logf(1.f + __expf(-fabsf(a[i]))), s1 = fminf(b[i], 0.f) - __logf(1.f + __expf(-fabsf(b[i]))); const float la = l0[bj][i], lbv = l1[bj][i];
;                     a[i] = la > 0.f ? __logf(la + (1.f - la) * __expf(s0)) : s0; b[i] = lbv > 0.f ? __logf(lbv + (1.f - lbv) * __expf(s1)) : s1; }
;                 *(f32x4*)(LF + (size_t)row * 512 + c) = a; *(f32x4*)(LF + (size_t)row * 512 + c + 4) = b; __builtin_amdgcn_sched_barrier(0); ) }
	v_cmp_gt_f32_e32 vcc, s97, v177
	v_sub_f32_e32 v167, v167, v168
	v_sub_f32_e32 v150, v150, v167
	v_cndmask_b32_e64 v178, 0, 32, vcc
	v_ldexp_f32 v177, v177, v178
	v_log_f32_e32 v177, v177
	v_mul_f32_e32 v168, 0x3fb8aa3b, v150
	v_exp_f32_e32 v168, v168
	v_sub_f32_e32 v178, 1.0, v130
	v_mul_f32_e32 v167, 0x3f317217, v177
	v_fma_f32 v167, v177, s52, -v167
	v_fmac_f32_e32 v167, 0x3377d1cf, v177
	v_fmac_f32_e32 v167, 0x3f317217, v177
	v_cmp_lt_f32_e64 s[8:9], |v177|, s53
	v_fma_f32 v168, v179, v168, v134
	s_nop 0
	v_cndmask_b32_e64 v167, v177, v167, s[8:9]
	v_cmp_gt_f32_e64 s[8:9], s97, v168
	s_nop 1
	v_cndmask_b32_e64 v177, 0, 32, s[8:9]
	v_ldexp_f32 v168, v168, v177
	v_cndmask_b32_e32 v177, 0, v216, vcc
	v_log_f32_e32 v168, v168
	v_sub_f32_e32 v167, v167, v177
	v_sub_f32_e32 v167, v146, v167
	v_mul_f32_e32 v177, 0x3fb8aa3b, v167
	v_exp_f32_e32 v177, v177
	v_mul_f32_e32 v146, 0x3f317217, v168
	v_fma_f32 v146, v168, s52, -v146
	v_fmac_f32_e32 v146, 0x3377d1cf, v168
	v_fmac_f32_e32 v146, 0x3f317217, v168
	v_cmp_lt_f32_e64 vcc, |v168|, s53
	v_fma_f32 v177, v178, v177, v130
	s_nop 0
	v_cndmask_b32_e32 v146, v168, v146, vcc
	v_cmp_gt_f32_e32 vcc, s97, v177
	v_cndmask_b32_e64 v168, 0, v216, s[8:9]
	v_sub_f32_e32 v146, v146, v168
	v_cndmask_b32_e64 v194, 0, 32, vcc
	v_ldexp_f32 v177, v177, v194
	v_log_f32_e32 v177, v177
	v_mul_f32_e64 v168, |v151|, s57
	v_exp_f32_e32 v168, v168
	v_cndmask_b32_e64 v146, v150, v146, s[12:13]
	v_mul_f32_e32 v150, 0x3f317217, v177
	v_fma_f32 v150, v177, s52, -v150
	v_fmac_f32_e32 v150, 0x3377d1cf, v177
	v_fmac_f32_e32 v150, 0x3f317217, v177
	v_cmp_lt_f32_e64 s[8:9], |v177|, s53
	v_add_f32_e32 v168, 1.0, v168
	v_min_f32_e32 v151, 0, v151
	v_cndmask_b32_e64 v150, v177, v150, s[8:9]
	v_cndmask_b32_e32 v177, 0, v216, vcc
	v_cmp_gt_f32_e32 vcc, s97, v168
	v_sub_f32_e32 v150, v150, v177
	v_cndmask_b32_e64 v150, v167, v150, s[10:11]
	v_cndmask_b32_e64 v177, 0, 32, vcc
	v_ldexp_f32 v168, v168, v177
	v_log_f32_e32 v168, v168
	v_mul_f32_e64 v177, |v147|, s57
	v_exp_f32_e32 v177, v177
	v_min_f32_e32 v147, 0, v147
	v_mul_f32_e32 v167, 0x3f317217, v168
	v_fma_f32 v167, v168, s52, -v167
	v_fmac_f32_e32 v167, 0x3377d1cf, v168
	v_fmac_f32_e32 v167, 0x3f317217, v168
	v_cmp_lt_f32_e64 s[8:9], |v168|, s53
	v_add_f32_e32 v177, 1.0, v177
	s_nop 0
	v_cndmask_b32_e64 v167, v168, v167, s[8:9]
	v_cndmask_b32_e32 v168, 0, v216, vcc
	v_cmp_gt_f32_e32 vcc, s97, v177
	v_sub_f32_e32 v167, v167, v168
	v_sub_f32_e32 v151, v151, v167
	v_cndmask_b32_e64 v194, 0, 32, vcc
	v_ldexp_f32 v177, v177, v194
	v_log_f32_e32 v177, v177
	v_mul_f32_e32 v168, 0x3fb8aa3b, v151
	v_exp_f32_e32 v168, v168
	v_mul_f32_e32 v167, 0x3f317217, v177
	v_fma_f32 v167, v177, s52, -v167
	v_fmac_f32_e32 v167, 0x3377d1cf, v177
	v_fmac_f32_e32 v167, 0x3f317217, v177
	v_cmp_lt_f32_e64 s[8:9], |v177|, s53
	s_nop 1
	v_cndmask_b32_e64 v167, v177, v167, s[8:9]
	v_sub_f32_e32 v177, 1.0, v135
	v_fma_f32 v168, v177, v168, v135
	v_cmp_gt_f32_e64 s[8:9], s97, v168
	s_nop 1
	v_cndmask_b32_e64 v194, 0, 32, s[8:9]
	v_ldexp_f32 v168, v168, v194
	v_cndmask_b32_e32 v194, 0, v216, vcc
	v_log_f32_e32 v168, v168
	v_sub_f32_e32 v167, v167, v194
	v_sub_f32_e32 v194, v147, v167
	v_mul_f32_e32 v167, 0x3fb8aa3b, v194
	v_exp_f32_e32 v195, v167
	v_mul_f32_e32 v147, 0x3f317217, v168
	v_fma_f32 v147, v168, s52, -v147
	v_fmac_f32_e32 v147, 0x3377d1cf, v168
	v_sub_f32_e32 v167, 1.0, v131
	v_fmac_f32_e32 v147, 0x3f317217, v168
	v_cmp_lt_f32_e64 vcc, |v168|, s53
	v_fma_f32 v195, v167, v195, v131
	s_nop 0
	v_cndmask_b32_e32 v147, v168, v147, vcc
	v_cmp_gt_f32_e32 vcc, s97, v195
	v_cndmask_b32_e64 v168, 0, v216, s[8:9]
	v_sub_f32_e32 v147, v147, v168
	v_cndmask_b32_e64 v204, 0, 32, vcc
	v_ldexp_f32 v195, v195, v204
	v_log_f32_e32 v195, v195
	v_cmp_lt_f32_e64 s[8:9], 0, v135
	v_cndmask_b32_e32 v168, 0, v216, vcc
	v_cmp_lt_f32_e32 vcc, 0, v131
	v_cndmask_b32_e64 v147, v151, v147, s[8:9]
	v_mul_f32_e32 v151, 0x3f317217, v195
	v_fma_f32 v151, v195, s52, -v151
	v_fmac_f32_e32 v151, 0x3377d1cf, v195
	v_fmac_f32_e32 v151, 0x3f317217, v195
	v_cmp_lt_f32_e64 s[40:41], |v195|, s53
	s_nop 1
	v_cndmask_b32_e64 v151, v195, v151, s[40:41]
	v_sub_f32_e32 v151, v151, v168
	v_cndmask_b32_e32 v151, v194, v151, vcc
	global_store_dwordx4 v[170:171], v[144:147], off offset:512
	global_store_dwordx4 v[170:171], v[148:151], off offset:528
	s_nop 1
	v_or_b32_e32 v148, 16, v166
	v_ashrrev_i32_e32 v149, 31, v148
	v_lshlrev_b64 v[144:145], 6, v[148:149]
	v_lshl_add_u64 v[144:145], v[160:161], 0, v[144:145]
	s_nop 0
	s_waitcnt lgkmcnt(0)
	s_nop 0
	s_nop 0
	s_nop 0
	s_nop 0
	s_nop 0
	s_nop 0
	s_nop 0
	s_waitcnt lgkmcnt(0)
	s_nop 0
	s_nop 0
	s_waitcnt lgkmcnt(0)
;     __device__ __forceinline__ void operator()(const f32x4 (&acc)[2][2][4][2], const pg8::Unit& u, int wr, int wc, int fr, int fq) const {
;     ...
;             WIN_LOOP( _Pragma("unroll") for (int i = 0; i < 4; ++i) { const float s0 = fminf(a[i], 0.f) - __logf(1.f + __expf(-fabsf(a[i]))), s1 = fminf(b[i], 0.f) - __logf(1.f + __expf(-fabsf(b[i]))); const float la = l0[bj][i], lbv = l1[bj][i];
;                     a[i] = la > 0.f ? __logf(la + (1.f - la) * __expf(s0)) : s0; b[i] = lbv > 0.f ? __logf(lbv + (1.f - lbv) * __expf(s1)) : s1; }
;                 *(f32x4*)(LF + (size_t)row * 512 + c) = a; *(f32x4*)(LF + (size_t)row * 512 + c + 4) = b; __builtin_amdgcn_sched_barrier(0); ) }
	s_nop 0
	s_nop 0
	v_mov_b32_e32 v168, v251
	v_lshlrev_b64 v[144:145], 11, v[148:149]
	v_lshl_add_u64 v[170:171], s[50:51], 0, v[144:145]
	v_lshl_add_u64 v[170:171], v[170:171], 0, v[192:193]
	v_pk_mul_f32 v[148:149], v[52:53], v[168:169] op_sel_hi:[1,0]
	v_pk_mul_f32 v[144:145], v[48:49], v[168:169] op_sel_hi:[1,0]
	v_min_f32_e32 v194, 0, v148
	v_mul_f32_e64 v148, |v148|, s57
	v_exp_f32_e32 v148, v148
	v_pk_mul_f32 v[150:151], v[54:55], v[168:169] op_sel_hi:[1,0]
	v_pk_mul_f32 v[146:147], v[50:51], v[168:169] op_sel_hi:[1,0]
	v_add_f32_e32 v148, 1.0, v148
	v_cmp_gt_f32_e64 s[40:41], s97, v148
	s_nop 1
	v_cndmask_b32_e64 v195, 0, 32, s[40:41]
	v_ldexp_f32 v148, v148, v195
	v_log_f32_e32 v148, v148
	s_nop 0
	v_mul_f32_e32 v195, 0x3f317217, v148
	v_fma_f32 v195, v148, s52, -v195
	v_fmac_f32_e32 v195, 0x3377d1cf, v148
	v_fmac_f32_e32 v195, 0x3f317217, v148
	v_cmp_lt_f32_e64 s[42:43], |v148|, s53
	s_nop 1
	v_cndmask_b32_e64 v148, v148, v195, s[42:43]
	v_cndmask_b32_e64 v195, 0, v216, s[40:41]
	v_sub_f32_e32 v148, v148, v195
	v_sub_f32_e32 v148, v194, v148
	v_min_f32_e32 v194, 0, v144
	v_mul_f32_e64 v144, |v144|, s57
	v_exp_f32_e32 v144, v144
	s_nop 0
	v_add_f32_e32 v144, 1.0, v144
	v_cmp_gt_f32_e64 s[40:41], s97, v144
	s_nop 1
	v_cndmask_b32_e64 v195, 0, 32, s[40:41]
	v_ldexp_f32 v144, v144, v195
	v_log_f32_e32 v144, v144
	s_nop 0
	v_mul_f32_e32 v195, 0x3f317217, v144
	v_fma_f32 v195, v144, s52, -v195
	v_fmac_f32_e32 v195, 0x3377d1cf, v144
	v_fmac_f32_e32 v195, 0x3f317217, v144
	v_cmp_lt_f32_e64 s[42:43], |v144|, s53
	s_nop 1
	v_cndmask_b32_e64 v144, v144, v195, s[42:43]
	v_cndmask_b32_e64 v195, 0, v216, s[40:41]
	v_sub_f32_e32 v144, v144, v195
	v_sub_f32_e32 v194, v194, v144
	v_mul_f32_e32 v144, 0x3fb8aa3b, v148
	v_exp_f32_e32 v144, v144
	s_nop 0
	v_fma_f32 v144, v190, v144, v140
	v_cmp_gt_f32_e64 s[40:41], s97, v144
	s_nop 1
	v_cndmask_b32_e64 v195, 0, 32, s[40:41]
	v_ldexp_f32 v144, v144, v195
	v_log_f32_e32 v144, v144
	s_nop 0
	v_mul_f32_e32 v195, 0x3f317217, v144
	v_fma_f32 v195, v144, s52, -v195
	v_fmac_f32_e32 v195, 0x3377d1cf, v144
	v_fmac_f32_e32 v195, 0x3f317217, v144
	v_cmp_lt_f32_e64 s[42:43], |v144|, s53
	s_nop 1
	v_cndmask_b32_e64 v144, v144, v195, s[42:43]
	v_cndmask_b32_e64 v195, 0, v216, s[40:41]
	v_sub_f32_e32 v144, v144, v195
	v_cndmask_b32_e64 v144, v148, v144, s[38:39]
	v_mul_f32_e32 v148, 0x3fb8aa3b, v194
	v_exp_f32_e32 v148, v148
	s_nop 0
	v_fma_f32 v148, v191, v148, v136
	v_cmp_gt_f32_e64 s[40:41], s97, v148
	s_nop 1
	v_cndmask_b32_e64 v195, 0, 32, s[40:41]
	v_ldexp_f32 v148, v148, v195
	v_log_f32_e32 v148, v148
	s_nop 0
	v_mul_f32_e32 v195, 0x3f317217, v148
	v_fma_f32 v195, v148, s52, -v195
	v_fmac_f32_e32 v195, 0x3377d1cf, v148
	v_fmac_f32_e32 v195, 0x3f317217, v148
	v_cmp_lt_f32_e64 s[42:43], |v148|, s53
	s_nop 1
	v_cndmask_b32_e64 v148, v148, v195, s[42:43]
	v_cndmask_b32_e64 v195, 0, v216, s[40:41]
	v_sub_f32_e32 v148, v148, v195
	v_cndmask_b32_e64 v148, v194, v148, s[36:37]
	v_min_f32_e32 v194, 0, v149
	v_mul_f32_e64 v149, |v149|, s57
	v_exp_f32_e32 v149, v149
	s_nop 0
	v_add_f32_e32 v149, 1.0, v149
	v_cmp_gt_f32_e64 s[40:41], s97, v149
	s_nop 1
	v_cndmask_b32_e64 v195, 0, 32, s[40:41]
	v_ldexp_f32 v149, v149, v195
	v_log_f32_e32 v149, v149
	s_nop 0
	v_mul_f32_e32 v195, 0x3f317217, v149
	v_fma_f32 v195, v149, s52, -v195
	v_fmac_f32_e32 v195, 0x3377d1cf, v149
	v_fmac_f32_e32 v195, 0x3f317217, v149
	v_cmp_lt_f32_e64 s[42:43], |v149|, s53
	s_nop 1
	v_cndmask_b32_e64 v149, v149, v195, s[42:43]
	v_cndmask_b32_e64 v195, 0, v216, s[40:41]
	v_sub_f32_e32 v149, v149, v195
	v_sub_f32_e32 v149, v194, v149
	v_min_f32_e32 v194, 0, v145
	v_mul_f32_e64 v145, |v145|, s57
	v_exp_f32_e32 v145, v145
	s_nop 0
	v_add_f32_e32 v145, 1.0, v145
	v_cmp_gt_f32_e64 s[40:41], s97, v145
	s_nop 1
	v_cndmask_b32_e64 v195, 0, 32, s[40:41]
	v_ldexp_f32 v145, v145, v195
	v_log_f32_e32 v145, v145
	s_nop 0
	v_mul_f32_e32 v195, 0x3f317217, v145
	v_fma_f32 v195, v145, s52, -v195
	v_fmac_f32_e32 v195, 0x3377d1cf, v145
	v_fmac_f32_e32 v195, 0x3f317217, v145
	v_cmp_lt_f32_e64 s[42:43], |v145|, s53
	s_nop 1
	v_cndmask_b32_e64 v145, v145, v195, s[42:43]
	v_cndmask_b32_e64 v195, 0, v216, s[40:41]
	v_sub_f32_e32 v145, v145, v195
	v_sub_f32_e32 v194, v194, v145
	v_mul_f32_e32 v145, 0x3fb8aa3b, v149
	v_exp_f32_e32 v145, v145
	s_nop 0
	v_fma_f32 v145, v188, v145, v141
	v_cmp_gt_f32_e64 s[40:41], s97, v145
	s_nop 1
	v_cndmask_b32_e64 v195, 0, 32, s[40:41]
	v_ldexp_f32 v145, v145, v195
	v_log_f32_e32 v145, v145
	s_nop 0
	v_mul_f32_e32 v195, 0x3f317217, v145
	v_fma_f32 v195, v145, s52, -v195
	v_fmac_f32_e32 v195, 0x3377d1cf, v145
	v_fmac_f32_e32 v195, 0x3f317217, v145
	v_cmp_lt_f32_e64 s[42:43], |v145|, s53
	s_nop 1
	v_cndmask_b32_e64 v145, v145, v195, s[42:43]
	v_cndmask_b32_e64 v195, 0, v216, s[40:41]
	v_sub_f32_e32 v145, v145, v195
	v_cndmask_b32_e64 v145, v149, v145, s[34:35]
	v_mul_f32_e32 v149, 0x3fb8aa3b, v194
	v_exp_f32_e32 v149, v149
	s_nop 0
	v_fma_f32 v149, v189, v149, v137
	v_cmp_gt_f32_e64 s[40:41], s97, v149
	s_nop 1
	v_cndmask_b32_e64 v195, 0, 32, s[40:41]
	v_ldexp_f32 v149, v149, v195
	v_log_f32_e32 v149, v149
	s_nop 0
	v_mul_f32_e32 v195, 0x3f317217, v149
	v_fma_f32 v195, v149, s52, -v195
	v_fmac_f32_e32 v195, 0x3377d1cf, v149
	v_fmac_f32_e32 v195, 0x3f317217, v149
	v_cmp_lt_f32_e64 s[42:43], |v149|, s53
	s_nop 1
	v_cndmask_b32_e64 v149, v149, v195, s[42:43]
	v_cndmask_b32_e64 v195, 0, v216, s[40:41]
	v_sub_f32_e32 v149, v149, v195
	v_cndmask_b32_e64 v149, v194, v149, s[30:31]
	v_min_f32_e32 v194, 0, v150
	v_mul_f32_e64 v150, |v150|, s57
	v_exp_f32_e32 v150, v150
	s_nop 0
	v_add_f32_e32 v150, 1.0, v150
	v_cmp_gt_f32_e64 s[40:41], s97, v150
;     __device__ __forceinline__ void operator()(const f32x4 (&acc)[2][2][4][2], const pg8::Unit& u, int wr, int wc, int fr, int fq) const {
;     ...
;             WIN_LOOP( _Pragma("unroll") for (int i = 0; i < 4; ++i) { const float s0 = fminf(a[i], 0.f) - __logf(1.f + __expf(-fabsf(a[i]))), s1 = fminf(b[i], 0.f) - __logf(1.f + __expf(-fabsf(b[i]))); const float la = l0[bj][i], lbv = l1[bj][i];
;                     a[i] = la > 0.f ? __logf(la + (1.f - la) * __expf(s0)) : s0; b[i] = lbv > 0.f ? __logf(lbv + (1.f - lbv) * __expf(s1)) : s1; }
;                 *(f32x4*)(LF + (size_t)row * 512 + c) = a; *(f32x4*)(LF + (size_t)row * 512 + c + 4) = b; __builtin_amdgcn_sched_barrier(0); ) }
	s_nop 1
	v_cndmask_b32_e64 v195, 0, 32, s[40:41]
	v_ldexp_f32 v150, v150, v195
	v_log_f32_e32 v150, v150
	s_nop 0
	v_mul_f32_e32 v195, 0x3f317217, v150
	v_fma_f32 v195, v150, s52, -v195
	v_fmac_f32_e32 v195, 0x3377d1cf, v150
	v_fmac_f32_e32 v195, 0x3f317217, v150
	v_cmp_lt_f32_e64 s[42:43], |v150|, s53
	s_nop 1
	v_cndmask_b32_e64 v150, v150, v195, s[42:43]
	v_cndmask_b32_e64 v195, 0, v216, s[40:41]
	v_sub_f32_e32 v150, v150, v195
	v_sub_f32_e32 v150, v194, v150
	v_min_f32_e32 v194, 0, v146
	v_mul_f32_e64 v146, |v146|, s57
	v_exp_f32_e32 v146, v146
	s_nop 0
	v_add_f32_e32 v146, 1.0, v146
	v_cmp_gt_f32_e64 s[40:41], s97, v146
	s_nop 1
	v_cndmask_b32_e64 v195, 0, 32, s[40:41]
	v_ldexp_f32 v146, v146, v195
	v_log_f32_e32 v146, v146
	s_nop 0
	v_mul_f32_e32 v195, 0x3f317217, v146
	v_fma_f32 v195, v146, s52, -v195
	v_fmac_f32_e32 v195, 0x3377d1cf, v146
	v_fmac_f32_e32 v195, 0x3f317217, v146
	v_cmp_lt_f32_e64 s[42:43], |v146|, s53
	s_nop 1
	v_cndmask_b32_e64 v146, v146, v195, s[42:43]
	v_cndmask_b32_e64 v195, 0, v216, s[40:41]
	v_sub_f32_e32 v146, v146, v195
	v_sub_f32_e32 v194, v194, v146
	v_mul_f32_e32 v146, 0x3fb8aa3b, v150
	v_exp_f32_e32 v146, v146
	s_nop 0
	v_fma_f32 v146, v187, v146, v142
	v_cmp_gt_f32_e64 s[40:41], s97, v146
	s_nop 1
	v_cndmask_b32_e64 v195, 0, 32, s[40:41]
	v_ldexp_f32 v146, v146, v195
	v_log_f32_e32 v146, v146
	s_nop 0
	v_mul_f32_e32 v195, 0x3f317217, v146
	v_fma_f32 v195, v146, s52, -v195
	v_fmac_f32_e32 v195, 0x3377d1cf, v146
	v_fmac_f32_e32 v195, 0x3f317217, v146
	v_cmp_lt_f32_e64 s[42:43], |v146|, s53
	s_nop 1
	v_cndmask_b32_e64 v146, v146, v195, s[42:43]
	v_cndmask_b32_e64 v195, 0, v216, s[40:41]
	v_sub_f32_e32 v146, v146, v195
	v_cndmask_b32_e64 v146, v150, v146, s[28:29]
	v_mul_f32_e32 v150, 0x3fb8aa3b, v194
	v_exp_f32_e32 v150, v150
	s_nop 0
	v_fma_f32 v150, v186, v150, v138
	v_cmp_gt_f32_e64 s[40:41], s97, v150
	s_nop 1
	v_cndmask_b32_e64 v195, 0, 32, s[40:41]
	v_ldexp_f32 v150, v150, v195
	v_log_f32_e32 v150, v150
	s_nop 0
	v_mul_f32_e32 v195, 0x3f317217, v150
	v_fma_f32 v195, v150, s52, -v195
	v_fmac_f32_e32 v195, 0x3377d1cf, v150
	v_fmac_f32_e32 v195, 0x3f317217, v150
	v_cmp_lt_f32_e64 s[42:43], |v150|, s53
	s_nop 1
	v_cndmask_b32_e64 v150, v150, v195, s[42:43]
	v_cndmask_b32_e64 v195, 0, v216, s[40:41]
	v_sub_f32_e32 v150, v150, v195
	v_cndmask_b32_e64 v150, v194, v150, s[26:27]
	v_min_f32_e32 v194, 0, v151
	v_mul_f32_e64 v151, |v151|, s57
	v_exp_f32_e32 v151, v151
	s_nop 0
	v_add_f32_e32 v151, 1.0, v151
	v_cmp_gt_f32_e64 s[40:41], s97, v151
	s_nop 1
	v_cndmask_b32_e64 v195, 0, 32, s[40:41]
	v_ldexp_f32 v151, v151, v195
	v_log_f32_e32 v151, v151
	s_nop 0
	v_mul_f32_e32 v195, 0x3f317217, v151
	v_fma_f32 v195, v151, s52, -v195
	v_fmac_f32_e32 v195, 0x3377d1cf, v151
	v_fmac_f32_e32 v195, 0x3f317217, v151
	v_cmp_lt_f32_e64 s[42:43], |v151|, s53
	s_nop 1
	v_cndmask_b32_e64 v151, v151, v195, s[42:43]
	v_cndmask_b32_e64 v195, 0, v216, s[40:41]
	v_sub_f32_e32 v151, v151, v195
	v_sub_f32_e32 v151, v194, v151
	v_min_f32_e32 v194, 0, v147
	v_mul_f32_e64 v147, |v147|, s57
	v_exp_f32_e32 v147, v147
	s_nop 0
	v_add_f32_e32 v147, 1.0, v147
	v_cmp_gt_f32_e64 s[40:41], s97, v147
	s_nop 1
	v_cndmask_b32_e64 v195, 0, 32, s[40:41]
	v_ldexp_f32 v147, v147, v195
	v_log_f32_e32 v147, v147
	s_nop 0
	v_mul_f32_e32 v195, 0x3f317217, v147
	v_fma_f32 v195, v147, s52, -v195
	v_fmac_f32_e32 v195, 0x3377d1cf, v147
	v_fmac_f32_e32 v195, 0x3f317217, v147
	v_cmp_lt_f32_e64 s[42:43], |v147|, s53
	s_nop 1
	v_cndmask_b32_e64 v147, v147, v195, s[42:43]
	v_cndmask_b32_e64 v195, 0, v216, s[40:41]
	v_sub_f32_e32 v147, v147, v195
	v_sub_f32_e32 v194, v194, v147
	v_mul_f32_e32 v147, 0x3fb8aa3b, v151
	v_exp_f32_e32 v147, v147
	s_nop 0
	v_fma_f32 v147, v185, v147, v143
	v_cmp_gt_f32_e64 s[40:41], s97, v147
	s_nop 1
	v_cndmask_b32_e64 v195, 0, 32, s[40:41]
	v_ldexp_f32 v147, v147, v195
	v_log_f32_e32 v147, v147
	s_nop 0
	v_mul_f32_e32 v195, 0x3f317217, v147
	v_fma_f32 v195, v147, s52, -v195
	v_fmac_f32_e32 v195, 0x3377d1cf, v147
	v_fmac_f32_e32 v195, 0x3f317217, v147
	v_cmp_lt_f32_e64 s[42:43], |v147|, s53
	s_nop 1
	v_cndmask_b32_e64 v147, v147, v195, s[42:43]
	v_cndmask_b32_e64 v195, 0, v216, s[40:41]
	v_sub_f32_e32 v147, v147, v195
	v_cndmask_b32_e64 v147, v151, v147, s[24:25]
	v_mul_f32_e32 v151, 0x3fb8aa3b, v194
	v_exp_f32_e32 v151, v151
	s_nop 0
	v_fma_f32 v151, v184, v151, v139
	v_cmp_gt_f32_e64 s[40:41], s97, v151
	s_nop 1
	v_cndmask_b32_e64 v195, 0, 32, s[40:41]
	v_ldexp_f32 v151, v151, v195
	v_log_f32_e32 v151, v151
	s_nop 0
	v_mul_f32_e32 v195, 0x3f317217, v151
	v_fma_f32 v195, v151, s52, -v195
	v_fmac_f32_e32 v195, 0x3377d1cf, v151
	v_fmac_f32_e32 v195, 0x3f317217, v151
	v_cmp_lt_f32_e64 s[42:43], |v151|, s53
	s_nop 1
	v_cndmask_b32_e64 v151, v151, v195, s[42:43]
	v_cndmask_b32_e64 v195, 0, v216, s[40:41]
	v_sub_f32_e32 v151, v151, v195
	v_cndmask_b32_e64 v151, v194, v151, s[22:23]
	global_store_dwordx4 v[170:171], v[144:147], off
	global_store_dwordx4 v[170:171], v[148:151], off offset:16
	s_nop 1
	v_pk_mul_f32 v[148:149], v[116:117], v[168:169] op_sel_hi:[1,0]
	v_pk_mul_f32 v[150:151], v[118:119], v[168:169] op_sel_hi:[1,0]
	v_pk_mul_f32 v[146:147], v[114:115], v[168:169] op_sel_hi:[1,0]
	v_pk_mul_f32 v[144:145], v[112:113], v[168:169] op_sel_hi:[1,0]
	v_min_f32_e32 v168, 0, v148
	v_mul_f32_e64 v148, |v148|, s57
	v_exp_f32_e32 v148, v148
	s_nop 0
	v_add_f32_e32 v148, 1.0, v148
	v_cmp_gt_f32_e64 s[40:41], s97, v148
	s_nop 1
	v_cndmask_b32_e64 v194, 0, 32, s[40:41]
	v_ldexp_f32 v148, v148, v194
	v_log_f32_e32 v148, v148
	s_nop 0
	v_mul_f32_e32 v194, 0x3f317217, v148
	v_fma_f32 v194, v148, s52, -v194
	v_fmac_f32_e32 v194, 0x3377d1cf, v148
;     __device__ __forceinline__ void operator()(const f32x4 (&acc)[2][2][4][2], const pg8::Unit& u, int wr, int wc, int fr, int fq) const {
;     ...
;             WIN_LOOP( _Pragma("unroll") for (int i = 0; i < 4; ++i) { const float s0 = fminf(a[i], 0.f) - __logf(1.f + __expf(-fabsf(a[i]))), s1 = fminf(b[i], 0.f) - __logf(1.f + __expf(-fabsf(b[i]))); const float la = l0[bj][i], lbv = l1[bj][i];
;                     a[i] = la > 0.f ? __logf(la + (1.f - la) * __expf(s0)) : s0; b[i] = lbv > 0.f ? __logf(lbv + (1.f - lbv) * __expf(s1)) : s1; }
;                 *(f32x4*)(LF + (size_t)row * 512 + c) = a; *(f32x4*)(LF + (size_t)row * 512 + c + 4) = b; __builtin_amdgcn_sched_barrier(0); ) }
	v_fmac_f32_e32 v194, 0x3f317217, v148
	v_cmp_lt_f32_e64 s[42:43], |v148|, s53
	s_nop 1
	v_cndmask_b32_e64 v148, v148, v194, s[42:43]
	v_cndmask_b32_e64 v194, 0, v216, s[40:41]
	v_sub_f32_e32 v148, v148, v194
	v_sub_f32_e32 v148, v168, v148
	v_min_f32_e32 v168, 0, v144
	v_mul_f32_e64 v144, |v144|, s57
	v_exp_f32_e32 v144, v144
	s_nop 0
	v_add_f32_e32 v144, 1.0, v144
	v_cmp_gt_f32_e64 s[40:41], s97, v144
	s_nop 1
	v_cndmask_b32_e64 v194, 0, 32, s[40:41]
	v_ldexp_f32 v144, v144, v194
	v_log_f32_e32 v144, v144
	s_nop 0
	v_mul_f32_e32 v194, 0x3f317217, v144
	v_fma_f32 v194, v144, s52, -v194
	v_fmac_f32_e32 v194, 0x3377d1cf, v144
	v_fmac_f32_e32 v194, 0x3f317217, v144
	v_cmp_lt_f32_e64 s[42:43], |v144|, s53
	s_nop 1
	v_cndmask_b32_e64 v144, v144, v194, s[42:43]
	v_cndmask_b32_e64 v194, 0, v216, s[40:41]
	v_sub_f32_e32 v144, v144, v194
	v_sub_f32_e32 v168, v168, v144
	v_mul_f32_e32 v144, 0x3fb8aa3b, v148
	v_exp_f32_e32 v144, v144
	s_nop 0
	v_fma_f32 v144, v183, v144, v132
	v_cmp_gt_f32_e64 s[40:41], s97, v144
	s_nop 1
	v_cndmask_b32_e64 v194, 0, 32, s[40:41]
	v_ldexp_f32 v144, v144, v194
	v_log_f32_e32 v144, v144
	s_nop 0
	v_mul_f32_e32 v194, 0x3f317217, v144
	v_fma_f32 v194, v144, s52, -v194
	v_fmac_f32_e32 v194, 0x3377d1cf, v144
	v_fmac_f32_e32 v194, 0x3f317217, v144
	v_cmp_lt_f32_e64 s[42:43], |v144|, s53
	s_nop 1
	v_cndmask_b32_e64 v144, v144, v194, s[42:43]
	v_cndmask_b32_e64 v194, 0, v216, s[40:41]
	v_sub_f32_e32 v144, v144, v194
	v_cndmask_b32_e64 v144, v148, v144, s[20:21]
	v_mul_f32_e32 v148, 0x3fb8aa3b, v168
	v_exp_f32_e32 v148, v148
	s_nop 0
	v_fma_f32 v148, v182, v148, v128
	v_cmp_gt_f32_e64 s[40:41], s97, v148
	s_nop 1
	v_cndmask_b32_e64 v194, 0, 32, s[40:41]
	v_ldexp_f32 v148, v148, v194
	v_log_f32_e32 v148, v148
	s_nop 0
	v_mul_f32_e32 v194, 0x3f317217, v148
	v_fma_f32 v194, v148, s52, -v194
	v_fmac_f32_e32 v194, 0x3377d1cf, v148
	v_fmac_f32_e32 v194, 0x3f317217, v148
	v_cmp_lt_f32_e64 s[42:43], |v148|, s53
	s_nop 1
	v_cndmask_b32_e64 v148, v148, v194, s[42:43]
	v_cndmask_b32_e64 v194, 0, v216, s[40:41]
	v_sub_f32_e32 v148, v148, v194
	v_cndmask_b32_e64 v148, v168, v148, s[18:19]
	v_min_f32_e32 v168, 0, v149
	v_mul_f32_e64 v149, |v149|, s57
	v_exp_f32_e32 v149, v149
	s_nop 0
	v_add_f32_e32 v149, 1.0, v149
	v_cmp_gt_f32_e64 s[40:41], s97, v149
	s_nop 1
	v_cndmask_b32_e64 v194, 0, 32, s[40:41]
	v_ldexp_f32 v149, v149, v194
	v_log_f32_e32 v149, v149
	s_nop 0
	v_mul_f32_e32 v194, 0x3f317217, v149
	v_fma_f32 v194, v149, s52, -v194
	v_fmac_f32_e32 v194, 0x3377d1cf, v149
	v_fmac_f32_e32 v194, 0x3f317217, v149
	v_cmp_lt_f32_e64 s[42:43], |v149|, s53
	s_nop 1
	v_cndmask_b32_e64 v149, v149, v194, s[42:43]
	v_cndmask_b32_e64 v194, 0, v216, s[40:41]
	v_sub_f32_e32 v149, v149, v194
	v_sub_f32_e32 v149, v168, v149
	v_min_f32_e32 v168, 0, v145
	v_mul_f32_e64 v145, |v145|, s57
	v_exp_f32_e32 v145, v145
	s_nop 0
	v_add_f32_e32 v145, 1.0, v145
	v_cmp_gt_f32_e64 s[40:41], s97, v145
	s_nop 1
	v_cndmask_b32_e64 v194, 0, 32, s[40:41]
	v_ldexp_f32 v145, v145, v194
	v_log_f32_e32 v145, v145
	s_nop 0
	v_mul_f32_e32 v194, 0x3f317217, v145
	v_fma_f32 v194, v145, s52, -v194
	v_fmac_f32_e32 v194, 0x3377d1cf, v145
	v_fmac_f32_e32 v194, 0x3f317217, v145
	v_cmp_lt_f32_e64 s[42:43], |v145|, s53
	s_nop 1
	v_cndmask_b32_e64 v145, v145, v194, s[42:43]
	v_cndmask_b32_e64 v194, 0, v216, s[40:41]
	v_sub_f32_e32 v145, v145, v194
	v_sub_f32_e32 v168, v168, v145
	v_mul_f32_e32 v145, 0x3fb8aa3b, v149
	v_exp_f32_e32 v145, v145
	s_nop 0
	v_fma_f32 v145, v181, v145, v133
	v_cmp_gt_f32_e64 s[40:41], s97, v145
	s_nop 1
	v_cndmask_b32_e64 v194, 0, 32, s[40:41]
	v_ldexp_f32 v145, v145, v194
	v_log_f32_e32 v145, v145
	s_nop 0
	v_mul_f32_e32 v194, 0x3f317217, v145
	v_fma_f32 v194, v145, s52, -v194
	v_fmac_f32_e32 v194, 0x3377d1cf, v145
	v_fmac_f32_e32 v194, 0x3f317217, v145
	v_cmp_lt_f32_e64 s[42:43], |v145|, s53
	s_nop 1
	v_cndmask_b32_e64 v145, v145, v194, s[42:43]
	v_cndmask_b32_e64 v194, 0, v216, s[40:41]
	v_sub_f32_e32 v145, v145, v194
	v_cndmask_b32_e64 v145, v149, v145, s[16:17]
	v_mul_f32_e32 v149, 0x3fb8aa3b, v168
	v_exp_f32_e32 v149, v149
	s_nop 0
	v_fma_f32 v149, v180, v149, v129
	v_cmp_gt_f32_e64 s[40:41], s97, v149
	s_nop 1
	v_cndmask_b32_e64 v194, 0, 32, s[40:41]
	v_ldexp_f32 v149, v149, v194
	v_log_f32_e32 v149, v149
	s_nop 0
	v_mul_f32_e32 v194, 0x3f317217, v149
	v_fma_f32 v194, v149, s52, -v194
	v_fmac_f32_e32 v194, 0x3377d1cf, v149
	v_fmac_f32_e32 v194, 0x3f317217, v149
	v_cmp_lt_f32_e64 s[42:43], |v149|, s53
	s_nop 1
	v_cndmask_b32_e64 v149, v149, v194, s[42:43]
	v_cndmask_b32_e64 v194, 0, v216, s[40:41]
	v_sub_f32_e32 v149, v149, v194
	v_cndmask_b32_e64 v149, v168, v149, s[14:15]
	v_min_f32_e32 v168, 0, v150
	v_mul_f32_e64 v150, |v150|, s57
	v_exp_f32_e32 v150, v150
	s_nop 0
	v_add_f32_e32 v150, 1.0, v150
	v_cmp_gt_f32_e64 s[40:41], s97, v150
	s_nop 1
	v_cndmask_b32_e64 v194, 0, 32, s[40:41]
	v_ldexp_f32 v150, v150, v194
	v_log_f32_e32 v150, v150
	s_nop 0
	v_mul_f32_e32 v194, 0x3f317217, v150
	v_fma_f32 v194, v150, s52, -v194
	v_fmac_f32_e32 v194, 0x3377d1cf, v150
	v_fmac_f32_e32 v194, 0x3f317217, v150
	v_cmp_lt_f32_e64 s[42:43], |v150|, s53
	s_nop 1
	v_cndmask_b32_e64 v150, v150, v194, s[42:43]
	v_cndmask_b32_e64 v194, 0, v216, s[40:41]
	v_sub_f32_e32 v150, v150, v194
	v_sub_f32_e32 v150, v168, v150
	v_min_f32_e32 v168, 0, v146
	v_mul_f32_e64 v146, |v146|, s57
	v_exp_f32_e32 v146, v146
	s_nop 0
	v_add_f32_e32 v146, 1.0, v146
	v_cmp_gt_f32_e64 s[40:41], s97, v146
	s_nop 1
	v_cndmask_b32_e64 v194, 0, 32, s[40:41]
	v_ldexp_f32 v146, v146, v194
	v_log_f32_e32 v146, v146
	s_nop 0
	v_mul_f32_e32 v194, 0x3f317217, v146
	v_fma_f32 v194, v146, s52, -v194
;     __device__ __forceinline__ void operator()(const f32x4 (&acc)[2][2][4][2], const pg8::Unit& u, int wr, int wc, int fr, int fq) const {
;     ...
;             WIN_LOOP( _Pragma("unroll") for (int i = 0; i < 4; ++i) { const float s0 = fminf(a[i], 0.f) - __logf(1.f + __expf(-fabsf(a[i]))), s1 = fminf(b[i], 0.f) - __logf(1.f + __expf(-fabsf(b[i]))); const float la = l0[bj][i], lbv = l1[bj][i];
;                     a[i] = la > 0.f ? __logf(la + (1.f - la) * __expf(s0)) : s0; b[i] = lbv > 0.f ? __logf(lbv + (1.f - lbv) * __expf(s1)) : s1; }
;                 *(f32x4*)(LF + (size_t)row * 512 + c) = a; *(f32x4*)(LF + (size_t)row * 512 + c + 4) = b; __builtin_amdgcn_sched_barrier(0); ) }
	v_fmac_f32_e32 v194, 0x3377d1cf, v146
	v_fmac_f32_e32 v194, 0x3f317217, v146
	v_cmp_lt_f32_e64 s[42:43], |v146|, s53
	s_nop 1
	v_cndmask_b32_e64 v146, v146, v194, s[42:43]
	v_cndmask_b32_e64 v194, 0, v216, s[40:41]
	v_sub_f32_e32 v146, v146, v194
	v_sub_f32_e32 v168, v168, v146
	v_mul_f32_e32 v146, 0x3fb8aa3b, v150
	v_exp_f32_e32 v146, v146
	s_nop 0
	v_fma_f32 v146, v179, v146, v134
	v_cmp_gt_f32_e64 s[40:41], s97, v146
	s_nop 1
	v_cndmask_b32_e64 v194, 0, 32, s[40:41]
	v_ldexp_f32 v146, v146, v194
	v_log_f32_e32 v146, v146
	s_nop 0
	v_mul_f32_e32 v194, 0x3f317217, v146
	v_fma_f32 v194, v146, s52, -v194
	v_fmac_f32_e32 v194, 0x3377d1cf, v146
	v_fmac_f32_e32 v194, 0x3f317217, v146
	v_cmp_lt_f32_e64 s[42:43], |v146|, s53
	s_nop 1
	v_cndmask_b32_e64 v146, v146, v194, s[42:43]
	v_cndmask_b32_e64 v194, 0, v216, s[40:41]
	v_sub_f32_e32 v146, v146, v194
	v_cndmask_b32_e64 v146, v150, v146, s[12:13]
	v_mul_f32_e32 v150, 0x3fb8aa3b, v168
	v_exp_f32_e32 v150, v150
	s_nop 0
	v_fma_f32 v150, v178, v150, v130
	v_cmp_gt_f32_e64 s[40:41], s97, v150
	s_nop 1
	v_cndmask_b32_e64 v194, 0, 32, s[40:41]
	v_ldexp_f32 v150, v150, v194
	v_log_f32_e32 v150, v150
	s_nop 0
	v_mul_f32_e32 v194, 0x3f317217, v150
	v_fma_f32 v194, v150, s52, -v194
	v_fmac_f32_e32 v194, 0x3377d1cf, v150
	v_fmac_f32_e32 v194, 0x3f317217, v150
	v_cmp_lt_f32_e64 s[42:43], |v150|, s53
	s_nop 1
	v_cndmask_b32_e64 v150, v150, v194, s[42:43]
	v_cndmask_b32_e64 v194, 0, v216, s[40:41]
	v_sub_f32_e32 v150, v150, v194
	v_cndmask_b32_e64 v150, v168, v150, s[10:11]
	v_min_f32_e32 v168, 0, v151
	v_mul_f32_e64 v151, |v151|, s57
	v_exp_f32_e32 v151, v151
	s_nop 0
	v_add_f32_e32 v151, 1.0, v151
	v_cmp_gt_f32_e64 s[40:41], s97, v151
	s_nop 1
	v_cndmask_b32_e64 v194, 0, 32, s[40:41]
	v_ldexp_f32 v151, v151, v194
	v_log_f32_e32 v151, v151
	s_nop 0
	v_mul_f32_e32 v194, 0x3f317217, v151
	v_fma_f32 v194, v151, s52, -v194
	v_fmac_f32_e32 v194, 0x3377d1cf, v151
	v_fmac_f32_e32 v194, 0x3f317217, v151
	v_cmp_lt_f32_e64 s[42:43], |v151|, s53
	s_nop 1
	v_cndmask_b32_e64 v151, v151, v194, s[42:43]
	v_cndmask_b32_e64 v194, 0, v216, s[40:41]
	v_sub_f32_e32 v151, v151, v194
	v_sub_f32_e32 v151, v168, v151
	v_min_f32_e32 v168, 0, v147
	v_mul_f32_e64 v147, |v147|, s57
	v_exp_f32_e32 v147, v147
	s_nop 0
	v_add_f32_e32 v147, 1.0, v147
	v_cmp_gt_f32_e64 s[40:41], s97, v147
	s_nop 1
	v_cndmask_b32_e64 v194, 0, 32, s[40:41]
	v_ldexp_f32 v147, v147, v194
	v_log_f32_e32 v147, v147
	s_nop 0
	v_mul_f32_e32 v194, 0x3f317217, v147
	v_fma_f32 v194, v147, s52, -v194
	v_fmac_f32_e32 v194, 0x3377d1cf, v147
	v_fmac_f32_e32 v194, 0x3f317217, v147
	v_cmp_lt_f32_e64 s[42:43], |v147|, s53
	s_nop 1
	v_cndmask_b32_e64 v147, v147, v194, s[42:43]
	v_cndmask_b32_e64 v194, 0, v216, s[40:41]
	v_sub_f32_e32 v147, v147, v194
	v_sub_f32_e32 v168, v168, v147
	v_mul_f32_e32 v147, 0x3fb8aa3b, v151
	v_exp_f32_e32 v147, v147
	s_nop 0
	v_fma_f32 v147, v177, v147, v135
	v_cmp_gt_f32_e64 s[40:41], s97, v147
	s_nop 1
	v_cndmask_b32_e64 v194, 0, 32, s[40:41]
	v_ldexp_f32 v147, v147, v194
	v_log_f32_e32 v147, v147
	s_nop 0
	v_mul_f32_e32 v194, 0x3f317217, v147
	v_fma_f32 v194, v147, s52, -v194
	v_fmac_f32_e32 v194, 0x3377d1cf, v147
	v_fmac_f32_e32 v194, 0x3f317217, v147
	v_cmp_lt_f32_e64 s[42:43], |v147|, s53
	s_nop 1
	v_cndmask_b32_e64 v147, v147, v194, s[42:43]
	v_cndmask_b32_e64 v194, 0, v216, s[40:41]
	v_sub_f32_e32 v147, v147, v194
	v_cndmask_b32_e64 v147, v151, v147, s[8:9]
	v_mul_f32_e32 v151, 0x3fb8aa3b, v168
	v_exp_f32_e32 v151, v151
	s_nop 0
	v_fma_f32 v151, v167, v151, v131
	v_cmp_gt_f32_e64 s[40:41], s97, v151
	s_nop 1
	v_cndmask_b32_e64 v194, 0, 32, s[40:41]
	v_ldexp_f32 v151, v151, v194
	v_log_f32_e32 v151, v151
	s_nop 0
	v_mul_f32_e32 v194, 0x3f317217, v151
	v_fma_f32 v194, v151, s52, -v194
	v_fmac_f32_e32 v194, 0x3377d1cf, v151
	v_fmac_f32_e32 v194, 0x3f317217, v151
	v_cmp_lt_f32_e64 s[42:43], |v151|, s53
	s_nop 1
	v_cndmask_b32_e64 v151, v151, v194, s[42:43]
	v_cndmask_b32_e64 v194, 0, v216, s[40:41]
	v_sub_f32_e32 v151, v151, v194
	v_cndmask_b32_e32 v151, v168, v151, vcc
	global_store_dwordx4 v[170:171], v[144:147], off offset:512
	global_store_dwordx4 v[170:171], v[148:151], off offset:528
	s_nop 1
	v_or_b32_e32 v148, 32, v166
	v_ashrrev_i32_e32 v149, 31, v148
	v_lshlrev_b64 v[144:145], 6, v[148:149]
	v_lshl_add_u64 v[144:145], v[160:161], 0, v[144:145]
	s_nop 0
	s_waitcnt lgkmcnt(0)
	s_nop 0
	s_nop 0
	s_nop 0
	s_nop 0
	s_nop 0
	s_nop 0
	s_nop 0
	s_waitcnt lgkmcnt(0)
	s_nop 0
	s_nop 0
	s_waitcnt lgkmcnt(0)
;     __device__ __forceinline__ void operator()(const f32x4 (&acc)[2][2][4][2], const pg8::Unit& u, int wr, int wc, int fr, int fq) const {
;     ...
;             WIN_LOOP( _Pragma("unroll") for (int i = 0; i < 4; ++i) { const float s0 = fminf(a[i], 0.f) - __logf(1.f + __expf(-fabsf(a[i]))), s1 = fminf(b[i], 0.f) - __logf(1.f + __expf(-fabsf(b[i]))); const float la = l0[bj][i], lbv = l1[bj][i];
;                     a[i] = la > 0.f ? __logf(la + (1.f - la) * __expf(s0)) : s0; b[i] = lbv > 0.f ? __logf(lbv + (1.f - lbv) * __expf(s1)) : s1; }
;                 *(f32x4*)(LF + (size_t)row * 512 + c) = a; *(f32x4*)(LF + (size_t)row * 512 + c + 4) = b; __builtin_amdgcn_sched_barrier(0); ) }
	s_nop 0
	s_nop 0
	v_mov_b32_e32 v168, v252
	v_lshlrev_b64 v[144:145], 11, v[148:149]
	v_lshl_add_u64 v[170:171], s[50:51], 0, v[144:145]
	v_lshl_add_u64 v[170:171], v[170:171], 0, v[192:193]
	v_pk_mul_f32 v[148:149], v[44:45], v[168:169] op_sel_hi:[1,0]
	v_pk_mul_f32 v[144:145], v[40:41], v[168:169] op_sel_hi:[1,0]
	v_min_f32_e32 v194, 0, v148
	v_mul_f32_e64 v148, |v148|, s57
	v_exp_f32_e32 v148, v148
	v_pk_mul_f32 v[150:151], v[46:47], v[168:169] op_sel_hi:[1,0]
	v_pk_mul_f32 v[146:147], v[42:43], v[168:169] op_sel_hi:[1,0]
	v_add_f32_e32 v148, 1.0, v148
	v_cmp_gt_f32_e64 s[40:41], s97, v148
	s_nop 1
	v_cndmask_b32_e64 v195, 0, 32, s[40:41]
	v_ldexp_f32 v148, v148, v195
	v_log_f32_e32 v148, v148
	s_nop 0
	v_mul_f32_e32 v195, 0x3f317217, v148
	v_fma_f32 v195, v148, s52, -v195
	v_fmac_f32_e32 v195, 0x3377d1cf, v148
	v_fmac_f32_e32 v195, 0x3f317217, v148
	v_cmp_lt_f32_e64 s[42:43], |v148|, s53
	s_nop 1
	v_cndmask_b32_e64 v148, v148, v195, s[42:43]
	v_cndmask_b32_e64 v195, 0, v216, s[40:41]
	v_sub_f32_e32 v148, v148, v195
	v_sub_f32_e32 v148, v194, v148
	v_min_f32_e32 v194, 0, v144
	v_mul_f32_e64 v144, |v144|, s57
	v_exp_f32_e32 v144, v144
	s_nop 0
	v_add_f32_e32 v144, 1.0, v144
	v_cmp_gt_f32_e64 s[40:41], s97, v144
	s_nop 1
	v_cndmask_b32_e64 v195, 0, 32, s[40:41]
	v_ldexp_f32 v144, v144, v195
	v_log_f32_e32 v144, v144
	s_nop 0
	v_mul_f32_e32 v195, 0x3f317217, v144
	v_fma_f32 v195, v144, s52, -v195
	v_fmac_f32_e32 v195, 0x3377d1cf, v144
	v_fmac_f32_e32 v195, 0x3f317217, v144
	v_cmp_lt_f32_e64 s[42:43], |v144|, s53
	s_nop 1
	v_cndmask_b32_e64 v144, v144, v195, s[42:43]
	v_cndmask_b32_e64 v195, 0, v216, s[40:41]
	v_sub_f32_e32 v144, v144, v195
	v_sub_f32_e32 v194, v194, v144
	v_mul_f32_e32 v144, 0x3fb8aa3b, v148
	v_exp_f32_e32 v144, v144
	s_nop 0
	v_fma_f32 v144, v190, v144, v140
	v_cmp_gt_f32_e64 s[40:41], s97, v144
	s_nop 1
	v_cndmask_b32_e64 v195, 0, 32, s[40:41]
	v_ldexp_f32 v144, v144, v195
	v_log_f32_e32 v144, v144
	s_nop 0
	v_mul_f32_e32 v195, 0x3f317217, v144
	v_fma_f32 v195, v144, s52, -v195
	v_fmac_f32_e32 v195, 0x3377d1cf, v144
	v_fmac_f32_e32 v195, 0x3f317217, v144
	v_cmp_lt_f32_e64 s[42:43], |v144|, s53
	s_nop 1
	v_cndmask_b32_e64 v144, v144, v195, s[42:43]
	v_cndmask_b32_e64 v195, 0, v216, s[40:41]
	v_sub_f32_e32 v144, v144, v195
	v_cndmask_b32_e64 v144, v148, v144, s[38:39]
	v_mul_f32_e32 v148, 0x3fb8aa3b, v194
	v_exp_f32_e32 v148, v148
	s_nop 0
	v_fma_f32 v148, v191, v148, v136
	v_cmp_gt_f32_e64 s[40:41], s97, v148
	s_nop 1
	v_cndmask_b32_e64 v195, 0, 32, s[40:41]
	v_ldexp_f32 v148, v148, v195
	v_log_f32_e32 v148, v148
	s_nop 0
	v_mul_f32_e32 v195, 0x3f317217, v148
	v_fma_f32 v195, v148, s52, -v195
	v_fmac_f32_e32 v195, 0x3377d1cf, v148
	v_fmac_f32_e32 v195, 0x3f317217, v148
	v_cmp_lt_f32_e64 s[42:43], |v148|, s53
	s_nop 1
	v_cndmask_b32_e64 v148, v148, v195, s[42:43]
	v_cndmask_b32_e64 v195, 0, v216, s[40:41]
	v_sub_f32_e32 v148, v148, v195
	v_cndmask_b32_e64 v148, v194, v148, s[36:37]
	v_min_f32_e32 v194, 0, v149
	v_mul_f32_e64 v149, |v149|, s57
	v_exp_f32_e32 v149, v149
	s_nop 0
	v_add_f32_e32 v149, 1.0, v149
	v_cmp_gt_f32_e64 s[40:41], s97, v149
	s_nop 1
	v_cndmask_b32_e64 v195, 0, 32, s[40:41]
	v_ldexp_f32 v149, v149, v195
	v_log_f32_e32 v149, v149
	s_nop 0
	v_mul_f32_e32 v195, 0x3f317217, v149
	v_fma_f32 v195, v149, s52, -v195
	v_fmac_f32_e32 v195, 0x3377d1cf, v149
	v_fmac_f32_e32 v195, 0x3f317217, v149
	v_cmp_lt_f32_e64 s[42:43], |v149|, s53
	s_nop 1
	v_cndmask_b32_e64 v149, v149, v195, s[42:43]
	v_cndmask_b32_e64 v195, 0, v216, s[40:41]
	v_sub_f32_e32 v149, v149, v195
	v_sub_f32_e32 v149, v194, v149
	v_min_f32_e32 v194, 0, v145
	v_mul_f32_e64 v145, |v145|, s57
	v_exp_f32_e32 v145, v145
	s_nop 0
	v_add_f32_e32 v145, 1.0, v145
	v_cmp_gt_f32_e64 s[40:41], s97, v145
	s_nop 1
	v_cndmask_b32_e64 v195, 0, 32, s[40:41]
	v_ldexp_f32 v145, v145, v195
	v_log_f32_e32 v145, v145
	s_nop 0
	v_mul_f32_e32 v195, 0x3f317217, v145
	v_fma_f32 v195, v145, s52, -v195
	v_fmac_f32_e32 v195, 0x3377d1cf, v145
	v_fmac_f32_e32 v195, 0x3f317217, v145
	v_cmp_lt_f32_e64 s[42:43], |v145|, s53
	s_nop 1
	v_cndmask_b32_e64 v145, v145, v195, s[42:43]
	v_cndmask_b32_e64 v195, 0, v216, s[40:41]
	v_sub_f32_e32 v145, v145, v195
	v_sub_f32_e32 v194, v194, v145
	v_mul_f32_e32 v145, 0x3fb8aa3b, v149
	v_exp_f32_e32 v145, v145
	s_nop 0
	v_fma_f32 v145, v188, v145, v141
	v_cmp_gt_f32_e64 s[40:41], s97, v145
	s_nop 1
	v_cndmask_b32_e64 v195, 0, 32, s[40:41]
	v_ldexp_f32 v145, v145, v195
	v_log_f32_e32 v145, v145
	s_nop 0
	v_mul_f32_e32 v195, 0x3f317217, v145
	v_fma_f32 v195, v145, s52, -v195
	v_fmac_f32_e32 v195, 0x3377d1cf, v145
	v_fmac_f32_e32 v195, 0x3f317217, v145
	v_cmp_lt_f32_e64 s[42:43], |v145|, s53
	s_nop 1
	v_cndmask_b32_e64 v145, v145, v195, s[42:43]
	v_cndmask_b32_e64 v195, 0, v216, s[40:41]
	v_sub_f32_e32 v145, v145, v195
	v_cndmask_b32_e64 v145, v149, v145, s[34:35]
	v_mul_f32_e32 v149, 0x3fb8aa3b, v194
	v_exp_f32_e32 v149, v149
	s_nop 0
	v_fma_f32 v149, v189, v149, v137
	v_cmp_gt_f32_e64 s[40:41], s97, v149
	s_nop 1
	v_cndmask_b32_e64 v195, 0, 32, s[40:41]
	v_ldexp_f32 v149, v149, v195
	v_log_f32_e32 v149, v149
	s_nop 0
	v_mul_f32_e32 v195, 0x3f317217, v149
	v_fma_f32 v195, v149, s52, -v195
	v_fmac_f32_e32 v195, 0x3377d1cf, v149
	v_fmac_f32_e32 v195, 0x3f317217, v149
	v_cmp_lt_f32_e64 s[42:43], |v149|, s53
	s_nop 1
	v_cndmask_b32_e64 v149, v149, v195, s[42:43]
	v_cndmask_b32_e64 v195, 0, v216, s[40:41]
	v_sub_f32_e32 v149, v149, v195
	v_cndmask_b32_e64 v149, v194, v149, s[30:31]
	v_min_f32_e32 v194, 0, v150
	v_mul_f32_e64 v150, |v150|, s57
	v_exp_f32_e32 v150, v150
	s_nop 0
	v_add_f32_e32 v150, 1.0, v150
	v_cmp_gt_f32_e64 s[40:41], s97, v150
;     __device__ __forceinline__ void operator()(const f32x4 (&acc)[2][2][4][2], const pg8::Unit& u, int wr, int wc, int fr, int fq) const {
;     ...
;             WIN_LOOP( _Pragma("unroll") for (int i = 0; i < 4; ++i) { const float s0 = fminf(a[i], 0.f) - __logf(1.f + __expf(-fabsf(a[i]))), s1 = fminf(b[i], 0.f) - __logf(1.f + __expf(-fabsf(b[i]))); const float la = l0[bj][i], lbv = l1[bj][i];
;                     a[i] = la > 0.f ? __logf(la + (1.f - la) * __expf(s0)) : s0; b[i] = lbv > 0.f ? __logf(lbv + (1.f - lbv) * __expf(s1)) : s1; }
;                 *(f32x4*)(LF + (size_t)row * 512 + c) = a; *(f32x4*)(LF + (size_t)row * 512 + c + 4) = b; __builtin_amdgcn_sched_barrier(0); ) }
	s_nop 1
	v_cndmask_b32_e64 v195, 0, 32, s[40:41]
	v_ldexp_f32 v150, v150, v195
	v_log_f32_e32 v150, v150
	s_nop 0
	v_mul_f32_e32 v195, 0x3f317217, v150
	v_fma_f32 v195, v150, s52, -v195
	v_fmac_f32_e32 v195, 0x3377d1cf, v150
	v_fmac_f32_e32 v195, 0x3f317217, v150
	v_cmp_lt_f32_e64 s[42:43], |v150|, s53
	s_nop 1
	v_cndmask_b32_e64 v150, v150, v195, s[42:43]
	v_cndmask_b32_e64 v195, 0, v216, s[40:41]
	v_sub_f32_e32 v150, v150, v195
	v_sub_f32_e32 v150, v194, v150
	v_min_f32_e32 v194, 0, v146
	v_mul_f32_e64 v146, |v146|, s57
	v_exp_f32_e32 v146, v146
	s_nop 0
	v_add_f32_e32 v146, 1.0, v146
	v_cmp_gt_f32_e64 s[40:41], s97, v146
	s_nop 1
	v_cndmask_b32_e64 v195, 0, 32, s[40:41]
	v_ldexp_f32 v146, v146, v195
	v_log_f32_e32 v146, v146
	s_nop 0
	v_mul_f32_e32 v195, 0x3f317217, v146
	v_fma_f32 v195, v146, s52, -v195
	v_fmac_f32_e32 v195, 0x3377d1cf, v146
	v_fmac_f32_e32 v195, 0x3f317217, v146
	v_cmp_lt_f32_e64 s[42:43], |v146|, s53
	s_nop 1
	v_cndmask_b32_e64 v146, v146, v195, s[42:43]
	v_cndmask_b32_e64 v195, 0, v216, s[40:41]
	v_sub_f32_e32 v146, v146, v195
	v_sub_f32_e32 v194, v194, v146
	v_mul_f32_e32 v146, 0x3fb8aa3b, v150
	v_exp_f32_e32 v146, v146
	s_nop 0
	v_fma_f32 v146, v187, v146, v142
	v_cmp_gt_f32_e64 s[40:41], s97, v146
	s_nop 1
	v_cndmask_b32_e64 v195, 0, 32, s[40:41]
	v_ldexp_f32 v146, v146, v195
	v_log_f32_e32 v146, v146
	s_nop 0
	v_mul_f32_e32 v195, 0x3f317217, v146
	v_fma_f32 v195, v146, s52, -v195
	v_fmac_f32_e32 v195, 0x3377d1cf, v146
	v_fmac_f32_e32 v195, 0x3f317217, v146
	v_cmp_lt_f32_e64 s[42:43], |v146|, s53
	s_nop 1
	v_cndmask_b32_e64 v146, v146, v195, s[42:43]
	v_cndmask_b32_e64 v195, 0, v216, s[40:41]
	v_sub_f32_e32 v146, v146, v195
	v_cndmask_b32_e64 v146, v150, v146, s[28:29]
	v_mul_f32_e32 v150, 0x3fb8aa3b, v194
	v_exp_f32_e32 v150, v150
	s_nop 0
	v_fma_f32 v150, v186, v150, v138
	v_cmp_gt_f32_e64 s[40:41], s97, v150
	s_nop 1
	v_cndmask_b32_e64 v195, 0, 32, s[40:41]
	v_ldexp_f32 v150, v150, v195
	v_log_f32_e32 v150, v150
	s_nop 0
	v_mul_f32_e32 v195, 0x3f317217, v150
	v_fma_f32 v195, v150, s52, -v195
	v_fmac_f32_e32 v195, 0x3377d1cf, v150
	v_fmac_f32_e32 v195, 0x3f317217, v150
	v_cmp_lt_f32_e64 s[42:43], |v150|, s53
	s_nop 1
	v_cndmask_b32_e64 v150, v150, v195, s[42:43]
	v_cndmask_b32_e64 v195, 0, v216, s[40:41]
	v_sub_f32_e32 v150, v150, v195
	v_cndmask_b32_e64 v150, v194, v150, s[26:27]
	v_min_f32_e32 v194, 0, v151
	v_mul_f32_e64 v151, |v151|, s57
	v_exp_f32_e32 v151, v151
	s_nop 0
	v_add_f32_e32 v151, 1.0, v151
	v_cmp_gt_f32_e64 s[40:41], s97, v151
	s_nop 1
	v_cndmask_b32_e64 v195, 0, 32, s[40:41]
	v_ldexp_f32 v151, v151, v195
	v_log_f32_e32 v151, v151
	s_nop 0
	v_mul_f32_e32 v195, 0x3f317217, v151
	v_fma_f32 v195, v151, s52, -v195
	v_fmac_f32_e32 v195, 0x3377d1cf, v151
	v_fmac_f32_e32 v195, 0x3f317217, v151
	v_cmp_lt_f32_e64 s[42:43], |v151|, s53
	s_nop 1
	v_cndmask_b32_e64 v151, v151, v195, s[42:43]
	v_cndmask_b32_e64 v195, 0, v216, s[40:41]
	v_sub_f32_e32 v151, v151, v195
	v_sub_f32_e32 v151, v194, v151
	v_min_f32_e32 v194, 0, v147
	v_mul_f32_e64 v147, |v147|, s57
	v_exp_f32_e32 v147, v147
	s_nop 0
	v_add_f32_e32 v147, 1.0, v147
	v_cmp_gt_f32_e64 s[40:41], s97, v147
	s_nop 1
	v_cndmask_b32_e64 v195, 0, 32, s[40:41]
	v_ldexp_f32 v147, v147, v195
	v_log_f32_e32 v147, v147
	s_nop 0
	v_mul_f32_e32 v195, 0x3f317217, v147
	v_fma_f32 v195, v147, s52, -v195
	v_fmac_f32_e32 v195, 0x3377d1cf, v147
	v_fmac_f32_e32 v195, 0x3f317217, v147
	v_cmp_lt_f32_e64 s[42:43], |v147|, s53
	s_nop 1
	v_cndmask_b32_e64 v147, v147, v195, s[42:43]
	v_cndmask_b32_e64 v195, 0, v216, s[40:41]
	v_sub_f32_e32 v147, v147, v195
	v_sub_f32_e32 v194, v194, v147
	v_mul_f32_e32 v147, 0x3fb8aa3b, v151
	v_exp_f32_e32 v147, v147
	s_nop 0
	v_fma_f32 v147, v185, v147, v143
	v_cmp_gt_f32_e64 s[40:41], s97, v147
	s_nop 1
	v_cndmask_b32_e64 v195, 0, 32, s[40:41]
	v_ldexp_f32 v147, v147, v195
	v_log_f32_e32 v147, v147
	s_nop 0
	v_mul_f32_e32 v195, 0x3f317217, v147
	v_fma_f32 v195, v147, s52, -v195
	v_fmac_f32_e32 v195, 0x3377d1cf, v147
	v_fmac_f32_e32 v195, 0x3f317217, v147
	v_cmp_lt_f32_e64 s[42:43], |v147|, s53
	s_nop 1
	v_cndmask_b32_e64 v147, v147, v195, s[42:43]
	v_cndmask_b32_e64 v195, 0, v216, s[40:41]
	v_sub_f32_e32 v147, v147, v195
	v_cndmask_b32_e64 v147, v151, v147, s[24:25]
	v_mul_f32_e32 v151, 0x3fb8aa3b, v194
	v_exp_f32_e32 v151, v151
	s_nop 0
	v_fma_f32 v151, v184, v151, v139
	v_cmp_gt_f32_e64 s[40:41], s97, v151
	s_nop 1
	v_cndmask_b32_e64 v195, 0, 32, s[40:41]
	v_ldexp_f32 v151, v151, v195
	v_log_f32_e32 v151, v151
	s_nop 0
	v_mul_f32_e32 v195, 0x3f317217, v151
	v_fma_f32 v195, v151, s52, -v195
	v_fmac_f32_e32 v195, 0x3377d1cf, v151
	v_fmac_f32_e32 v195, 0x3f317217, v151
	v_cmp_lt_f32_e64 s[42:43], |v151|, s53
	s_nop 1
	v_cndmask_b32_e64 v151, v151, v195, s[42:43]
	v_cndmask_b32_e64 v195, 0, v216, s[40:41]
	v_sub_f32_e32 v151, v151, v195
	v_cndmask_b32_e64 v151, v194, v151, s[22:23]
	global_store_dwordx4 v[170:171], v[144:147], off
	global_store_dwordx4 v[170:171], v[148:151], off offset:16
	s_nop 1
	v_pk_mul_f32 v[148:149], v[108:109], v[168:169] op_sel_hi:[1,0]
	v_pk_mul_f32 v[150:151], v[110:111], v[168:169] op_sel_hi:[1,0]
	v_pk_mul_f32 v[146:147], v[106:107], v[168:169] op_sel_hi:[1,0]
	v_pk_mul_f32 v[144:145], v[104:105], v[168:169] op_sel_hi:[1,0]
	v_min_f32_e32 v168, 0, v148
	v_mul_f32_e64 v148, |v148|, s57
	v_exp_f32_e32 v148, v148
	s_nop 0
	v_add_f32_e32 v148, 1.0, v148
	v_cmp_gt_f32_e64 s[40:41], s97, v148
	s_nop 1
	v_cndmask_b32_e64 v194, 0, 32, s[40:41]
	v_ldexp_f32 v148, v148, v194
	v_log_f32_e32 v148, v148
	s_nop 0
	v_mul_f32_e32 v194, 0x3f317217, v148
	v_fma_f32 v194, v148, s52, -v194
	v_fmac_f32_e32 v194, 0x3377d1cf, v148
;     __device__ __forceinline__ void operator()(const f32x4 (&acc)[2][2][4][2], const pg8::Unit& u, int wr, int wc, int fr, int fq) const {
;     ...
;             WIN_LOOP( _Pragma("unroll") for (int i = 0; i < 4; ++i) { const float s0 = fminf(a[i], 0.f) - __logf(1.f + __expf(-fabsf(a[i]))), s1 = fminf(b[i], 0.f) - __logf(1.f + __expf(-fabsf(b[i]))); const float la = l0[bj][i], lbv = l1[bj][i];
;                     a[i] = la > 0.f ? __logf(la + (1.f - la) * __expf(s0)) : s0; b[i] = lbv > 0.f ? __logf(lbv + (1.f - lbv) * __expf(s1)) : s1; }
;                 *(f32x4*)(LF + (size_t)row * 512 + c) = a; *(f32x4*)(LF + (size_t)row * 512 + c + 4) = b; __builtin_amdgcn_sched_barrier(0); ) }
	v_fmac_f32_e32 v194, 0x3f317217, v148
	v_cmp_lt_f32_e64 s[42:43], |v148|, s53
	s_nop 1
	v_cndmask_b32_e64 v148, v148, v194, s[42:43]
	v_cndmask_b32_e64 v194, 0, v216, s[40:41]
	v_sub_f32_e32 v148, v148, v194
	v_sub_f32_e32 v148, v168, v148
	v_min_f32_e32 v168, 0, v144
	v_mul_f32_e64 v144, |v144|, s57
	v_exp_f32_e32 v144, v144
	s_nop 0
	v_add_f32_e32 v144, 1.0, v144
	v_cmp_gt_f32_e64 s[40:41], s97, v144
	s_nop 1
	v_cndmask_b32_e64 v194, 0, 32, s[40:41]
	v_ldexp_f32 v144, v144, v194
	v_log_f32_e32 v144, v144
	s_nop 0
	v_mul_f32_e32 v194, 0x3f317217, v144
	v_fma_f32 v194, v144, s52, -v194
	v_fmac_f32_e32 v194, 0x3377d1cf, v144
	v_fmac_f32_e32 v194, 0x3f317217, v144
	v_cmp_lt_f32_e64 s[42:43], |v144|, s53
	s_nop 1
	v_cndmask_b32_e64 v144, v144, v194, s[42:43]
	v_cndmask_b32_e64 v194, 0, v216, s[40:41]
	v_sub_f32_e32 v144, v144, v194
	v_sub_f32_e32 v168, v168, v144
	v_mul_f32_e32 v144, 0x3fb8aa3b, v148
	v_exp_f32_e32 v144, v144
	s_nop 0
	v_fma_f32 v144, v183, v144, v132
	v_cmp_gt_f32_e64 s[40:41], s97, v144
	s_nop 1
	v_cndmask_b32_e64 v194, 0, 32, s[40:41]
	v_ldexp_f32 v144, v144, v194
	v_log_f32_e32 v144, v144
	s_nop 0
	v_mul_f32_e32 v194, 0x3f317217, v144
	v_fma_f32 v194, v144, s52, -v194
	v_fmac_f32_e32 v194, 0x3377d1cf, v144
	v_fmac_f32_e32 v194, 0x3f317217, v144
	v_cmp_lt_f32_e64 s[42:43], |v144|, s53
	s_nop 1
	v_cndmask_b32_e64 v144, v144, v194, s[42:43]
	v_cndmask_b32_e64 v194, 0, v216, s[40:41]
	v_sub_f32_e32 v144, v144, v194
	v_cndmask_b32_e64 v144, v148, v144, s[20:21]
	v_mul_f32_e32 v148, 0x3fb8aa3b, v168
	v_exp_f32_e32 v148, v148
	s_nop 0
	v_fma_f32 v148, v182, v148, v128
	v_cmp_gt_f32_e64 s[40:41], s97, v148
	s_nop 1
	v_cndmask_b32_e64 v194, 0, 32, s[40:41]
	v_ldexp_f32 v148, v148, v194
	v_log_f32_e32 v148, v148
	s_nop 0
	v_mul_f32_e32 v194, 0x3f317217, v148
	v_fma_f32 v194, v148, s52, -v194
	v_fmac_f32_e32 v194, 0x3377d1cf, v148
	v_fmac_f32_e32 v194, 0x3f317217, v148
	v_cmp_lt_f32_e64 s[42:43], |v148|, s53
	s_nop 1
	v_cndmask_b32_e64 v148, v148, v194, s[42:43]
	v_cndmask_b32_e64 v194, 0, v216, s[40:41]
	v_sub_f32_e32 v148, v148, v194
	v_cndmask_b32_e64 v148, v168, v148, s[18:19]
	v_min_f32_e32 v168, 0, v149
	v_mul_f32_e64 v149, |v149|, s57
	v_exp_f32_e32 v149, v149
	s_nop 0
	v_add_f32_e32 v149, 1.0, v149
	v_cmp_gt_f32_e64 s[40:41], s97, v149
	s_nop 1
	v_cndmask_b32_e64 v194, 0, 32, s[40:41]
	v_ldexp_f32 v149, v149, v194
	v_log_f32_e32 v149, v149
	s_nop 0
	v_mul_f32_e32 v194, 0x3f317217, v149
	v_fma_f32 v194, v149, s52, -v194
	v_fmac_f32_e32 v194, 0x3377d1cf, v149
	v_fmac_f32_e32 v194, 0x3f317217, v149
	v_cmp_lt_f32_e64 s[42:43], |v149|, s53
	s_nop 1
	v_cndmask_b32_e64 v149, v149, v194, s[42:43]
	v_cndmask_b32_e64 v194, 0, v216, s[40:41]
	v_sub_f32_e32 v149, v149, v194
	v_sub_f32_e32 v149, v168, v149
	v_min_f32_e32 v168, 0, v145
	v_mul_f32_e64 v145, |v145|, s57
	v_exp_f32_e32 v145, v145
	s_nop 0
	v_add_f32_e32 v145, 1.0, v145
	v_cmp_gt_f32_e64 s[40:41], s97, v145
	s_nop 1
	v_cndmask_b32_e64 v194, 0, 32, s[40:41]
	v_ldexp_f32 v145, v145, v194
	v_log_f32_e32 v145, v145
	s_nop 0
	v_mul_f32_e32 v194, 0x3f317217, v145
	v_fma_f32 v194, v145, s52, -v194
	v_fmac_f32_e32 v194, 0x3377d1cf, v145
	v_fmac_f32_e32 v194, 0x3f317217, v145
	v_cmp_lt_f32_e64 s[42:43], |v145|, s53
	s_nop 1
	v_cndmask_b32_e64 v145, v145, v194, s[42:43]
	v_cndmask_b32_e64 v194, 0, v216, s[40:41]
	v_sub_f32_e32 v145, v145, v194
	v_sub_f32_e32 v168, v168, v145
	v_mul_f32_e32 v145, 0x3fb8aa3b, v149
	v_exp_f32_e32 v145, v145
	s_nop 0
	v_fma_f32 v145, v181, v145, v133
	v_cmp_gt_f32_e64 s[40:41], s97, v145
	s_nop 1
	v_cndmask_b32_e64 v194, 0, 32, s[40:41]
	v_ldexp_f32 v145, v145, v194
	v_log_f32_e32 v145, v145
	s_nop 0
	v_mul_f32_e32 v194, 0x3f317217, v145
	v_fma_f32 v194, v145, s52, -v194
	v_fmac_f32_e32 v194, 0x3377d1cf, v145
	v_fmac_f32_e32 v194, 0x3f317217, v145
	v_cmp_lt_f32_e64 s[42:43], |v145|, s53
	s_nop 1
	v_cndmask_b32_e64 v145, v145, v194, s[42:43]
	v_cndmask_b32_e64 v194, 0, v216, s[40:41]
	v_sub_f32_e32 v145, v145, v194
	v_cndmask_b32_e64 v145, v149, v145, s[16:17]
	v_mul_f32_e32 v149, 0x3fb8aa3b, v168
	v_exp_f32_e32 v149, v149
	s_nop 0
	v_fma_f32 v149, v180, v149, v129
	v_cmp_gt_f32_e64 s[40:41], s97, v149
	s_nop 1
	v_cndmask_b32_e64 v194, 0, 32, s[40:41]
	v_ldexp_f32 v149, v149, v194
	v_log_f32_e32 v149, v149
	s_nop 0
	v_mul_f32_e32 v194, 0x3f317217, v149
	v_fma_f32 v194, v149, s52, -v194
	v_fmac_f32_e32 v194, 0x3377d1cf, v149
	v_fmac_f32_e32 v194, 0x3f317217, v149
	v_cmp_lt_f32_e64 s[42:43], |v149|, s53
	s_nop 1
	v_cndmask_b32_e64 v149, v149, v194, s[42:43]
	v_cndmask_b32_e64 v194, 0, v216, s[40:41]
	v_sub_f32_e32 v149, v149, v194
	v_cndmask_b32_e64 v149, v168, v149, s[14:15]
	v_min_f32_e32 v168, 0, v150
	v_mul_f32_e64 v150, |v150|, s57
	v_exp_f32_e32 v150, v150
	s_nop 0
	v_add_f32_e32 v150, 1.0, v150
	v_cmp_gt_f32_e64 s[40:41], s97, v150
	s_nop 1
	v_cndmask_b32_e64 v194, 0, 32, s[40:41]
	v_ldexp_f32 v150, v150, v194
	v_log_f32_e32 v150, v150
	s_nop 0
	v_mul_f32_e32 v194, 0x3f317217, v150
	v_fma_f32 v194, v150, s52, -v194
	v_fmac_f32_e32 v194, 0x3377d1cf, v150
	v_fmac_f32_e32 v194, 0x3f317217, v150
	v_cmp_lt_f32_e64 s[42:43], |v150|, s53
	s_nop 1
	v_cndmask_b32_e64 v150, v150, v194, s[42:43]
	v_cndmask_b32_e64 v194, 0, v216, s[40:41]
	v_sub_f32_e32 v150, v150, v194
	v_sub_f32_e32 v150, v168, v150
	v_min_f32_e32 v168, 0, v146
	v_mul_f32_e64 v146, |v146|, s57
	v_exp_f32_e32 v146, v146
	s_nop 0
	v_add_f32_e32 v146, 1.0, v146
	v_cmp_gt_f32_e64 s[40:41], s97, v146
	s_nop 1
	v_cndmask_b32_e64 v194, 0, 32, s[40:41]
	v_ldexp_f32 v146, v146, v194
	v_log_f32_e32 v146, v146
	s_nop 0
	v_mul_f32_e32 v194, 0x3f317217, v146
	v_fma_f32 v194, v146, s52, -v194
;     __device__ __forceinline__ void operator()(const f32x4 (&acc)[2][2][4][2], const pg8::Unit& u, int wr, int wc, int fr, int fq) const {
;     ...
;             WIN_LOOP( _Pragma("unroll") for (int i = 0; i < 4; ++i) { const float s0 = fminf(a[i], 0.f) - __logf(1.f + __expf(-fabsf(a[i]))), s1 = fminf(b[i], 0.f) - __logf(1.f + __expf(-fabsf(b[i]))); const float la = l0[bj][i], lbv = l1[bj][i];
;                     a[i] = la > 0.f ? __logf(la + (1.f - la) * __expf(s0)) : s0; b[i] = lbv > 0.f ? __logf(lbv + (1.f - lbv) * __expf(s1)) : s1; }
;                 *(f32x4*)(LF + (size_t)row * 512 + c) = a; *(f32x4*)(LF + (size_t)row * 512 + c + 4) = b; __builtin_amdgcn_sched_barrier(0); ) }
	v_fmac_f32_e32 v194, 0x3377d1cf, v146
	v_fmac_f32_e32 v194, 0x3f317217, v146
	v_cmp_lt_f32_e64 s[42:43], |v146|, s53
	s_nop 1
	v_cndmask_b32_e64 v146, v146, v194, s[42:43]
	v_cndmask_b32_e64 v194, 0, v216, s[40:41]
	v_sub_f32_e32 v146, v146, v194
	v_sub_f32_e32 v168, v168, v146
	v_mul_f32_e32 v146, 0x3fb8aa3b, v150
	v_exp_f32_e32 v146, v146
	s_nop 0
	v_fma_f32 v146, v179, v146, v134
	v_cmp_gt_f32_e64 s[40:41], s97, v146
	s_nop 1
	v_cndmask_b32_e64 v194, 0, 32, s[40:41]
	v_ldexp_f32 v146, v146, v194
	v_log_f32_e32 v146, v146
	s_nop 0
	v_mul_f32_e32 v194, 0x3f317217, v146
	v_fma_f32 v194, v146, s52, -v194
	v_fmac_f32_e32 v194, 0x3377d1cf, v146
	v_fmac_f32_e32 v194, 0x3f317217, v146
	v_cmp_lt_f32_e64 s[42:43], |v146|, s53
	s_nop 1
	v_cndmask_b32_e64 v146, v146, v194, s[42:43]
	v_cndmask_b32_e64 v194, 0, v216, s[40:41]
	v_sub_f32_e32 v146, v146, v194
	v_cndmask_b32_e64 v146, v150, v146, s[12:13]
	v_mul_f32_e32 v150, 0x3fb8aa3b, v168
	v_exp_f32_e32 v150, v150
	s_nop 0
	v_fma_f32 v150, v178, v150, v130
	v_cmp_gt_f32_e64 s[40:41], s97, v150
	s_nop 1
	v_cndmask_b32_e64 v194, 0, 32, s[40:41]
	v_ldexp_f32 v150, v150, v194
	v_log_f32_e32 v150, v150
	s_nop 0
	v_mul_f32_e32 v194, 0x3f317217, v150
	v_fma_f32 v194, v150, s52, -v194
	v_fmac_f32_e32 v194, 0x3377d1cf, v150
	v_fmac_f32_e32 v194, 0x3f317217, v150
	v_cmp_lt_f32_e64 s[42:43], |v150|, s53
	s_nop 1
	v_cndmask_b32_e64 v150, v150, v194, s[42:43]
	v_cndmask_b32_e64 v194, 0, v216, s[40:41]
	v_sub_f32_e32 v150, v150, v194
	v_cndmask_b32_e64 v150, v168, v150, s[10:11]
	v_min_f32_e32 v168, 0, v151
	v_mul_f32_e64 v151, |v151|, s57
	v_exp_f32_e32 v151, v151
	s_nop 0
	v_add_f32_e32 v151, 1.0, v151
	v_cmp_gt_f32_e64 s[40:41], s97, v151
	s_nop 1
	v_cndmask_b32_e64 v194, 0, 32, s[40:41]
	v_ldexp_f32 v151, v151, v194
	v_log_f32_e32 v151, v151
	s_nop 0
	v_mul_f32_e32 v194, 0x3f317217, v151
	v_fma_f32 v194, v151, s52, -v194
	v_fmac_f32_e32 v194, 0x3377d1cf, v151
	v_fmac_f32_e32 v194, 0x3f317217, v151
	v_cmp_lt_f32_e64 s[42:43], |v151|, s53
	s_nop 1
	v_cndmask_b32_e64 v151, v151, v194, s[42:43]
	v_cndmask_b32_e64 v194, 0, v216, s[40:41]
	v_sub_f32_e32 v151, v151, v194
	v_sub_f32_e32 v151, v168, v151
	v_min_f32_e32 v168, 0, v147
	v_mul_f32_e64 v147, |v147|, s57
	v_exp_f32_e32 v147, v147
	s_nop 0
	v_add_f32_e32 v147, 1.0, v147
	v_cmp_gt_f32_e64 s[40:41], s97, v147
	s_nop 1
	v_cndmask_b32_e64 v194, 0, 32, s[40:41]
	v_ldexp_f32 v147, v147, v194
	v_log_f32_e32 v147, v147
	s_nop 0
	v_mul_f32_e32 v194, 0x3f317217, v147
	v_fma_f32 v194, v147, s52, -v194
	v_fmac_f32_e32 v194, 0x3377d1cf, v147
	v_fmac_f32_e32 v194, 0x3f317217, v147
	v_cmp_lt_f32_e64 s[42:43], |v147|, s53
	s_nop 1
	v_cndmask_b32_e64 v147, v147, v194, s[42:43]
	v_cndmask_b32_e64 v194, 0, v216, s[40:41]
	v_sub_f32_e32 v147, v147, v194
	v_sub_f32_e32 v168, v168, v147
	v_mul_f32_e32 v147, 0x3fb8aa3b, v151
	v_exp_f32_e32 v147, v147
	s_nop 0
	v_fma_f32 v147, v177, v147, v135
	v_cmp_gt_f32_e64 s[40:41], s97, v147
	s_nop 1
	v_cndmask_b32_e64 v194, 0, 32, s[40:41]
	v_ldexp_f32 v147, v147, v194
	v_log_f32_e32 v147, v147
	s_nop 0
	v_mul_f32_e32 v194, 0x3f317217, v147
	v_fma_f32 v194, v147, s52, -v194
	v_fmac_f32_e32 v194, 0x3377d1cf, v147
	v_fmac_f32_e32 v194, 0x3f317217, v147
	v_cmp_lt_f32_e64 s[42:43], |v147|, s53
	s_nop 1
	v_cndmask_b32_e64 v147, v147, v194, s[42:43]
	v_cndmask_b32_e64 v194, 0, v216, s[40:41]
	v_sub_f32_e32 v147, v147, v194
	v_cndmask_b32_e64 v147, v151, v147, s[8:9]
	v_mul_f32_e32 v151, 0x3fb8aa3b, v168
	v_exp_f32_e32 v151, v151
	s_nop 0
	v_fma_f32 v151, v167, v151, v131
	v_cmp_gt_f32_e64 s[40:41], s97, v151
	s_nop 1
	v_cndmask_b32_e64 v194, 0, 32, s[40:41]
	v_ldexp_f32 v151, v151, v194
	v_log_f32_e32 v151, v151
	s_nop 0
	v_mul_f32_e32 v194, 0x3f317217, v151
	v_fma_f32 v194, v151, s52, -v194
	v_fmac_f32_e32 v194, 0x3377d1cf, v151
	v_fmac_f32_e32 v194, 0x3f317217, v151
	v_cmp_lt_f32_e64 s[42:43], |v151|, s53
	s_nop 1
	v_cndmask_b32_e64 v151, v151, v194, s[42:43]
	v_cndmask_b32_e64 v194, 0, v216, s[40:41]
	v_sub_f32_e32 v151, v151, v194
	v_cndmask_b32_e32 v151, v168, v151, vcc
	global_store_dwordx4 v[170:171], v[144:147], off offset:512
	global_store_dwordx4 v[170:171], v[148:151], off offset:528
	s_nop 1
	v_or_b32_e32 v148, 48, v166
	v_ashrrev_i32_e32 v149, 31, v148
	v_lshlrev_b64 v[144:145], 6, v[148:149]
	v_lshl_add_u64 v[144:145], v[160:161], 0, v[144:145]
	s_nop 0
	s_waitcnt lgkmcnt(0)
	s_nop 0
	s_nop 0
	s_nop 0
	s_nop 0
	s_nop 0
	s_nop 0
	s_nop 0
	s_waitcnt lgkmcnt(0)
	s_nop 0
	s_nop 0
	s_waitcnt lgkmcnt(0)
;     __device__ __forceinline__ void operator()(const f32x4 (&acc)[2][2][4][2], const pg8::Unit& u, int wr, int wc, int fr, int fq) const {
;     ...
;             WIN_LOOP( _Pragma("unroll") for (int i = 0; i < 4; ++i) { const float s0 = fminf(a[i], 0.f) - __logf(1.f + __expf(-fabsf(a[i]))), s1 = fminf(b[i], 0.f) - __logf(1.f + __expf(-fabsf(b[i]))); const float la = l0[bj][i], lbv = l1[bj][i];
;                     a[i] = la > 0.f ? __logf(la + (1.f - la) * __expf(s0)) : s0; b[i] = lbv > 0.f ? __logf(lbv + (1.f - lbv) * __expf(s1)) : s1; }
;                 *(f32x4*)(LF + (size_t)row * 512 + c) = a; *(f32x4*)(LF + (size_t)row * 512 + c + 4) = b; __builtin_amdgcn_sched_barrier(0); ) }
	s_nop 0
	s_nop 0
	v_mov_b32_e32 v168, v253
	v_lshlrev_b64 v[144:145], 11, v[148:149]
	v_lshl_add_u64 v[170:171], s[50:51], 0, v[144:145]
	v_lshl_add_u64 v[170:171], v[170:171], 0, v[192:193]
	v_pk_mul_f32 v[148:149], v[36:37], v[168:169] op_sel_hi:[1,0]
	v_pk_mul_f32 v[144:145], v[32:33], v[168:169] op_sel_hi:[1,0]
	v_min_f32_e32 v194, 0, v148
	v_mul_f32_e64 v148, |v148|, s57
	v_exp_f32_e32 v148, v148
	v_pk_mul_f32 v[150:151], v[38:39], v[168:169] op_sel_hi:[1,0]
	v_pk_mul_f32 v[146:147], v[34:35], v[168:169] op_sel_hi:[1,0]
	v_add_f32_e32 v148, 1.0, v148
	v_cmp_gt_f32_e64 s[40:41], s97, v148
	s_nop 1
	v_cndmask_b32_e64 v195, 0, 32, s[40:41]
	v_ldexp_f32 v148, v148, v195
	v_log_f32_e32 v148, v148
	s_nop 0
	v_mul_f32_e32 v195, 0x3f317217, v148
	v_fma_f32 v195, v148, s52, -v195
	v_fmac_f32_e32 v195, 0x3377d1cf, v148
	v_fmac_f32_e32 v195, 0x3f317217, v148
	v_cmp_lt_f32_e64 s[42:43], |v148|, s53
	s_nop 1
	v_cndmask_b32_e64 v148, v148, v195, s[42:43]
	v_cndmask_b32_e64 v195, 0, v216, s[40:41]
	v_sub_f32_e32 v148, v148, v195
	v_sub_f32_e32 v148, v194, v148
	v_min_f32_e32 v194, 0, v144
	v_mul_f32_e64 v144, |v144|, s57
	v_exp_f32_e32 v144, v144
	s_nop 0
	v_add_f32_e32 v144, 1.0, v144
	v_cmp_gt_f32_e64 s[40:41], s97, v144
	s_nop 1
	v_cndmask_b32_e64 v195, 0, 32, s[40:41]
	v_ldexp_f32 v144, v144, v195
	v_log_f32_e32 v144, v144
	s_nop 0
	v_mul_f32_e32 v195, 0x3f317217, v144
	v_fma_f32 v195, v144, s52, -v195
	v_fmac_f32_e32 v195, 0x3377d1cf, v144
	v_fmac_f32_e32 v195, 0x3f317217, v144
	v_cmp_lt_f32_e64 s[42:43], |v144|, s53
	s_nop 1
	v_cndmask_b32_e64 v144, v144, v195, s[42:43]
	v_cndmask_b32_e64 v195, 0, v216, s[40:41]
	v_sub_f32_e32 v144, v144, v195
	v_sub_f32_e32 v194, v194, v144
	v_mul_f32_e32 v144, 0x3fb8aa3b, v148
	v_exp_f32_e32 v144, v144
	s_nop 0
	v_fma_f32 v144, v190, v144, v140
	v_cmp_gt_f32_e64 s[40:41], s97, v144
	s_nop 1
	v_cndmask_b32_e64 v195, 0, 32, s[40:41]
	v_ldexp_f32 v144, v144, v195
	v_log_f32_e32 v144, v144
	s_nop 0
	v_mul_f32_e32 v195, 0x3f317217, v144
	v_fma_f32 v195, v144, s52, -v195
	v_fmac_f32_e32 v195, 0x3377d1cf, v144
	v_fmac_f32_e32 v195, 0x3f317217, v144
	v_cmp_lt_f32_e64 s[42:43], |v144|, s53
	s_nop 1
	v_cndmask_b32_e64 v144, v144, v195, s[42:43]
	v_cndmask_b32_e64 v195, 0, v216, s[40:41]
	v_sub_f32_e32 v144, v144, v195
	v_cndmask_b32_e64 v144, v148, v144, s[38:39]
	v_mul_f32_e32 v148, 0x3fb8aa3b, v194
	v_exp_f32_e32 v148, v148
	s_nop 0
	v_fma_f32 v148, v191, v148, v136
	v_cmp_gt_f32_e64 s[40:41], s97, v148
	s_nop 1
	v_cndmask_b32_e64 v195, 0, 32, s[40:41]
	v_ldexp_f32 v148, v148, v195
	v_log_f32_e32 v148, v148
	s_nop 0
	v_mul_f32_e32 v195, 0x3f317217, v148
	v_fma_f32 v195, v148, s52, -v195
	v_fmac_f32_e32 v195, 0x3377d1cf, v148
	v_fmac_f32_e32 v195, 0x3f317217, v148
	v_cmp_lt_f32_e64 s[42:43], |v148|, s53
	s_nop 1
	v_cndmask_b32_e64 v148, v148, v195, s[42:43]
	v_cndmask_b32_e64 v195, 0, v216, s[40:41]
	v_sub_f32_e32 v148, v148, v195
	v_cndmask_b32_e64 v148, v194, v148, s[36:37]
	v_min_f32_e32 v194, 0, v149
	v_mul_f32_e64 v149, |v149|, s57
	v_exp_f32_e32 v149, v149
	s_nop 0
	v_add_f32_e32 v149, 1.0, v149
	v_cmp_gt_f32_e64 s[40:41], s97, v149
	s_nop 1
	v_cndmask_b32_e64 v195, 0, 32, s[40:41]
	v_ldexp_f32 v149, v149, v195
	v_log_f32_e32 v149, v149
	s_nop 0
	v_mul_f32_e32 v195, 0x3f317217, v149
	v_fma_f32 v195, v149, s52, -v195
	v_fmac_f32_e32 v195, 0x3377d1cf, v149
	v_fmac_f32_e32 v195, 0x3f317217, v149
	v_cmp_lt_f32_e64 s[42:43], |v149|, s53
	s_nop 1
	v_cndmask_b32_e64 v149, v149, v195, s[42:43]
	v_cndmask_b32_e64 v195, 0, v216, s[40:41]
	v_sub_f32_e32 v149, v149, v195
	v_sub_f32_e32 v149, v194, v149
	v_min_f32_e32 v194, 0, v145
	v_mul_f32_e64 v145, |v145|, s57
	v_exp_f32_e32 v145, v145
	s_nop 0
	v_add_f32_e32 v145, 1.0, v145
	v_cmp_gt_f32_e64 s[40:41], s97, v145
	s_nop 1
	v_cndmask_b32_e64 v195, 0, 32, s[40:41]
	v_ldexp_f32 v145, v145, v195
	v_log_f32_e32 v145, v145
	s_nop 0
	v_mul_f32_e32 v195, 0x3f317217, v145
	v_fma_f32 v195, v145, s52, -v195
	v_fmac_f32_e32 v195, 0x3377d1cf, v145
	v_fmac_f32_e32 v195, 0x3f317217, v145
	v_cmp_lt_f32_e64 s[42:43], |v145|, s53
	s_nop 1
	v_cndmask_b32_e64 v145, v145, v195, s[42:43]
	v_cndmask_b32_e64 v195, 0, v216, s[40:41]
	v_sub_f32_e32 v145, v145, v195
	v_sub_f32_e32 v194, v194, v145
	v_mul_f32_e32 v145, 0x3fb8aa3b, v149
	v_exp_f32_e32 v145, v145
	s_nop 0
	v_fma_f32 v145, v188, v145, v141
	v_cmp_gt_f32_e64 s[40:41], s97, v145
	s_nop 1
	v_cndmask_b32_e64 v195, 0, 32, s[40:41]
	v_ldexp_f32 v145, v145, v195
	v_log_f32_e32 v145, v145
	s_nop 0
	v_mul_f32_e32 v195, 0x3f317217, v145
	v_fma_f32 v195, v145, s52, -v195
	v_fmac_f32_e32 v195, 0x3377d1cf, v145
	v_fmac_f32_e32 v195, 0x3f317217, v145
	v_cmp_lt_f32_e64 s[42:43], |v145|, s53
	s_nop 1
	v_cndmask_b32_e64 v145, v145, v195, s[42:43]
	v_cndmask_b32_e64 v195, 0, v216, s[40:41]
	v_sub_f32_e32 v145, v145, v195
	v_cndmask_b32_e64 v145, v149, v145, s[34:35]
	v_mul_f32_e32 v149, 0x3fb8aa3b, v194
	v_exp_f32_e32 v149, v149
	s_nop 0
	v_fma_f32 v149, v189, v149, v137
	v_cmp_gt_f32_e64 s[40:41], s97, v149
	s_nop 1
	v_cndmask_b32_e64 v195, 0, 32, s[40:41]
	v_ldexp_f32 v149, v149, v195
	v_log_f32_e32 v149, v149
	s_nop 0
	v_mul_f32_e32 v195, 0x3f317217, v149
	v_fma_f32 v195, v149, s52, -v195
	v_fmac_f32_e32 v195, 0x3377d1cf, v149
	v_fmac_f32_e32 v195, 0x3f317217, v149
	v_cmp_lt_f32_e64 s[42:43], |v149|, s53
	s_nop 1
	v_cndmask_b32_e64 v149, v149, v195, s[42:43]
	v_cndmask_b32_e64 v195, 0, v216, s[40:41]
	v_sub_f32_e32 v149, v149, v195
	v_cndmask_b32_e64 v149, v194, v149, s[30:31]
	v_min_f32_e32 v194, 0, v150
	v_mul_f32_e64 v150, |v150|, s57
	v_exp_f32_e32 v150, v150
	s_nop 0
	v_add_f32_e32 v150, 1.0, v150
	v_cmp_gt_f32_e64 s[40:41], s97, v150
;     __device__ __forceinline__ void operator()(const f32x4 (&acc)[2][2][4][2], const pg8::Unit& u, int wr, int wc, int fr, int fq) const {
;     ...
;             WIN_LOOP( _Pragma("unroll") for (int i = 0; i < 4; ++i) { const float s0 = fminf(a[i], 0.f) - __logf(1.f + __expf(-fabsf(a[i]))), s1 = fminf(b[i], 0.f) - __logf(1.f + __expf(-fabsf(b[i]))); const float la = l0[bj][i], lbv = l1[bj][i];
;                     a[i] = la > 0.f ? __logf(la + (1.f - la) * __expf(s0)) : s0; b[i] = lbv > 0.f ? __logf(lbv + (1.f - lbv) * __expf(s1)) : s1; }
;                 *(f32x4*)(LF + (size_t)row * 512 + c) = a; *(f32x4*)(LF + (size_t)row * 512 + c + 4) = b; __builtin_amdgcn_sched_barrier(0); ) }
	s_nop 1
	v_cndmask_b32_e64 v195, 0, 32, s[40:41]
	v_ldexp_f32 v150, v150, v195
	v_log_f32_e32 v150, v150
	s_nop 0
	v_mul_f32_e32 v195, 0x3f317217, v150
	v_fma_f32 v195, v150, s52, -v195
	v_fmac_f32_e32 v195, 0x3377d1cf, v150
	v_fmac_f32_e32 v195, 0x3f317217, v150
	v_cmp_lt_f32_e64 s[42:43], |v150|, s53
	s_nop 1
	v_cndmask_b32_e64 v150, v150, v195, s[42:43]
	v_cndmask_b32_e64 v195, 0, v216, s[40:41]
	v_sub_f32_e32 v150, v150, v195
	v_sub_f32_e32 v150, v194, v150
	v_min_f32_e32 v194, 0, v146
	v_mul_f32_e64 v146, |v146|, s57
	v_exp_f32_e32 v146, v146
	s_nop 0
	v_add_f32_e32 v146, 1.0, v146
	v_cmp_gt_f32_e64 s[40:41], s97, v146
	s_nop 1
	v_cndmask_b32_e64 v195, 0, 32, s[40:41]
	v_ldexp_f32 v146, v146, v195
	v_log_f32_e32 v146, v146
	s_nop 0
	v_mul_f32_e32 v195, 0x3f317217, v146
	v_fma_f32 v195, v146, s52, -v195
	v_fmac_f32_e32 v195, 0x3377d1cf, v146
	v_fmac_f32_e32 v195, 0x3f317217, v146
	v_cmp_lt_f32_e64 s[42:43], |v146|, s53
	s_nop 1
	v_cndmask_b32_e64 v146, v146, v195, s[42:43]
	v_cndmask_b32_e64 v195, 0, v216, s[40:41]
	v_sub_f32_e32 v146, v146, v195
	v_sub_f32_e32 v194, v194, v146
	v_mul_f32_e32 v146, 0x3fb8aa3b, v150
	v_exp_f32_e32 v146, v146
	s_nop 0
	v_fma_f32 v146, v187, v146, v142
	v_cmp_gt_f32_e64 s[40:41], s97, v146
	s_nop 1
	v_cndmask_b32_e64 v195, 0, 32, s[40:41]
	v_ldexp_f32 v146, v146, v195
	v_log_f32_e32 v146, v146
	s_nop 0
	v_mul_f32_e32 v195, 0x3f317217, v146
	v_fma_f32 v195, v146, s52, -v195
	v_fmac_f32_e32 v195, 0x3377d1cf, v146
	v_fmac_f32_e32 v195, 0x3f317217, v146
	v_cmp_lt_f32_e64 s[42:43], |v146|, s53
	s_nop 1
	v_cndmask_b32_e64 v146, v146, v195, s[42:43]
	v_cndmask_b32_e64 v195, 0, v216, s[40:41]
	v_sub_f32_e32 v146, v146, v195
	v_cndmask_b32_e64 v146, v150, v146, s[28:29]
	v_mul_f32_e32 v150, 0x3fb8aa3b, v194
	v_exp_f32_e32 v150, v150
	s_nop 0
	v_fma_f32 v150, v186, v150, v138
	v_cmp_gt_f32_e64 s[40:41], s97, v150
	s_nop 1
	v_cndmask_b32_e64 v195, 0, 32, s[40:41]
	v_ldexp_f32 v150, v150, v195
	v_log_f32_e32 v150, v150
	s_nop 0
	v_mul_f32_e32 v195, 0x3f317217, v150
	v_fma_f32 v195, v150, s52, -v195
	v_fmac_f32_e32 v195, 0x3377d1cf, v150
	v_fmac_f32_e32 v195, 0x3f317217, v150
	v_cmp_lt_f32_e64 s[42:43], |v150|, s53
	s_nop 1
	v_cndmask_b32_e64 v150, v150, v195, s[42:43]
	v_cndmask_b32_e64 v195, 0, v216, s[40:41]
	v_sub_f32_e32 v150, v150, v195
	v_cndmask_b32_e64 v150, v194, v150, s[26:27]
	v_min_f32_e32 v194, 0, v151
	v_mul_f32_e64 v151, |v151|, s57
	v_exp_f32_e32 v151, v151
	s_nop 0
	v_add_f32_e32 v151, 1.0, v151
	v_cmp_gt_f32_e64 s[40:41], s97, v151
	s_nop 1
	v_cndmask_b32_e64 v195, 0, 32, s[40:41]
	v_ldexp_f32 v151, v151, v195
	v_log_f32_e32 v151, v151
	s_nop 0
	v_mul_f32_e32 v195, 0x3f317217, v151
	v_fma_f32 v195, v151, s52, -v195
	v_fmac_f32_e32 v195, 0x3377d1cf, v151
	v_fmac_f32_e32 v195, 0x3f317217, v151
	v_cmp_lt_f32_e64 s[42:43], |v151|, s53
	s_nop 1
	v_cndmask_b32_e64 v151, v151, v195, s[42:43]
	v_cndmask_b32_e64 v195, 0, v216, s[40:41]
	v_sub_f32_e32 v151, v151, v195
	v_sub_f32_e32 v151, v194, v151
	v_min_f32_e32 v194, 0, v147
	v_mul_f32_e64 v147, |v147|, s57
	v_exp_f32_e32 v147, v147
	s_nop 0
	v_add_f32_e32 v147, 1.0, v147
	v_cmp_gt_f32_e64 s[40:41], s97, v147
	s_nop 1
	v_cndmask_b32_e64 v195, 0, 32, s[40:41]
	v_ldexp_f32 v147, v147, v195
	v_log_f32_e32 v147, v147
	s_nop 0
	v_mul_f32_e32 v195, 0x3f317217, v147
	v_fma_f32 v195, v147, s52, -v195
	v_fmac_f32_e32 v195, 0x3377d1cf, v147
	v_fmac_f32_e32 v195, 0x3f317217, v147
	v_cmp_lt_f32_e64 s[42:43], |v147|, s53
	s_nop 1
	v_cndmask_b32_e64 v147, v147, v195, s[42:43]
	v_cndmask_b32_e64 v195, 0, v216, s[40:41]
	v_sub_f32_e32 v147, v147, v195
	v_sub_f32_e32 v194, v194, v147
	v_mul_f32_e32 v147, 0x3fb8aa3b, v151
	v_exp_f32_e32 v147, v147
	s_nop 0
	v_fma_f32 v147, v185, v147, v143
	v_cmp_gt_f32_e64 s[40:41], s97, v147
	s_nop 1
	v_cndmask_b32_e64 v195, 0, 32, s[40:41]
	v_ldexp_f32 v147, v147, v195
	v_log_f32_e32 v147, v147
	s_nop 0
	v_mul_f32_e32 v195, 0x3f317217, v147
	v_fma_f32 v195, v147, s52, -v195
	v_fmac_f32_e32 v195, 0x3377d1cf, v147
	v_fmac_f32_e32 v195, 0x3f317217, v147
	v_cmp_lt_f32_e64 s[42:43], |v147|, s53
	s_nop 1
	v_cndmask_b32_e64 v147, v147, v195, s[42:43]
	v_cndmask_b32_e64 v195, 0, v216, s[40:41]
	v_sub_f32_e32 v147, v147, v195
	v_cndmask_b32_e64 v147, v151, v147, s[24:25]
	v_mul_f32_e32 v151, 0x3fb8aa3b, v194
	v_exp_f32_e32 v151, v151
	s_nop 0
	v_fma_f32 v151, v184, v151, v139
	v_cmp_gt_f32_e64 s[40:41], s97, v151
	s_nop 1
	v_cndmask_b32_e64 v195, 0, 32, s[40:41]
	v_ldexp_f32 v151, v151, v195
	v_log_f32_e32 v151, v151
	s_nop 0
	v_mul_f32_e32 v195, 0x3f317217, v151
	v_fma_f32 v195, v151, s52, -v195
	v_fmac_f32_e32 v195, 0x3377d1cf, v151
	v_fmac_f32_e32 v195, 0x3f317217, v151
	v_cmp_lt_f32_e64 s[42:43], |v151|, s53
	s_nop 1
	v_cndmask_b32_e64 v151, v151, v195, s[42:43]
	v_cndmask_b32_e64 v195, 0, v216, s[40:41]
	v_sub_f32_e32 v151, v151, v195
	v_cndmask_b32_e64 v151, v194, v151, s[22:23]
	global_store_dwordx4 v[170:171], v[144:147], off
	global_store_dwordx4 v[170:171], v[148:151], off offset:16
	s_nop 1
	v_pk_mul_f32 v[148:149], v[100:101], v[168:169] op_sel_hi:[1,0]
	v_pk_mul_f32 v[150:151], v[102:103], v[168:169] op_sel_hi:[1,0]
	v_pk_mul_f32 v[146:147], v[98:99], v[168:169] op_sel_hi:[1,0]
	v_pk_mul_f32 v[144:145], v[96:97], v[168:169] op_sel_hi:[1,0]
	v_min_f32_e32 v168, 0, v148
	v_mul_f32_e64 v148, |v148|, s57
	v_exp_f32_e32 v148, v148
	s_nop 0
	v_add_f32_e32 v148, 1.0, v148
	v_cmp_gt_f32_e64 s[40:41], s97, v148
	s_nop 1
	v_cndmask_b32_e64 v194, 0, 32, s[40:41]
	v_ldexp_f32 v148, v148, v194
	v_log_f32_e32 v148, v148
	s_nop 0
	v_mul_f32_e32 v194, 0x3f317217, v148
	v_fma_f32 v194, v148, s52, -v194
	v_fmac_f32_e32 v194, 0x3377d1cf, v148
;     __device__ __forceinline__ void operator()(const f32x4 (&acc)[2][2][4][2], const pg8::Unit& u, int wr, int wc, int fr, int fq) const {
;     ...
;             WIN_LOOP( _Pragma("unroll") for (int i = 0; i < 4; ++i) { const float s0 = fminf(a[i], 0.f) - __logf(1.f + __expf(-fabsf(a[i]))), s1 = fminf(b[i], 0.f) - __logf(1.f + __expf(-fabsf(b[i]))); const float la = l0[bj][i], lbv = l1[bj][i];
;                     a[i] = la > 0.f ? __logf(la + (1.f - la) * __expf(s0)) : s0; b[i] = lbv > 0.f ? __logf(lbv + (1.f - lbv) * __expf(s1)) : s1; }
;                 *(f32x4*)(LF + (size_t)row * 512 + c) = a; *(f32x4*)(LF + (size_t)row * 512 + c + 4) = b; __builtin_amdgcn_sched_barrier(0); ) }
	v_fmac_f32_e32 v194, 0x3f317217, v148
	v_cmp_lt_f32_e64 s[42:43], |v148|, s53
	s_nop 1
	v_cndmask_b32_e64 v148, v148, v194, s[42:43]
	v_cndmask_b32_e64 v194, 0, v216, s[40:41]
	v_sub_f32_e32 v148, v148, v194
	v_sub_f32_e32 v148, v168, v148
	v_min_f32_e32 v168, 0, v144
	v_mul_f32_e64 v144, |v144|, s57
	v_exp_f32_e32 v144, v144
	s_nop 0
	v_add_f32_e32 v144, 1.0, v144
	v_cmp_gt_f32_e64 s[40:41], s97, v144
	s_nop 1
	v_cndmask_b32_e64 v194, 0, 32, s[40:41]
	v_ldexp_f32 v144, v144, v194
	v_log_f32_e32 v144, v144
	s_nop 0
	v_mul_f32_e32 v194, 0x3f317217, v144
	v_fma_f32 v194, v144, s52, -v194
	v_fmac_f32_e32 v194, 0x3377d1cf, v144
	v_fmac_f32_e32 v194, 0x3f317217, v144
	v_cmp_lt_f32_e64 s[42:43], |v144|, s53
	s_nop 1
	v_cndmask_b32_e64 v144, v144, v194, s[42:43]
	v_cndmask_b32_e64 v194, 0, v216, s[40:41]
	v_sub_f32_e32 v144, v144, v194
	v_sub_f32_e32 v168, v168, v144
	v_mul_f32_e32 v144, 0x3fb8aa3b, v148
	v_exp_f32_e32 v144, v144
	s_nop 0
	v_fma_f32 v144, v183, v144, v132
	v_cmp_gt_f32_e64 s[40:41], s97, v144
	s_nop 1
	v_cndmask_b32_e64 v194, 0, 32, s[40:41]
	v_ldexp_f32 v144, v144, v194
	v_log_f32_e32 v144, v144
	s_nop 0
	v_mul_f32_e32 v194, 0x3f317217, v144
	v_fma_f32 v194, v144, s52, -v194
	v_fmac_f32_e32 v194, 0x3377d1cf, v144
	v_fmac_f32_e32 v194, 0x3f317217, v144
	v_cmp_lt_f32_e64 s[42:43], |v144|, s53
	s_nop 1
	v_cndmask_b32_e64 v144, v144, v194, s[42:43]
	v_cndmask_b32_e64 v194, 0, v216, s[40:41]
	v_sub_f32_e32 v144, v144, v194
	v_cndmask_b32_e64 v144, v148, v144, s[20:21]
	v_mul_f32_e32 v148, 0x3fb8aa3b, v168
	v_exp_f32_e32 v148, v148
	s_nop 0
	v_fma_f32 v148, v182, v148, v128
	v_cmp_gt_f32_e64 s[40:41], s97, v148
	s_nop 1
	v_cndmask_b32_e64 v194, 0, 32, s[40:41]
	v_ldexp_f32 v148, v148, v194
	v_log_f32_e32 v148, v148
	s_nop 0
	v_mul_f32_e32 v194, 0x3f317217, v148
	v_fma_f32 v194, v148, s52, -v194
	v_fmac_f32_e32 v194, 0x3377d1cf, v148
	v_fmac_f32_e32 v194, 0x3f317217, v148
	v_cmp_lt_f32_e64 s[42:43], |v148|, s53
	s_nop 1
	v_cndmask_b32_e64 v148, v148, v194, s[42:43]
	v_cndmask_b32_e64 v194, 0, v216, s[40:41]
	v_sub_f32_e32 v148, v148, v194
	v_cndmask_b32_e64 v148, v168, v148, s[18:19]
	v_min_f32_e32 v168, 0, v149
	v_mul_f32_e64 v149, |v149|, s57
	v_exp_f32_e32 v149, v149
	s_nop 0
	v_add_f32_e32 v149, 1.0, v149
	v_cmp_gt_f32_e64 s[40:41], s97, v149
	s_nop 1
	v_cndmask_b32_e64 v194, 0, 32, s[40:41]
	v_ldexp_f32 v149, v149, v194
	v_log_f32_e32 v149, v149
	s_nop 0
	v_mul_f32_e32 v194, 0x3f317217, v149
	v_fma_f32 v194, v149, s52, -v194
	v_fmac_f32_e32 v194, 0x3377d1cf, v149
	v_fmac_f32_e32 v194, 0x3f317217, v149
	v_cmp_lt_f32_e64 s[42:43], |v149|, s53
	s_nop 1
	v_cndmask_b32_e64 v149, v149, v194, s[42:43]
	v_cndmask_b32_e64 v194, 0, v216, s[40:41]
	v_sub_f32_e32 v149, v149, v194
	v_sub_f32_e32 v149, v168, v149
	v_min_f32_e32 v168, 0, v145
	v_mul_f32_e64 v145, |v145|, s57
	v_exp_f32_e32 v145, v145
	s_nop 0
	v_add_f32_e32 v145, 1.0, v145
	v_cmp_gt_f32_e64 s[40:41], s97, v145
	s_nop 1
	v_cndmask_b32_e64 v194, 0, 32, s[40:41]
	v_ldexp_f32 v145, v145, v194
	v_log_f32_e32 v145, v145
	s_nop 0
	v_mul_f32_e32 v194, 0x3f317217, v145
	v_fma_f32 v194, v145, s52, -v194
	v_fmac_f32_e32 v194, 0x3377d1cf, v145
	v_fmac_f32_e32 v194, 0x3f317217, v145
	v_cmp_lt_f32_e64 s[42:43], |v145|, s53
	s_nop 1
	v_cndmask_b32_e64 v145, v145, v194, s[42:43]
	v_cndmask_b32_e64 v194, 0, v216, s[40:41]
	v_sub_f32_e32 v145, v145, v194
	v_sub_f32_e32 v168, v168, v145
	v_mul_f32_e32 v145, 0x3fb8aa3b, v149
	v_exp_f32_e32 v145, v145
	s_nop 0
	v_fma_f32 v145, v181, v145, v133
	v_cmp_gt_f32_e64 s[40:41], s97, v145
	s_nop 1
	v_cndmask_b32_e64 v194, 0, 32, s[40:41]
	v_ldexp_f32 v145, v145, v194
	v_log_f32_e32 v145, v145
	s_nop 0
	v_mul_f32_e32 v194, 0x3f317217, v145
	v_fma_f32 v194, v145, s52, -v194
	v_fmac_f32_e32 v194, 0x3377d1cf, v145
	v_fmac_f32_e32 v194, 0x3f317217, v145
	v_cmp_lt_f32_e64 s[42:43], |v145|, s53
	s_nop 1
	v_cndmask_b32_e64 v145, v145, v194, s[42:43]
	v_cndmask_b32_e64 v194, 0, v216, s[40:41]
	v_sub_f32_e32 v145, v145, v194
	v_cndmask_b32_e64 v145, v149, v145, s[16:17]
	v_mul_f32_e32 v149, 0x3fb8aa3b, v168
	v_exp_f32_e32 v149, v149
	s_nop 0
	v_fma_f32 v149, v180, v149, v129
	v_cmp_gt_f32_e64 s[40:41], s97, v149
	s_nop 1
	v_cndmask_b32_e64 v194, 0, 32, s[40:41]
	v_ldexp_f32 v149, v149, v194
	v_log_f32_e32 v149, v149
	s_nop 0
	v_mul_f32_e32 v194, 0x3f317217, v149
	v_fma_f32 v194, v149, s52, -v194
	v_fmac_f32_e32 v194, 0x3377d1cf, v149
	v_fmac_f32_e32 v194, 0x3f317217, v149
	v_cmp_lt_f32_e64 s[42:43], |v149|, s53
	s_nop 1
	v_cndmask_b32_e64 v149, v149, v194, s[42:43]
	v_cndmask_b32_e64 v194, 0, v216, s[40:41]
	v_sub_f32_e32 v149, v149, v194
	v_cndmask_b32_e64 v149, v168, v149, s[14:15]
	v_min_f32_e32 v168, 0, v150
	v_mul_f32_e64 v150, |v150|, s57
	v_exp_f32_e32 v150, v150
	s_nop 0
	v_add_f32_e32 v150, 1.0, v150
	v_cmp_gt_f32_e64 s[40:41], s97, v150
	s_nop 1
	v_cndmask_b32_e64 v194, 0, 32, s[40:41]
	v_ldexp_f32 v150, v150, v194
	v_log_f32_e32 v150, v150
	s_nop 0
	v_mul_f32_e32 v194, 0x3f317217, v150
	v_fma_f32 v194, v150, s52, -v194
	v_fmac_f32_e32 v194, 0x3377d1cf, v150
	v_fmac_f32_e32 v194, 0x3f317217, v150
	v_cmp_lt_f32_e64 s[42:43], |v150|, s53
	s_nop 1
	v_cndmask_b32_e64 v150, v150, v194, s[42:43]
	v_cndmask_b32_e64 v194, 0, v216, s[40:41]
	v_sub_f32_e32 v150, v150, v194
	v_sub_f32_e32 v150, v168, v150
	v_min_f32_e32 v168, 0, v146
	v_mul_f32_e64 v146, |v146|, s57
	v_exp_f32_e32 v146, v146
	s_nop 0
	v_add_f32_e32 v146, 1.0, v146
	v_cmp_gt_f32_e64 s[40:41], s97, v146
	s_nop 1
	v_cndmask_b32_e64 v194, 0, 32, s[40:41]
	v_ldexp_f32 v146, v146, v194
	v_log_f32_e32 v146, v146
	s_nop 0
	v_mul_f32_e32 v194, 0x3f317217, v146
	v_fma_f32 v194, v146, s52, -v194
;     __device__ __forceinline__ void operator()(const f32x4 (&acc)[2][2][4][2], const pg8::Unit& u, int wr, int wc, int fr, int fq) const {
;     ...
;             WIN_LOOP( _Pragma("unroll") for (int i = 0; i < 4; ++i) { const float s0 = fminf(a[i], 0.f) - __logf(1.f + __expf(-fabsf(a[i]))), s1 = fminf(b[i], 0.f) - __logf(1.f + __expf(-fabsf(b[i]))); const float la = l0[bj][i], lbv = l1[bj][i];
;                     a[i] = la > 0.f ? __logf(la + (1.f - la) * __expf(s0)) : s0; b[i] = lbv > 0.f ? __logf(lbv + (1.f - lbv) * __expf(s1)) : s1; }
;                 *(f32x4*)(LF + (size_t)row * 512 + c) = a; *(f32x4*)(LF + (size_t)row * 512 + c + 4) = b; __builtin_amdgcn_sched_barrier(0); ) }
	v_fmac_f32_e32 v194, 0x3377d1cf, v146
	v_fmac_f32_e32 v194, 0x3f317217, v146
	v_cmp_lt_f32_e64 s[42:43], |v146|, s53
	s_nop 1
	v_cndmask_b32_e64 v146, v146, v194, s[42:43]
	v_cndmask_b32_e64 v194, 0, v216, s[40:41]
	v_sub_f32_e32 v146, v146, v194
	v_sub_f32_e32 v168, v168, v146
	v_mul_f32_e32 v146, 0x3fb8aa3b, v150
	v_exp_f32_e32 v146, v146
	s_nop 0
	v_fma_f32 v146, v179, v146, v134
	v_cmp_gt_f32_e64 s[40:41], s97, v146
	s_nop 1
	v_cndmask_b32_e64 v194, 0, 32, s[40:41]
	v_ldexp_f32 v146, v146, v194
	v_log_f32_e32 v146, v146
	s_nop 0
	v_mul_f32_e32 v194, 0x3f317217, v146
	v_fma_f32 v194, v146, s52, -v194
	v_fmac_f32_e32 v194, 0x3377d1cf, v146
	v_fmac_f32_e32 v194, 0x3f317217, v146
	v_cmp_lt_f32_e64 s[42:43], |v146|, s53
	s_nop 1
	v_cndmask_b32_e64 v146, v146, v194, s[42:43]
	v_cndmask_b32_e64 v194, 0, v216, s[40:41]
	v_sub_f32_e32 v146, v146, v194
	v_cndmask_b32_e64 v146, v150, v146, s[12:13]
	v_mul_f32_e32 v150, 0x3fb8aa3b, v168
	v_exp_f32_e32 v150, v150
	s_nop 0
	v_fma_f32 v150, v178, v150, v130
	v_cmp_gt_f32_e64 s[40:41], s97, v150
	s_nop 1
	v_cndmask_b32_e64 v194, 0, 32, s[40:41]
	v_ldexp_f32 v150, v150, v194
	v_log_f32_e32 v150, v150
	s_nop 0
	v_mul_f32_e32 v194, 0x3f317217, v150
	v_fma_f32 v194, v150, s52, -v194
	v_fmac_f32_e32 v194, 0x3377d1cf, v150
	v_fmac_f32_e32 v194, 0x3f317217, v150
	v_cmp_lt_f32_e64 s[42:43], |v150|, s53
	s_nop 1
	v_cndmask_b32_e64 v150, v150, v194, s[42:43]
	v_cndmask_b32_e64 v194, 0, v216, s[40:41]
	v_sub_f32_e32 v150, v150, v194
	v_cndmask_b32_e64 v150, v168, v150, s[10:11]
	v_min_f32_e32 v168, 0, v151
	v_mul_f32_e64 v151, |v151|, s57
	v_exp_f32_e32 v151, v151
	s_nop 0
	v_add_f32_e32 v151, 1.0, v151
	v_cmp_gt_f32_e64 s[40:41], s97, v151
	s_nop 1
	v_cndmask_b32_e64 v194, 0, 32, s[40:41]
	v_ldexp_f32 v151, v151, v194
	v_log_f32_e32 v151, v151
	s_nop 0
	v_mul_f32_e32 v194, 0x3f317217, v151
	v_fma_f32 v194, v151, s52, -v194
	v_fmac_f32_e32 v194, 0x3377d1cf, v151
	v_fmac_f32_e32 v194, 0x3f317217, v151
	v_cmp_lt_f32_e64 s[42:43], |v151|, s53
	s_nop 1
	v_cndmask_b32_e64 v151, v151, v194, s[42:43]
	v_cndmask_b32_e64 v194, 0, v216, s[40:41]
	v_sub_f32_e32 v151, v151, v194
	v_sub_f32_e32 v151, v168, v151
	v_min_f32_e32 v168, 0, v147
	v_mul_f32_e64 v147, |v147|, s57
	v_exp_f32_e32 v147, v147
	s_nop 0
	v_add_f32_e32 v147, 1.0, v147
	v_cmp_gt_f32_e64 s[40:41], s97, v147
	s_nop 1
	v_cndmask_b32_e64 v194, 0, 32, s[40:41]
	v_ldexp_f32 v147, v147, v194
	v_log_f32_e32 v147, v147
	s_nop 0
	v_mul_f32_e32 v194, 0x3f317217, v147
	v_fma_f32 v194, v147, s52, -v194
	v_fmac_f32_e32 v194, 0x3377d1cf, v147
	v_fmac_f32_e32 v194, 0x3f317217, v147
	v_cmp_lt_f32_e64 s[42:43], |v147|, s53
	s_nop 1
	v_cndmask_b32_e64 v147, v147, v194, s[42:43]
	v_cndmask_b32_e64 v194, 0, v216, s[40:41]
	v_sub_f32_e32 v147, v147, v194
	v_sub_f32_e32 v168, v168, v147
	v_mul_f32_e32 v147, 0x3fb8aa3b, v151
	v_exp_f32_e32 v147, v147
	s_nop 0
	v_fma_f32 v147, v177, v147, v135
	v_cmp_gt_f32_e64 s[40:41], s97, v147
	s_nop 1
	v_cndmask_b32_e64 v194, 0, 32, s[40:41]
	v_ldexp_f32 v147, v147, v194
	v_log_f32_e32 v147, v147
	s_nop 0
	v_mul_f32_e32 v194, 0x3f317217, v147
	v_fma_f32 v194, v147, s52, -v194
	v_fmac_f32_e32 v194, 0x3377d1cf, v147
	v_fmac_f32_e32 v194, 0x3f317217, v147
	v_cmp_lt_f32_e64 s[42:43], |v147|, s53
	s_nop 1
	v_cndmask_b32_e64 v147, v147, v194, s[42:43]
	v_cndmask_b32_e64 v194, 0, v216, s[40:41]
	v_sub_f32_e32 v147, v147, v194
	v_cndmask_b32_e64 v147, v151, v147, s[8:9]
	v_mul_f32_e32 v151, 0x3fb8aa3b, v168
	v_exp_f32_e32 v151, v151
	s_nop 0
	v_fma_f32 v151, v167, v151, v131
	v_cmp_gt_f32_e64 s[40:41], s97, v151
	s_nop 1
	v_cndmask_b32_e64 v194, 0, 32, s[40:41]
	v_ldexp_f32 v151, v151, v194
	v_log_f32_e32 v151, v151
	s_nop 0
	v_mul_f32_e32 v194, 0x3f317217, v151
	v_fma_f32 v194, v151, s52, -v194
	v_fmac_f32_e32 v194, 0x3377d1cf, v151
	v_fmac_f32_e32 v194, 0x3f317217, v151
	v_cmp_lt_f32_e64 s[42:43], |v151|, s53
	s_nop 1
	v_cndmask_b32_e64 v151, v151, v194, s[42:43]
	v_cndmask_b32_e64 v194, 0, v216, s[40:41]
	v_sub_f32_e32 v151, v151, v194
	v_cndmask_b32_e32 v151, v168, v151, vcc
	global_store_dwordx4 v[170:171], v[144:147], off offset:512
	global_store_dwordx4 v[170:171], v[148:151], off offset:528
	s_nop 1
	v_add_u32_e32 v148, 0x80, v166
	v_ashrrev_i32_e32 v149, 31, v148
	v_lshlrev_b64 v[144:145], 6, v[148:149]
	v_lshl_add_u64 v[144:145], v[160:161], 0, v[144:145]
	s_nop 0
	s_waitcnt lgkmcnt(0)
	s_nop 0
	s_nop 0
	s_nop 0
	s_nop 0
	s_nop 0
	s_nop 0
	s_nop 0
	s_waitcnt lgkmcnt(0)
	s_nop 0
	s_nop 0
	s_waitcnt lgkmcnt(0)
;     __device__ __forceinline__ void operator()(const f32x4 (&acc)[2][2][4][2], const pg8::Unit& u, int wr, int wc, int fr, int fq) const {
;     ...
;             WIN_LOOP( _Pragma("unroll") for (int i = 0; i < 4; ++i) { const float s0 = fminf(a[i], 0.f) - __logf(1.f + __expf(-fabsf(a[i]))), s1 = fminf(b[i], 0.f) - __logf(1.f + __expf(-fabsf(b[i]))); const float la = l0[bj][i], lbv = l1[bj][i];
;                     a[i] = la > 0.f ? __logf(la + (1.f - la) * __expf(s0)) : s0; b[i] = lbv > 0.f ? __logf(lbv + (1.f - lbv) * __expf(s1)) : s1; }
;                 *(f32x4*)(LF + (size_t)row * 512 + c) = a; *(f32x4*)(LF + (size_t)row * 512 + c + 4) = b; __builtin_amdgcn_sched_barrier(0); ) }
	s_nop 0
	s_nop 0
	v_mov_b32_e32 v168, v254
	v_lshlrev_b64 v[144:145], 11, v[148:149]
	v_lshl_add_u64 v[170:171], s[50:51], 0, v[144:145]
	v_lshl_add_u64 v[170:171], v[170:171], 0, v[192:193]
	v_pk_mul_f32 v[148:149], v[28:29], v[168:169] op_sel_hi:[1,0]
	v_pk_mul_f32 v[144:145], v[24:25], v[168:169] op_sel_hi:[1,0]
	v_min_f32_e32 v194, 0, v148
	v_mul_f32_e64 v148, |v148|, s57
	v_exp_f32_e32 v148, v148
	v_pk_mul_f32 v[150:151], v[30:31], v[168:169] op_sel_hi:[1,0]
	v_pk_mul_f32 v[146:147], v[26:27], v[168:169] op_sel_hi:[1,0]
	v_add_f32_e32 v148, 1.0, v148
	v_cmp_gt_f32_e64 s[40:41], s97, v148
	s_nop 1
	v_cndmask_b32_e64 v195, 0, 32, s[40:41]
	v_ldexp_f32 v148, v148, v195
	v_log_f32_e32 v148, v148
	s_nop 0
	v_mul_f32_e32 v195, 0x3f317217, v148
	v_fma_f32 v195, v148, s52, -v195
	v_fmac_f32_e32 v195, 0x3377d1cf, v148
	v_fmac_f32_e32 v195, 0x3f317217, v148
	v_cmp_lt_f32_e64 s[42:43], |v148|, s53
	s_nop 1
	v_cndmask_b32_e64 v148, v148, v195, s[42:43]
	v_cndmask_b32_e64 v195, 0, v216, s[40:41]
	v_sub_f32_e32 v148, v148, v195
	v_sub_f32_e32 v148, v194, v148
	v_min_f32_e32 v194, 0, v144
	v_mul_f32_e64 v144, |v144|, s57
	v_exp_f32_e32 v144, v144
	s_nop 0
	v_add_f32_e32 v144, 1.0, v144
	v_cmp_gt_f32_e64 s[40:41], s97, v144
	s_nop 1
	v_cndmask_b32_e64 v195, 0, 32, s[40:41]
	v_ldexp_f32 v144, v144, v195
	v_log_f32_e32 v144, v144
	s_nop 0
	v_mul_f32_e32 v195, 0x3f317217, v144
	v_fma_f32 v195, v144, s52, -v195
	v_fmac_f32_e32 v195, 0x3377d1cf, v144
	v_fmac_f32_e32 v195, 0x3f317217, v144
	v_cmp_lt_f32_e64 s[42:43], |v144|, s53
	s_nop 1
	v_cndmask_b32_e64 v144, v144, v195, s[42:43]
	v_cndmask_b32_e64 v195, 0, v216, s[40:41]
	v_sub_f32_e32 v144, v144, v195
	v_sub_f32_e32 v194, v194, v144
	v_mul_f32_e32 v144, 0x3fb8aa3b, v148
	v_exp_f32_e32 v144, v144
	s_nop 0
	v_fma_f32 v144, v190, v144, v140
	v_cmp_gt_f32_e64 s[40:41], s97, v144
	s_nop 1
	v_cndmask_b32_e64 v195, 0, 32, s[40:41]
	v_ldexp_f32 v144, v144, v195
	v_log_f32_e32 v144, v144
	s_nop 0
	v_mul_f32_e32 v195, 0x3f317217, v144
	v_fma_f32 v195, v144, s52, -v195
	v_fmac_f32_e32 v195, 0x3377d1cf, v144
	v_fmac_f32_e32 v195, 0x3f317217, v144
	v_cmp_lt_f32_e64 s[42:43], |v144|, s53
	s_nop 1
	v_cndmask_b32_e64 v144, v144, v195, s[42:43]
	v_cndmask_b32_e64 v195, 0, v216, s[40:41]
	v_sub_f32_e32 v144, v144, v195
	v_cndmask_b32_e64 v144, v148, v144, s[38:39]
	v_mul_f32_e32 v148, 0x3fb8aa3b, v194
	v_exp_f32_e32 v148, v148
	s_nop 0
	v_fma_f32 v148, v191, v148, v136
	v_cmp_gt_f32_e64 s[40:41], s97, v148
	s_nop 1
	v_cndmask_b32_e64 v195, 0, 32, s[40:41]
	v_ldexp_f32 v148, v148, v195
	v_log_f32_e32 v148, v148
	s_nop 0
	v_mul_f32_e32 v195, 0x3f317217, v148
	v_fma_f32 v195, v148, s52, -v195
	v_fmac_f32_e32 v195, 0x3377d1cf, v148
	v_fmac_f32_e32 v195, 0x3f317217, v148
	v_cmp_lt_f32_e64 s[42:43], |v148|, s53
	s_nop 1
	v_cndmask_b32_e64 v148, v148, v195, s[42:43]
	v_cndmask_b32_e64 v195, 0, v216, s[40:41]
	v_sub_f32_e32 v148, v148, v195
	v_cndmask_b32_e64 v148, v194, v148, s[36:37]
	v_min_f32_e32 v194, 0, v149
	v_mul_f32_e64 v149, |v149|, s57
	v_exp_f32_e32 v149, v149
	s_nop 0
	v_add_f32_e32 v149, 1.0, v149
	v_cmp_gt_f32_e64 s[40:41], s97, v149
	s_nop 1
	v_cndmask_b32_e64 v195, 0, 32, s[40:41]
	v_ldexp_f32 v149, v149, v195
	v_log_f32_e32 v149, v149
	s_nop 0
	v_mul_f32_e32 v195, 0x3f317217, v149
	v_fma_f32 v195, v149, s52, -v195
	v_fmac_f32_e32 v195, 0x3377d1cf, v149
	v_fmac_f32_e32 v195, 0x3f317217, v149
	v_cmp_lt_f32_e64 s[42:43], |v149|, s53
	s_nop 1
	v_cndmask_b32_e64 v149, v149, v195, s[42:43]
	v_cndmask_b32_e64 v195, 0, v216, s[40:41]
	v_sub_f32_e32 v149, v149, v195
	v_sub_f32_e32 v149, v194, v149
	v_min_f32_e32 v194, 0, v145
	v_mul_f32_e64 v145, |v145|, s57
	v_exp_f32_e32 v145, v145
	s_nop 0
	v_add_f32_e32 v145, 1.0, v145
	v_cmp_gt_f32_e64 s[40:41], s97, v145
	s_nop 1
	v_cndmask_b32_e64 v195, 0, 32, s[40:41]
	v_ldexp_f32 v145, v145, v195
	v_log_f32_e32 v145, v145
	s_nop 0
	v_mul_f32_e32 v195, 0x3f317217, v145
	v_fma_f32 v195, v145, s52, -v195
	v_fmac_f32_e32 v195, 0x3377d1cf, v145
	v_fmac_f32_e32 v195, 0x3f317217, v145
	v_cmp_lt_f32_e64 s[42:43], |v145|, s53
	s_nop 1
	v_cndmask_b32_e64 v145, v145, v195, s[42:43]
	v_cndmask_b32_e64 v195, 0, v216, s[40:41]
	v_sub_f32_e32 v145, v145, v195
	v_sub_f32_e32 v194, v194, v145
	v_mul_f32_e32 v145, 0x3fb8aa3b, v149
	v_exp_f32_e32 v145, v145
	s_nop 0
	v_fma_f32 v145, v188, v145, v141
	v_cmp_gt_f32_e64 s[40:41], s97, v145
	s_nop 1
	v_cndmask_b32_e64 v195, 0, 32, s[40:41]
	v_ldexp_f32 v145, v145, v195
	v_log_f32_e32 v145, v145
	s_nop 0
	v_mul_f32_e32 v195, 0x3f317217, v145
	v_fma_f32 v195, v145, s52, -v195
	v_fmac_f32_e32 v195, 0x3377d1cf, v145
	v_fmac_f32_e32 v195, 0x3f317217, v145
	v_cmp_lt_f32_e64 s[42:43], |v145|, s53
	s_nop 1
	v_cndmask_b32_e64 v145, v145, v195, s[42:43]
	v_cndmask_b32_e64 v195, 0, v216, s[40:41]
	v_sub_f32_e32 v145, v145, v195
	v_cndmask_b32_e64 v145, v149, v145, s[34:35]
	v_mul_f32_e32 v149, 0x3fb8aa3b, v194
	v_exp_f32_e32 v149, v149
	s_nop 0
	v_fma_f32 v149, v189, v149, v137
	v_cmp_gt_f32_e64 s[40:41], s97, v149
	s_nop 1
	v_cndmask_b32_e64 v195, 0, 32, s[40:41]
	v_ldexp_f32 v149, v149, v195
	v_log_f32_e32 v149, v149
	s_nop 0
	v_mul_f32_e32 v195, 0x3f317217, v149
	v_fma_f32 v195, v149, s52, -v195
	v_fmac_f32_e32 v195, 0x3377d1cf, v149
	v_fmac_f32_e32 v195, 0x3f317217, v149
	v_cmp_lt_f32_e64 s[42:43], |v149|, s53
	s_nop 1
	v_cndmask_b32_e64 v149, v149, v195, s[42:43]
	v_cndmask_b32_e64 v195, 0, v216, s[40:41]
	v_sub_f32_e32 v149, v149, v195
	v_cndmask_b32_e64 v149, v194, v149, s[30:31]
	v_min_f32_e32 v194, 0, v150
	v_mul_f32_e64 v150, |v150|, s57
	v_exp_f32_e32 v150, v150
	s_nop 0
	v_add_f32_e32 v150, 1.0, v150
	v_cmp_gt_f32_e64 s[40:41], s97, v150
;     __device__ __forceinline__ void operator()(const f32x4 (&acc)[2][2][4][2], const pg8::Unit& u, int wr, int wc, int fr, int fq) const {
;     ...
;             WIN_LOOP( _Pragma("unroll") for (int i = 0; i < 4; ++i) { const float s0 = fminf(a[i], 0.f) - __logf(1.f + __expf(-fabsf(a[i]))), s1 = fminf(b[i], 0.f) - __logf(1.f + __expf(-fabsf(b[i]))); const float la = l0[bj][i], lbv = l1[bj][i];
;                     a[i] = la > 0.f ? __logf(la + (1.f - la) * __expf(s0)) : s0; b[i] = lbv > 0.f ? __logf(lbv + (1.f - lbv) * __expf(s1)) : s1; }
;                 *(f32x4*)(LF + (size_t)row * 512 + c) = a; *(f32x4*)(LF + (size_t)row * 512 + c + 4) = b; __builtin_amdgcn_sched_barrier(0); ) }
	s_nop 1
	v_cndmask_b32_e64 v195, 0, 32, s[40:41]
	v_ldexp_f32 v150, v150, v195
	v_log_f32_e32 v150, v150
	s_nop 0
	v_mul_f32_e32 v195, 0x3f317217, v150
	v_fma_f32 v195, v150, s52, -v195
	v_fmac_f32_e32 v195, 0x3377d1cf, v150
	v_fmac_f32_e32 v195, 0x3f317217, v150
	v_cmp_lt_f32_e64 s[42:43], |v150|, s53
	s_nop 1
	v_cndmask_b32_e64 v150, v150, v195, s[42:43]
	v_cndmask_b32_e64 v195, 0, v216, s[40:41]
	v_sub_f32_e32 v150, v150, v195
	v_sub_f32_e32 v150, v194, v150
	v_min_f32_e32 v194, 0, v146
	v_mul_f32_e64 v146, |v146|, s57
	v_exp_f32_e32 v146, v146
	s_nop 0
	v_add_f32_e32 v146, 1.0, v146
	v_cmp_gt_f32_e64 s[40:41], s97, v146
	s_nop 1
	v_cndmask_b32_e64 v195, 0, 32, s[40:41]
	v_ldexp_f32 v146, v146, v195
	v_log_f32_e32 v146, v146
	s_nop 0
	v_mul_f32_e32 v195, 0x3f317217, v146
	v_fma_f32 v195, v146, s52, -v195
	v_fmac_f32_e32 v195, 0x3377d1cf, v146
	v_fmac_f32_e32 v195, 0x3f317217, v146
	v_cmp_lt_f32_e64 s[42:43], |v146|, s53
	s_nop 1
	v_cndmask_b32_e64 v146, v146, v195, s[42:43]
	v_cndmask_b32_e64 v195, 0, v216, s[40:41]
	v_sub_f32_e32 v146, v146, v195
	v_sub_f32_e32 v194, v194, v146
	v_mul_f32_e32 v146, 0x3fb8aa3b, v150
	v_exp_f32_e32 v146, v146
	s_nop 0
	v_fma_f32 v146, v187, v146, v142
	v_cmp_gt_f32_e64 s[40:41], s97, v146
	s_nop 1
	v_cndmask_b32_e64 v195, 0, 32, s[40:41]
	v_ldexp_f32 v146, v146, v195
	v_log_f32_e32 v146, v146
	s_nop 0
	v_mul_f32_e32 v195, 0x3f317217, v146
	v_fma_f32 v195, v146, s52, -v195
	v_fmac_f32_e32 v195, 0x3377d1cf, v146
	v_fmac_f32_e32 v195, 0x3f317217, v146
	v_cmp_lt_f32_e64 s[42:43], |v146|, s53
	s_nop 1
	v_cndmask_b32_e64 v146, v146, v195, s[42:43]
	v_cndmask_b32_e64 v195, 0, v216, s[40:41]
	v_sub_f32_e32 v146, v146, v195
	v_cndmask_b32_e64 v146, v150, v146, s[28:29]
	v_mul_f32_e32 v150, 0x3fb8aa3b, v194
	v_exp_f32_e32 v150, v150
	s_nop 0
	v_fma_f32 v150, v186, v150, v138
	v_cmp_gt_f32_e64 s[40:41], s97, v150
	s_nop 1
	v_cndmask_b32_e64 v195, 0, 32, s[40:41]
	v_ldexp_f32 v150, v150, v195
	v_log_f32_e32 v150, v150
	s_nop 0
	v_mul_f32_e32 v195, 0x3f317217, v150
	v_fma_f32 v195, v150, s52, -v195
	v_fmac_f32_e32 v195, 0x3377d1cf, v150
	v_fmac_f32_e32 v195, 0x3f317217, v150
	v_cmp_lt_f32_e64 s[42:43], |v150|, s53
	s_nop 1
	v_cndmask_b32_e64 v150, v150, v195, s[42:43]
	v_cndmask_b32_e64 v195, 0, v216, s[40:41]
	v_sub_f32_e32 v150, v150, v195
	v_cndmask_b32_e64 v150, v194, v150, s[26:27]
	v_min_f32_e32 v194, 0, v151
	v_mul_f32_e64 v151, |v151|, s57
	v_exp_f32_e32 v151, v151
	s_nop 0
	v_add_f32_e32 v151, 1.0, v151
	v_cmp_gt_f32_e64 s[40:41], s97, v151
	s_nop 1
	v_cndmask_b32_e64 v195, 0, 32, s[40:41]
	v_ldexp_f32 v151, v151, v195
	v_log_f32_e32 v151, v151
	s_nop 0
	v_mul_f32_e32 v195, 0x3f317217, v151
	v_fma_f32 v195, v151, s52, -v195
	v_fmac_f32_e32 v195, 0x3377d1cf, v151
	v_fmac_f32_e32 v195, 0x3f317217, v151
	v_cmp_lt_f32_e64 s[42:43], |v151|, s53
	s_nop 1
	v_cndmask_b32_e64 v151, v151, v195, s[42:43]
	v_cndmask_b32_e64 v195, 0, v216, s[40:41]
	v_sub_f32_e32 v151, v151, v195
	v_sub_f32_e32 v151, v194, v151
	v_min_f32_e32 v194, 0, v147
	v_mul_f32_e64 v147, |v147|, s57
	v_exp_f32_e32 v147, v147
	s_nop 0
	v_add_f32_e32 v147, 1.0, v147
	v_cmp_gt_f32_e64 s[40:41], s97, v147
	s_nop 1
	v_cndmask_b32_e64 v195, 0, 32, s[40:41]
	v_ldexp_f32 v147, v147, v195
	v_log_f32_e32 v147, v147
	s_nop 0
	v_mul_f32_e32 v195, 0x3f317217, v147
	v_fma_f32 v195, v147, s52, -v195
	v_fmac_f32_e32 v195, 0x3377d1cf, v147
	v_fmac_f32_e32 v195, 0x3f317217, v147
	v_cmp_lt_f32_e64 s[42:43], |v147|, s53
	s_nop 1
	v_cndmask_b32_e64 v147, v147, v195, s[42:43]
	v_cndmask_b32_e64 v195, 0, v216, s[40:41]
	v_sub_f32_e32 v147, v147, v195
	v_sub_f32_e32 v194, v194, v147
	v_mul_f32_e32 v147, 0x3fb8aa3b, v151
	v_exp_f32_e32 v147, v147
	s_nop 0
	v_fma_f32 v147, v185, v147, v143
	v_cmp_gt_f32_e64 s[40:41], s97, v147
	s_nop 1
	v_cndmask_b32_e64 v195, 0, 32, s[40:41]
	v_ldexp_f32 v147, v147, v195
	v_log_f32_e32 v147, v147
	s_nop 0
	v_mul_f32_e32 v195, 0x3f317217, v147
	v_fma_f32 v195, v147, s52, -v195
	v_fmac_f32_e32 v195, 0x3377d1cf, v147
	v_fmac_f32_e32 v195, 0x3f317217, v147
	v_cmp_lt_f32_e64 s[42:43], |v147|, s53
	s_nop 1
	v_cndmask_b32_e64 v147, v147, v195, s[42:43]
	v_cndmask_b32_e64 v195, 0, v216, s[40:41]
	v_sub_f32_e32 v147, v147, v195
	v_cndmask_b32_e64 v147, v151, v147, s[24:25]
	v_mul_f32_e32 v151, 0x3fb8aa3b, v194
	v_exp_f32_e32 v151, v151
	s_nop 0
	v_fma_f32 v151, v184, v151, v139
	v_cmp_gt_f32_e64 s[40:41], s97, v151
	s_nop 1
	v_cndmask_b32_e64 v195, 0, 32, s[40:41]
	v_ldexp_f32 v151, v151, v195
	v_log_f32_e32 v151, v151
	s_nop 0
	v_mul_f32_e32 v195, 0x3f317217, v151
	v_fma_f32 v195, v151, s52, -v195
	v_fmac_f32_e32 v195, 0x3377d1cf, v151
	v_fmac_f32_e32 v195, 0x3f317217, v151
	v_cmp_lt_f32_e64 s[42:43], |v151|, s53
	s_nop 1
	v_cndmask_b32_e64 v151, v151, v195, s[42:43]
	v_cndmask_b32_e64 v195, 0, v216, s[40:41]
	v_sub_f32_e32 v151, v151, v195
	v_cndmask_b32_e64 v151, v194, v151, s[22:23]
	global_store_dwordx4 v[170:171], v[144:147], off
	global_store_dwordx4 v[170:171], v[148:151], off offset:16
	s_nop 1
	v_pk_mul_f32 v[148:149], v[92:93], v[168:169] op_sel_hi:[1,0]
	v_pk_mul_f32 v[150:151], v[94:95], v[168:169] op_sel_hi:[1,0]
	v_pk_mul_f32 v[146:147], v[90:91], v[168:169] op_sel_hi:[1,0]
	v_pk_mul_f32 v[144:145], v[88:89], v[168:169] op_sel_hi:[1,0]
	v_min_f32_e32 v168, 0, v148
	v_mul_f32_e64 v148, |v148|, s57
	v_exp_f32_e32 v148, v148
	s_nop 0
	v_add_f32_e32 v148, 1.0, v148
	v_cmp_gt_f32_e64 s[40:41], s97, v148
	s_nop 1
	v_cndmask_b32_e64 v194, 0, 32, s[40:41]
	v_ldexp_f32 v148, v148, v194
	v_log_f32_e32 v148, v148
	s_nop 0
	v_mul_f32_e32 v194, 0x3f317217, v148
	v_fma_f32 v194, v148, s52, -v194
	v_fmac_f32_e32 v194, 0x3377d1cf, v148
;     __device__ __forceinline__ void operator()(const f32x4 (&acc)[2][2][4][2], const pg8::Unit& u, int wr, int wc, int fr, int fq) const {
;     ...
;             WIN_LOOP( _Pragma("unroll") for (int i = 0; i < 4; ++i) { const float s0 = fminf(a[i], 0.f) - __logf(1.f + __expf(-fabsf(a[i]))), s1 = fminf(b[i], 0.f) - __logf(1.f + __expf(-fabsf(b[i]))); const float la = l0[bj][i], lbv = l1[bj][i];
;                     a[i] = la > 0.f ? __logf(la + (1.f - la) * __expf(s0)) : s0; b[i] = lbv > 0.f ? __logf(lbv + (1.f - lbv) * __expf(s1)) : s1; }
;                 *(f32x4*)(LF + (size_t)row * 512 + c) = a; *(f32x4*)(LF + (size_t)row * 512 + c + 4) = b; __builtin_amdgcn_sched_barrier(0); ) }
	v_fmac_f32_e32 v194, 0x3f317217, v148
	v_cmp_lt_f32_e64 s[42:43], |v148|, s53
	s_nop 1
	v_cndmask_b32_e64 v148, v148, v194, s[42:43]
	v_cndmask_b32_e64 v194, 0, v216, s[40:41]
	v_sub_f32_e32 v148, v148, v194
	v_sub_f32_e32 v148, v168, v148
	v_min_f32_e32 v168, 0, v144
	v_mul_f32_e64 v144, |v144|, s57
	v_exp_f32_e32 v144, v144
	s_nop 0
	v_add_f32_e32 v144, 1.0, v144
	v_cmp_gt_f32_e64 s[40:41], s97, v144
	s_nop 1
	v_cndmask_b32_e64 v194, 0, 32, s[40:41]
	v_ldexp_f32 v144, v144, v194
	v_log_f32_e32 v144, v144
	s_nop 0
	v_mul_f32_e32 v194, 0x3f317217, v144
	v_fma_f32 v194, v144, s52, -v194
	v_fmac_f32_e32 v194, 0x3377d1cf, v144
	v_fmac_f32_e32 v194, 0x3f317217, v144
	v_cmp_lt_f32_e64 s[42:43], |v144|, s53
	s_nop 1
	v_cndmask_b32_e64 v144, v144, v194, s[42:43]
	v_cndmask_b32_e64 v194, 0, v216, s[40:41]
	v_sub_f32_e32 v144, v144, v194
	v_sub_f32_e32 v168, v168, v144
	v_mul_f32_e32 v144, 0x3fb8aa3b, v148
	v_exp_f32_e32 v144, v144
	s_nop 0
	v_fma_f32 v144, v183, v144, v132
	v_cmp_gt_f32_e64 s[40:41], s97, v144
	s_nop 1
	v_cndmask_b32_e64 v194, 0, 32, s[40:41]
	v_ldexp_f32 v144, v144, v194
	v_log_f32_e32 v144, v144
	s_nop 0
	v_mul_f32_e32 v194, 0x3f317217, v144
	v_fma_f32 v194, v144, s52, -v194
	v_fmac_f32_e32 v194, 0x3377d1cf, v144
	v_fmac_f32_e32 v194, 0x3f317217, v144
	v_cmp_lt_f32_e64 s[42:43], |v144|, s53
	s_nop 1
	v_cndmask_b32_e64 v144, v144, v194, s[42:43]
	v_cndmask_b32_e64 v194, 0, v216, s[40:41]
	v_sub_f32_e32 v144, v144, v194
	v_cndmask_b32_e64 v144, v148, v144, s[20:21]
	v_mul_f32_e32 v148, 0x3fb8aa3b, v168
	v_exp_f32_e32 v148, v148
	s_nop 0
	v_fma_f32 v148, v182, v148, v128
	v_cmp_gt_f32_e64 s[40:41], s97, v148
	s_nop 1
	v_cndmask_b32_e64 v194, 0, 32, s[40:41]
	v_ldexp_f32 v148, v148, v194
	v_log_f32_e32 v148, v148
	s_nop 0
	v_mul_f32_e32 v194, 0x3f317217, v148
	v_fma_f32 v194, v148, s52, -v194
	v_fmac_f32_e32 v194, 0x3377d1cf, v148
	v_fmac_f32_e32 v194, 0x3f317217, v148
	v_cmp_lt_f32_e64 s[42:43], |v148|, s53
	s_nop 1
	v_cndmask_b32_e64 v148, v148, v194, s[42:43]
	v_cndmask_b32_e64 v194, 0, v216, s[40:41]
	v_sub_f32_e32 v148, v148, v194
	v_cndmask_b32_e64 v148, v168, v148, s[18:19]
	v_min_f32_e32 v168, 0, v149
	v_mul_f32_e64 v149, |v149|, s57
	v_exp_f32_e32 v149, v149
	s_nop 0
	v_add_f32_e32 v149, 1.0, v149
	v_cmp_gt_f32_e64 s[40:41], s97, v149
	s_nop 1
	v_cndmask_b32_e64 v194, 0, 32, s[40:41]
	v_ldexp_f32 v149, v149, v194
	v_log_f32_e32 v149, v149
	s_nop 0
	v_mul_f32_e32 v194, 0x3f317217, v149
	v_fma_f32 v194, v149, s52, -v194
	v_fmac_f32_e32 v194, 0x3377d1cf, v149
	v_fmac_f32_e32 v194, 0x3f317217, v149
	v_cmp_lt_f32_e64 s[42:43], |v149|, s53
	s_nop 1
	v_cndmask_b32_e64 v149, v149, v194, s[42:43]
	v_cndmask_b32_e64 v194, 0, v216, s[40:41]
	v_sub_f32_e32 v149, v149, v194
	v_sub_f32_e32 v149, v168, v149
	v_min_f32_e32 v168, 0, v145
	v_mul_f32_e64 v145, |v145|, s57
	v_exp_f32_e32 v145, v145
	s_nop 0
	v_add_f32_e32 v145, 1.0, v145
	v_cmp_gt_f32_e64 s[40:41], s97, v145
	s_nop 1
	v_cndmask_b32_e64 v194, 0, 32, s[40:41]
	v_ldexp_f32 v145, v145, v194
	v_log_f32_e32 v145, v145
	s_nop 0
	v_mul_f32_e32 v194, 0x3f317217, v145
	v_fma_f32 v194, v145, s52, -v194
	v_fmac_f32_e32 v194, 0x3377d1cf, v145
	v_fmac_f32_e32 v194, 0x3f317217, v145
	v_cmp_lt_f32_e64 s[42:43], |v145|, s53
	s_nop 1
	v_cndmask_b32_e64 v145, v145, v194, s[42:43]
	v_cndmask_b32_e64 v194, 0, v216, s[40:41]
	v_sub_f32_e32 v145, v145, v194
	v_sub_f32_e32 v168, v168, v145
	v_mul_f32_e32 v145, 0x3fb8aa3b, v149
	v_exp_f32_e32 v145, v145
	s_nop 0
	v_fma_f32 v145, v181, v145, v133
	v_cmp_gt_f32_e64 s[40:41], s97, v145
	s_nop 1
	v_cndmask_b32_e64 v194, 0, 32, s[40:41]
	v_ldexp_f32 v145, v145, v194
	v_log_f32_e32 v145, v145
	s_nop 0
	v_mul_f32_e32 v194, 0x3f317217, v145
	v_fma_f32 v194, v145, s52, -v194
	v_fmac_f32_e32 v194, 0x3377d1cf, v145
	v_fmac_f32_e32 v194, 0x3f317217, v145
	v_cmp_lt_f32_e64 s[42:43], |v145|, s53
	s_nop 1
	v_cndmask_b32_e64 v145, v145, v194, s[42:43]
	v_cndmask_b32_e64 v194, 0, v216, s[40:41]
	v_sub_f32_e32 v145, v145, v194
	v_cndmask_b32_e64 v145, v149, v145, s[16:17]
	v_mul_f32_e32 v149, 0x3fb8aa3b, v168
	v_exp_f32_e32 v149, v149
	s_nop 0
	v_fma_f32 v149, v180, v149, v129
	v_cmp_gt_f32_e64 s[40:41], s97, v149
	s_nop 1
	v_cndmask_b32_e64 v194, 0, 32, s[40:41]
	v_ldexp_f32 v149, v149, v194
	v_log_f32_e32 v149, v149
	s_nop 0
	v_mul_f32_e32 v194, 0x3f317217, v149
	v_fma_f32 v194, v149, s52, -v194
	v_fmac_f32_e32 v194, 0x3377d1cf, v149
	v_fmac_f32_e32 v194, 0x3f317217, v149
	v_cmp_lt_f32_e64 s[42:43], |v149|, s53
	s_nop 1
	v_cndmask_b32_e64 v149, v149, v194, s[42:43]
	v_cndmask_b32_e64 v194, 0, v216, s[40:41]
	v_sub_f32_e32 v149, v149, v194
	v_cndmask_b32_e64 v149, v168, v149, s[14:15]
	v_min_f32_e32 v168, 0, v150
	v_mul_f32_e64 v150, |v150|, s57
	v_exp_f32_e32 v150, v150
	s_nop 0
	v_add_f32_e32 v150, 1.0, v150
	v_cmp_gt_f32_e64 s[40:41], s97, v150
	s_nop 1
	v_cndmask_b32_e64 v194, 0, 32, s[40:41]
	v_ldexp_f32 v150, v150, v194
	v_log_f32_e32 v150, v150
	s_nop 0
	v_mul_f32_e32 v194, 0x3f317217, v150
	v_fma_f32 v194, v150, s52, -v194
	v_fmac_f32_e32 v194, 0x3377d1cf, v150
	v_fmac_f32_e32 v194, 0x3f317217, v150
	v_cmp_lt_f32_e64 s[42:43], |v150|, s53
	s_nop 1
	v_cndmask_b32_e64 v150, v150, v194, s[42:43]
	v_cndmask_b32_e64 v194, 0, v216, s[40:41]
	v_sub_f32_e32 v150, v150, v194
	v_sub_f32_e32 v150, v168, v150
	v_min_f32_e32 v168, 0, v146
	v_mul_f32_e64 v146, |v146|, s57
	v_exp_f32_e32 v146, v146
	s_nop 0
	v_add_f32_e32 v146, 1.0, v146
	v_cmp_gt_f32_e64 s[40:41], s97, v146
	s_nop 1
	v_cndmask_b32_e64 v194, 0, 32, s[40:41]
	v_ldexp_f32 v146, v146, v194
	v_log_f32_e32 v146, v146
	s_nop 0
	v_mul_f32_e32 v194, 0x3f317217, v146
	v_fma_f32 v194, v146, s52, -v194
; __device__ __forceinline__ float row_rstd(const float* ssq, int row, int fq) {
;     const f32x4 v = *(const f32x4*)(ssq + (size_t)row * 16 + fq * 4);
;     float s = (v[0] + v[1]) + (v[2] + v[3]);
;     s += __shfl_xor(s, 16); s += __shfl_xor(s, 32);
;     return __builtin_amdgcn_rsqf(s * (1.f / DM) + EPS);
; }
;     __device__ __forceinline__ void operator()(const f32x4 (&acc)[2][2][4][2], const pg8::Unit& u, int wr, int wc, int fr, int fq) const {
;     ...
;             WIN_LOOP( _Pragma("unroll") for (int i = 0; i < 4; ++i) { const float s0 = fminf(a[i], 0.f) - __logf(1.f + __expf(-fabsf(a[i]))), s1 = fminf(b[i], 0.f) - __logf(1.f + __expf(-fabsf(b[i]))); const float la = l0[bj][i], lbv = l1[bj][i];
;                     a[i] = la > 0.f ? __logf(la + (1.f - la) * __expf(s0)) : s0; b[i] = lbv > 0.f ? __logf(lbv + (1.f - lbv) * __expf(s1)) : s1; }
;                 *(f32x4*)(LF + (size_t)row * 512 + c) = a; *(f32x4*)(LF + (size_t)row * 512 + c + 4) = b; __builtin_amdgcn_sched_barrier(0); ) }
	v_fmac_f32_e32 v194, 0x3377d1cf, v146
	v_fmac_f32_e32 v194, 0x3f317217, v146
	v_cmp_lt_f32_e64 s[42:43], |v146|, s53
	s_nop 1
	v_cndmask_b32_e64 v146, v146, v194, s[42:43]
	v_cndmask_b32_e64 v194, 0, v216, s[40:41]
	v_sub_f32_e32 v146, v146, v194
	v_sub_f32_e32 v168, v168, v146
	v_mul_f32_e32 v146, 0x3fb8aa3b, v150
	v_exp_f32_e32 v146, v146
	s_nop 0
	v_fma_f32 v146, v179, v146, v134
	v_cmp_gt_f32_e64 s[40:41], s97, v146
	s_nop 1
	v_cndmask_b32_e64 v194, 0, 32, s[40:41]
	v_ldexp_f32 v146, v146, v194
	v_log_f32_e32 v146, v146
	s_nop 0
	v_mul_f32_e32 v194, 0x3f317217, v146
	v_fma_f32 v194, v146, s52, -v194
	v_fmac_f32_e32 v194, 0x3377d1cf, v146
	v_fmac_f32_e32 v194, 0x3f317217, v146
	v_cmp_lt_f32_e64 s[42:43], |v146|, s53
	s_nop 1
	v_cndmask_b32_e64 v146, v146, v194, s[42:43]
	v_cndmask_b32_e64 v194, 0, v216, s[40:41]
	v_sub_f32_e32 v146, v146, v194
	v_cndmask_b32_e64 v146, v150, v146, s[12:13]
	v_mul_f32_e32 v150, 0x3fb8aa3b, v168
	v_exp_f32_e32 v150, v150
	s_nop 0
	v_fma_f32 v150, v178, v150, v130
	v_cmp_gt_f32_e64 s[40:41], s97, v150
	s_nop 1
	v_cndmask_b32_e64 v194, 0, 32, s[40:41]
	v_ldexp_f32 v150, v150, v194
	v_log_f32_e32 v150, v150
	s_nop 0
	v_mul_f32_e32 v194, 0x3f317217, v150
	v_fma_f32 v194, v150, s52, -v194
	v_fmac_f32_e32 v194, 0x3377d1cf, v150
	v_fmac_f32_e32 v194, 0x3f317217, v150
	v_cmp_lt_f32_e64 s[42:43], |v150|, s53
	s_nop 1
	v_cndmask_b32_e64 v150, v150, v194, s[42:43]
	v_cndmask_b32_e64 v194, 0, v216, s[40:41]
	v_sub_f32_e32 v150, v150, v194
	v_cndmask_b32_e64 v150, v168, v150, s[10:11]
	v_min_f32_e32 v168, 0, v151
	v_mul_f32_e64 v151, |v151|, s57
	v_exp_f32_e32 v151, v151
	s_nop 0
	v_add_f32_e32 v151, 1.0, v151
	v_cmp_gt_f32_e64 s[40:41], s97, v151
	s_nop 1
	v_cndmask_b32_e64 v194, 0, 32, s[40:41]
	v_ldexp_f32 v151, v151, v194
	v_log_f32_e32 v151, v151
	s_nop 0
	v_mul_f32_e32 v194, 0x3f317217, v151
	v_fma_f32 v194, v151, s52, -v194
	v_fmac_f32_e32 v194, 0x3377d1cf, v151
	v_fmac_f32_e32 v194, 0x3f317217, v151
	v_cmp_lt_f32_e64 s[42:43], |v151|, s53
	s_nop 1
	v_cndmask_b32_e64 v151, v151, v194, s[42:43]
	v_cndmask_b32_e64 v194, 0, v216, s[40:41]
	v_sub_f32_e32 v151, v151, v194
	v_sub_f32_e32 v151, v168, v151
	v_min_f32_e32 v168, 0, v147
	v_mul_f32_e64 v147, |v147|, s57
	v_exp_f32_e32 v147, v147
	s_nop 0
	v_add_f32_e32 v147, 1.0, v147
	v_cmp_gt_f32_e64 s[40:41], s97, v147
	s_nop 1
	v_cndmask_b32_e64 v194, 0, 32, s[40:41]
	v_ldexp_f32 v147, v147, v194
	v_log_f32_e32 v147, v147
	s_nop 0
	v_mul_f32_e32 v194, 0x3f317217, v147
	v_fma_f32 v194, v147, s52, -v194
	v_fmac_f32_e32 v194, 0x3377d1cf, v147
	v_fmac_f32_e32 v194, 0x3f317217, v147
	v_cmp_lt_f32_e64 s[42:43], |v147|, s53
	s_nop 1
	v_cndmask_b32_e64 v147, v147, v194, s[42:43]
	v_cndmask_b32_e64 v194, 0, v216, s[40:41]
	v_sub_f32_e32 v147, v147, v194
	v_sub_f32_e32 v168, v168, v147
	v_mul_f32_e32 v147, 0x3fb8aa3b, v151
	v_exp_f32_e32 v147, v147
	s_nop 0
	v_fma_f32 v147, v177, v147, v135
	v_cmp_gt_f32_e64 s[40:41], s97, v147
	s_nop 1
	v_cndmask_b32_e64 v194, 0, 32, s[40:41]
	v_ldexp_f32 v147, v147, v194
	v_log_f32_e32 v147, v147
	s_nop 0
	v_mul_f32_e32 v194, 0x3f317217, v147
	v_fma_f32 v194, v147, s52, -v194
	v_fmac_f32_e32 v194, 0x3377d1cf, v147
	v_fmac_f32_e32 v194, 0x3f317217, v147
	v_cmp_lt_f32_e64 s[42:43], |v147|, s53
	s_nop 1
	v_cndmask_b32_e64 v147, v147, v194, s[42:43]
	v_cndmask_b32_e64 v194, 0, v216, s[40:41]
	v_sub_f32_e32 v147, v147, v194
	v_cndmask_b32_e64 v147, v151, v147, s[8:9]
	v_mul_f32_e32 v151, 0x3fb8aa3b, v168
	v_exp_f32_e32 v151, v151
	s_nop 0
	v_fma_f32 v151, v167, v151, v131
	v_cmp_gt_f32_e64 s[40:41], s97, v151
	s_nop 1
	v_cndmask_b32_e64 v194, 0, 32, s[40:41]
	v_ldexp_f32 v151, v151, v194
	v_log_f32_e32 v151, v151
	s_nop 0
	v_mul_f32_e32 v194, 0x3f317217, v151
	v_fma_f32 v194, v151, s52, -v194
	v_fmac_f32_e32 v194, 0x3377d1cf, v151
	v_fmac_f32_e32 v194, 0x3f317217, v151
	v_cmp_lt_f32_e64 s[42:43], |v151|, s53
	s_nop 1
	v_cndmask_b32_e64 v151, v151, v194, s[42:43]
	v_cndmask_b32_e64 v194, 0, v216, s[40:41]
	v_sub_f32_e32 v151, v151, v194
	v_cndmask_b32_e32 v151, v168, v151, vcc
	global_store_dwordx4 v[170:171], v[144:147], off offset:512
	global_store_dwordx4 v[170:171], v[148:151], off offset:528
	s_nop 1
	v_add_u32_e32 v148, 0x90, v166
	v_ashrrev_i32_e32 v149, 31, v148
	v_lshlrev_b64 v[144:145], 6, v[148:149]
	v_lshl_add_u64 v[144:145], v[160:161], 0, v[144:145]
	s_nop 0
	s_waitcnt lgkmcnt(0)
	s_nop 0
	s_nop 0
	s_nop 0
	s_nop 0
	s_nop 0
	s_nop 0
	s_nop 0
	s_waitcnt lgkmcnt(0)
	s_nop 0
	s_nop 0
	s_waitcnt lgkmcnt(0)
;     __device__ __forceinline__ void operator()(const f32x4 (&acc)[2][2][4][2], const pg8::Unit& u, int wr, int wc, int fr, int fq) const {
;     ...
;             WIN_LOOP( _Pragma("unroll") for (int i = 0; i < 4; ++i) { const float s0 = fminf(a[i], 0.f) - __logf(1.f + __expf(-fabsf(a[i]))), s1 = fminf(b[i], 0.f) - __logf(1.f + __expf(-fabsf(b[i]))); const float la = l0[bj][i], lbv = l1[bj][i];
;                     a[i] = la > 0.f ? __logf(la + (1.f - la) * __expf(s0)) : s0; b[i] = lbv > 0.f ? __logf(lbv + (1.f - lbv) * __expf(s1)) : s1; }
;                 *(f32x4*)(LF + (size_t)row * 512 + c) = a; *(f32x4*)(LF + (size_t)row * 512 + c + 4) = b; __builtin_amdgcn_sched_barrier(0); ) }
	s_nop 0
	s_nop 0
	v_mov_b32_e32 v168, v240
	v_lshlrev_b64 v[144:145], 11, v[148:149]
	v_lshl_add_u64 v[170:171], s[50:51], 0, v[144:145]
	v_lshl_add_u64 v[170:171], v[170:171], 0, v[192:193]
	v_pk_mul_f32 v[148:149], v[20:21], v[168:169] op_sel_hi:[1,0]
	v_pk_mul_f32 v[144:145], v[16:17], v[168:169] op_sel_hi:[1,0]
	v_min_f32_e32 v194, 0, v148
	v_mul_f32_e64 v148, |v148|, s57
	v_exp_f32_e32 v148, v148
	v_pk_mul_f32 v[150:151], v[22:23], v[168:169] op_sel_hi:[1,0]
	v_pk_mul_f32 v[146:147], v[18:19], v[168:169] op_sel_hi:[1,0]
	v_add_f32_e32 v148, 1.0, v148
	v_cmp_gt_f32_e64 s[40:41], s97, v148
	s_nop 1
	v_cndmask_b32_e64 v195, 0, 32, s[40:41]
	v_ldexp_f32 v148, v148, v195
	v_log_f32_e32 v148, v148
	s_nop 0
	v_mul_f32_e32 v195, 0x3f317217, v148
	v_fma_f32 v195, v148, s52, -v195
	v_fmac_f32_e32 v195, 0x3377d1cf, v148
	v_fmac_f32_e32 v195, 0x3f317217, v148
	v_cmp_lt_f32_e64 s[42:43], |v148|, s53
	s_nop 1
	v_cndmask_b32_e64 v148, v148, v195, s[42:43]
	v_cndmask_b32_e64 v195, 0, v216, s[40:41]
	v_sub_f32_e32 v148, v148, v195
	v_sub_f32_e32 v148, v194, v148
	v_min_f32_e32 v194, 0, v144
	v_mul_f32_e64 v144, |v144|, s57
	v_exp_f32_e32 v144, v144
	s_nop 0
	v_add_f32_e32 v144, 1.0, v144
	v_cmp_gt_f32_e64 s[40:41], s97, v144
	s_nop 1
	v_cndmask_b32_e64 v195, 0, 32, s[40:41]
	v_ldexp_f32 v144, v144, v195
	v_log_f32_e32 v144, v144
	s_nop 0
	v_mul_f32_e32 v195, 0x3f317217, v144
	v_fma_f32 v195, v144, s52, -v195
	v_fmac_f32_e32 v195, 0x3377d1cf, v144
	v_fmac_f32_e32 v195, 0x3f317217, v144
	v_cmp_lt_f32_e64 s[42:43], |v144|, s53
	s_nop 1
	v_cndmask_b32_e64 v144, v144, v195, s[42:43]
	v_cndmask_b32_e64 v195, 0, v216, s[40:41]
	v_sub_f32_e32 v144, v144, v195
	v_sub_f32_e32 v194, v194, v144
	v_mul_f32_e32 v144, 0x3fb8aa3b, v148
	v_exp_f32_e32 v144, v144
	s_nop 0
	v_fma_f32 v144, v190, v144, v140
	v_cmp_gt_f32_e64 s[40:41], s97, v144
	s_nop 1
	v_cndmask_b32_e64 v195, 0, 32, s[40:41]
	v_ldexp_f32 v144, v144, v195
	v_log_f32_e32 v144, v144
	s_nop 0
	v_mul_f32_e32 v195, 0x3f317217, v144
	v_fma_f32 v195, v144, s52, -v195
	v_fmac_f32_e32 v195, 0x3377d1cf, v144
	v_fmac_f32_e32 v195, 0x3f317217, v144
	v_cmp_lt_f32_e64 s[42:43], |v144|, s53
	s_nop 1
	v_cndmask_b32_e64 v144, v144, v195, s[42:43]
	v_cndmask_b32_e64 v195, 0, v216, s[40:41]
	v_sub_f32_e32 v144, v144, v195
	v_cndmask_b32_e64 v144, v148, v144, s[38:39]
	v_mul_f32_e32 v148, 0x3fb8aa3b, v194
	v_exp_f32_e32 v148, v148
	s_nop 0
	v_fma_f32 v148, v191, v148, v136
	v_cmp_gt_f32_e64 s[40:41], s97, v148
	s_nop 1
	v_cndmask_b32_e64 v195, 0, 32, s[40:41]
	v_ldexp_f32 v148, v148, v195
	v_log_f32_e32 v148, v148
	s_nop 0
	v_mul_f32_e32 v195, 0x3f317217, v148
	v_fma_f32 v195, v148, s52, -v195
	v_fmac_f32_e32 v195, 0x3377d1cf, v148
	v_fmac_f32_e32 v195, 0x3f317217, v148
	v_cmp_lt_f32_e64 s[42:43], |v148|, s53
	s_nop 1
	v_cndmask_b32_e64 v148, v148, v195, s[42:43]
	v_cndmask_b32_e64 v195, 0, v216, s[40:41]
	v_sub_f32_e32 v148, v148, v195
	v_cndmask_b32_e64 v148, v194, v148, s[36:37]
	v_min_f32_e32 v194, 0, v149
	v_mul_f32_e64 v149, |v149|, s57
	v_exp_f32_e32 v149, v149
	s_nop 0
	v_add_f32_e32 v149, 1.0, v149
	v_cmp_gt_f32_e64 s[40:41], s97, v149
	s_nop 1
	v_cndmask_b32_e64 v195, 0, 32, s[40:41]
	v_ldexp_f32 v149, v149, v195
	v_log_f32_e32 v149, v149
	s_nop 0
	v_mul_f32_e32 v195, 0x3f317217, v149
	v_fma_f32 v195, v149, s52, -v195
	v_fmac_f32_e32 v195, 0x3377d1cf, v149
	v_fmac_f32_e32 v195, 0x3f317217, v149
	v_cmp_lt_f32_e64 s[42:43], |v149|, s53
	s_nop 1
	v_cndmask_b32_e64 v149, v149, v195, s[42:43]
	v_cndmask_b32_e64 v195, 0, v216, s[40:41]
	v_sub_f32_e32 v149, v149, v195
	v_sub_f32_e32 v149, v194, v149
	v_min_f32_e32 v194, 0, v145
	v_mul_f32_e64 v145, |v145|, s57
	v_exp_f32_e32 v145, v145
	s_nop 0
	v_add_f32_e32 v145, 1.0, v145
	v_cmp_gt_f32_e64 s[40:41], s97, v145
	s_nop 1
	v_cndmask_b32_e64 v195, 0, 32, s[40:41]
	v_ldexp_f32 v145, v145, v195
	v_log_f32_e32 v145, v145
	s_nop 0
	v_mul_f32_e32 v195, 0x3f317217, v145
	v_fma_f32 v195, v145, s52, -v195
	v_fmac_f32_e32 v195, 0x3377d1cf, v145
	v_fmac_f32_e32 v195, 0x3f317217, v145
	v_cmp_lt_f32_e64 s[42:43], |v145|, s53
	s_nop 1
	v_cndmask_b32_e64 v145, v145, v195, s[42:43]
	v_cndmask_b32_e64 v195, 0, v216, s[40:41]
	v_sub_f32_e32 v145, v145, v195
	v_sub_f32_e32 v194, v194, v145
	v_mul_f32_e32 v145, 0x3fb8aa3b, v149
	v_exp_f32_e32 v145, v145
	s_nop 0
	v_fma_f32 v145, v188, v145, v141
	v_cmp_gt_f32_e64 s[40:41], s97, v145
	s_nop 1
	v_cndmask_b32_e64 v195, 0, 32, s[40:41]
	v_ldexp_f32 v145, v145, v195
	v_log_f32_e32 v145, v145
	s_nop 0
	v_mul_f32_e32 v195, 0x3f317217, v145
	v_fma_f32 v195, v145, s52, -v195
	v_fmac_f32_e32 v195, 0x3377d1cf, v145
	v_fmac_f32_e32 v195, 0x3f317217, v145
	v_cmp_lt_f32_e64 s[42:43], |v145|, s53
	s_nop 1
	v_cndmask_b32_e64 v145, v145, v195, s[42:43]
	v_cndmask_b32_e64 v195, 0, v216, s[40:41]
	v_sub_f32_e32 v145, v145, v195
	v_cndmask_b32_e64 v145, v149, v145, s[34:35]
	v_mul_f32_e32 v149, 0x3fb8aa3b, v194
	v_exp_f32_e32 v149, v149
	s_nop 0
	v_fma_f32 v149, v189, v149, v137
	v_cmp_gt_f32_e64 s[40:41], s97, v149
	s_nop 1
	v_cndmask_b32_e64 v195, 0, 32, s[40:41]
	v_ldexp_f32 v149, v149, v195
	v_log_f32_e32 v149, v149
	s_nop 0
	v_mul_f32_e32 v195, 0x3f317217, v149
	v_fma_f32 v195, v149, s52, -v195
	v_fmac_f32_e32 v195, 0x3377d1cf, v149
	v_fmac_f32_e32 v195, 0x3f317217, v149
	v_cmp_lt_f32_e64 s[42:43], |v149|, s53
	s_nop 1
	v_cndmask_b32_e64 v149, v149, v195, s[42:43]
	v_cndmask_b32_e64 v195, 0, v216, s[40:41]
	v_sub_f32_e32 v149, v149, v195
	v_cndmask_b32_e64 v149, v194, v149, s[30:31]
	v_min_f32_e32 v194, 0, v150
	v_mul_f32_e64 v150, |v150|, s57
	v_exp_f32_e32 v150, v150
	s_nop 0
	v_add_f32_e32 v150, 1.0, v150
	v_cmp_gt_f32_e64 s[40:41], s97, v150
;     __device__ __forceinline__ void operator()(const f32x4 (&acc)[2][2][4][2], const pg8::Unit& u, int wr, int wc, int fr, int fq) const {
;     ...
;             WIN_LOOP( _Pragma("unroll") for (int i = 0; i < 4; ++i) { const float s0 = fminf(a[i], 0.f) - __logf(1.f + __expf(-fabsf(a[i]))), s1 = fminf(b[i], 0.f) - __logf(1.f + __expf(-fabsf(b[i]))); const float la = l0[bj][i], lbv = l1[bj][i];
;                     a[i] = la > 0.f ? __logf(la + (1.f - la) * __expf(s0)) : s0; b[i] = lbv > 0.f ? __logf(lbv + (1.f - lbv) * __expf(s1)) : s1; }
;                 *(f32x4*)(LF + (size_t)row * 512 + c) = a; *(f32x4*)(LF + (size_t)row * 512 + c + 4) = b; __builtin_amdgcn_sched_barrier(0); ) }
	s_nop 1
	v_cndmask_b32_e64 v195, 0, 32, s[40:41]
	v_ldexp_f32 v150, v150, v195
	v_log_f32_e32 v150, v150
	s_nop 0
	v_mul_f32_e32 v195, 0x3f317217, v150
	v_fma_f32 v195, v150, s52, -v195
	v_fmac_f32_e32 v195, 0x3377d1cf, v150
	v_fmac_f32_e32 v195, 0x3f317217, v150
	v_cmp_lt_f32_e64 s[42:43], |v150|, s53
	s_nop 1
	v_cndmask_b32_e64 v150, v150, v195, s[42:43]
	v_cndmask_b32_e64 v195, 0, v216, s[40:41]
	v_sub_f32_e32 v150, v150, v195
	v_sub_f32_e32 v150, v194, v150
	v_min_f32_e32 v194, 0, v146
	v_mul_f32_e64 v146, |v146|, s57
	v_exp_f32_e32 v146, v146
	s_nop 0
	v_add_f32_e32 v146, 1.0, v146
	v_cmp_gt_f32_e64 s[40:41], s97, v146
	s_nop 1
	v_cndmask_b32_e64 v195, 0, 32, s[40:41]
	v_ldexp_f32 v146, v146, v195
	v_log_f32_e32 v146, v146
	s_nop 0
	v_mul_f32_e32 v195, 0x3f317217, v146
	v_fma_f32 v195, v146, s52, -v195
	v_fmac_f32_e32 v195, 0x3377d1cf, v146
	v_fmac_f32_e32 v195, 0x3f317217, v146
	v_cmp_lt_f32_e64 s[42:43], |v146|, s53
	s_nop 1
	v_cndmask_b32_e64 v146, v146, v195, s[42:43]
	v_cndmask_b32_e64 v195, 0, v216, s[40:41]
	v_sub_f32_e32 v146, v146, v195
	v_sub_f32_e32 v194, v194, v146
	v_mul_f32_e32 v146, 0x3fb8aa3b, v150
	v_exp_f32_e32 v146, v146
	s_nop 0
	v_fma_f32 v146, v187, v146, v142
	v_cmp_gt_f32_e64 s[40:41], s97, v146
	s_nop 1
	v_cndmask_b32_e64 v195, 0, 32, s[40:41]
	v_ldexp_f32 v146, v146, v195
	v_log_f32_e32 v146, v146
	s_nop 0
	v_mul_f32_e32 v195, 0x3f317217, v146
	v_fma_f32 v195, v146, s52, -v195
	v_fmac_f32_e32 v195, 0x3377d1cf, v146
	v_fmac_f32_e32 v195, 0x3f317217, v146
	v_cmp_lt_f32_e64 s[42:43], |v146|, s53
	s_nop 1
	v_cndmask_b32_e64 v146, v146, v195, s[42:43]
	v_cndmask_b32_e64 v195, 0, v216, s[40:41]
	v_sub_f32_e32 v146, v146, v195
	v_cndmask_b32_e64 v146, v150, v146, s[28:29]
	v_mul_f32_e32 v150, 0x3fb8aa3b, v194
	v_exp_f32_e32 v150, v150
	s_nop 0
	v_fma_f32 v150, v186, v150, v138
	v_cmp_gt_f32_e64 s[40:41], s97, v150
	s_nop 1
	v_cndmask_b32_e64 v195, 0, 32, s[40:41]
	v_ldexp_f32 v150, v150, v195
	v_log_f32_e32 v150, v150
	s_nop 0
	v_mul_f32_e32 v195, 0x3f317217, v150
	v_fma_f32 v195, v150, s52, -v195
	v_fmac_f32_e32 v195, 0x3377d1cf, v150
	v_fmac_f32_e32 v195, 0x3f317217, v150
	v_cmp_lt_f32_e64 s[42:43], |v150|, s53
	s_nop 1
	v_cndmask_b32_e64 v150, v150, v195, s[42:43]
	v_cndmask_b32_e64 v195, 0, v216, s[40:41]
	v_sub_f32_e32 v150, v150, v195
	v_cndmask_b32_e64 v150, v194, v150, s[26:27]
	v_min_f32_e32 v194, 0, v151
	v_mul_f32_e64 v151, |v151|, s57
	v_exp_f32_e32 v151, v151
	s_nop 0
	v_add_f32_e32 v151, 1.0, v151
	v_cmp_gt_f32_e64 s[40:41], s97, v151
	s_nop 1
	v_cndmask_b32_e64 v195, 0, 32, s[40:41]
	v_ldexp_f32 v151, v151, v195
	v_log_f32_e32 v151, v151
	s_nop 0
	v_mul_f32_e32 v195, 0x3f317217, v151
	v_fma_f32 v195, v151, s52, -v195
	v_fmac_f32_e32 v195, 0x3377d1cf, v151
	v_fmac_f32_e32 v195, 0x3f317217, v151
	v_cmp_lt_f32_e64 s[42:43], |v151|, s53
	s_nop 1
	v_cndmask_b32_e64 v151, v151, v195, s[42:43]
	v_cndmask_b32_e64 v195, 0, v216, s[40:41]
	v_sub_f32_e32 v151, v151, v195
	v_sub_f32_e32 v151, v194, v151
	v_min_f32_e32 v194, 0, v147
	v_mul_f32_e64 v147, |v147|, s57
	v_exp_f32_e32 v147, v147
	s_nop 0
	v_add_f32_e32 v147, 1.0, v147
	v_cmp_gt_f32_e64 s[40:41], s97, v147
	s_nop 1
	v_cndmask_b32_e64 v195, 0, 32, s[40:41]
	v_ldexp_f32 v147, v147, v195
	v_log_f32_e32 v147, v147
	s_nop 0
	v_mul_f32_e32 v195, 0x3f317217, v147
	v_fma_f32 v195, v147, s52, -v195
	v_fmac_f32_e32 v195, 0x3377d1cf, v147
	v_fmac_f32_e32 v195, 0x3f317217, v147
	v_cmp_lt_f32_e64 s[42:43], |v147|, s53
	s_nop 1
	v_cndmask_b32_e64 v147, v147, v195, s[42:43]
	v_cndmask_b32_e64 v195, 0, v216, s[40:41]
	v_sub_f32_e32 v147, v147, v195
	v_sub_f32_e32 v194, v194, v147
	v_mul_f32_e32 v147, 0x3fb8aa3b, v151
	v_exp_f32_e32 v147, v147
	s_nop 0
	v_fma_f32 v147, v185, v147, v143
	v_cmp_gt_f32_e64 s[40:41], s97, v147
	s_nop 1
	v_cndmask_b32_e64 v195, 0, 32, s[40:41]
	v_ldexp_f32 v147, v147, v195
	v_log_f32_e32 v147, v147
	s_nop 0
	v_mul_f32_e32 v195, 0x3f317217, v147
	v_fma_f32 v195, v147, s52, -v195
	v_fmac_f32_e32 v195, 0x3377d1cf, v147
	v_fmac_f32_e32 v195, 0x3f317217, v147
	v_cmp_lt_f32_e64 s[42:43], |v147|, s53
	s_nop 1
	v_cndmask_b32_e64 v147, v147, v195, s[42:43]
	v_cndmask_b32_e64 v195, 0, v216, s[40:41]
	v_sub_f32_e32 v147, v147, v195
	v_cndmask_b32_e64 v147, v151, v147, s[24:25]
	v_mul_f32_e32 v151, 0x3fb8aa3b, v194
	v_exp_f32_e32 v151, v151
	s_nop 0
	v_fma_f32 v151, v184, v151, v139
	v_cmp_gt_f32_e64 s[40:41], s97, v151
	s_nop 1
	v_cndmask_b32_e64 v195, 0, 32, s[40:41]
	v_ldexp_f32 v151, v151, v195
	v_log_f32_e32 v151, v151
	s_nop 0
	v_mul_f32_e32 v195, 0x3f317217, v151
	v_fma_f32 v195, v151, s52, -v195
	v_fmac_f32_e32 v195, 0x3377d1cf, v151
	v_fmac_f32_e32 v195, 0x3f317217, v151
	v_cmp_lt_f32_e64 s[42:43], |v151|, s53
	s_nop 1
	v_cndmask_b32_e64 v151, v151, v195, s[42:43]
	v_cndmask_b32_e64 v195, 0, v216, s[40:41]
	v_sub_f32_e32 v151, v151, v195
	v_cndmask_b32_e64 v151, v194, v151, s[22:23]
	global_store_dwordx4 v[170:171], v[144:147], off
	global_store_dwordx4 v[170:171], v[148:151], off offset:16
	s_nop 1
	v_pk_mul_f32 v[148:149], v[84:85], v[168:169] op_sel_hi:[1,0]
	v_pk_mul_f32 v[150:151], v[86:87], v[168:169] op_sel_hi:[1,0]
	v_pk_mul_f32 v[146:147], v[82:83], v[168:169] op_sel_hi:[1,0]
	v_pk_mul_f32 v[144:145], v[80:81], v[168:169] op_sel_hi:[1,0]
	v_min_f32_e32 v168, 0, v148
	v_mul_f32_e64 v148, |v148|, s57
	v_exp_f32_e32 v148, v148
	s_nop 0
	v_add_f32_e32 v148, 1.0, v148
	v_cmp_gt_f32_e64 s[40:41], s97, v148
	s_nop 1
	v_cndmask_b32_e64 v194, 0, 32, s[40:41]
	v_ldexp_f32 v148, v148, v194
	v_log_f32_e32 v148, v148
	s_nop 0
	v_mul_f32_e32 v194, 0x3f317217, v148
	v_fma_f32 v194, v148, s52, -v194
	v_fmac_f32_e32 v194, 0x3377d1cf, v148
;     __device__ __forceinline__ void operator()(const f32x4 (&acc)[2][2][4][2], const pg8::Unit& u, int wr, int wc, int fr, int fq) const {
;     ...
;             WIN_LOOP( _Pragma("unroll") for (int i = 0; i < 4; ++i) { const float s0 = fminf(a[i], 0.f) - __logf(1.f + __expf(-fabsf(a[i]))), s1 = fminf(b[i], 0.f) - __logf(1.f + __expf(-fabsf(b[i]))); const float la = l0[bj][i], lbv = l1[bj][i];
;                     a[i] = la > 0.f ? __logf(la + (1.f - la) * __expf(s0)) : s0; b[i] = lbv > 0.f ? __logf(lbv + (1.f - lbv) * __expf(s1)) : s1; }
;                 *(f32x4*)(LF + (size_t)row * 512 + c) = a; *(f32x4*)(LF + (size_t)row * 512 + c + 4) = b; __builtin_amdgcn_sched_barrier(0); ) }
	v_fmac_f32_e32 v194, 0x3f317217, v148
	v_cmp_lt_f32_e64 s[42:43], |v148|, s53
	s_nop 1
	v_cndmask_b32_e64 v148, v148, v194, s[42:43]
	v_cndmask_b32_e64 v194, 0, v216, s[40:41]
	v_sub_f32_e32 v148, v148, v194
	v_sub_f32_e32 v148, v168, v148
	v_min_f32_e32 v168, 0, v144
	v_mul_f32_e64 v144, |v144|, s57
	v_exp_f32_e32 v144, v144
	s_nop 0
	v_add_f32_e32 v144, 1.0, v144
	v_cmp_gt_f32_e64 s[40:41], s97, v144
	s_nop 1
	v_cndmask_b32_e64 v194, 0, 32, s[40:41]
	v_ldexp_f32 v144, v144, v194
	v_log_f32_e32 v144, v144
	s_nop 0
	v_mul_f32_e32 v194, 0x3f317217, v144
	v_fma_f32 v194, v144, s52, -v194
	v_fmac_f32_e32 v194, 0x3377d1cf, v144
	v_fmac_f32_e32 v194, 0x3f317217, v144
	v_cmp_lt_f32_e64 s[42:43], |v144|, s53
	s_nop 1
	v_cndmask_b32_e64 v144, v144, v194, s[42:43]
	v_cndmask_b32_e64 v194, 0, v216, s[40:41]
	v_sub_f32_e32 v144, v144, v194
	v_sub_f32_e32 v168, v168, v144
	v_mul_f32_e32 v144, 0x3fb8aa3b, v148
	v_exp_f32_e32 v144, v144
	s_nop 0
	v_fma_f32 v144, v183, v144, v132
	v_cmp_gt_f32_e64 s[40:41], s97, v144
	s_nop 1
	v_cndmask_b32_e64 v194, 0, 32, s[40:41]
	v_ldexp_f32 v144, v144, v194
	v_log_f32_e32 v144, v144
	s_nop 0
	v_mul_f32_e32 v194, 0x3f317217, v144
	v_fma_f32 v194, v144, s52, -v194
	v_fmac_f32_e32 v194, 0x3377d1cf, v144
	v_fmac_f32_e32 v194, 0x3f317217, v144
	v_cmp_lt_f32_e64 s[42:43], |v144|, s53
	s_nop 1
	v_cndmask_b32_e64 v144, v144, v194, s[42:43]
	v_cndmask_b32_e64 v194, 0, v216, s[40:41]
	v_sub_f32_e32 v144, v144, v194
	v_cndmask_b32_e64 v144, v148, v144, s[20:21]
	v_mul_f32_e32 v148, 0x3fb8aa3b, v168
	v_exp_f32_e32 v148, v148
	s_nop 0
	v_fma_f32 v148, v182, v148, v128
	v_cmp_gt_f32_e64 s[40:41], s97, v148
	s_nop 1
	v_cndmask_b32_e64 v194, 0, 32, s[40:41]
	v_ldexp_f32 v148, v148, v194
	v_log_f32_e32 v148, v148
	s_nop 0
	v_mul_f32_e32 v194, 0x3f317217, v148
	v_fma_f32 v194, v148, s52, -v194
	v_fmac_f32_e32 v194, 0x3377d1cf, v148
	v_fmac_f32_e32 v194, 0x3f317217, v148
	v_cmp_lt_f32_e64 s[42:43], |v148|, s53
	s_nop 1
	v_cndmask_b32_e64 v148, v148, v194, s[42:43]
	v_cndmask_b32_e64 v194, 0, v216, s[40:41]
	v_sub_f32_e32 v148, v148, v194
	v_cndmask_b32_e64 v148, v168, v148, s[18:19]
	v_min_f32_e32 v168, 0, v149
	v_mul_f32_e64 v149, |v149|, s57
	v_exp_f32_e32 v149, v149
	s_nop 0
	v_add_f32_e32 v149, 1.0, v149
	v_cmp_gt_f32_e64 s[40:41], s97, v149
	s_nop 1
	v_cndmask_b32_e64 v194, 0, 32, s[40:41]
	v_ldexp_f32 v149, v149, v194
	v_log_f32_e32 v149, v149
	s_nop 0
	v_mul_f32_e32 v194, 0x3f317217, v149
	v_fma_f32 v194, v149, s52, -v194
	v_fmac_f32_e32 v194, 0x3377d1cf, v149
	v_fmac_f32_e32 v194, 0x3f317217, v149
	v_cmp_lt_f32_e64 s[42:43], |v149|, s53
	s_nop 1
	v_cndmask_b32_e64 v149, v149, v194, s[42:43]
	v_cndmask_b32_e64 v194, 0, v216, s[40:41]
	v_sub_f32_e32 v149, v149, v194
	v_sub_f32_e32 v149, v168, v149
	v_min_f32_e32 v168, 0, v145
	v_mul_f32_e64 v145, |v145|, s57
	v_exp_f32_e32 v145, v145
	s_nop 0
	v_add_f32_e32 v145, 1.0, v145
	v_cmp_gt_f32_e64 s[40:41], s97, v145
	s_nop 1
	v_cndmask_b32_e64 v194, 0, 32, s[40:41]
	v_ldexp_f32 v145, v145, v194
	v_log_f32_e32 v145, v145
	s_nop 0
	v_mul_f32_e32 v194, 0x3f317217, v145
	v_fma_f32 v194, v145, s52, -v194
	v_fmac_f32_e32 v194, 0x3377d1cf, v145
	v_fmac_f32_e32 v194, 0x3f317217, v145
	v_cmp_lt_f32_e64 s[42:43], |v145|, s53
	s_nop 1
	v_cndmask_b32_e64 v145, v145, v194, s[42:43]
	v_cndmask_b32_e64 v194, 0, v216, s[40:41]
	v_sub_f32_e32 v145, v145, v194
	v_sub_f32_e32 v168, v168, v145
	v_mul_f32_e32 v145, 0x3fb8aa3b, v149
	v_exp_f32_e32 v145, v145
	s_nop 0
	v_fma_f32 v145, v181, v145, v133
	v_cmp_gt_f32_e64 s[40:41], s97, v145
	s_nop 1
	v_cndmask_b32_e64 v194, 0, 32, s[40:41]
	v_ldexp_f32 v145, v145, v194
	v_log_f32_e32 v145, v145
	s_nop 0
	v_mul_f32_e32 v194, 0x3f317217, v145
	v_fma_f32 v194, v145, s52, -v194
	v_fmac_f32_e32 v194, 0x3377d1cf, v145
	v_fmac_f32_e32 v194, 0x3f317217, v145
	v_cmp_lt_f32_e64 s[42:43], |v145|, s53
	s_nop 1
	v_cndmask_b32_e64 v145, v145, v194, s[42:43]
	v_cndmask_b32_e64 v194, 0, v216, s[40:41]
	v_sub_f32_e32 v145, v145, v194
	v_cndmask_b32_e64 v145, v149, v145, s[16:17]
	v_mul_f32_e32 v149, 0x3fb8aa3b, v168
	v_exp_f32_e32 v149, v149
	s_nop 0
	v_fma_f32 v149, v180, v149, v129
	v_cmp_gt_f32_e64 s[40:41], s97, v149
	s_nop 1
	v_cndmask_b32_e64 v194, 0, 32, s[40:41]
	v_ldexp_f32 v149, v149, v194
	v_log_f32_e32 v149, v149
	s_nop 0
	v_mul_f32_e32 v194, 0x3f317217, v149
	v_fma_f32 v194, v149, s52, -v194
	v_fmac_f32_e32 v194, 0x3377d1cf, v149
	v_fmac_f32_e32 v194, 0x3f317217, v149
	v_cmp_lt_f32_e64 s[42:43], |v149|, s53
	s_nop 1
	v_cndmask_b32_e64 v149, v149, v194, s[42:43]
	v_cndmask_b32_e64 v194, 0, v216, s[40:41]
	v_sub_f32_e32 v149, v149, v194
	v_cndmask_b32_e64 v149, v168, v149, s[14:15]
	v_min_f32_e32 v168, 0, v150
	v_mul_f32_e64 v150, |v150|, s57
	v_exp_f32_e32 v150, v150
	s_nop 0
	v_add_f32_e32 v150, 1.0, v150
	v_cmp_gt_f32_e64 s[40:41], s97, v150
	s_nop 1
	v_cndmask_b32_e64 v194, 0, 32, s[40:41]
	v_ldexp_f32 v150, v150, v194
	v_log_f32_e32 v150, v150
	s_nop 0
	v_mul_f32_e32 v194, 0x3f317217, v150
	v_fma_f32 v194, v150, s52, -v194
	v_fmac_f32_e32 v194, 0x3377d1cf, v150
	v_fmac_f32_e32 v194, 0x3f317217, v150
	v_cmp_lt_f32_e64 s[42:43], |v150|, s53
	s_nop 1
	v_cndmask_b32_e64 v150, v150, v194, s[42:43]
	v_cndmask_b32_e64 v194, 0, v216, s[40:41]
	v_sub_f32_e32 v150, v150, v194
	v_sub_f32_e32 v150, v168, v150
	v_min_f32_e32 v168, 0, v146
	v_mul_f32_e64 v146, |v146|, s57
	v_exp_f32_e32 v146, v146
	s_nop 0
	v_add_f32_e32 v146, 1.0, v146
	v_cmp_gt_f32_e64 s[40:41], s97, v146
	s_nop 1
	v_cndmask_b32_e64 v194, 0, 32, s[40:41]
	v_ldexp_f32 v146, v146, v194
	v_log_f32_e32 v146, v146
	s_nop 0
	v_mul_f32_e32 v194, 0x3f317217, v146
	v_fma_f32 v194, v146, s52, -v194
; __device__ __forceinline__ float row_rstd(const float* ssq, int row, int fq) {
;     const f32x4 v = *(const f32x4*)(ssq + (size_t)row * 16 + fq * 4);
;     float s = (v[0] + v[1]) + (v[2] + v[3]);
;     s += __shfl_xor(s, 16); s += __shfl_xor(s, 32);
;     return __builtin_amdgcn_rsqf(s * (1.f / DM) + EPS);
; }
;     __device__ __forceinline__ void operator()(const f32x4 (&acc)[2][2][4][2], const pg8::Unit& u, int wr, int wc, int fr, int fq) const {
;     ...
;             WIN_LOOP( _Pragma("unroll") for (int i = 0; i < 4; ++i) { const float s0 = fminf(a[i], 0.f) - __logf(1.f + __expf(-fabsf(a[i]))), s1 = fminf(b[i], 0.f) - __logf(1.f + __expf(-fabsf(b[i]))); const float la = l0[bj][i], lbv = l1[bj][i];
;                     a[i] = la > 0.f ? __logf(la + (1.f - la) * __expf(s0)) : s0; b[i] = lbv > 0.f ? __logf(lbv + (1.f - lbv) * __expf(s1)) : s1; }
;                 *(f32x4*)(LF + (size_t)row * 512 + c) = a; *(f32x4*)(LF + (size_t)row * 512 + c + 4) = b; __builtin_amdgcn_sched_barrier(0); ) }
	v_fmac_f32_e32 v194, 0x3377d1cf, v146
	v_fmac_f32_e32 v194, 0x3f317217, v146
	v_cmp_lt_f32_e64 s[42:43], |v146|, s53
	s_nop 1
	v_cndmask_b32_e64 v146, v146, v194, s[42:43]
	v_cndmask_b32_e64 v194, 0, v216, s[40:41]
	v_sub_f32_e32 v146, v146, v194
	v_sub_f32_e32 v168, v168, v146
	v_mul_f32_e32 v146, 0x3fb8aa3b, v150
	v_exp_f32_e32 v146, v146
	s_nop 0
	v_fma_f32 v146, v179, v146, v134
	v_cmp_gt_f32_e64 s[40:41], s97, v146
	s_nop 1
	v_cndmask_b32_e64 v194, 0, 32, s[40:41]
	v_ldexp_f32 v146, v146, v194
	v_log_f32_e32 v146, v146
	s_nop 0
	v_mul_f32_e32 v194, 0x3f317217, v146
	v_fma_f32 v194, v146, s52, -v194
	v_fmac_f32_e32 v194, 0x3377d1cf, v146
	v_fmac_f32_e32 v194, 0x3f317217, v146
	v_cmp_lt_f32_e64 s[42:43], |v146|, s53
	s_nop 1
	v_cndmask_b32_e64 v146, v146, v194, s[42:43]
	v_cndmask_b32_e64 v194, 0, v216, s[40:41]
	v_sub_f32_e32 v146, v146, v194
	v_cndmask_b32_e64 v146, v150, v146, s[12:13]
	v_mul_f32_e32 v150, 0x3fb8aa3b, v168
	v_exp_f32_e32 v150, v150
	s_nop 0
	v_fma_f32 v150, v178, v150, v130
	v_cmp_gt_f32_e64 s[40:41], s97, v150
	s_nop 1
	v_cndmask_b32_e64 v194, 0, 32, s[40:41]
	v_ldexp_f32 v150, v150, v194
	v_log_f32_e32 v150, v150
	s_nop 0
	v_mul_f32_e32 v194, 0x3f317217, v150
	v_fma_f32 v194, v150, s52, -v194
	v_fmac_f32_e32 v194, 0x3377d1cf, v150
	v_fmac_f32_e32 v194, 0x3f317217, v150
	v_cmp_lt_f32_e64 s[42:43], |v150|, s53
	s_nop 1
	v_cndmask_b32_e64 v150, v150, v194, s[42:43]
	v_cndmask_b32_e64 v194, 0, v216, s[40:41]
	v_sub_f32_e32 v150, v150, v194
	v_cndmask_b32_e64 v150, v168, v150, s[10:11]
	v_min_f32_e32 v168, 0, v151
	v_mul_f32_e64 v151, |v151|, s57
	v_exp_f32_e32 v151, v151
	s_nop 0
	v_add_f32_e32 v151, 1.0, v151
	v_cmp_gt_f32_e64 s[40:41], s97, v151
	s_nop 1
	v_cndmask_b32_e64 v194, 0, 32, s[40:41]
	v_ldexp_f32 v151, v151, v194
	v_log_f32_e32 v151, v151
	s_nop 0
	v_mul_f32_e32 v194, 0x3f317217, v151
	v_fma_f32 v194, v151, s52, -v194
	v_fmac_f32_e32 v194, 0x3377d1cf, v151
	v_fmac_f32_e32 v194, 0x3f317217, v151
	v_cmp_lt_f32_e64 s[42:43], |v151|, s53
	s_nop 1
	v_cndmask_b32_e64 v151, v151, v194, s[42:43]
	v_cndmask_b32_e64 v194, 0, v216, s[40:41]
	v_sub_f32_e32 v151, v151, v194
	v_sub_f32_e32 v151, v168, v151
	v_min_f32_e32 v168, 0, v147
	v_mul_f32_e64 v147, |v147|, s57
	v_exp_f32_e32 v147, v147
	s_nop 0
	v_add_f32_e32 v147, 1.0, v147
	v_cmp_gt_f32_e64 s[40:41], s97, v147
	s_nop 1
	v_cndmask_b32_e64 v194, 0, 32, s[40:41]
	v_ldexp_f32 v147, v147, v194
	v_log_f32_e32 v147, v147
	s_nop 0
	v_mul_f32_e32 v194, 0x3f317217, v147
	v_fma_f32 v194, v147, s52, -v194
	v_fmac_f32_e32 v194, 0x3377d1cf, v147
	v_fmac_f32_e32 v194, 0x3f317217, v147
	v_cmp_lt_f32_e64 s[42:43], |v147|, s53
	s_nop 1
	v_cndmask_b32_e64 v147, v147, v194, s[42:43]
	v_cndmask_b32_e64 v194, 0, v216, s[40:41]
	v_sub_f32_e32 v147, v147, v194
	v_sub_f32_e32 v168, v168, v147
	v_mul_f32_e32 v147, 0x3fb8aa3b, v151
	v_exp_f32_e32 v147, v147
	s_nop 0
	v_fma_f32 v147, v177, v147, v135
	v_cmp_gt_f32_e64 s[40:41], s97, v147
	s_nop 1
	v_cndmask_b32_e64 v194, 0, 32, s[40:41]
	v_ldexp_f32 v147, v147, v194
	v_log_f32_e32 v147, v147
	s_nop 0
	v_mul_f32_e32 v194, 0x3f317217, v147
	v_fma_f32 v194, v147, s52, -v194
	v_fmac_f32_e32 v194, 0x3377d1cf, v147
	v_fmac_f32_e32 v194, 0x3f317217, v147
	v_cmp_lt_f32_e64 s[42:43], |v147|, s53
	s_nop 1
	v_cndmask_b32_e64 v147, v147, v194, s[42:43]
	v_cndmask_b32_e64 v194, 0, v216, s[40:41]
	v_sub_f32_e32 v147, v147, v194
	v_cndmask_b32_e64 v147, v151, v147, s[8:9]
	v_mul_f32_e32 v151, 0x3fb8aa3b, v168
	v_exp_f32_e32 v151, v151
	s_nop 0
	v_fma_f32 v151, v167, v151, v131
	v_cmp_gt_f32_e64 s[40:41], s97, v151
	s_nop 1
	v_cndmask_b32_e64 v194, 0, 32, s[40:41]
	v_ldexp_f32 v151, v151, v194
	v_log_f32_e32 v151, v151
	s_nop 0
	v_mul_f32_e32 v194, 0x3f317217, v151
	v_fma_f32 v194, v151, s52, -v194
	v_fmac_f32_e32 v194, 0x3377d1cf, v151
	v_fmac_f32_e32 v194, 0x3f317217, v151
	v_cmp_lt_f32_e64 s[42:43], |v151|, s53
	s_nop 1
	v_cndmask_b32_e64 v151, v151, v194, s[42:43]
	v_cndmask_b32_e64 v194, 0, v216, s[40:41]
	v_sub_f32_e32 v151, v151, v194
	v_cndmask_b32_e32 v151, v168, v151, vcc
	global_store_dwordx4 v[170:171], v[144:147], off offset:512
	global_store_dwordx4 v[170:171], v[148:151], off offset:528
	s_nop 1
	v_add_u32_e32 v148, 0xa0, v166
	v_ashrrev_i32_e32 v149, 31, v148
	v_lshlrev_b64 v[144:145], 6, v[148:149]
	v_lshl_add_u64 v[144:145], v[160:161], 0, v[144:145]
	s_nop 0
	s_waitcnt lgkmcnt(0)
	s_nop 0
	s_nop 0
	s_nop 0
	s_nop 0
	s_nop 0
	s_nop 0
	s_nop 0
	s_waitcnt lgkmcnt(0)
	s_nop 0
	s_nop 0
	s_waitcnt lgkmcnt(0)
;     __device__ __forceinline__ void operator()(const f32x4 (&acc)[2][2][4][2], const pg8::Unit& u, int wr, int wc, int fr, int fq) const {
;     ...
;             WIN_LOOP( _Pragma("unroll") for (int i = 0; i < 4; ++i) { const float s0 = fminf(a[i], 0.f) - __logf(1.f + __expf(-fabsf(a[i]))), s1 = fminf(b[i], 0.f) - __logf(1.f + __expf(-fabsf(b[i]))); const float la = l0[bj][i], lbv = l1[bj][i];
;                     a[i] = la > 0.f ? __logf(la + (1.f - la) * __expf(s0)) : s0; b[i] = lbv > 0.f ? __logf(lbv + (1.f - lbv) * __expf(s1)) : s1; }
;                 *(f32x4*)(LF + (size_t)row * 512 + c) = a; *(f32x4*)(LF + (size_t)row * 512 + c + 4) = b; __builtin_amdgcn_sched_barrier(0); ) }
	s_nop 0
	s_nop 0
	v_mov_b32_e32 v168, v241
	v_lshlrev_b64 v[144:145], 11, v[148:149]
	v_lshl_add_u64 v[170:171], s[50:51], 0, v[144:145]
	v_lshl_add_u64 v[170:171], v[170:171], 0, v[192:193]
	v_pk_mul_f32 v[148:149], v[12:13], v[168:169] op_sel_hi:[1,0]
	v_pk_mul_f32 v[144:145], v[8:9], v[168:169] op_sel_hi:[1,0]
	v_min_f32_e32 v194, 0, v148
	v_mul_f32_e64 v148, |v148|, s57
	v_exp_f32_e32 v148, v148
	v_pk_mul_f32 v[150:151], v[14:15], v[168:169] op_sel_hi:[1,0]
	v_pk_mul_f32 v[146:147], v[10:11], v[168:169] op_sel_hi:[1,0]
	v_add_f32_e32 v148, 1.0, v148
	v_cmp_gt_f32_e64 s[40:41], s97, v148
	s_nop 1
	v_cndmask_b32_e64 v195, 0, 32, s[40:41]
	v_ldexp_f32 v148, v148, v195
	v_log_f32_e32 v148, v148
	s_nop 0
	v_mul_f32_e32 v195, 0x3f317217, v148
	v_fma_f32 v195, v148, s52, -v195
	v_fmac_f32_e32 v195, 0x3377d1cf, v148
	v_fmac_f32_e32 v195, 0x3f317217, v148
	v_cmp_lt_f32_e64 s[42:43], |v148|, s53
	s_nop 1
	v_cndmask_b32_e64 v148, v148, v195, s[42:43]
	v_cndmask_b32_e64 v195, 0, v216, s[40:41]
	v_sub_f32_e32 v148, v148, v195
	v_sub_f32_e32 v148, v194, v148
	v_min_f32_e32 v194, 0, v144
	v_mul_f32_e64 v144, |v144|, s57
	v_exp_f32_e32 v144, v144
	s_nop 0
	v_add_f32_e32 v144, 1.0, v144
	v_cmp_gt_f32_e64 s[40:41], s97, v144
	s_nop 1
	v_cndmask_b32_e64 v195, 0, 32, s[40:41]
	v_ldexp_f32 v144, v144, v195
	v_log_f32_e32 v144, v144
	s_nop 0
	v_mul_f32_e32 v195, 0x3f317217, v144
	v_fma_f32 v195, v144, s52, -v195
	v_fmac_f32_e32 v195, 0x3377d1cf, v144
	v_fmac_f32_e32 v195, 0x3f317217, v144
	v_cmp_lt_f32_e64 s[42:43], |v144|, s53
	s_nop 1
	v_cndmask_b32_e64 v144, v144, v195, s[42:43]
	v_cndmask_b32_e64 v195, 0, v216, s[40:41]
	v_sub_f32_e32 v144, v144, v195
	v_sub_f32_e32 v194, v194, v144
	v_mul_f32_e32 v144, 0x3fb8aa3b, v148
	v_exp_f32_e32 v144, v144
	s_nop 0
	v_fma_f32 v144, v190, v144, v140
	v_cmp_gt_f32_e64 s[40:41], s97, v144
	s_nop 1
	v_cndmask_b32_e64 v195, 0, 32, s[40:41]
	v_ldexp_f32 v144, v144, v195
	v_log_f32_e32 v144, v144
	s_nop 0
	v_mul_f32_e32 v195, 0x3f317217, v144
	v_fma_f32 v195, v144, s52, -v195
	v_fmac_f32_e32 v195, 0x3377d1cf, v144
	v_fmac_f32_e32 v195, 0x3f317217, v144
	v_cmp_lt_f32_e64 s[42:43], |v144|, s53
	s_nop 1
	v_cndmask_b32_e64 v144, v144, v195, s[42:43]
	v_cndmask_b32_e64 v195, 0, v216, s[40:41]
	v_sub_f32_e32 v144, v144, v195
	v_cndmask_b32_e64 v144, v148, v144, s[38:39]
	v_mul_f32_e32 v148, 0x3fb8aa3b, v194
	v_exp_f32_e32 v148, v148
	s_nop 0
	v_fma_f32 v148, v191, v148, v136
	v_cmp_gt_f32_e64 s[40:41], s97, v148
	s_nop 1
	v_cndmask_b32_e64 v195, 0, 32, s[40:41]
	v_ldexp_f32 v148, v148, v195
	v_log_f32_e32 v148, v148
	s_nop 0
	v_mul_f32_e32 v195, 0x3f317217, v148
	v_fma_f32 v195, v148, s52, -v195
	v_fmac_f32_e32 v195, 0x3377d1cf, v148
	v_fmac_f32_e32 v195, 0x3f317217, v148
	v_cmp_lt_f32_e64 s[42:43], |v148|, s53
	s_nop 1
	v_cndmask_b32_e64 v148, v148, v195, s[42:43]
	v_cndmask_b32_e64 v195, 0, v216, s[40:41]
	v_sub_f32_e32 v148, v148, v195
	v_cndmask_b32_e64 v148, v194, v148, s[36:37]
	v_min_f32_e32 v194, 0, v149
	v_mul_f32_e64 v149, |v149|, s57
	v_exp_f32_e32 v149, v149
	s_nop 0
	v_add_f32_e32 v149, 1.0, v149
	v_cmp_gt_f32_e64 s[40:41], s97, v149
	s_nop 1
	v_cndmask_b32_e64 v195, 0, 32, s[40:41]
	v_ldexp_f32 v149, v149, v195
	v_log_f32_e32 v149, v149
	s_nop 0
	v_mul_f32_e32 v195, 0x3f317217, v149
	v_fma_f32 v195, v149, s52, -v195
	v_fmac_f32_e32 v195, 0x3377d1cf, v149
	v_fmac_f32_e32 v195, 0x3f317217, v149
	v_cmp_lt_f32_e64 s[42:43], |v149|, s53
	s_nop 1
	v_cndmask_b32_e64 v149, v149, v195, s[42:43]
	v_cndmask_b32_e64 v195, 0, v216, s[40:41]
	v_sub_f32_e32 v149, v149, v195
	v_sub_f32_e32 v149, v194, v149
	v_min_f32_e32 v194, 0, v145
	v_mul_f32_e64 v145, |v145|, s57
	v_exp_f32_e32 v145, v145
	s_nop 0
	v_add_f32_e32 v145, 1.0, v145
	v_cmp_gt_f32_e64 s[40:41], s97, v145
	s_nop 1
	v_cndmask_b32_e64 v195, 0, 32, s[40:41]
	v_ldexp_f32 v145, v145, v195
	v_log_f32_e32 v145, v145
	s_nop 0
	v_mul_f32_e32 v195, 0x3f317217, v145
	v_fma_f32 v195, v145, s52, -v195
	v_fmac_f32_e32 v195, 0x3377d1cf, v145
	v_fmac_f32_e32 v195, 0x3f317217, v145
	v_cmp_lt_f32_e64 s[42:43], |v145|, s53
	s_nop 1
	v_cndmask_b32_e64 v145, v145, v195, s[42:43]
	v_cndmask_b32_e64 v195, 0, v216, s[40:41]
	v_sub_f32_e32 v145, v145, v195
	v_sub_f32_e32 v194, v194, v145
	v_mul_f32_e32 v145, 0x3fb8aa3b, v149
	v_exp_f32_e32 v145, v145
	s_nop 0
	v_fma_f32 v145, v188, v145, v141
	v_cmp_gt_f32_e64 s[40:41], s97, v145
	s_nop 1
	v_cndmask_b32_e64 v195, 0, 32, s[40:41]
	v_ldexp_f32 v145, v145, v195
	v_log_f32_e32 v145, v145
	s_nop 0
	v_mul_f32_e32 v195, 0x3f317217, v145
	v_fma_f32 v195, v145, s52, -v195
	v_fmac_f32_e32 v195, 0x3377d1cf, v145
	v_fmac_f32_e32 v195, 0x3f317217, v145
	v_cmp_lt_f32_e64 s[42:43], |v145|, s53
	s_nop 1
	v_cndmask_b32_e64 v145, v145, v195, s[42:43]
	v_cndmask_b32_e64 v195, 0, v216, s[40:41]
	v_sub_f32_e32 v145, v145, v195
	v_cndmask_b32_e64 v145, v149, v145, s[34:35]
	v_mul_f32_e32 v149, 0x3fb8aa3b, v194
	v_exp_f32_e32 v149, v149
	s_nop 0
	v_fma_f32 v149, v189, v149, v137
	v_cmp_gt_f32_e64 s[40:41], s97, v149
	s_nop 1
	v_cndmask_b32_e64 v195, 0, 32, s[40:41]
	v_ldexp_f32 v149, v149, v195
	v_log_f32_e32 v149, v149
	s_nop 0
	v_mul_f32_e32 v195, 0x3f317217, v149
	v_fma_f32 v195, v149, s52, -v195
	v_fmac_f32_e32 v195, 0x3377d1cf, v149
	v_fmac_f32_e32 v195, 0x3f317217, v149
	v_cmp_lt_f32_e64 s[42:43], |v149|, s53
	s_nop 1
	v_cndmask_b32_e64 v149, v149, v195, s[42:43]
	v_cndmask_b32_e64 v195, 0, v216, s[40:41]
	v_sub_f32_e32 v149, v149, v195
	v_cndmask_b32_e64 v149, v194, v149, s[30:31]
	v_min_f32_e32 v194, 0, v150
	v_mul_f32_e64 v150, |v150|, s57
	v_exp_f32_e32 v150, v150
	s_nop 0
	v_add_f32_e32 v150, 1.0, v150
	v_cmp_gt_f32_e64 s[40:41], s97, v150
	s_nop 1
;     __device__ __forceinline__ void operator()(const f32x4 (&acc)[2][2][4][2], const pg8::Unit& u, int wr, int wc, int fr, int fq) const {
;     ...
;             WIN_LOOP( _Pragma("unroll") for (int i = 0; i < 4; ++i) { const float s0 = fminf(a[i], 0.f) - __logf(1.f + __expf(-fabsf(a[i]))), s1 = fminf(b[i], 0.f) - __logf(1.f + __expf(-fabsf(b[i]))); const float la = l0[bj][i], lbv = l1[bj][i];
;                     a[i] = la > 0.f ? __logf(la + (1.f - la) * __expf(s0)) : s0; b[i] = lbv > 0.f ? __logf(lbv + (1.f - lbv) * __expf(s1)) : s1; }
;                 *(f32x4*)(LF + (size_t)row * 512 + c) = a; *(f32x4*)(LF + (size_t)row * 512 + c + 4) = b; __builtin_amdgcn_sched_barrier(0); ) }
	v_cndmask_b32_e64 v195, 0, 32, s[40:41]
	v_ldexp_f32 v150, v150, v195
	v_log_f32_e32 v150, v150
	s_nop 0
	v_mul_f32_e32 v195, 0x3f317217, v150
	v_fma_f32 v195, v150, s52, -v195
	v_fmac_f32_e32 v195, 0x3377d1cf, v150
	v_fmac_f32_e32 v195, 0x3f317217, v150
	v_cmp_lt_f32_e64 s[42:43], |v150|, s53
	s_nop 1
	v_cndmask_b32_e64 v150, v150, v195, s[42:43]
	v_cndmask_b32_e64 v195, 0, v216, s[40:41]
	v_sub_f32_e32 v150, v150, v195
	v_sub_f32_e32 v150, v194, v150
	v_min_f32_e32 v194, 0, v146
	v_mul_f32_e64 v146, |v146|, s57
	v_exp_f32_e32 v146, v146
	s_nop 0
	v_add_f32_e32 v146, 1.0, v146
	v_cmp_gt_f32_e64 s[40:41], s97, v146
	s_nop 1
	v_cndmask_b32_e64 v195, 0, 32, s[40:41]
	v_ldexp_f32 v146, v146, v195
	v_log_f32_e32 v146, v146
	s_nop 0
	v_mul_f32_e32 v195, 0x3f317217, v146
	v_fma_f32 v195, v146, s52, -v195
	v_fmac_f32_e32 v195, 0x3377d1cf, v146
	v_fmac_f32_e32 v195, 0x3f317217, v146
	v_cmp_lt_f32_e64 s[42:43], |v146|, s53
	s_nop 1
	v_cndmask_b32_e64 v146, v146, v195, s[42:43]
	v_cndmask_b32_e64 v195, 0, v216, s[40:41]
	v_sub_f32_e32 v146, v146, v195
	v_sub_f32_e32 v194, v194, v146
	v_mul_f32_e32 v146, 0x3fb8aa3b, v150
	v_exp_f32_e32 v146, v146
	s_nop 0
	v_fma_f32 v146, v187, v146, v142
	v_cmp_gt_f32_e64 s[40:41], s97, v146
	s_nop 1
	v_cndmask_b32_e64 v195, 0, 32, s[40:41]
	v_ldexp_f32 v146, v146, v195
	v_log_f32_e32 v146, v146
	s_nop 0
	v_mul_f32_e32 v195, 0x3f317217, v146
	v_fma_f32 v195, v146, s52, -v195
	v_fmac_f32_e32 v195, 0x3377d1cf, v146
	v_fmac_f32_e32 v195, 0x3f317217, v146
	v_cmp_lt_f32_e64 s[42:43], |v146|, s53
	s_nop 1
	v_cndmask_b32_e64 v146, v146, v195, s[42:43]
	v_cndmask_b32_e64 v195, 0, v216, s[40:41]
	v_sub_f32_e32 v146, v146, v195
	v_cndmask_b32_e64 v146, v150, v146, s[28:29]
	v_mul_f32_e32 v150, 0x3fb8aa3b, v194
	v_exp_f32_e32 v150, v150
	s_nop 0
	v_fma_f32 v150, v186, v150, v138
	v_cmp_gt_f32_e64 s[40:41], s97, v150
	s_nop 1
	v_cndmask_b32_e64 v195, 0, 32, s[40:41]
	v_ldexp_f32 v150, v150, v195
	v_log_f32_e32 v150, v150
	s_nop 0
	v_mul_f32_e32 v195, 0x3f317217, v150
	v_fma_f32 v195, v150, s52, -v195
	v_fmac_f32_e32 v195, 0x3377d1cf, v150
	v_fmac_f32_e32 v195, 0x3f317217, v150
	v_cmp_lt_f32_e64 s[42:43], |v150|, s53
	s_nop 1
	v_cndmask_b32_e64 v150, v150, v195, s[42:43]
	v_cndmask_b32_e64 v195, 0, v216, s[40:41]
	v_sub_f32_e32 v150, v150, v195
	v_cndmask_b32_e64 v150, v194, v150, s[26:27]
	v_min_f32_e32 v194, 0, v151
	v_mul_f32_e64 v151, |v151|, s57
	v_exp_f32_e32 v151, v151
	s_nop 0
	v_add_f32_e32 v151, 1.0, v151
	v_cmp_gt_f32_e64 s[40:41], s97, v151
	s_nop 1
	v_cndmask_b32_e64 v195, 0, 32, s[40:41]
	v_ldexp_f32 v151, v151, v195
	v_log_f32_e32 v151, v151
	s_nop 0
	v_mul_f32_e32 v195, 0x3f317217, v151
	v_fma_f32 v195, v151, s52, -v195
	v_fmac_f32_e32 v195, 0x3377d1cf, v151
	v_fmac_f32_e32 v195, 0x3f317217, v151
	v_cmp_lt_f32_e64 s[42:43], |v151|, s53
	s_nop 1
	v_cndmask_b32_e64 v151, v151, v195, s[42:43]
	v_cndmask_b32_e64 v195, 0, v216, s[40:41]
	v_sub_f32_e32 v151, v151, v195
	v_sub_f32_e32 v151, v194, v151
	v_min_f32_e32 v194, 0, v147
	v_mul_f32_e64 v147, |v147|, s57
	v_exp_f32_e32 v147, v147
	s_nop 0
	v_add_f32_e32 v147, 1.0, v147
	v_cmp_gt_f32_e64 s[40:41], s97, v147
	s_nop 1
	v_cndmask_b32_e64 v195, 0, 32, s[40:41]
	v_ldexp_f32 v147, v147, v195
	v_log_f32_e32 v147, v147
	s_nop 0
	v_mul_f32_e32 v195, 0x3f317217, v147
	v_fma_f32 v195, v147, s52, -v195
	v_fmac_f32_e32 v195, 0x3377d1cf, v147
	v_fmac_f32_e32 v195, 0x3f317217, v147
	v_cmp_lt_f32_e64 s[42:43], |v147|, s53
	s_nop 1
	v_cndmask_b32_e64 v147, v147, v195, s[42:43]
	v_cndmask_b32_e64 v195, 0, v216, s[40:41]
	v_sub_f32_e32 v147, v147, v195
	v_sub_f32_e32 v194, v194, v147
	v_mul_f32_e32 v147, 0x3fb8aa3b, v151
	v_exp_f32_e32 v147, v147
	s_nop 0
	v_fma_f32 v147, v185, v147, v143
	v_cmp_gt_f32_e64 s[40:41], s97, v147
	s_nop 1
	v_cndmask_b32_e64 v195, 0, 32, s[40:41]
	v_ldexp_f32 v147, v147, v195
	v_log_f32_e32 v147, v147
	s_nop 0
	v_mul_f32_e32 v195, 0x3f317217, v147
	v_fma_f32 v195, v147, s52, -v195
	v_fmac_f32_e32 v195, 0x3377d1cf, v147
	v_fmac_f32_e32 v195, 0x3f317217, v147
	v_cmp_lt_f32_e64 s[42:43], |v147|, s53
	s_nop 1
	v_cndmask_b32_e64 v147, v147, v195, s[42:43]
	v_cndmask_b32_e64 v195, 0, v216, s[40:41]
	v_sub_f32_e32 v147, v147, v195
	v_cndmask_b32_e64 v147, v151, v147, s[24:25]
	v_mul_f32_e32 v151, 0x3fb8aa3b, v194
	v_exp_f32_e32 v151, v151
	s_nop 0
	v_fma_f32 v151, v184, v151, v139
	v_cmp_gt_f32_e64 s[40:41], s97, v151
	s_nop 1
	v_cndmask_b32_e64 v195, 0, 32, s[40:41]
	v_ldexp_f32 v151, v151, v195
	v_log_f32_e32 v151, v151
	s_nop 0
	v_mul_f32_e32 v195, 0x3f317217, v151
	v_fma_f32 v195, v151, s52, -v195
	v_fmac_f32_e32 v195, 0x3377d1cf, v151
	v_fmac_f32_e32 v195, 0x3f317217, v151
	v_cmp_lt_f32_e64 s[42:43], |v151|, s53
	s_nop 1
	v_cndmask_b32_e64 v151, v151, v195, s[42:43]
	v_cndmask_b32_e64 v195, 0, v216, s[40:41]
	v_sub_f32_e32 v151, v151, v195
	v_cndmask_b32_e64 v151, v194, v151, s[22:23]
	global_store_dwordx4 v[170:171], v[144:147], off
	global_store_dwordx4 v[170:171], v[148:151], off offset:16
	s_nop 1
	v_pk_mul_f32 v[148:149], v[76:77], v[168:169] op_sel_hi:[1,0]
	v_pk_mul_f32 v[150:151], v[78:79], v[168:169] op_sel_hi:[1,0]
	v_pk_mul_f32 v[146:147], v[74:75], v[168:169] op_sel_hi:[1,0]
	v_pk_mul_f32 v[144:145], v[72:73], v[168:169] op_sel_hi:[1,0]
	v_min_f32_e32 v168, 0, v148
	v_mul_f32_e64 v148, |v148|, s57
	v_exp_f32_e32 v148, v148
	s_nop 0
	v_add_f32_e32 v148, 1.0, v148
	v_cmp_gt_f32_e64 s[40:41], s97, v148
	s_nop 1
	v_cndmask_b32_e64 v194, 0, 32, s[40:41]
	v_ldexp_f32 v148, v148, v194
	v_log_f32_e32 v148, v148
	s_nop 0
	v_mul_f32_e32 v194, 0x3f317217, v148
	v_fma_f32 v194, v148, s52, -v194
	v_fmac_f32_e32 v194, 0x3377d1cf, v148
;     __device__ __forceinline__ void operator()(const f32x4 (&acc)[2][2][4][2], const pg8::Unit& u, int wr, int wc, int fr, int fq) const {
;     ...
;             WIN_LOOP( _Pragma("unroll") for (int i = 0; i < 4; ++i) { const float s0 = fminf(a[i], 0.f) - __logf(1.f + __expf(-fabsf(a[i]))), s1 = fminf(b[i], 0.f) - __logf(1.f + __expf(-fabsf(b[i]))); const float la = l0[bj][i], lbv = l1[bj][i];
;                     a[i] = la > 0.f ? __logf(la + (1.f - la) * __expf(s0)) : s0; b[i] = lbv > 0.f ? __logf(lbv + (1.f - lbv) * __expf(s1)) : s1; }
;                 *(f32x4*)(LF + (size_t)row * 512 + c) = a; *(f32x4*)(LF + (size_t)row * 512 + c + 4) = b; __builtin_amdgcn_sched_barrier(0); ) }
	v_fmac_f32_e32 v194, 0x3f317217, v148
	v_cmp_lt_f32_e64 s[42:43], |v148|, s53
	s_nop 1
	v_cndmask_b32_e64 v148, v148, v194, s[42:43]
	v_cndmask_b32_e64 v194, 0, v216, s[40:41]
	v_sub_f32_e32 v148, v148, v194
	v_sub_f32_e32 v148, v168, v148
	v_min_f32_e32 v168, 0, v144
	v_mul_f32_e64 v144, |v144|, s57
	v_exp_f32_e32 v144, v144
	s_nop 0
	v_add_f32_e32 v144, 1.0, v144
	v_cmp_gt_f32_e64 s[40:41], s97, v144
	s_nop 1
	v_cndmask_b32_e64 v194, 0, 32, s[40:41]
	v_ldexp_f32 v144, v144, v194
	v_log_f32_e32 v144, v144
	s_nop 0
	v_mul_f32_e32 v194, 0x3f317217, v144
	v_fma_f32 v194, v144, s52, -v194
	v_fmac_f32_e32 v194, 0x3377d1cf, v144
	v_fmac_f32_e32 v194, 0x3f317217, v144
	v_cmp_lt_f32_e64 s[42:43], |v144|, s53
	s_nop 1
	v_cndmask_b32_e64 v144, v144, v194, s[42:43]
	v_cndmask_b32_e64 v194, 0, v216, s[40:41]
	v_sub_f32_e32 v144, v144, v194
	v_sub_f32_e32 v168, v168, v144
	v_mul_f32_e32 v144, 0x3fb8aa3b, v148
	v_exp_f32_e32 v144, v144
	s_nop 0
	v_fma_f32 v144, v183, v144, v132
	v_cmp_gt_f32_e64 s[40:41], s97, v144
	s_nop 1
	v_cndmask_b32_e64 v194, 0, 32, s[40:41]
	v_ldexp_f32 v144, v144, v194
	v_log_f32_e32 v144, v144
	s_nop 0
	v_mul_f32_e32 v194, 0x3f317217, v144
	v_fma_f32 v194, v144, s52, -v194
	v_fmac_f32_e32 v194, 0x3377d1cf, v144
	v_fmac_f32_e32 v194, 0x3f317217, v144
	v_cmp_lt_f32_e64 s[42:43], |v144|, s53
	s_nop 1
	v_cndmask_b32_e64 v144, v144, v194, s[42:43]
	v_cndmask_b32_e64 v194, 0, v216, s[40:41]
	v_sub_f32_e32 v144, v144, v194
	v_cndmask_b32_e64 v144, v148, v144, s[20:21]
	v_mul_f32_e32 v148, 0x3fb8aa3b, v168
	v_exp_f32_e32 v148, v148
	s_nop 0
	v_fma_f32 v148, v182, v148, v128
	v_cmp_gt_f32_e64 s[40:41], s97, v148
	s_nop 1
	v_cndmask_b32_e64 v194, 0, 32, s[40:41]
	v_ldexp_f32 v148, v148, v194
	v_log_f32_e32 v148, v148
	s_nop 0
	v_mul_f32_e32 v194, 0x3f317217, v148
	v_fma_f32 v194, v148, s52, -v194
	v_fmac_f32_e32 v194, 0x3377d1cf, v148
	v_fmac_f32_e32 v194, 0x3f317217, v148
	v_cmp_lt_f32_e64 s[42:43], |v148|, s53
	s_nop 1
	v_cndmask_b32_e64 v148, v148, v194, s[42:43]
	v_cndmask_b32_e64 v194, 0, v216, s[40:41]
	v_sub_f32_e32 v148, v148, v194
	v_cndmask_b32_e64 v148, v168, v148, s[18:19]
	v_min_f32_e32 v168, 0, v149
	v_mul_f32_e64 v149, |v149|, s57
	v_exp_f32_e32 v149, v149
	s_nop 0
	v_add_f32_e32 v149, 1.0, v149
	v_cmp_gt_f32_e64 s[40:41], s97, v149
	s_nop 1
	v_cndmask_b32_e64 v194, 0, 32, s[40:41]
	v_ldexp_f32 v149, v149, v194
	v_log_f32_e32 v149, v149
	s_nop 0
	v_mul_f32_e32 v194, 0x3f317217, v149
	v_fma_f32 v194, v149, s52, -v194
	v_fmac_f32_e32 v194, 0x3377d1cf, v149
	v_fmac_f32_e32 v194, 0x3f317217, v149
	v_cmp_lt_f32_e64 s[42:43], |v149|, s53
	s_nop 1
	v_cndmask_b32_e64 v149, v149, v194, s[42:43]
	v_cndmask_b32_e64 v194, 0, v216, s[40:41]
	v_sub_f32_e32 v149, v149, v194
	v_sub_f32_e32 v149, v168, v149
	v_min_f32_e32 v168, 0, v145
	v_mul_f32_e64 v145, |v145|, s57
	v_exp_f32_e32 v145, v145
	s_nop 0
	v_add_f32_e32 v145, 1.0, v145
	v_cmp_gt_f32_e64 s[40:41], s97, v145
	s_nop 1
	v_cndmask_b32_e64 v194, 0, 32, s[40:41]
	v_ldexp_f32 v145, v145, v194
	v_log_f32_e32 v145, v145
	s_nop 0
	v_mul_f32_e32 v194, 0x3f317217, v145
	v_fma_f32 v194, v145, s52, -v194
	v_fmac_f32_e32 v194, 0x3377d1cf, v145
	v_fmac_f32_e32 v194, 0x3f317217, v145
	v_cmp_lt_f32_e64 s[42:43], |v145|, s53
	s_nop 1
	v_cndmask_b32_e64 v145, v145, v194, s[42:43]
	v_cndmask_b32_e64 v194, 0, v216, s[40:41]
	v_sub_f32_e32 v145, v145, v194
	v_sub_f32_e32 v168, v168, v145
	v_mul_f32_e32 v145, 0x3fb8aa3b, v149
	v_exp_f32_e32 v145, v145
	s_nop 0
	v_fma_f32 v145, v181, v145, v133
	v_cmp_gt_f32_e64 s[40:41], s97, v145
	s_nop 1
	v_cndmask_b32_e64 v194, 0, 32, s[40:41]
	v_ldexp_f32 v145, v145, v194
	v_log_f32_e32 v145, v145
	s_nop 0
	v_mul_f32_e32 v194, 0x3f317217, v145
	v_fma_f32 v194, v145, s52, -v194
	v_fmac_f32_e32 v194, 0x3377d1cf, v145
	v_fmac_f32_e32 v194, 0x3f317217, v145
	v_cmp_lt_f32_e64 s[42:43], |v145|, s53
	s_nop 1
	v_cndmask_b32_e64 v145, v145, v194, s[42:43]
	v_cndmask_b32_e64 v194, 0, v216, s[40:41]
	v_sub_f32_e32 v145, v145, v194
	v_cndmask_b32_e64 v145, v149, v145, s[16:17]
	v_mul_f32_e32 v149, 0x3fb8aa3b, v168
	v_exp_f32_e32 v149, v149
	s_nop 0
	v_fma_f32 v149, v180, v149, v129
	v_cmp_gt_f32_e64 s[40:41], s97, v149
	s_nop 1
	v_cndmask_b32_e64 v194, 0, 32, s[40:41]
	v_ldexp_f32 v149, v149, v194
	v_log_f32_e32 v149, v149
	s_nop 0
	v_mul_f32_e32 v194, 0x3f317217, v149
	v_fma_f32 v194, v149, s52, -v194
	v_fmac_f32_e32 v194, 0x3377d1cf, v149
	v_fmac_f32_e32 v194, 0x3f317217, v149
	v_cmp_lt_f32_e64 s[42:43], |v149|, s53
	s_nop 1
	v_cndmask_b32_e64 v149, v149, v194, s[42:43]
	v_cndmask_b32_e64 v194, 0, v216, s[40:41]
	v_sub_f32_e32 v149, v149, v194
	v_cndmask_b32_e64 v149, v168, v149, s[14:15]
	v_min_f32_e32 v168, 0, v150
	v_mul_f32_e64 v150, |v150|, s57
	v_exp_f32_e32 v150, v150
	s_nop 0
	v_add_f32_e32 v150, 1.0, v150
	v_cmp_gt_f32_e64 s[40:41], s97, v150
	s_nop 1
	v_cndmask_b32_e64 v194, 0, 32, s[40:41]
	v_ldexp_f32 v150, v150, v194
	v_log_f32_e32 v150, v150
	s_nop 0
	v_mul_f32_e32 v194, 0x3f317217, v150
	v_fma_f32 v194, v150, s52, -v194
	v_fmac_f32_e32 v194, 0x3377d1cf, v150
	v_fmac_f32_e32 v194, 0x3f317217, v150
	v_cmp_lt_f32_e64 s[42:43], |v150|, s53
	s_nop 1
	v_cndmask_b32_e64 v150, v150, v194, s[42:43]
	v_cndmask_b32_e64 v194, 0, v216, s[40:41]
	v_sub_f32_e32 v150, v150, v194
	v_sub_f32_e32 v150, v168, v150
	v_min_f32_e32 v168, 0, v146
	v_mul_f32_e64 v146, |v146|, s57
	v_exp_f32_e32 v146, v146
	s_nop 0
	v_add_f32_e32 v146, 1.0, v146
	v_cmp_gt_f32_e64 s[40:41], s97, v146
	s_nop 1
	v_cndmask_b32_e64 v194, 0, 32, s[40:41]
	v_ldexp_f32 v146, v146, v194
	v_log_f32_e32 v146, v146
	s_nop 0
	v_mul_f32_e32 v194, 0x3f317217, v146
	v_fma_f32 v194, v146, s52, -v194
; __device__ __forceinline__ float row_rstd(const float* ssq, int row, int fq) {
;     const f32x4 v = *(const f32x4*)(ssq + (size_t)row * 16 + fq * 4);
;     float s = (v[0] + v[1]) + (v[2] + v[3]);
;     s += __shfl_xor(s, 16); s += __shfl_xor(s, 32);
;     return __builtin_amdgcn_rsqf(s * (1.f / DM) + EPS);
; }
;     __device__ __forceinline__ void operator()(const f32x4 (&acc)[2][2][4][2], const pg8::Unit& u, int wr, int wc, int fr, int fq) const {
;     ...
;             WIN_LOOP( _Pragma("unroll") for (int i = 0; i < 4; ++i) { const float s0 = fminf(a[i], 0.f) - __logf(1.f + __expf(-fabsf(a[i]))), s1 = fminf(b[i], 0.f) - __logf(1.f + __expf(-fabsf(b[i]))); const float la = l0[bj][i], lbv = l1[bj][i];
;                     a[i] = la > 0.f ? __logf(la + (1.f - la) * __expf(s0)) : s0; b[i] = lbv > 0.f ? __logf(lbv + (1.f - lbv) * __expf(s1)) : s1; }
;                 *(f32x4*)(LF + (size_t)row * 512 + c) = a; *(f32x4*)(LF + (size_t)row * 512 + c + 4) = b; __builtin_amdgcn_sched_barrier(0); ) }
	v_fmac_f32_e32 v194, 0x3377d1cf, v146
	v_fmac_f32_e32 v194, 0x3f317217, v146
	v_cmp_lt_f32_e64 s[42:43], |v146|, s53
	s_nop 1
	v_cndmask_b32_e64 v146, v146, v194, s[42:43]
	v_cndmask_b32_e64 v194, 0, v216, s[40:41]
	v_sub_f32_e32 v146, v146, v194
	v_sub_f32_e32 v168, v168, v146
	v_mul_f32_e32 v146, 0x3fb8aa3b, v150
	v_exp_f32_e32 v146, v146
	s_nop 0
	v_fma_f32 v146, v179, v146, v134
	v_cmp_gt_f32_e64 s[40:41], s97, v146
	s_nop 1
	v_cndmask_b32_e64 v194, 0, 32, s[40:41]
	v_ldexp_f32 v146, v146, v194
	v_log_f32_e32 v146, v146
	s_nop 0
	v_mul_f32_e32 v194, 0x3f317217, v146
	v_fma_f32 v194, v146, s52, -v194
	v_fmac_f32_e32 v194, 0x3377d1cf, v146
	v_fmac_f32_e32 v194, 0x3f317217, v146
	v_cmp_lt_f32_e64 s[42:43], |v146|, s53
	s_nop 1
	v_cndmask_b32_e64 v146, v146, v194, s[42:43]
	v_cndmask_b32_e64 v194, 0, v216, s[40:41]
	v_sub_f32_e32 v146, v146, v194
	v_cndmask_b32_e64 v146, v150, v146, s[12:13]
	v_mul_f32_e32 v150, 0x3fb8aa3b, v168
	v_exp_f32_e32 v150, v150
	s_nop 0
	v_fma_f32 v150, v178, v150, v130
	v_cmp_gt_f32_e64 s[40:41], s97, v150
	s_nop 1
	v_cndmask_b32_e64 v194, 0, 32, s[40:41]
	v_ldexp_f32 v150, v150, v194
	v_log_f32_e32 v150, v150
	s_nop 0
	v_mul_f32_e32 v194, 0x3f317217, v150
	v_fma_f32 v194, v150, s52, -v194
	v_fmac_f32_e32 v194, 0x3377d1cf, v150
	v_fmac_f32_e32 v194, 0x3f317217, v150
	v_cmp_lt_f32_e64 s[42:43], |v150|, s53
	s_nop 1
	v_cndmask_b32_e64 v150, v150, v194, s[42:43]
	v_cndmask_b32_e64 v194, 0, v216, s[40:41]
	v_sub_f32_e32 v150, v150, v194
	v_cndmask_b32_e64 v150, v168, v150, s[10:11]
	v_min_f32_e32 v168, 0, v151
	v_mul_f32_e64 v151, |v151|, s57
	v_exp_f32_e32 v151, v151
	s_nop 0
	v_add_f32_e32 v151, 1.0, v151
	v_cmp_gt_f32_e64 s[40:41], s97, v151
	s_nop 1
	v_cndmask_b32_e64 v194, 0, 32, s[40:41]
	v_ldexp_f32 v151, v151, v194
	v_log_f32_e32 v151, v151
	s_nop 0
	v_mul_f32_e32 v194, 0x3f317217, v151
	v_fma_f32 v194, v151, s52, -v194
	v_fmac_f32_e32 v194, 0x3377d1cf, v151
	v_fmac_f32_e32 v194, 0x3f317217, v151
	v_cmp_lt_f32_e64 s[42:43], |v151|, s53
	s_nop 1
	v_cndmask_b32_e64 v151, v151, v194, s[42:43]
	v_cndmask_b32_e64 v194, 0, v216, s[40:41]
	v_sub_f32_e32 v151, v151, v194
	v_sub_f32_e32 v151, v168, v151
	v_min_f32_e32 v168, 0, v147
	v_mul_f32_e64 v147, |v147|, s57
	v_exp_f32_e32 v147, v147
	s_nop 0
	v_add_f32_e32 v147, 1.0, v147
	v_cmp_gt_f32_e64 s[40:41], s97, v147
	s_nop 1
	v_cndmask_b32_e64 v194, 0, 32, s[40:41]
	v_ldexp_f32 v147, v147, v194
	v_log_f32_e32 v147, v147
	s_nop 0
	v_mul_f32_e32 v194, 0x3f317217, v147
	v_fma_f32 v194, v147, s52, -v194
	v_fmac_f32_e32 v194, 0x3377d1cf, v147
	v_fmac_f32_e32 v194, 0x3f317217, v147
	v_cmp_lt_f32_e64 s[42:43], |v147|, s53
	s_nop 1
	v_cndmask_b32_e64 v147, v147, v194, s[42:43]
	v_cndmask_b32_e64 v194, 0, v216, s[40:41]
	v_sub_f32_e32 v147, v147, v194
	v_sub_f32_e32 v168, v168, v147
	v_mul_f32_e32 v147, 0x3fb8aa3b, v151
	v_exp_f32_e32 v147, v147
	s_nop 0
	v_fma_f32 v147, v177, v147, v135
	v_cmp_gt_f32_e64 s[40:41], s97, v147
	s_nop 1
	v_cndmask_b32_e64 v194, 0, 32, s[40:41]
	v_ldexp_f32 v147, v147, v194
	v_log_f32_e32 v147, v147
	s_nop 0
	v_mul_f32_e32 v194, 0x3f317217, v147
	v_fma_f32 v194, v147, s52, -v194
	v_fmac_f32_e32 v194, 0x3377d1cf, v147
	v_fmac_f32_e32 v194, 0x3f317217, v147
	v_cmp_lt_f32_e64 s[42:43], |v147|, s53
	s_nop 1
	v_cndmask_b32_e64 v147, v147, v194, s[42:43]
	v_cndmask_b32_e64 v194, 0, v216, s[40:41]
	v_sub_f32_e32 v147, v147, v194
	v_cndmask_b32_e64 v147, v151, v147, s[8:9]
	v_mul_f32_e32 v151, 0x3fb8aa3b, v168
	v_exp_f32_e32 v151, v151
	s_nop 0
	v_fma_f32 v151, v167, v151, v131
	v_cmp_gt_f32_e64 s[40:41], s97, v151
	s_nop 1
	v_cndmask_b32_e64 v194, 0, 32, s[40:41]
	v_ldexp_f32 v151, v151, v194
	v_log_f32_e32 v151, v151
	s_nop 0
	v_mul_f32_e32 v194, 0x3f317217, v151
	v_fma_f32 v194, v151, s52, -v194
	v_fmac_f32_e32 v194, 0x3377d1cf, v151
	v_fmac_f32_e32 v194, 0x3f317217, v151
	v_cmp_lt_f32_e64 s[42:43], |v151|, s53
	s_nop 1
	v_cndmask_b32_e64 v151, v151, v194, s[42:43]
	v_cndmask_b32_e64 v194, 0, v216, s[40:41]
	v_sub_f32_e32 v151, v151, v194
	v_cndmask_b32_e32 v151, v168, v151, vcc
	global_store_dwordx4 v[170:171], v[144:147], off offset:512
	global_store_dwordx4 v[170:171], v[148:151], off offset:528
	s_nop 1
	v_add_u32_e32 v148, 0xb0, v166
	v_ashrrev_i32_e32 v149, 31, v148
	v_lshlrev_b64 v[144:145], 6, v[148:149]
	v_lshl_add_u64 v[144:145], v[160:161], 0, v[144:145]
	s_nop 0
	s_waitcnt lgkmcnt(0)
	s_nop 0
	s_nop 0
	s_nop 0
	s_nop 0
	v_lshlrev_b64 v[146:147], 11, v[148:149]
	s_nop 0
	s_nop 0
	v_lshl_add_u64 v[146:147], s[50:51], 0, v[146:147]
	v_lshl_add_u64 v[146:147], v[146:147], 0, v[192:193]
	s_waitcnt lgkmcnt(0)
	s_nop 0
	s_nop 0
	s_waitcnt lgkmcnt(0)
;     __device__ __forceinline__ void operator()(const f32x4 (&acc)[2][2][4][2], const pg8::Unit& u, int wr, int wc, int fr, int fq) const {
;     ...
;             WIN_LOOP( _Pragma("unroll") for (int i = 0; i < 4; ++i) { const float s0 = fminf(a[i], 0.f) - __logf(1.f + __expf(-fabsf(a[i]))), s1 = fminf(b[i], 0.f) - __logf(1.f + __expf(-fabsf(b[i]))); const float la = l0[bj][i], lbv = l1[bj][i];
;                     a[i] = la > 0.f ? __logf(la + (1.f - la) * __expf(s0)) : s0; b[i] = lbv > 0.f ? __logf(lbv + (1.f - lbv) * __expf(s1)) : s1; }
;                 *(f32x4*)(LF + (size_t)row * 512 + c) = a; *(f32x4*)(LF + (size_t)row * 512 + c + 4) = b; __builtin_amdgcn_sched_barrier(0); ) }
	s_nop 0
	s_nop 0
	v_mov_b32_e32 v144, v245
	s_nop 0
	v_pk_mul_f32 v[170:171], v[4:5], v[144:145] op_sel_hi:[1,0]
	v_pk_mul_f32 v[150:151], v[6:7], v[144:145] op_sel_hi:[1,0]
	v_pk_mul_f32 v[148:149], v[2:3], v[144:145] op_sel_hi:[1,0]
	v_pk_mul_f32 v[168:169], v[0:1], v[144:145] op_sel_hi:[1,0]
	v_min_f32_e32 v145, 0, v170
	v_mul_f32_e64 v170, |v170|, s57
	v_exp_f32_e32 v170, v170
	s_nop 0
	v_add_f32_e32 v170, 1.0, v170
	v_cmp_gt_f32_e64 s[40:41], s97, v170
	s_nop 1
	v_cndmask_b32_e64 v194, 0, 32, s[40:41]
	v_ldexp_f32 v170, v170, v194
	v_log_f32_e32 v170, v170
	s_nop 0
	v_mul_f32_e32 v194, 0x3f317217, v170
	v_fma_f32 v194, v170, s52, -v194
	v_fmac_f32_e32 v194, 0x3377d1cf, v170
	v_fmac_f32_e32 v194, 0x3f317217, v170
	v_cmp_lt_f32_e64 s[42:43], |v170|, s53
	s_nop 1
	v_cndmask_b32_e64 v170, v170, v194, s[42:43]
	v_cndmask_b32_e64 v194, 0, v216, s[40:41]
	v_sub_f32_e32 v170, v170, v194
	v_sub_f32_e32 v145, v145, v170
	v_min_f32_e32 v170, 0, v168
	v_mul_f32_e64 v168, |v168|, s57
	v_exp_f32_e32 v168, v168
	s_nop 0
	v_add_f32_e32 v168, 1.0, v168
	v_cmp_gt_f32_e64 s[40:41], s97, v168
	s_nop 1
	v_cndmask_b32_e64 v194, 0, 32, s[40:41]
	v_ldexp_f32 v168, v168, v194
	v_log_f32_e32 v168, v168
	s_nop 0
	v_mul_f32_e32 v194, 0x3f317217, v168
	v_fma_f32 v194, v168, s52, -v194
	v_fmac_f32_e32 v194, 0x3377d1cf, v168
	v_fmac_f32_e32 v194, 0x3f317217, v168
	v_cmp_lt_f32_e64 s[42:43], |v168|, s53
	s_nop 1
	v_cndmask_b32_e64 v168, v168, v194, s[42:43]
	v_cndmask_b32_e64 v194, 0, v216, s[40:41]
	v_sub_f32_e32 v168, v168, v194
	v_sub_f32_e32 v168, v170, v168
	v_mul_f32_e32 v170, 0x3fb8aa3b, v145
	v_exp_f32_e32 v170, v170
	s_nop 0
	v_fma_f32 v140, v190, v170, v140
	v_cmp_gt_f32_e64 s[40:41], s97, v140
	s_nop 1
	v_cndmask_b32_e64 v170, 0, 32, s[40:41]
	v_ldexp_f32 v140, v140, v170
	v_log_f32_e32 v140, v140
	s_nop 0
	v_mul_f32_e32 v170, 0x3f317217, v140
	v_fma_f32 v170, v140, s52, -v170
	v_fmac_f32_e32 v170, 0x3377d1cf, v140
	v_fmac_f32_e32 v170, 0x3f317217, v140
	v_cmp_lt_f32_e64 s[42:43], |v140|, s53
	s_nop 1
	v_cndmask_b32_e64 v140, v140, v170, s[42:43]
	v_cndmask_b32_e64 v170, 0, v216, s[40:41]
	v_sub_f32_e32 v140, v140, v170
	v_cndmask_b32_e64 v140, v145, v140, s[38:39]
	v_mul_f32_e32 v145, 0x3fb8aa3b, v168
	v_exp_f32_e32 v145, v145
	v_readlane_b32 s42, v255, 57
	v_readlane_b32 s43, v255, 58
	v_fma_f32 v136, v191, v145, v136
	v_cmp_gt_f32_e64 s[38:39], s97, v136
	s_nop 1
	v_cndmask_b32_e64 v145, 0, 32, s[38:39]
	v_ldexp_f32 v136, v136, v145
	v_log_f32_e32 v136, v136
	s_nop 0
	v_mul_f32_e32 v145, 0x3f317217, v136
	v_fma_f32 v145, v136, s52, -v145
	v_fmac_f32_e32 v145, 0x3377d1cf, v136
	v_fmac_f32_e32 v145, 0x3f317217, v136
	v_cmp_lt_f32_e64 s[40:41], |v136|, s53
	s_nop 1
	v_cndmask_b32_e64 v136, v136, v145, s[40:41]
	v_cndmask_b32_e64 v145, 0, v216, s[38:39]
	v_sub_f32_e32 v136, v136, v145
	v_cndmask_b32_e64 v136, v168, v136, s[36:37]
	v_mul_f32_e64 v168, |v171|, s57
	v_exp_f32_e32 v168, v168
	v_min_f32_e32 v145, 0, v171
	s_mov_b32 s40, s2
	v_add_f32_e32 v168, 1.0, v168
	v_cmp_gt_f32_e64 s[36:37], s97, v168
	s_nop 1
	v_cndmask_b32_e64 v170, 0, 32, s[36:37]
	v_ldexp_f32 v168, v168, v170
	v_log_f32_e32 v168, v168
	s_nop 0
	v_mul_f32_e32 v170, 0x3f317217, v168
	v_fma_f32 v170, v168, s52, -v170
	v_fmac_f32_e32 v170, 0x3377d1cf, v168
	v_fmac_f32_e32 v170, 0x3f317217, v168
	v_cmp_lt_f32_e64 s[38:39], |v168|, s53
	s_nop 1
	v_cndmask_b32_e64 v168, v168, v170, s[38:39]
	v_cndmask_b32_e64 v170, 0, v216, s[36:37]
	v_sub_f32_e32 v168, v168, v170
	v_sub_f32_e32 v145, v145, v168
	v_min_f32_e32 v168, 0, v169
	v_mul_f32_e64 v169, |v169|, s57
	v_exp_f32_e32 v169, v169
	s_nop 0
	v_add_f32_e32 v169, 1.0, v169
	v_cmp_gt_f32_e64 s[36:37], s97, v169
	s_nop 1
	v_cndmask_b32_e64 v170, 0, 32, s[36:37]
	v_ldexp_f32 v169, v169, v170
	v_log_f32_e32 v169, v169
	s_nop 0
	v_mul_f32_e32 v170, 0x3f317217, v169
	v_fma_f32 v170, v169, s52, -v170
	v_fmac_f32_e32 v170, 0x3377d1cf, v169
	v_fmac_f32_e32 v170, 0x3f317217, v169
	v_cmp_lt_f32_e64 s[38:39], |v169|, s53
	s_nop 1
	v_cndmask_b32_e64 v169, v169, v170, s[38:39]
	v_cndmask_b32_e64 v170, 0, v216, s[36:37]
	v_sub_f32_e32 v169, v169, v170
	v_sub_f32_e32 v168, v168, v169
	v_mul_f32_e32 v169, 0x3fb8aa3b, v145
	v_exp_f32_e32 v169, v169
	s_nop 0
	v_fma_f32 v141, v188, v169, v141
	v_cmp_gt_f32_e64 s[36:37], s97, v141
	s_nop 1
	v_cndmask_b32_e64 v169, 0, 32, s[36:37]
	v_ldexp_f32 v141, v141, v169
	v_log_f32_e32 v141, v141
	s_nop 0
	v_mul_f32_e32 v169, 0x3f317217, v141
	v_fma_f32 v169, v141, s52, -v169
	v_fmac_f32_e32 v169, 0x3377d1cf, v141
	v_fmac_f32_e32 v169, 0x3f317217, v141
	v_cmp_lt_f32_e64 s[38:39], |v141|, s53
	s_nop 1
	v_cndmask_b32_e64 v141, v141, v169, s[38:39]
	v_cndmask_b32_e64 v169, 0, v216, s[36:37]
	v_sub_f32_e32 v141, v141, v169
	v_cndmask_b32_e64 v141, v145, v141, s[34:35]
	v_mul_f32_e32 v145, 0x3fb8aa3b, v168
	v_exp_f32_e32 v145, v145
	v_readlane_b32 s38, v255, 53
	v_readlane_b32 s39, v255, 54
	v_fma_f32 v137, v189, v145, v137
	v_cmp_gt_f32_e64 s[34:35], s97, v137
	s_nop 1
	v_cndmask_b32_e64 v145, 0, 32, s[34:35]
	v_ldexp_f32 v137, v137, v145
	v_log_f32_e32 v137, v137
	s_nop 0
	v_mul_f32_e32 v145, 0x3f317217, v137
	v_fma_f32 v145, v137, s52, -v145
	v_fmac_f32_e32 v145, 0x3377d1cf, v137
	v_fmac_f32_e32 v145, 0x3f317217, v137
	v_cmp_lt_f32_e64 s[36:37], |v137|, s53
	s_nop 1
	v_cndmask_b32_e64 v137, v137, v145, s[36:37]
	v_cndmask_b32_e64 v145, 0, v216, s[34:35]
	v_sub_f32_e32 v137, v137, v145
	v_min_f32_e32 v145, 0, v150
	v_mul_f32_e64 v150, |v150|, s57
	v_exp_f32_e32 v150, v150
	v_cndmask_b32_e64 v137, v168, v137, s[30:31]
	v_readlane_b32 s36, v255, 51
	v_readlane_b32 s37, v255, 52
	v_add_f32_e32 v150, 1.0, v150
;     __device__ __forceinline__ void operator()(const f32x4 (&acc)[2][2][4][2], const pg8::Unit& u, int wr, int wc, int fr, int fq) const {
;     ...
;             WIN_LOOP( _Pragma("unroll") for (int i = 0; i < 4; ++i) { const float s0 = fminf(a[i], 0.f) - __logf(1.f + __expf(-fabsf(a[i]))), s1 = fminf(b[i], 0.f) - __logf(1.f + __expf(-fabsf(b[i]))); const float la = l0[bj][i], lbv = l1[bj][i];
;                     a[i] = la > 0.f ? __logf(la + (1.f - la) * __expf(s0)) : s0; b[i] = lbv > 0.f ? __logf(lbv + (1.f - lbv) * __expf(s1)) : s1; }
;                 *(f32x4*)(LF + (size_t)row * 512 + c) = a; *(f32x4*)(LF + (size_t)row * 512 + c + 4) = b; __builtin_amdgcn_sched_barrier(0); ) }
	v_cmp_gt_f32_e64 s[30:31], s97, v150
	s_nop 1
	v_cndmask_b32_e64 v168, 0, 32, s[30:31]
	v_ldexp_f32 v150, v150, v168
	v_log_f32_e32 v150, v150
	s_nop 0
	v_mul_f32_e32 v168, 0x3f317217, v150
	v_fma_f32 v168, v150, s52, -v168
	v_fmac_f32_e32 v168, 0x3377d1cf, v150
	v_fmac_f32_e32 v168, 0x3f317217, v150
	v_cmp_lt_f32_e64 s[34:35], |v150|, s53
	s_nop 1
	v_cndmask_b32_e64 v150, v150, v168, s[34:35]
	v_cndmask_b32_e64 v168, 0, v216, s[30:31]
	v_sub_f32_e32 v150, v150, v168
	v_sub_f32_e32 v145, v145, v150
	v_min_f32_e32 v150, 0, v148
	v_mul_f32_e64 v148, |v148|, s57
	v_exp_f32_e32 v148, v148
	s_nop 0
	v_add_f32_e32 v148, 1.0, v148
	v_cmp_gt_f32_e64 s[30:31], s97, v148
	s_nop 1
	v_cndmask_b32_e64 v168, 0, 32, s[30:31]
	v_ldexp_f32 v148, v148, v168
	v_log_f32_e32 v148, v148
	s_nop 0
	v_mul_f32_e32 v168, 0x3f317217, v148
	v_fma_f32 v168, v148, s52, -v168
	v_fmac_f32_e32 v168, 0x3377d1cf, v148
	v_fmac_f32_e32 v168, 0x3f317217, v148
	v_cmp_lt_f32_e64 s[34:35], |v148|, s53
	s_nop 1
	v_cndmask_b32_e64 v148, v148, v168, s[34:35]
	v_cndmask_b32_e64 v168, 0, v216, s[30:31]
	v_sub_f32_e32 v148, v148, v168
	v_sub_f32_e32 v148, v150, v148
	v_mul_f32_e32 v150, 0x3fb8aa3b, v145
	v_exp_f32_e32 v150, v150
	s_nop 0
	v_fma_f32 v142, v187, v150, v142
	v_cmp_gt_f32_e64 s[30:31], s97, v142
	s_nop 1
	v_cndmask_b32_e64 v150, 0, 32, s[30:31]
	v_ldexp_f32 v142, v142, v150
	v_log_f32_e32 v142, v142
	s_nop 0
	v_mul_f32_e32 v150, 0x3f317217, v142
	v_fma_f32 v150, v142, s52, -v150
	v_fmac_f32_e32 v150, 0x3377d1cf, v142
	v_fmac_f32_e32 v150, 0x3f317217, v142
	v_cmp_lt_f32_e64 s[34:35], |v142|, s53
	s_nop 1
	v_cndmask_b32_e64 v142, v142, v150, s[34:35]
	v_cndmask_b32_e64 v150, 0, v216, s[30:31]
	v_sub_f32_e32 v142, v142, v150
	v_cndmask_b32_e64 v142, v145, v142, s[28:29]
	v_mul_f32_e32 v145, 0x3fb8aa3b, v148
	v_exp_f32_e32 v145, v145
	v_readlane_b32 s34, v255, 49
	v_readlane_b32 s35, v255, 50
	v_fma_f32 v138, v186, v145, v138
	v_cmp_gt_f32_e64 s[28:29], s97, v138
	s_nop 1
	v_cndmask_b32_e64 v145, 0, 32, s[28:29]
	v_ldexp_f32 v138, v138, v145
	v_log_f32_e32 v138, v138
	s_nop 0
	v_mul_f32_e32 v145, 0x3f317217, v138
	v_fma_f32 v145, v138, s52, -v145
	v_fmac_f32_e32 v145, 0x3377d1cf, v138
	v_fmac_f32_e32 v145, 0x3f317217, v138
	v_cmp_lt_f32_e64 s[30:31], |v138|, s53
	s_nop 1
	v_cndmask_b32_e64 v138, v138, v145, s[30:31]
	v_cndmask_b32_e64 v145, 0, v216, s[28:29]
	v_sub_f32_e32 v138, v138, v145
	v_cndmask_b32_e64 v138, v148, v138, s[26:27]
	v_mul_f32_e64 v148, |v151|, s57
	v_exp_f32_e32 v148, v148
	v_min_f32_e32 v145, 0, v151
	v_readlane_b32 s30, v255, 47
	v_readlane_b32 s31, v255, 48
	v_add_f32_e32 v148, 1.0, v148
	v_cmp_gt_f32_e64 s[26:27], s97, v148
	s_nop 1
	v_cndmask_b32_e64 v150, 0, 32, s[26:27]
	v_ldexp_f32 v148, v148, v150
	v_log_f32_e32 v148, v148
	s_nop 0
	v_mul_f32_e32 v150, 0x3f317217, v148
	v_fma_f32 v150, v148, s52, -v150
	v_fmac_f32_e32 v150, 0x3377d1cf, v148
	v_fmac_f32_e32 v150, 0x3f317217, v148
	v_cmp_lt_f32_e64 s[28:29], |v148|, s53
	s_nop 1
	v_cndmask_b32_e64 v148, v148, v150, s[28:29]
	v_cndmask_b32_e64 v150, 0, v216, s[26:27]
	v_sub_f32_e32 v148, v148, v150
	v_sub_f32_e32 v145, v145, v148
	v_min_f32_e32 v148, 0, v149
	v_mul_f32_e64 v149, |v149|, s57
	v_exp_f32_e32 v149, v149
	s_nop 0
	v_add_f32_e32 v149, 1.0, v149
	v_cmp_gt_f32_e64 s[26:27], s97, v149
	s_nop 1
	v_cndmask_b32_e64 v150, 0, 32, s[26:27]
	v_ldexp_f32 v149, v149, v150
	v_log_f32_e32 v149, v149
	s_nop 0
	v_mul_f32_e32 v150, 0x3f317217, v149
	v_fma_f32 v150, v149, s52, -v150
	v_fmac_f32_e32 v150, 0x3377d1cf, v149
	v_fmac_f32_e32 v150, 0x3f317217, v149
	v_cmp_lt_f32_e64 s[28:29], |v149|, s53
	s_nop 1
	v_cndmask_b32_e64 v149, v149, v150, s[28:29]
	v_cndmask_b32_e64 v150, 0, v216, s[26:27]
	v_sub_f32_e32 v149, v149, v150
	v_sub_f32_e32 v148, v148, v149
	v_mul_f32_e32 v149, 0x3fb8aa3b, v145
	v_exp_f32_e32 v149, v149
	s_nop 0
	v_fmac_f32_e32 v143, v185, v149
	v_cmp_gt_f32_e64 s[26:27], s97, v143
	s_nop 1
	v_cndmask_b32_e64 v149, 0, 32, s[26:27]
	v_ldexp_f32 v143, v143, v149
	v_log_f32_e32 v143, v143
	s_nop 0
	v_mul_f32_e32 v149, 0x3f317217, v143
	v_fma_f32 v149, v143, s52, -v149
	v_fmac_f32_e32 v149, 0x3377d1cf, v143
	v_fmac_f32_e32 v149, 0x3f317217, v143
	v_cmp_lt_f32_e64 s[28:29], |v143|, s53
	s_nop 1
	v_cndmask_b32_e64 v143, v143, v149, s[28:29]
	v_cndmask_b32_e64 v149, 0, v216, s[26:27]
	v_sub_f32_e32 v143, v143, v149
	v_cndmask_b32_e64 v143, v145, v143, s[24:25]
	v_mul_f32_e32 v145, 0x3fb8aa3b, v148
	v_exp_f32_e32 v145, v145
	s_mov_b32 s29, s91
	s_mov_b32 s28, s95
	v_fmac_f32_e32 v139, v184, v145
	v_cmp_gt_f32_e64 s[24:25], s97, v139
	s_nop 1
	v_cndmask_b32_e64 v145, 0, 32, s[24:25]
	v_ldexp_f32 v139, v139, v145
	v_log_f32_e32 v139, v139
	s_nop 0
	v_mul_f32_e32 v145, 0x3f317217, v139
	v_fma_f32 v145, v139, s52, -v145
	v_fmac_f32_e32 v145, 0x3377d1cf, v139
	v_fmac_f32_e32 v145, 0x3f317217, v139
	v_cmp_lt_f32_e64 s[26:27], |v139|, s53
	s_nop 1
	v_cndmask_b32_e64 v139, v139, v145, s[26:27]
	v_cndmask_b32_e64 v145, 0, v216, s[24:25]
	v_readlane_b32 s27, v255, 56
	v_readlane_b32 s26, v255, 31
	v_sub_f32_e32 v139, v139, v145
	v_cndmask_b32_e64 v139, v148, v139, s[22:23]
	global_store_dwordx4 v[146:147], v[140:143], off
	global_store_dwordx4 v[146:147], v[136:139], off offset:16
	s_nop 0
	v_pk_mul_f32 v[142:143], v[68:69], v[144:145] op_sel_hi:[1,0]
	v_pk_mul_f32 v[138:139], v[70:71], v[144:145] op_sel_hi:[1,0]
	v_pk_mul_f32 v[136:137], v[66:67], v[144:145] op_sel_hi:[1,0]
	v_pk_mul_f32 v[140:141], v[64:65], v[144:145] op_sel_hi:[1,0]
	v_min_f32_e32 v144, 0, v142
	v_mul_f32_e64 v142, |v142|, s57
	v_exp_f32_e32 v142, v142
	s_nop 0
	v_add_f32_e32 v142, 1.0, v142
	v_cmp_gt_f32_e64 s[22:23], s97, v142
;     __device__ __forceinline__ void operator()(const f32x4 (&acc)[2][2][4][2], const pg8::Unit& u, int wr, int wc, int fr, int fq) const {
;     ...
;             WIN_LOOP( _Pragma("unroll") for (int i = 0; i < 4; ++i) { const float s0 = fminf(a[i], 0.f) - __logf(1.f + __expf(-fabsf(a[i]))), s1 = fminf(b[i], 0.f) - __logf(1.f + __expf(-fabsf(b[i]))); const float la = l0[bj][i], lbv = l1[bj][i];
;                     a[i] = la > 0.f ? __logf(la + (1.f - la) * __expf(s0)) : s0; b[i] = lbv > 0.f ? __logf(lbv + (1.f - lbv) * __expf(s1)) : s1; }
;                 *(f32x4*)(LF + (size_t)row * 512 + c) = a; *(f32x4*)(LF + (size_t)row * 512 + c + 4) = b; __builtin_amdgcn_sched_barrier(0); ) }
	s_nop 1
	v_cndmask_b32_e64 v145, 0, 32, s[22:23]
	v_ldexp_f32 v142, v142, v145
	v_log_f32_e32 v142, v142
	s_nop 0
	v_mul_f32_e32 v145, 0x3f317217, v142
	v_fma_f32 v145, v142, s52, -v145
	v_fmac_f32_e32 v145, 0x3377d1cf, v142
	v_fmac_f32_e32 v145, 0x3f317217, v142
	v_cmp_lt_f32_e64 s[24:25], |v142|, s53
	s_nop 1
	v_cndmask_b32_e64 v142, v142, v145, s[24:25]
	v_cndmask_b32_e64 v145, 0, v216, s[22:23]
	v_sub_f32_e32 v142, v142, v145
	v_sub_f32_e32 v142, v144, v142
	v_min_f32_e32 v144, 0, v140
	v_mul_f32_e64 v140, |v140|, s57
	v_exp_f32_e32 v140, v140
	s_nop 0
	v_add_f32_e32 v140, 1.0, v140
	v_cmp_gt_f32_e64 s[22:23], s97, v140
	s_nop 1
	v_cndmask_b32_e64 v145, 0, 32, s[22:23]
	v_ldexp_f32 v140, v140, v145
	v_log_f32_e32 v140, v140
	s_nop 0
	v_mul_f32_e32 v145, 0x3f317217, v140
	v_fma_f32 v145, v140, s52, -v145
	v_fmac_f32_e32 v145, 0x3377d1cf, v140
	v_fmac_f32_e32 v145, 0x3f317217, v140
	v_cmp_lt_f32_e64 s[24:25], |v140|, s53
	s_nop 1
	v_cndmask_b32_e64 v140, v140, v145, s[24:25]
	v_cndmask_b32_e64 v145, 0, v216, s[22:23]
	v_sub_f32_e32 v140, v140, v145
	v_sub_f32_e32 v140, v144, v140
	v_mul_f32_e32 v144, 0x3fb8aa3b, v142
	v_exp_f32_e32 v144, v144
	s_nop 0
	v_fma_f32 v132, v183, v144, v132
	v_cmp_gt_f32_e64 s[22:23], s97, v132
	s_nop 1
	v_cndmask_b32_e64 v144, 0, 32, s[22:23]
	v_ldexp_f32 v132, v132, v144
	v_log_f32_e32 v132, v132
	s_nop 0
	v_mul_f32_e32 v144, 0x3f317217, v132
	v_fma_f32 v144, v132, s52, -v144
	v_fmac_f32_e32 v144, 0x3377d1cf, v132
	v_fmac_f32_e32 v144, 0x3f317217, v132
	v_cmp_lt_f32_e64 s[24:25], |v132|, s53
	s_nop 1
	v_cndmask_b32_e64 v132, v132, v144, s[24:25]
	v_cndmask_b32_e64 v144, 0, v216, s[22:23]
	v_sub_f32_e32 v132, v132, v144
	v_cndmask_b32_e64 v132, v142, v132, s[20:21]
	v_mul_f32_e32 v142, 0x3fb8aa3b, v140
	v_exp_f32_e32 v142, v142
	s_nop 0
	v_fma_f32 v128, v182, v142, v128
	v_cmp_gt_f32_e64 s[20:21], s97, v128
	s_nop 1
	v_cndmask_b32_e64 v142, 0, 32, s[20:21]
	v_ldexp_f32 v128, v128, v142
	v_log_f32_e32 v128, v128
	s_nop 0
	v_mul_f32_e32 v142, 0x3f317217, v128
	v_fma_f32 v142, v128, s52, -v142
	v_fmac_f32_e32 v142, 0x3377d1cf, v128
	v_fmac_f32_e32 v142, 0x3f317217, v128
	v_cmp_lt_f32_e64 s[22:23], |v128|, s53
	s_nop 1
	v_cndmask_b32_e64 v128, v128, v142, s[22:23]
	v_cndmask_b32_e64 v142, 0, v216, s[20:21]
	v_sub_f32_e32 v128, v128, v142
	v_mul_f32_e64 v142, |v143|, s57
	v_exp_f32_e32 v142, v142
	v_cndmask_b32_e64 v128, v140, v128, s[18:19]
	v_min_f32_e32 v140, 0, v143
	v_readlane_b32 s23, v255, 55
	v_add_f32_e32 v142, 1.0, v142
	v_cmp_gt_f32_e64 s[18:19], s97, v142
	s_nop 1
	v_cndmask_b32_e64 v143, 0, 32, s[18:19]
	v_ldexp_f32 v142, v142, v143
	v_log_f32_e32 v142, v142
	s_nop 0
	v_mul_f32_e32 v143, 0x3f317217, v142
	v_fma_f32 v143, v142, s52, -v143
	v_fmac_f32_e32 v143, 0x3377d1cf, v142
	v_fmac_f32_e32 v143, 0x3f317217, v142
	v_cmp_lt_f32_e64 s[20:21], |v142|, s53
	s_nop 1
	v_cndmask_b32_e64 v142, v142, v143, s[20:21]
	v_cndmask_b32_e64 v143, 0, v216, s[18:19]
	v_sub_f32_e32 v142, v142, v143
	v_sub_f32_e32 v140, v140, v142
	v_min_f32_e32 v142, 0, v141
	v_mul_f32_e64 v141, |v141|, s57
	v_exp_f32_e32 v141, v141
	s_nop 0
	v_add_f32_e32 v141, 1.0, v141
	v_cmp_gt_f32_e64 s[18:19], s97, v141
	s_nop 1
	v_cndmask_b32_e64 v143, 0, 32, s[18:19]
	v_ldexp_f32 v141, v141, v143
	v_log_f32_e32 v141, v141
	s_nop 0
	v_mul_f32_e32 v143, 0x3f317217, v141
	v_fma_f32 v143, v141, s52, -v143
	v_fmac_f32_e32 v143, 0x3377d1cf, v141
	v_fmac_f32_e32 v143, 0x3f317217, v141
	v_cmp_lt_f32_e64 s[20:21], |v141|, s53
	s_nop 1
	v_cndmask_b32_e64 v141, v141, v143, s[20:21]
	v_cndmask_b32_e64 v143, 0, v216, s[18:19]
	v_sub_f32_e32 v141, v141, v143
	v_sub_f32_e32 v141, v142, v141
	v_mul_f32_e32 v142, 0x3fb8aa3b, v140
	v_exp_f32_e32 v142, v142
	s_nop 0
	v_fma_f32 v133, v181, v142, v133
	v_cmp_gt_f32_e64 s[18:19], s97, v133
	s_nop 1
	v_cndmask_b32_e64 v142, 0, 32, s[18:19]
	v_ldexp_f32 v133, v133, v142
	v_log_f32_e32 v133, v133
	s_nop 0
	v_mul_f32_e32 v142, 0x3f317217, v133
	v_fma_f32 v142, v133, s52, -v142
	v_fmac_f32_e32 v142, 0x3377d1cf, v133
	v_fmac_f32_e32 v142, 0x3f317217, v133
	v_cmp_lt_f32_e64 s[20:21], |v133|, s53
	s_nop 1
	v_cndmask_b32_e64 v133, v133, v142, s[20:21]
	v_cndmask_b32_e64 v142, 0, v216, s[18:19]
	v_sub_f32_e32 v133, v133, v142
	v_cndmask_b32_e64 v133, v140, v133, s[16:17]
	v_mul_f32_e32 v140, 0x3fb8aa3b, v141
	v_exp_f32_e32 v140, v140
	s_nop 0
	v_fma_f32 v129, v180, v140, v129
	v_cmp_gt_f32_e64 s[16:17], s97, v129
	s_nop 1
	v_cndmask_b32_e64 v140, 0, 32, s[16:17]
	v_ldexp_f32 v129, v129, v140
	v_log_f32_e32 v129, v129
	s_nop 0
	v_mul_f32_e32 v140, 0x3f317217, v129
	v_fma_f32 v140, v129, s52, -v140
	v_fmac_f32_e32 v140, 0x3377d1cf, v129
	v_fmac_f32_e32 v140, 0x3f317217, v129
	v_cmp_lt_f32_e64 s[18:19], |v129|, s53
	s_nop 1
	v_cndmask_b32_e64 v129, v129, v140, s[18:19]
	v_cndmask_b32_e64 v140, 0, v216, s[16:17]
	v_sub_f32_e32 v129, v129, v140
	v_min_f32_e32 v140, 0, v138
	v_mul_f32_e64 v138, |v138|, s57
	v_exp_f32_e32 v138, v138
	v_cndmask_b32_e64 v129, v141, v129, s[14:15]
	v_add_f32_e32 v138, 1.0, v138
;     __device__ __forceinline__ void operator()(const f32x4 (&acc)[2][2][4][2], const pg8::Unit& u, int wr, int wc, int fr, int fq) const {
;     ...
;             WIN_LOOP( _Pragma("unroll") for (int i = 0; i < 4; ++i) { const float s0 = fminf(a[i], 0.f) - __logf(1.f + __expf(-fabsf(a[i]))), s1 = fminf(b[i], 0.f) - __logf(1.f + __expf(-fabsf(b[i]))); const float la = l0[bj][i], lbv = l1[bj][i];
;                     a[i] = la > 0.f ? __logf(la + (1.f - la) * __expf(s0)) : s0; b[i] = lbv > 0.f ? __logf(lbv + (1.f - lbv) * __expf(s1)) : s1; }
;                 *(f32x4*)(LF + (size_t)row * 512 + c) = a; *(f32x4*)(LF + (size_t)row * 512 + c + 4) = b; __builtin_amdgcn_sched_barrier(0); ) }
	v_cmp_gt_f32_e64 s[14:15], s97, v138
	s_nop 1
	v_cndmask_b32_e64 v141, 0, 32, s[14:15]
	v_ldexp_f32 v138, v138, v141
	v_log_f32_e32 v138, v138
	s_nop 0
	v_mul_f32_e32 v141, 0x3f317217, v138
	v_fma_f32 v141, v138, s52, -v141
	v_fmac_f32_e32 v141, 0x3377d1cf, v138
	v_fmac_f32_e32 v141, 0x3f317217, v138
	v_cmp_lt_f32_e64 s[16:17], |v138|, s53
	s_nop 1
	v_cndmask_b32_e64 v138, v138, v141, s[16:17]
	v_cndmask_b32_e64 v141, 0, v216, s[14:15]
	v_sub_f32_e32 v138, v138, v141
	v_sub_f32_e32 v138, v140, v138
	v_min_f32_e32 v140, 0, v136
	v_mul_f32_e64 v136, |v136|, s57
	v_exp_f32_e32 v136, v136
	s_nop 0
	v_add_f32_e32 v136, 1.0, v136
	v_cmp_gt_f32_e64 s[14:15], s97, v136
	s_nop 1
	v_cndmask_b32_e64 v141, 0, 32, s[14:15]
	v_ldexp_f32 v136, v136, v141
	v_log_f32_e32 v136, v136
	s_nop 0
	v_mul_f32_e32 v141, 0x3f317217, v136
	v_fma_f32 v141, v136, s52, -v141
	v_fmac_f32_e32 v141, 0x3377d1cf, v136
	v_fmac_f32_e32 v141, 0x3f317217, v136
	v_cmp_lt_f32_e64 s[16:17], |v136|, s53
	s_nop 1
	v_cndmask_b32_e64 v136, v136, v141, s[16:17]
	v_cndmask_b32_e64 v141, 0, v216, s[14:15]
	v_sub_f32_e32 v136, v136, v141
	v_sub_f32_e32 v136, v140, v136
	v_mul_f32_e32 v140, 0x3fb8aa3b, v138
	v_exp_f32_e32 v140, v140
	s_nop 0
	v_fma_f32 v134, v179, v140, v134
	v_cmp_gt_f32_e64 s[14:15], s97, v134
	s_nop 1
	v_cndmask_b32_e64 v140, 0, 32, s[14:15]
	v_ldexp_f32 v134, v134, v140
	v_log_f32_e32 v134, v134
	s_nop 0
	v_mul_f32_e32 v140, 0x3f317217, v134
	v_fma_f32 v140, v134, s52, -v140
	v_fmac_f32_e32 v140, 0x3377d1cf, v134
	v_fmac_f32_e32 v140, 0x3f317217, v134
	v_cmp_lt_f32_e64 s[16:17], |v134|, s53
	s_nop 1
	v_cndmask_b32_e64 v134, v134, v140, s[16:17]
	v_cndmask_b32_e64 v140, 0, v216, s[14:15]
	v_sub_f32_e32 v134, v134, v140
	v_cndmask_b32_e64 v134, v138, v134, s[12:13]
	v_mul_f32_e32 v138, 0x3fb8aa3b, v136
	v_exp_f32_e32 v138, v138
	s_nop 0
	v_fma_f32 v130, v178, v138, v130
	v_cmp_gt_f32_e64 s[12:13], s97, v130
	s_nop 1
	v_cndmask_b32_e64 v138, 0, 32, s[12:13]
	v_ldexp_f32 v130, v130, v138
	v_log_f32_e32 v130, v130
	s_nop 0
	v_mul_f32_e32 v138, 0x3f317217, v130
	v_fma_f32 v138, v130, s52, -v138
	v_fmac_f32_e32 v138, 0x3377d1cf, v130
	v_fmac_f32_e32 v138, 0x3f317217, v130
	v_cmp_lt_f32_e64 s[14:15], |v130|, s53
	s_nop 1
	v_cndmask_b32_e64 v130, v130, v138, s[14:15]
	v_cndmask_b32_e64 v138, 0, v216, s[12:13]
	v_sub_f32_e32 v130, v130, v138
	v_mul_f32_e64 v138, |v139|, s57
	v_exp_f32_e32 v138, v138
	v_cndmask_b32_e64 v130, v136, v130, s[10:11]
	v_min_f32_e32 v136, 0, v139
	v_add_f32_e32 v138, 1.0, v138
	v_cmp_gt_f32_e64 s[10:11], s97, v138
	s_nop 1
	v_cndmask_b32_e64 v139, 0, 32, s[10:11]
	v_ldexp_f32 v138, v138, v139
	v_log_f32_e32 v138, v138
	s_nop 0
	v_mul_f32_e32 v139, 0x3f317217, v138
	v_fma_f32 v139, v138, s52, -v139
	v_fmac_f32_e32 v139, 0x3377d1cf, v138
	v_fmac_f32_e32 v139, 0x3f317217, v138
	v_cmp_lt_f32_e64 s[12:13], |v138|, s53
	s_nop 1
	v_cndmask_b32_e64 v138, v138, v139, s[12:13]
	v_cndmask_b32_e64 v139, 0, v216, s[10:11]
	v_sub_f32_e32 v138, v138, v139
	v_sub_f32_e32 v136, v136, v138
	v_min_f32_e32 v138, 0, v137
	v_mul_f32_e64 v137, |v137|, s57
	v_exp_f32_e32 v137, v137
	s_nop 0
	v_add_f32_e32 v137, 1.0, v137
	v_cmp_gt_f32_e64 s[10:11], s97, v137
	s_nop 1
	v_cndmask_b32_e64 v139, 0, 32, s[10:11]
	v_ldexp_f32 v137, v137, v139
	v_log_f32_e32 v137, v137
	s_nop 0
	v_mul_f32_e32 v139, 0x3f317217, v137
	v_fma_f32 v139, v137, s52, -v139
	v_fmac_f32_e32 v139, 0x3377d1cf, v137
	v_fmac_f32_e32 v139, 0x3f317217, v137
	v_cmp_lt_f32_e64 s[12:13], |v137|, s53
	s_nop 1
	v_cndmask_b32_e64 v137, v137, v139, s[12:13]
	v_cndmask_b32_e64 v139, 0, v216, s[10:11]
	v_sub_f32_e32 v137, v137, v139
	v_sub_f32_e32 v137, v138, v137
	v_mul_f32_e32 v138, 0x3fb8aa3b, v136
	v_exp_f32_e32 v138, v138
	s_nop 0
	v_fmac_f32_e32 v135, v177, v138
	v_cmp_gt_f32_e64 s[10:11], s97, v135
	s_nop 1
	v_cndmask_b32_e64 v138, 0, 32, s[10:11]
	v_ldexp_f32 v135, v135, v138
	v_log_f32_e32 v135, v135
	s_nop 0
	v_mul_f32_e32 v138, 0x3f317217, v135
	v_fma_f32 v138, v135, s52, -v138
	v_fmac_f32_e32 v138, 0x3377d1cf, v135
	v_fmac_f32_e32 v138, 0x3f317217, v135
	v_cmp_lt_f32_e64 s[12:13], |v135|, s53
	s_nop 1
	v_cndmask_b32_e64 v135, v135, v138, s[12:13]
	v_cndmask_b32_e64 v138, 0, v216, s[10:11]
	v_sub_f32_e32 v135, v135, v138
	v_cndmask_b32_e64 v135, v136, v135, s[8:9]
	v_mul_f32_e32 v136, 0x3fb8aa3b, v137
	v_exp_f32_e32 v136, v136
	s_nop 0
	v_fmac_f32_e32 v131, v167, v136
	v_cmp_gt_f32_e64 s[8:9], s97, v131
	s_nop 1
	v_cndmask_b32_e64 v136, 0, 32, s[8:9]
	v_ldexp_f32 v131, v131, v136
	v_log_f32_e32 v131, v131
	s_nop 0
	v_mul_f32_e32 v136, 0x3f317217, v131
	v_fma_f32 v136, v131, s52, -v136
	v_fmac_f32_e32 v136, 0x3377d1cf, v131
	v_fmac_f32_e32 v136, 0x3f317217, v131
	v_cmp_lt_f32_e64 s[10:11], |v131|, s53
	s_nop 1
	v_cndmask_b32_e64 v131, v131, v136, s[10:11]
	v_cndmask_b32_e64 v136, 0, v216, s[8:9]
	v_sub_f32_e32 v131, v131, v136
	v_cndmask_b32_e32 v131, v137, v131, vcc
	global_store_dwordx4 v[146:147], v[132:135], off offset:512
	global_store_dwordx4 v[146:147], v[128:131], off offset:528

; __device__ __forceinline__ float silu_f(float x) { return x * __builtin_amdgcn_rcpf(1.f + __expf(-x)); }
; __device__ __forceinline__ v4u pack8(const f32x4 a, const f32x4 b) { v4u w; w.x = cvt_pk_bf16(a[0], a[1]); w.y = cvt_pk_bf16(a[2], a[3]); w.z = cvt_pk_bf16(b[0], b[1]); w.w = cvt_pk_bf16(b[2], b[3]); return w; }
; __device__ __forceinline__ float row_rstd(const float* ssq, int row, int fq) {
;     const f32x4 v = *(const f32x4*)(ssq + (size_t)row * 16 + fq * 4);
;     float s = (v[0] + v[1]) + (v[2] + v[3]);
;     s += __shfl_xor(s, 16); s += __shfl_xor(s, 32);
;     return __builtin_amdgcn_rsqf(s * (1.f / DM) + EPS);
; }
;     __device__ __forceinline__ void operator()(const f32x4 (&acc)[2][2][4][2], const pg8::Unit& u, int wr, int wc, int fr, int fq) const {
;     ...
;         if (grp == 0) { WIN_LOOP( _Pragma("unroll") for (int i = 0; i < 4; ++i) { a[i] = silu_f(a[i]); b[i] = silu_f(b[i]); } *(v4u*)(QO + (size_t)row * DM + c) = pack8(a, b); ) }
.LBB0_417:
	s_and_b64 vcc, exec, s[8:9]
	s_cbranch_vccz .LBB0_419
	v_and_b32_e32 v129, 64, v215
	v_xor_b32_e32 v128, 16, v215
	v_add_u32_e32 v129, 64, v129
	v_cmp_lt_i32_e32 vcc, v128, v129
	v_xor_b32_e32 v130, 32, v215
	v_ashrrev_i32_e32 v167, 31, v166
	v_cndmask_b32_e32 v128, v215, v128, vcc
	v_cmp_lt_i32_e32 vcc, v130, v129
	v_lshlrev_b32_e32 v128, 2, v128
	v_lshlrev_b32_e32 v192, 1, v176
	v_cndmask_b32_e32 v129, v215, v130, vcc
	v_lshlrev_b64 v[130:131], 6, v[166:167]
	v_lshl_add_u64 v[130:131], v[160:161], 0, v[130:131]
	s_nop 0
	v_lshlrev_b32_e32 v129, 2, v129
	s_waitcnt lgkmcnt(0)
	s_nop 0
	s_nop 0
	s_nop 0
	s_nop 0
	s_nop 0
	s_nop 0
	s_nop 0
	s_waitcnt lgkmcnt(0)
	s_nop 0
	s_nop 0
	s_waitcnt lgkmcnt(0)
	s_nop 0
	s_nop 0
	v_mov_b32_e32 v134, v250
	v_lshlrev_b64 v[130:131], 11, v[166:167]
	v_lshl_add_u64 v[136:137], s[44:45], 0, v[130:131]
	v_lshl_add_u64 v[136:137], v[136:137], 0, v[192:193]
	v_pk_mul_f32 v[132:133], v[60:61], v[134:135] op_sel_hi:[1,0]
	v_pk_mul_f32 v[130:131], v[62:63], v[134:135] op_sel_hi:[1,0]
	v_pk_mul_f32 v[138:139], v[58:59], v[134:135] op_sel_hi:[1,0]
	v_pk_mul_f32 v[140:141], v[56:57], v[134:135] op_sel_hi:[1,0]
	v_mul_f32_e32 v135, 0xbfb8aa3b, v132
	v_exp_f32_e32 v135, v135
	s_nop 0
	v_add_f32_e32 v135, 1.0, v135
	v_rcp_f32_e32 v142, v135
	v_mul_f32_e32 v135, 0xbfb8aa3b, v140
	v_exp_f32_e32 v135, v135
	s_nop 0
	v_add_f32_e32 v135, 1.0, v135
	v_rcp_f32_e32 v144, v135
	v_mul_f32_e32 v135, 0xbfb8aa3b, v133
	v_exp_f32_e32 v135, v135
	s_nop 0
	v_add_f32_e32 v135, 1.0, v135
	v_rcp_f32_e32 v143, v135
	v_mul_f32_e32 v135, 0xbfb8aa3b, v141
	v_exp_f32_e32 v135, v135
	v_pk_mul_f32 v[132:133], v[132:133], v[142:143]
	v_add_f32_e32 v135, 1.0, v135
	v_rcp_f32_e32 v145, v135
	v_mul_f32_e32 v135, 0xbfb8aa3b, v130
	v_exp_f32_e32 v135, v135
	v_pk_mul_f32 v[140:141], v[140:141], v[144:145]
	v_add_f32_e32 v135, 1.0, v135
	v_rcp_f32_e32 v142, v135
	v_mul_f32_e32 v135, 0xbfb8aa3b, v138
	v_exp_f32_e32 v135, v135
	s_nop 0
	v_add_f32_e32 v135, 1.0, v135
	v_rcp_f32_e32 v144, v135
	v_mul_f32_e32 v135, 0xbfb8aa3b, v131
	v_exp_f32_e32 v135, v135
	s_nop 0
	v_add_f32_e32 v135, 1.0, v135
	v_rcp_f32_e32 v143, v135
	v_pk_mul_f32 v[120:121], v[120:121], v[134:135] op_sel_hi:[1,0]
	v_pk_mul_f32 v[124:125], v[124:125], v[134:135] op_sel_hi:[1,0]
	v_pk_mul_f32 v[122:123], v[122:123], v[134:135] op_sel_hi:[1,0]
	v_pk_mul_f32 v[142:143], v[130:131], v[142:143]
	v_mul_f32_e32 v130, 0xbfb8aa3b, v139
	v_exp_f32_e32 v130, v130
	v_cvt_pk_bf16_f32 v131, v142, v143
	v_pk_mul_f32 v[126:127], v[126:127], v[134:135] op_sel_hi:[1,0]
	v_add_f32_e32 v130, 1.0, v130
	v_rcp_f32_e32 v145, v130
	v_cvt_pk_bf16_f32 v130, v132, v133
	v_cvt_pk_bf16_f32 v132, v140, v141
	v_pk_mul_f32 v[138:139], v[138:139], v[144:145]
	s_nop 0
	v_cvt_pk_bf16_f32 v133, v138, v139
	global_store_dwordx4 v[136:137], v[130:133], off
	s_nop 1
	v_mul_f32_e32 v131, 0xbfb8aa3b, v120
	v_exp_f32_e32 v131, v131
	v_mul_f32_e32 v130, 0xbfb8aa3b, v124
	v_exp_f32_e32 v130, v130
	v_add_f32_e32 v131, 1.0, v131
	v_rcp_f32_e32 v132, v131
	v_mul_f32_e32 v131, 0xbfb8aa3b, v125
	v_exp_f32_e32 v131, v131
	v_add_f32_e32 v130, 1.0, v130
	v_rcp_f32_e32 v130, v130
	v_add_f32_e32 v131, 1.0, v131
	v_rcp_f32_e32 v131, v131
	s_nop 0
	v_pk_mul_f32 v[124:125], v[124:125], v[130:131]
	v_mul_f32_e32 v130, 0xbfb8aa3b, v121
	v_exp_f32_e32 v130, v130
	s_nop 0
	v_add_f32_e32 v130, 1.0, v130
	v_rcp_f32_e32 v133, v130
	s_nop 0
	v_pk_mul_f32 v[130:131], v[120:121], v[132:133]
	v_mul_f32_e32 v121, 0xbfb8aa3b, v122
	v_exp_f32_e32 v121, v121
	v_mul_f32_e32 v120, 0xbfb8aa3b, v126
	v_exp_f32_e32 v120, v120
	v_add_f32_e32 v121, 1.0, v121
	v_rcp_f32_e32 v132, v121
	v_mul_f32_e32 v121, 0xbfb8aa3b, v127
	v_exp_f32_e32 v121, v121
	v_add_f32_e32 v120, 1.0, v120
	v_rcp_f32_e32 v120, v120
	v_add_f32_e32 v121, 1.0, v121
	v_rcp_f32_e32 v121, v121
	s_nop 0
	v_pk_mul_f32 v[126:127], v[126:127], v[120:121]
	v_mul_f32_e32 v120, 0xbfb8aa3b, v123
	v_exp_f32_e32 v120, v120
	v_cvt_pk_bf16_f32 v121, v126, v127
	v_add_f32_e32 v120, 1.0, v120
	v_rcp_f32_e32 v133, v120
	v_cvt_pk_bf16_f32 v120, v124, v125
	v_or_b32_e32 v124, 16, v166
	v_ashrrev_i32_e32 v125, 31, v124
	v_pk_mul_f32 v[132:133], v[122:123], v[132:133]
	v_cvt_pk_bf16_f32 v122, v130, v131
	v_cvt_pk_bf16_f32 v123, v132, v133
	global_store_dwordx4 v[136:137], v[120:123], off offset:256
	s_nop 1
	v_lshlrev_b64 v[120:121], 6, v[124:125]
	v_lshl_add_u64 v[120:121], v[160:161], 0, v[120:121]
	s_nop 0
	s_waitcnt lgkmcnt(0)
	s_nop 0
	s_nop 0
	s_nop 0
	s_nop 0
	s_nop 0
	s_nop 0
	s_nop 0
	s_waitcnt lgkmcnt(0)
	s_nop 0
	s_nop 0
	s_waitcnt lgkmcnt(0)
; __device__ __forceinline__ float silu_f(float x) { return x * __builtin_amdgcn_rcpf(1.f + __expf(-x)); }
; __device__ __forceinline__ v4u pack8(const f32x4 a, const f32x4 b) { v4u w; w.x = cvt_pk_bf16(a[0], a[1]); w.y = cvt_pk_bf16(a[2], a[3]); w.z = cvt_pk_bf16(b[0], b[1]); w.w = cvt_pk_bf16(b[2], b[3]); return w; }
; __device__ __forceinline__ float row_rstd(const float* ssq, int row, int fq) {
;     const f32x4 v = *(const f32x4*)(ssq + (size_t)row * 16 + fq * 4);
;     float s = (v[0] + v[1]) + (v[2] + v[3]);
;     s += __shfl_xor(s, 16); s += __shfl_xor(s, 32);
;     return __builtin_amdgcn_rsqf(s * (1.f / DM) + EPS);
; }
;     __device__ __forceinline__ void operator()(const f32x4 (&acc)[2][2][4][2], const pg8::Unit& u, int wr, int wc, int fr, int fq) const {
;     ...
;         if (grp == 0) { WIN_LOOP( _Pragma("unroll") for (int i = 0; i < 4; ++i) { a[i] = silu_f(a[i]); b[i] = silu_f(b[i]); } *(v4u*)(QO + (size_t)row * DM + c) = pack8(a, b); ) }
	s_nop 0
	s_nop 0
	v_mov_b32_e32 v122, v251
	v_lshlrev_b64 v[120:121], 11, v[124:125]
	v_lshl_add_u64 v[120:121], s[44:45], 0, v[120:121]
	v_lshl_add_u64 v[120:121], v[120:121], 0, v[192:193]
	v_pk_mul_f32 v[126:127], v[52:53], v[122:123] op_sel_hi:[1,0]
	v_pk_mul_f32 v[124:125], v[54:55], v[122:123] op_sel_hi:[1,0]
	v_pk_mul_f32 v[130:131], v[50:51], v[122:123] op_sel_hi:[1,0]
	v_pk_mul_f32 v[132:133], v[48:49], v[122:123] op_sel_hi:[1,0]
	v_mul_f32_e32 v123, 0xbfb8aa3b, v126
	v_exp_f32_e32 v123, v123
	s_nop 0
	v_add_f32_e32 v123, 1.0, v123
	v_rcp_f32_e32 v134, v123
	v_mul_f32_e32 v123, 0xbfb8aa3b, v132
	v_exp_f32_e32 v123, v123
	s_nop 0
	v_add_f32_e32 v123, 1.0, v123
	v_rcp_f32_e32 v136, v123
	v_mul_f32_e32 v123, 0xbfb8aa3b, v127
	v_exp_f32_e32 v123, v123
	s_nop 0
	v_add_f32_e32 v123, 1.0, v123
	v_rcp_f32_e32 v135, v123
	v_mul_f32_e32 v123, 0xbfb8aa3b, v133
	v_exp_f32_e32 v123, v123
	v_pk_mul_f32 v[126:127], v[126:127], v[134:135]
	v_add_f32_e32 v123, 1.0, v123
	v_rcp_f32_e32 v137, v123
	v_mul_f32_e32 v123, 0xbfb8aa3b, v124
	v_exp_f32_e32 v123, v123
	v_pk_mul_f32 v[132:133], v[132:133], v[136:137]
	v_add_f32_e32 v123, 1.0, v123
	v_rcp_f32_e32 v134, v123
	v_mul_f32_e32 v123, 0xbfb8aa3b, v130
	v_exp_f32_e32 v123, v123
	s_nop 0
	v_add_f32_e32 v123, 1.0, v123
	v_rcp_f32_e32 v136, v123
	v_mul_f32_e32 v123, 0xbfb8aa3b, v125
	v_exp_f32_e32 v123, v123
	s_nop 0
	v_add_f32_e32 v123, 1.0, v123
	v_rcp_f32_e32 v135, v123
	v_mul_f32_e32 v123, 0xbfb8aa3b, v131
	v_exp_f32_e32 v123, v123
	v_pk_mul_f32 v[134:135], v[124:125], v[134:135]
	v_cvt_pk_bf16_f32 v124, v126, v127
	v_add_f32_e32 v123, 1.0, v123
	v_rcp_f32_e32 v137, v123
	v_cvt_pk_bf16_f32 v125, v134, v135
	v_cvt_pk_bf16_f32 v126, v132, v133
	v_pk_mul_f32 v[116:117], v[116:117], v[122:123] op_sel_hi:[1,0]
	v_pk_mul_f32 v[130:131], v[130:131], v[136:137]
	v_pk_mul_f32 v[114:115], v[114:115], v[122:123] op_sel_hi:[1,0]
	v_cvt_pk_bf16_f32 v127, v130, v131
	global_store_dwordx4 v[120:121], v[124:127], off
	s_nop 1
	v_pk_mul_f32 v[124:125], v[118:119], v[122:123] op_sel_hi:[1,0]
	v_pk_mul_f32 v[118:119], v[112:113], v[122:123] op_sel_hi:[1,0]
	v_mul_f32_e32 v112, 0xbfb8aa3b, v116
	v_mul_f32_e32 v113, 0xbfb8aa3b, v118
	v_exp_f32_e32 v113, v113
	v_exp_f32_e32 v112, v112
	v_add_f32_e32 v113, 1.0, v113
	v_rcp_f32_e32 v122, v113
	v_mul_f32_e32 v113, 0xbfb8aa3b, v117
	v_exp_f32_e32 v113, v113
	v_add_f32_e32 v112, 1.0, v112
	v_rcp_f32_e32 v112, v112
	v_add_f32_e32 v113, 1.0, v113
	v_rcp_f32_e32 v113, v113
	s_nop 0
	v_pk_mul_f32 v[112:113], v[116:117], v[112:113]
	v_mul_f32_e32 v116, 0xbfb8aa3b, v119
	v_exp_f32_e32 v116, v116
	v_cvt_pk_bf16_f32 v112, v112, v113
	v_add_f32_e32 v116, 1.0, v116
	v_rcp_f32_e32 v123, v116
	s_nop 0
	v_pk_mul_f32 v[116:117], v[118:119], v[122:123]
	v_mul_f32_e32 v118, 0xbfb8aa3b, v124
	v_mul_f32_e32 v119, 0xbfb8aa3b, v125
	v_exp_f32_e32 v118, v118
	v_exp_f32_e32 v119, v119
	v_add_f32_e32 v118, 1.0, v118
	v_add_f32_e32 v119, 1.0, v119
	v_rcp_f32_e32 v122, v118
	v_mul_f32_e32 v118, 0xbfb8aa3b, v114
	v_rcp_f32_e32 v123, v119
	v_mul_f32_e32 v119, 0xbfb8aa3b, v115
	v_exp_f32_e32 v118, v118
	v_exp_f32_e32 v119, v119
	v_pk_mul_f32 v[122:123], v[124:125], v[122:123]
	v_add_f32_e32 v118, 1.0, v118
	v_add_f32_e32 v119, 1.0, v119
	v_rcp_f32_e32 v118, v118
	v_rcp_f32_e32 v119, v119
	v_cvt_pk_bf16_f32 v113, v122, v123
	v_pk_mul_f32 v[118:119], v[114:115], v[118:119]
	v_cvt_pk_bf16_f32 v114, v116, v117
	v_or_b32_e32 v116, 32, v166
	v_cvt_pk_bf16_f32 v115, v118, v119
	v_ashrrev_i32_e32 v117, 31, v116
	global_store_dwordx4 v[120:121], v[112:115], off offset:256
	s_nop 1
	v_lshlrev_b64 v[112:113], 6, v[116:117]
	v_lshl_add_u64 v[112:113], v[160:161], 0, v[112:113]
	s_nop 0
	s_waitcnt lgkmcnt(0)
	s_nop 0
	s_nop 0
	s_nop 0
	s_nop 0
	s_nop 0
	s_nop 0
	s_nop 0
	s_waitcnt lgkmcnt(0)
	s_nop 0
	s_nop 0
	s_waitcnt lgkmcnt(0)
	s_nop 0
	s_nop 0
	v_mov_b32_e32 v114, v252
	v_lshlrev_b64 v[112:113], 11, v[116:117]
	v_lshl_add_u64 v[112:113], s[44:45], 0, v[112:113]
	v_lshl_add_u64 v[112:113], v[112:113], 0, v[192:193]
	v_pk_mul_f32 v[118:119], v[44:45], v[114:115] op_sel_hi:[1,0]
	v_pk_mul_f32 v[116:117], v[46:47], v[114:115] op_sel_hi:[1,0]
	v_pk_mul_f32 v[120:121], v[42:43], v[114:115] op_sel_hi:[1,0]
	v_pk_mul_f32 v[122:123], v[40:41], v[114:115] op_sel_hi:[1,0]
	v_mul_f32_e32 v115, 0xbfb8aa3b, v118
	v_exp_f32_e32 v115, v115
	s_nop 0
	v_add_f32_e32 v115, 1.0, v115
	v_rcp_f32_e32 v124, v115
	v_mul_f32_e32 v115, 0xbfb8aa3b, v122
	v_exp_f32_e32 v115, v115
	s_nop 0
	v_add_f32_e32 v115, 1.0, v115
	v_rcp_f32_e32 v126, v115
	v_mul_f32_e32 v115, 0xbfb8aa3b, v119
	v_exp_f32_e32 v115, v115
	s_nop 0
	v_add_f32_e32 v115, 1.0, v115
	v_rcp_f32_e32 v125, v115
	v_mul_f32_e32 v115, 0xbfb8aa3b, v123
	v_exp_f32_e32 v115, v115
	v_pk_mul_f32 v[118:119], v[118:119], v[124:125]
	v_add_f32_e32 v115, 1.0, v115
	v_rcp_f32_e32 v127, v115
	v_mul_f32_e32 v115, 0xbfb8aa3b, v116
	v_exp_f32_e32 v115, v115
	v_pk_mul_f32 v[122:123], v[122:123], v[126:127]
	v_add_f32_e32 v115, 1.0, v115
	v_rcp_f32_e32 v124, v115
	v_mul_f32_e32 v115, 0xbfb8aa3b, v120
	v_exp_f32_e32 v115, v115
	s_nop 0
	v_add_f32_e32 v115, 1.0, v115
	v_rcp_f32_e32 v126, v115
	v_mul_f32_e32 v115, 0xbfb8aa3b, v117
	v_exp_f32_e32 v115, v115
	s_nop 0
	v_add_f32_e32 v115, 1.0, v115
	v_rcp_f32_e32 v125, v115
	v_mul_f32_e32 v115, 0xbfb8aa3b, v121
	v_exp_f32_e32 v115, v115
	v_pk_mul_f32 v[124:125], v[116:117], v[124:125]
	v_cvt_pk_bf16_f32 v116, v118, v119
	v_add_f32_e32 v115, 1.0, v115
	v_rcp_f32_e32 v127, v115
	v_pk_mul_f32 v[110:111], v[110:111], v[114:115] op_sel_hi:[1,0]
	v_pk_mul_f32 v[108:109], v[108:109], v[114:115] op_sel_hi:[1,0]
	v_pk_mul_f32 v[106:107], v[106:107], v[114:115] op_sel_hi:[1,0]
; __device__ __forceinline__ float silu_f(float x) { return x * __builtin_amdgcn_rcpf(1.f + __expf(-x)); }
; __device__ __forceinline__ v4u pack8(const f32x4 a, const f32x4 b) { v4u w; w.x = cvt_pk_bf16(a[0], a[1]); w.y = cvt_pk_bf16(a[2], a[3]); w.z = cvt_pk_bf16(b[0], b[1]); w.w = cvt_pk_bf16(b[2], b[3]); return w; }
; __device__ __forceinline__ float row_rstd(const float* ssq, int row, int fq) {
;     const f32x4 v = *(const f32x4*)(ssq + (size_t)row * 16 + fq * 4);
;     float s = (v[0] + v[1]) + (v[2] + v[3]);
;     s += __shfl_xor(s, 16); s += __shfl_xor(s, 32);
;     return __builtin_amdgcn_rsqf(s * (1.f / DM) + EPS);
; }
;     __device__ __forceinline__ void operator()(const f32x4 (&acc)[2][2][4][2], const pg8::Unit& u, int wr, int wc, int fr, int fq) const {
;     ...
;         if (grp == 0) { WIN_LOOP( _Pragma("unroll") for (int i = 0; i < 4; ++i) { a[i] = silu_f(a[i]); b[i] = silu_f(b[i]); } *(v4u*)(QO + (size_t)row * DM + c) = pack8(a, b); ) }
	v_pk_mul_f32 v[114:115], v[104:105], v[114:115] op_sel_hi:[1,0]
	v_pk_mul_f32 v[120:121], v[120:121], v[126:127]
	v_mul_f32_e32 v105, 0xbfb8aa3b, v114
	v_exp_f32_e32 v105, v105
	v_cvt_pk_bf16_f32 v117, v124, v125
	v_cvt_pk_bf16_f32 v118, v122, v123
	v_cvt_pk_bf16_f32 v119, v120, v121
	v_add_f32_e32 v105, 1.0, v105
	global_store_dwordx4 v[112:113], v[116:119], off
	v_mul_f32_e32 v104, 0xbfb8aa3b, v108
	v_exp_f32_e32 v104, v104
	v_rcp_f32_e32 v116, v105
	v_mul_f32_e32 v105, 0xbfb8aa3b, v109
	v_exp_f32_e32 v105, v105
	v_add_f32_e32 v104, 1.0, v104
	v_rcp_f32_e32 v104, v104
	v_add_f32_e32 v105, 1.0, v105
	v_rcp_f32_e32 v105, v105
	s_nop 0
	v_pk_mul_f32 v[104:105], v[108:109], v[104:105]
	v_mul_f32_e32 v108, 0xbfb8aa3b, v115
	v_exp_f32_e32 v108, v108
	v_cvt_pk_bf16_f32 v104, v104, v105
	v_add_f32_e32 v108, 1.0, v108
	v_rcp_f32_e32 v117, v108
	s_nop 0
	v_pk_mul_f32 v[108:109], v[114:115], v[116:117]
	v_mul_f32_e32 v114, 0xbfb8aa3b, v110
	v_mul_f32_e32 v115, 0xbfb8aa3b, v111
	v_exp_f32_e32 v114, v114
	v_exp_f32_e32 v115, v115
	v_add_f32_e32 v114, 1.0, v114
	v_add_f32_e32 v115, 1.0, v115
	v_rcp_f32_e32 v116, v114
	v_mul_f32_e32 v114, 0xbfb8aa3b, v106
	v_rcp_f32_e32 v117, v115
	v_mul_f32_e32 v115, 0xbfb8aa3b, v107
	v_exp_f32_e32 v114, v114
	v_exp_f32_e32 v115, v115
	v_pk_mul_f32 v[110:111], v[110:111], v[116:117]
	v_add_f32_e32 v114, 1.0, v114
	v_add_f32_e32 v115, 1.0, v115
	v_rcp_f32_e32 v114, v114
	v_rcp_f32_e32 v115, v115
	v_cvt_pk_bf16_f32 v105, v110, v111
	v_pk_mul_f32 v[114:115], v[106:107], v[114:115]
	v_cvt_pk_bf16_f32 v106, v108, v109
	v_or_b32_e32 v108, 48, v166
	v_cvt_pk_bf16_f32 v107, v114, v115
	v_ashrrev_i32_e32 v109, 31, v108
	global_store_dwordx4 v[112:113], v[104:107], off offset:256
	s_nop 1
	v_lshlrev_b64 v[104:105], 6, v[108:109]
	v_lshl_add_u64 v[104:105], v[160:161], 0, v[104:105]
	s_nop 0
	s_waitcnt lgkmcnt(0)
	s_nop 0
	s_nop 0
	s_nop 0
	s_nop 0
	s_nop 0
	s_nop 0
	s_nop 0
	s_waitcnt lgkmcnt(0)
	s_nop 0
	s_nop 0
	s_waitcnt lgkmcnt(0)
	s_nop 0
	s_nop 0
	v_mov_b32_e32 v110, v253
	v_lshlrev_b64 v[104:105], 11, v[108:109]
	v_lshl_add_u64 v[108:109], s[44:45], 0, v[104:105]
	v_lshl_add_u64 v[108:109], v[108:109], 0, v[192:193]
	v_pk_mul_f32 v[106:107], v[36:37], v[110:111] op_sel_hi:[1,0]
	v_pk_mul_f32 v[104:105], v[38:39], v[110:111] op_sel_hi:[1,0]
	v_pk_mul_f32 v[112:113], v[34:35], v[110:111] op_sel_hi:[1,0]
	v_pk_mul_f32 v[114:115], v[32:33], v[110:111] op_sel_hi:[1,0]
	v_mul_f32_e32 v111, 0xbfb8aa3b, v106
	v_exp_f32_e32 v111, v111
	s_nop 0
	v_add_f32_e32 v111, 1.0, v111
	v_rcp_f32_e32 v116, v111
	v_mul_f32_e32 v111, 0xbfb8aa3b, v114
	v_exp_f32_e32 v111, v111
	s_nop 0
	v_add_f32_e32 v111, 1.0, v111
	v_rcp_f32_e32 v118, v111
	v_mul_f32_e32 v111, 0xbfb8aa3b, v107
	v_exp_f32_e32 v111, v111
	s_nop 0
	v_add_f32_e32 v111, 1.0, v111
	v_rcp_f32_e32 v117, v111
	v_mul_f32_e32 v111, 0xbfb8aa3b, v115
	v_exp_f32_e32 v111, v111
	v_pk_mul_f32 v[106:107], v[106:107], v[116:117]
	v_add_f32_e32 v111, 1.0, v111
	v_rcp_f32_e32 v119, v111
	v_mul_f32_e32 v111, 0xbfb8aa3b, v104
	v_exp_f32_e32 v111, v111
	v_pk_mul_f32 v[114:115], v[114:115], v[118:119]
	v_add_f32_e32 v111, 1.0, v111
	v_rcp_f32_e32 v116, v111
	v_mul_f32_e32 v111, 0xbfb8aa3b, v112
	v_exp_f32_e32 v111, v111
	s_nop 0
	v_add_f32_e32 v111, 1.0, v111
	v_rcp_f32_e32 v118, v111
	v_mul_f32_e32 v111, 0xbfb8aa3b, v105
	v_exp_f32_e32 v111, v111
	s_nop 0
	v_add_f32_e32 v111, 1.0, v111
	v_rcp_f32_e32 v117, v111
	v_pk_mul_f32 v[96:97], v[96:97], v[110:111] op_sel_hi:[1,0]
	v_pk_mul_f32 v[100:101], v[100:101], v[110:111] op_sel_hi:[1,0]
	v_pk_mul_f32 v[98:99], v[98:99], v[110:111] op_sel_hi:[1,0]
	v_pk_mul_f32 v[116:117], v[104:105], v[116:117]
	v_mul_f32_e32 v104, 0xbfb8aa3b, v113
	v_exp_f32_e32 v104, v104
	v_cvt_pk_bf16_f32 v105, v116, v117
	v_pk_mul_f32 v[102:103], v[102:103], v[110:111] op_sel_hi:[1,0]
	v_add_f32_e32 v104, 1.0, v104
	v_rcp_f32_e32 v119, v104
	v_cvt_pk_bf16_f32 v104, v106, v107
	v_cvt_pk_bf16_f32 v106, v114, v115
	v_pk_mul_f32 v[112:113], v[112:113], v[118:119]
	s_nop 0
	v_cvt_pk_bf16_f32 v107, v112, v113
	global_store_dwordx4 v[108:109], v[104:107], off
	s_nop 1
	v_mul_f32_e32 v105, 0xbfb8aa3b, v96
	v_exp_f32_e32 v105, v105
	v_mul_f32_e32 v104, 0xbfb8aa3b, v100
	v_exp_f32_e32 v104, v104
	v_add_f32_e32 v105, 1.0, v105
	v_rcp_f32_e32 v106, v105
	v_mul_f32_e32 v105, 0xbfb8aa3b, v101
	v_exp_f32_e32 v105, v105
	v_add_f32_e32 v104, 1.0, v104
	v_rcp_f32_e32 v104, v104
	v_add_f32_e32 v105, 1.0, v105
	v_rcp_f32_e32 v105, v105
	s_nop 0
	v_pk_mul_f32 v[100:101], v[100:101], v[104:105]
	v_mul_f32_e32 v104, 0xbfb8aa3b, v97
	v_exp_f32_e32 v104, v104
	s_nop 0
	v_add_f32_e32 v104, 1.0, v104
	v_rcp_f32_e32 v107, v104
	s_nop 0
	v_pk_mul_f32 v[104:105], v[96:97], v[106:107]
	v_mul_f32_e32 v97, 0xbfb8aa3b, v98
	v_exp_f32_e32 v97, v97
	v_mul_f32_e32 v96, 0xbfb8aa3b, v102
	v_exp_f32_e32 v96, v96
	v_add_f32_e32 v97, 1.0, v97
	v_rcp_f32_e32 v106, v97
	v_mul_f32_e32 v97, 0xbfb8aa3b, v103
	v_exp_f32_e32 v97, v97
	v_add_f32_e32 v96, 1.0, v96
	v_rcp_f32_e32 v96, v96
	v_add_f32_e32 v97, 1.0, v97
	v_rcp_f32_e32 v97, v97
	s_nop 0
	v_pk_mul_f32 v[102:103], v[102:103], v[96:97]
	v_mul_f32_e32 v96, 0xbfb8aa3b, v99
	v_exp_f32_e32 v96, v96
	v_cvt_pk_bf16_f32 v97, v102, v103
	v_add_f32_e32 v96, 1.0, v96
	v_rcp_f32_e32 v107, v96
	v_cvt_pk_bf16_f32 v96, v100, v101
	v_add_u32_e32 v100, 0x80, v166
	v_ashrrev_i32_e32 v101, 31, v100
	v_pk_mul_f32 v[106:107], v[98:99], v[106:107]
	v_cvt_pk_bf16_f32 v98, v104, v105
	v_cvt_pk_bf16_f32 v99, v106, v107
	global_store_dwordx4 v[108:109], v[96:99], off offset:256
	s_nop 1
	v_lshlrev_b64 v[96:97], 6, v[100:101]
	v_lshl_add_u64 v[96:97], v[160:161], 0, v[96:97]
	s_nop 0
	s_waitcnt lgkmcnt(0)
; __device__ __forceinline__ float silu_f(float x) { return x * __builtin_amdgcn_rcpf(1.f + __expf(-x)); }
; __device__ __forceinline__ v4u pack8(const f32x4 a, const f32x4 b) { v4u w; w.x = cvt_pk_bf16(a[0], a[1]); w.y = cvt_pk_bf16(a[2], a[3]); w.z = cvt_pk_bf16(b[0], b[1]); w.w = cvt_pk_bf16(b[2], b[3]); return w; }
; __device__ __forceinline__ float row_rstd(const float* ssq, int row, int fq) {
;     const f32x4 v = *(const f32x4*)(ssq + (size_t)row * 16 + fq * 4);
;     float s = (v[0] + v[1]) + (v[2] + v[3]);
;     s += __shfl_xor(s, 16); s += __shfl_xor(s, 32);
;     return __builtin_amdgcn_rsqf(s * (1.f / DM) + EPS);
; }
;     __device__ __forceinline__ void operator()(const f32x4 (&acc)[2][2][4][2], const pg8::Unit& u, int wr, int wc, int fr, int fq) const {
;     ...
;         if (grp == 0) { WIN_LOOP( _Pragma("unroll") for (int i = 0; i < 4; ++i) { a[i] = silu_f(a[i]); b[i] = silu_f(b[i]); } *(v4u*)(QO + (size_t)row * DM + c) = pack8(a, b); ) }
	s_nop 0
	s_nop 0
	s_nop 0
	s_nop 0
	s_nop 0
	s_nop 0
	s_nop 0
	s_waitcnt lgkmcnt(0)
	s_nop 0
	s_nop 0
	s_waitcnt lgkmcnt(0)
	s_nop 0
	s_nop 0
	v_mov_b32_e32 v102, v254
	v_lshlrev_b64 v[96:97], 11, v[100:101]
	v_lshl_add_u64 v[100:101], s[44:45], 0, v[96:97]
	v_lshl_add_u64 v[100:101], v[100:101], 0, v[192:193]
	v_pk_mul_f32 v[98:99], v[28:29], v[102:103] op_sel_hi:[1,0]
	v_pk_mul_f32 v[96:97], v[30:31], v[102:103] op_sel_hi:[1,0]
	v_pk_mul_f32 v[104:105], v[26:27], v[102:103] op_sel_hi:[1,0]
	v_pk_mul_f32 v[106:107], v[24:25], v[102:103] op_sel_hi:[1,0]
	v_mul_f32_e32 v103, 0xbfb8aa3b, v98
	v_exp_f32_e32 v103, v103
	s_nop 0
	v_add_f32_e32 v103, 1.0, v103
	v_rcp_f32_e32 v108, v103
	v_mul_f32_e32 v103, 0xbfb8aa3b, v106
	v_exp_f32_e32 v103, v103
	s_nop 0
	v_add_f32_e32 v103, 1.0, v103
	v_rcp_f32_e32 v110, v103
	v_mul_f32_e32 v103, 0xbfb8aa3b, v99
	v_exp_f32_e32 v103, v103
	s_nop 0
	v_add_f32_e32 v103, 1.0, v103
	v_rcp_f32_e32 v109, v103
	v_mul_f32_e32 v103, 0xbfb8aa3b, v107
	v_exp_f32_e32 v103, v103
	v_pk_mul_f32 v[98:99], v[98:99], v[108:109]
	v_add_f32_e32 v103, 1.0, v103
	v_rcp_f32_e32 v111, v103
	v_mul_f32_e32 v103, 0xbfb8aa3b, v96
	v_exp_f32_e32 v103, v103
	v_pk_mul_f32 v[106:107], v[106:107], v[110:111]
	v_add_f32_e32 v103, 1.0, v103
	v_rcp_f32_e32 v108, v103
	v_mul_f32_e32 v103, 0xbfb8aa3b, v104
	v_exp_f32_e32 v103, v103
	s_nop 0
	v_add_f32_e32 v103, 1.0, v103
	v_rcp_f32_e32 v110, v103
	v_mul_f32_e32 v103, 0xbfb8aa3b, v97
	v_exp_f32_e32 v103, v103
	s_nop 0
	v_add_f32_e32 v103, 1.0, v103
	v_rcp_f32_e32 v109, v103
	v_pk_mul_f32 v[88:89], v[88:89], v[102:103] op_sel_hi:[1,0]
	v_pk_mul_f32 v[92:93], v[92:93], v[102:103] op_sel_hi:[1,0]
	v_pk_mul_f32 v[90:91], v[90:91], v[102:103] op_sel_hi:[1,0]
	v_pk_mul_f32 v[108:109], v[96:97], v[108:109]
	v_mul_f32_e32 v96, 0xbfb8aa3b, v105
	v_exp_f32_e32 v96, v96
	v_cvt_pk_bf16_f32 v97, v108, v109
	v_pk_mul_f32 v[94:95], v[94:95], v[102:103] op_sel_hi:[1,0]
	v_add_f32_e32 v96, 1.0, v96
	v_rcp_f32_e32 v111, v96
	v_cvt_pk_bf16_f32 v96, v98, v99
	v_cvt_pk_bf16_f32 v98, v106, v107
	v_pk_mul_f32 v[104:105], v[104:105], v[110:111]
	s_nop 0
	v_cvt_pk_bf16_f32 v99, v104, v105
	global_store_dwordx4 v[100:101], v[96:99], off
	s_nop 1
	v_mul_f32_e32 v97, 0xbfb8aa3b, v88
	v_exp_f32_e32 v97, v97
	v_mul_f32_e32 v96, 0xbfb8aa3b, v92
	v_exp_f32_e32 v96, v96
	v_add_f32_e32 v97, 1.0, v97
	v_rcp_f32_e32 v98, v97
	v_mul_f32_e32 v97, 0xbfb8aa3b, v93
	v_exp_f32_e32 v97, v97
	v_add_f32_e32 v96, 1.0, v96
	v_rcp_f32_e32 v96, v96
	v_add_f32_e32 v97, 1.0, v97
	v_rcp_f32_e32 v97, v97
	s_nop 0
	v_pk_mul_f32 v[92:93], v[92:93], v[96:97]
	v_mul_f32_e32 v96, 0xbfb8aa3b, v89
	v_exp_f32_e32 v96, v96
	s_nop 0
	v_add_f32_e32 v96, 1.0, v96
	v_rcp_f32_e32 v99, v96
	s_nop 0
	v_pk_mul_f32 v[96:97], v[88:89], v[98:99]
	v_mul_f32_e32 v89, 0xbfb8aa3b, v90
	v_exp_f32_e32 v89, v89
	v_mul_f32_e32 v88, 0xbfb8aa3b, v94
	v_exp_f32_e32 v88, v88
	v_add_f32_e32 v89, 1.0, v89
	v_rcp_f32_e32 v98, v89
	v_mul_f32_e32 v89, 0xbfb8aa3b, v95
	v_exp_f32_e32 v89, v89
	v_add_f32_e32 v88, 1.0, v88
	v_rcp_f32_e32 v88, v88
	v_add_f32_e32 v89, 1.0, v89
	v_rcp_f32_e32 v89, v89
	s_nop 0
	v_pk_mul_f32 v[94:95], v[94:95], v[88:89]
	v_mul_f32_e32 v88, 0xbfb8aa3b, v91
	v_exp_f32_e32 v88, v88
	v_cvt_pk_bf16_f32 v89, v94, v95
	v_add_f32_e32 v88, 1.0, v88
	v_rcp_f32_e32 v99, v88
	v_cvt_pk_bf16_f32 v88, v92, v93
	v_add_u32_e32 v92, 0x90, v166
	v_ashrrev_i32_e32 v93, 31, v92
	v_pk_mul_f32 v[98:99], v[90:91], v[98:99]
	v_cvt_pk_bf16_f32 v90, v96, v97
	v_cvt_pk_bf16_f32 v91, v98, v99
	global_store_dwordx4 v[100:101], v[88:91], off offset:256
	s_nop 1
	v_lshlrev_b64 v[88:89], 6, v[92:93]
	v_lshl_add_u64 v[88:89], v[160:161], 0, v[88:89]
	s_nop 0
	s_waitcnt lgkmcnt(0)
	s_nop 0
	s_nop 0
	s_nop 0
	s_nop 0
	s_nop 0
	s_nop 0
	s_nop 0
	s_waitcnt lgkmcnt(0)
	s_nop 0
	s_nop 0
	s_waitcnt lgkmcnt(0)
	s_nop 0
	s_nop 0
	v_mov_b32_e32 v94, v240
	v_lshlrev_b64 v[88:89], 11, v[92:93]
	v_lshl_add_u64 v[92:93], s[44:45], 0, v[88:89]
	v_lshl_add_u64 v[92:93], v[92:93], 0, v[192:193]
	v_pk_mul_f32 v[90:91], v[20:21], v[94:95] op_sel_hi:[1,0]
	v_pk_mul_f32 v[88:89], v[22:23], v[94:95] op_sel_hi:[1,0]
	v_pk_mul_f32 v[96:97], v[18:19], v[94:95] op_sel_hi:[1,0]
	v_pk_mul_f32 v[98:99], v[16:17], v[94:95] op_sel_hi:[1,0]
	v_mul_f32_e32 v95, 0xbfb8aa3b, v90
	v_exp_f32_e32 v95, v95
	s_nop 0
	v_add_f32_e32 v95, 1.0, v95
	v_rcp_f32_e32 v100, v95
	v_mul_f32_e32 v95, 0xbfb8aa3b, v98
	v_exp_f32_e32 v95, v95
	s_nop 0
	v_add_f32_e32 v95, 1.0, v95
	v_rcp_f32_e32 v102, v95
	v_mul_f32_e32 v95, 0xbfb8aa3b, v91
	v_exp_f32_e32 v95, v95
	s_nop 0
	v_add_f32_e32 v95, 1.0, v95
	v_rcp_f32_e32 v101, v95
	v_mul_f32_e32 v95, 0xbfb8aa3b, v99
	v_exp_f32_e32 v95, v95
	v_pk_mul_f32 v[90:91], v[90:91], v[100:101]
	v_add_f32_e32 v95, 1.0, v95
	v_rcp_f32_e32 v103, v95
	v_mul_f32_e32 v95, 0xbfb8aa3b, v88
	v_exp_f32_e32 v95, v95
	v_pk_mul_f32 v[98:99], v[98:99], v[102:103]
	v_add_f32_e32 v95, 1.0, v95
	v_rcp_f32_e32 v100, v95
	v_mul_f32_e32 v95, 0xbfb8aa3b, v96
	v_exp_f32_e32 v95, v95
	s_nop 0
	v_add_f32_e32 v95, 1.0, v95
	v_rcp_f32_e32 v102, v95
	v_mul_f32_e32 v95, 0xbfb8aa3b, v89
	v_exp_f32_e32 v95, v95
	s_nop 0
	v_add_f32_e32 v95, 1.0, v95
	v_rcp_f32_e32 v101, v95
	v_pk_mul_f32 v[80:81], v[80:81], v[94:95] op_sel_hi:[1,0]
	v_pk_mul_f32 v[84:85], v[84:85], v[94:95] op_sel_hi:[1,0]
	v_pk_mul_f32 v[82:83], v[82:83], v[94:95] op_sel_hi:[1,0]
	v_pk_mul_f32 v[100:101], v[88:89], v[100:101]
	v_mul_f32_e32 v88, 0xbfb8aa3b, v97
	v_exp_f32_e32 v88, v88
	v_cvt_pk_bf16_f32 v89, v100, v101
	v_pk_mul_f32 v[86:87], v[86:87], v[94:95] op_sel_hi:[1,0]
	v_add_f32_e32 v88, 1.0, v88
	v_rcp_f32_e32 v103, v88
	v_cvt_pk_bf16_f32 v88, v90, v91
; __device__ __forceinline__ float silu_f(float x) { return x * __builtin_amdgcn_rcpf(1.f + __expf(-x)); }
; __device__ __forceinline__ v4u pack8(const f32x4 a, const f32x4 b) { v4u w; w.x = cvt_pk_bf16(a[0], a[1]); w.y = cvt_pk_bf16(a[2], a[3]); w.z = cvt_pk_bf16(b[0], b[1]); w.w = cvt_pk_bf16(b[2], b[3]); return w; }
; __device__ __forceinline__ float row_rstd(const float* ssq, int row, int fq) {
;     const f32x4 v = *(const f32x4*)(ssq + (size_t)row * 16 + fq * 4);
;     float s = (v[0] + v[1]) + (v[2] + v[3]);
;     s += __shfl_xor(s, 16); s += __shfl_xor(s, 32);
;     return __builtin_amdgcn_rsqf(s * (1.f / DM) + EPS);
; }
;     __device__ __forceinline__ void operator()(const f32x4 (&acc)[2][2][4][2], const pg8::Unit& u, int wr, int wc, int fr, int fq) const {
;     ...
;         if (grp == 0) { WIN_LOOP( _Pragma("unroll") for (int i = 0; i < 4; ++i) { a[i] = silu_f(a[i]); b[i] = silu_f(b[i]); } *(v4u*)(QO + (size_t)row * DM + c) = pack8(a, b); ) }
	v_cvt_pk_bf16_f32 v90, v98, v99
	v_pk_mul_f32 v[96:97], v[96:97], v[102:103]
	s_nop 0
	v_cvt_pk_bf16_f32 v91, v96, v97
	global_store_dwordx4 v[92:93], v[88:91], off
	s_nop 1
	v_mul_f32_e32 v89, 0xbfb8aa3b, v80
	v_exp_f32_e32 v89, v89
	v_mul_f32_e32 v88, 0xbfb8aa3b, v84
	v_exp_f32_e32 v88, v88
	v_add_f32_e32 v89, 1.0, v89
	v_rcp_f32_e32 v90, v89
	v_mul_f32_e32 v89, 0xbfb8aa3b, v85
	v_exp_f32_e32 v89, v89
	v_add_f32_e32 v88, 1.0, v88
	v_rcp_f32_e32 v88, v88
	v_add_f32_e32 v89, 1.0, v89
	v_rcp_f32_e32 v89, v89
	s_nop 0
	v_pk_mul_f32 v[84:85], v[84:85], v[88:89]
	v_mul_f32_e32 v88, 0xbfb8aa3b, v81
	v_exp_f32_e32 v88, v88
	s_nop 0
	v_add_f32_e32 v88, 1.0, v88
	v_rcp_f32_e32 v91, v88
	s_nop 0
	v_pk_mul_f32 v[88:89], v[80:81], v[90:91]
	v_mul_f32_e32 v81, 0xbfb8aa3b, v82
	v_exp_f32_e32 v81, v81
	v_mul_f32_e32 v80, 0xbfb8aa3b, v86
	v_exp_f32_e32 v80, v80
	v_add_f32_e32 v81, 1.0, v81
	v_rcp_f32_e32 v90, v81
	v_mul_f32_e32 v81, 0xbfb8aa3b, v87
	v_exp_f32_e32 v81, v81
	v_add_f32_e32 v80, 1.0, v80
	v_rcp_f32_e32 v80, v80
	v_add_f32_e32 v81, 1.0, v81
	v_rcp_f32_e32 v81, v81
	s_nop 0
	v_pk_mul_f32 v[86:87], v[86:87], v[80:81]
	v_mul_f32_e32 v80, 0xbfb8aa3b, v83
	v_exp_f32_e32 v80, v80
	v_cvt_pk_bf16_f32 v81, v86, v87
	v_add_f32_e32 v80, 1.0, v80
	v_rcp_f32_e32 v91, v80
	v_cvt_pk_bf16_f32 v80, v84, v85
	v_add_u32_e32 v84, 0xa0, v166
	v_ashrrev_i32_e32 v85, 31, v84
	v_pk_mul_f32 v[90:91], v[82:83], v[90:91]
	v_cvt_pk_bf16_f32 v82, v88, v89
	v_cvt_pk_bf16_f32 v83, v90, v91
	global_store_dwordx4 v[92:93], v[80:83], off offset:256
	s_nop 1
	v_lshlrev_b64 v[80:81], 6, v[84:85]
	v_lshl_add_u64 v[80:81], v[160:161], 0, v[80:81]
	s_nop 0
	s_waitcnt lgkmcnt(0)
	s_nop 0
	s_nop 0
	s_nop 0
	s_nop 0
	s_nop 0
	s_nop 0
	s_nop 0
	s_waitcnt lgkmcnt(0)
	s_nop 0
	s_nop 0
	s_waitcnt lgkmcnt(0)
	s_nop 0
	s_nop 0
	v_mov_b32_e32 v86, v241
	v_lshlrev_b64 v[80:81], 11, v[84:85]
	v_lshl_add_u64 v[84:85], s[44:45], 0, v[80:81]
	v_lshl_add_u64 v[84:85], v[84:85], 0, v[192:193]
	v_pk_mul_f32 v[82:83], v[12:13], v[86:87] op_sel_hi:[1,0]
	v_pk_mul_f32 v[80:81], v[14:15], v[86:87] op_sel_hi:[1,0]
	v_pk_mul_f32 v[88:89], v[10:11], v[86:87] op_sel_hi:[1,0]
	v_pk_mul_f32 v[90:91], v[8:9], v[86:87] op_sel_hi:[1,0]
	v_mul_f32_e32 v87, 0xbfb8aa3b, v82
	v_exp_f32_e32 v87, v87
	s_nop 0
	v_add_f32_e32 v87, 1.0, v87
	v_rcp_f32_e32 v92, v87
	v_mul_f32_e32 v87, 0xbfb8aa3b, v90
	v_exp_f32_e32 v87, v87
	s_nop 0
	v_add_f32_e32 v87, 1.0, v87
	v_rcp_f32_e32 v94, v87
	v_mul_f32_e32 v87, 0xbfb8aa3b, v83
	v_exp_f32_e32 v87, v87
	s_nop 0
	v_add_f32_e32 v87, 1.0, v87
	v_rcp_f32_e32 v93, v87
	v_mul_f32_e32 v87, 0xbfb8aa3b, v91
	v_exp_f32_e32 v87, v87
	v_pk_mul_f32 v[82:83], v[82:83], v[92:93]
	v_add_f32_e32 v87, 1.0, v87
	v_rcp_f32_e32 v95, v87
	v_mul_f32_e32 v87, 0xbfb8aa3b, v80
	v_exp_f32_e32 v87, v87
	v_pk_mul_f32 v[90:91], v[90:91], v[94:95]
	v_add_f32_e32 v87, 1.0, v87
	v_rcp_f32_e32 v92, v87
	v_mul_f32_e32 v87, 0xbfb8aa3b, v88
	v_exp_f32_e32 v87, v87
	s_nop 0
	v_add_f32_e32 v87, 1.0, v87
	v_rcp_f32_e32 v94, v87
	v_mul_f32_e32 v87, 0xbfb8aa3b, v81
	v_exp_f32_e32 v87, v87
	s_nop 0
	v_add_f32_e32 v87, 1.0, v87
	v_rcp_f32_e32 v93, v87
	v_pk_mul_f32 v[72:73], v[72:73], v[86:87] op_sel_hi:[1,0]
	v_pk_mul_f32 v[76:77], v[76:77], v[86:87] op_sel_hi:[1,0]
	v_pk_mul_f32 v[74:75], v[74:75], v[86:87] op_sel_hi:[1,0]
	v_pk_mul_f32 v[92:93], v[80:81], v[92:93]
	v_mul_f32_e32 v80, 0xbfb8aa3b, v89
	v_exp_f32_e32 v80, v80
	v_cvt_pk_bf16_f32 v81, v92, v93
	v_pk_mul_f32 v[78:79], v[78:79], v[86:87] op_sel_hi:[1,0]
	v_add_f32_e32 v80, 1.0, v80
	v_rcp_f32_e32 v95, v80
	v_cvt_pk_bf16_f32 v80, v82, v83
	v_cvt_pk_bf16_f32 v82, v90, v91
	v_pk_mul_f32 v[88:89], v[88:89], v[94:95]
	s_nop 0
	v_cvt_pk_bf16_f32 v83, v88, v89
	global_store_dwordx4 v[84:85], v[80:83], off
	s_nop 1
	v_mul_f32_e32 v81, 0xbfb8aa3b, v72
	v_exp_f32_e32 v81, v81
	v_mul_f32_e32 v80, 0xbfb8aa3b, v76
	v_exp_f32_e32 v80, v80
	v_add_f32_e32 v81, 1.0, v81
	v_rcp_f32_e32 v82, v81
	v_mul_f32_e32 v81, 0xbfb8aa3b, v77
	v_exp_f32_e32 v81, v81
	v_add_f32_e32 v80, 1.0, v80
	v_rcp_f32_e32 v80, v80
	v_add_f32_e32 v81, 1.0, v81
	v_rcp_f32_e32 v81, v81
	s_nop 0
	v_pk_mul_f32 v[76:77], v[76:77], v[80:81]
	v_mul_f32_e32 v80, 0xbfb8aa3b, v73
	v_exp_f32_e32 v80, v80
	s_nop 0
	v_add_f32_e32 v80, 1.0, v80
	v_rcp_f32_e32 v83, v80
	s_nop 0
	v_pk_mul_f32 v[80:81], v[72:73], v[82:83]
	v_mul_f32_e32 v73, 0xbfb8aa3b, v74
	v_exp_f32_e32 v73, v73
	v_mul_f32_e32 v72, 0xbfb8aa3b, v78
	v_exp_f32_e32 v72, v72
	v_add_f32_e32 v73, 1.0, v73
	v_rcp_f32_e32 v82, v73
	v_mul_f32_e32 v73, 0xbfb8aa3b, v79
	v_exp_f32_e32 v73, v73
	v_add_f32_e32 v72, 1.0, v72
	v_rcp_f32_e32 v72, v72
	v_add_f32_e32 v73, 1.0, v73
	v_rcp_f32_e32 v73, v73
	s_nop 0
	v_pk_mul_f32 v[78:79], v[78:79], v[72:73]
	v_mul_f32_e32 v72, 0xbfb8aa3b, v75
	v_exp_f32_e32 v72, v72
	v_cvt_pk_bf16_f32 v73, v78, v79
	v_add_f32_e32 v72, 1.0, v72
	v_rcp_f32_e32 v83, v72
	v_cvt_pk_bf16_f32 v72, v76, v77
	v_add_u32_e32 v76, 0xb0, v166
	v_ashrrev_i32_e32 v77, 31, v76
	v_pk_mul_f32 v[82:83], v[74:75], v[82:83]
	v_cvt_pk_bf16_f32 v74, v80, v81
	v_cvt_pk_bf16_f32 v75, v82, v83
	global_store_dwordx4 v[84:85], v[72:75], off offset:256
	s_nop 1
	v_lshlrev_b64 v[72:73], 6, v[76:77]
	v_lshl_add_u64 v[72:73], v[160:161], 0, v[72:73]
	s_nop 0
	s_waitcnt lgkmcnt(0)
; __device__ __forceinline__ float silu_f(float x) { return x * __builtin_amdgcn_rcpf(1.f + __expf(-x)); }
; __device__ __forceinline__ v4u pack8(const f32x4 a, const f32x4 b) { v4u w; w.x = cvt_pk_bf16(a[0], a[1]); w.y = cvt_pk_bf16(a[2], a[3]); w.z = cvt_pk_bf16(b[0], b[1]); w.w = cvt_pk_bf16(b[2], b[3]); return w; }
; __device__ __forceinline__ float row_rstd(const float* ssq, int row, int fq) {
;     const f32x4 v = *(const f32x4*)(ssq + (size_t)row * 16 + fq * 4);
;     float s = (v[0] + v[1]) + (v[2] + v[3]);
;     s += __shfl_xor(s, 16); s += __shfl_xor(s, 32);
;     return __builtin_amdgcn_rsqf(s * (1.f / DM) + EPS);
; }
;     __device__ __forceinline__ void operator()(const f32x4 (&acc)[2][2][4][2], const pg8::Unit& u, int wr, int wc, int fr, int fq) const {
;     ...
;         if (grp == 0) { WIN_LOOP( _Pragma("unroll") for (int i = 0; i < 4; ++i) { a[i] = silu_f(a[i]); b[i] = silu_f(b[i]); } *(v4u*)(QO + (size_t)row * DM + c) = pack8(a, b); ) }
	s_nop 0
	s_nop 0
	s_nop 0
	s_nop 0
	s_nop 0
	s_nop 0
	s_nop 0
	s_waitcnt lgkmcnt(0)
	s_nop 0
	s_nop 0
	s_waitcnt lgkmcnt(0)
	s_nop 0
	s_nop 0
	v_mov_b32_e32 v78, v245
	v_lshlrev_b64 v[72:73], 11, v[76:77]
	v_lshl_add_u64 v[76:77], s[44:45], 0, v[72:73]
	v_lshl_add_u64 v[76:77], v[76:77], 0, v[192:193]
	v_pk_mul_f32 v[74:75], v[4:5], v[78:79] op_sel_hi:[1,0]
	v_pk_mul_f32 v[72:73], v[6:7], v[78:79] op_sel_hi:[1,0]
	v_pk_mul_f32 v[80:81], v[2:3], v[78:79] op_sel_hi:[1,0]
	v_pk_mul_f32 v[82:83], v[0:1], v[78:79] op_sel_hi:[1,0]
	v_mul_f32_e32 v79, 0xbfb8aa3b, v74
	v_exp_f32_e32 v79, v79
	s_nop 0
	v_add_f32_e32 v79, 1.0, v79
	v_rcp_f32_e32 v84, v79
	v_mul_f32_e32 v79, 0xbfb8aa3b, v82
	v_exp_f32_e32 v79, v79
	s_nop 0
	v_add_f32_e32 v79, 1.0, v79
	v_rcp_f32_e32 v86, v79
	v_mul_f32_e32 v79, 0xbfb8aa3b, v75
	v_exp_f32_e32 v79, v79
	s_nop 0
	v_add_f32_e32 v79, 1.0, v79
	v_rcp_f32_e32 v85, v79
	v_mul_f32_e32 v79, 0xbfb8aa3b, v83
	v_exp_f32_e32 v79, v79
	v_pk_mul_f32 v[74:75], v[74:75], v[84:85]
	v_add_f32_e32 v79, 1.0, v79
	v_rcp_f32_e32 v87, v79
	v_mul_f32_e32 v79, 0xbfb8aa3b, v72
	v_exp_f32_e32 v79, v79
	v_pk_mul_f32 v[82:83], v[82:83], v[86:87]
	v_add_f32_e32 v79, 1.0, v79
	v_rcp_f32_e32 v84, v79
	v_mul_f32_e32 v79, 0xbfb8aa3b, v80
	v_exp_f32_e32 v79, v79
	s_nop 0
	v_add_f32_e32 v79, 1.0, v79
	v_rcp_f32_e32 v86, v79
	v_mul_f32_e32 v79, 0xbfb8aa3b, v73
	v_exp_f32_e32 v79, v79
	s_nop 0
	v_add_f32_e32 v79, 1.0, v79
	v_rcp_f32_e32 v85, v79
	v_pk_mul_f32 v[64:65], v[64:65], v[78:79] op_sel_hi:[1,0]
	v_pk_mul_f32 v[68:69], v[68:69], v[78:79] op_sel_hi:[1,0]
	v_pk_mul_f32 v[66:67], v[66:67], v[78:79] op_sel_hi:[1,0]
	v_pk_mul_f32 v[84:85], v[72:73], v[84:85]
	v_mul_f32_e32 v72, 0xbfb8aa3b, v81
	v_exp_f32_e32 v72, v72
	v_cvt_pk_bf16_f32 v73, v84, v85
	v_pk_mul_f32 v[70:71], v[70:71], v[78:79] op_sel_hi:[1,0]
	v_add_f32_e32 v72, 1.0, v72
	v_rcp_f32_e32 v87, v72
	v_cvt_pk_bf16_f32 v72, v74, v75
	v_cvt_pk_bf16_f32 v74, v82, v83
	v_pk_mul_f32 v[80:81], v[80:81], v[86:87]
	s_nop 0
	v_cvt_pk_bf16_f32 v75, v80, v81
	global_store_dwordx4 v[76:77], v[72:75], off
	s_nop 1
	v_mul_f32_e32 v73, 0xbfb8aa3b, v64
	v_exp_f32_e32 v73, v73
	v_mul_f32_e32 v72, 0xbfb8aa3b, v68
	v_exp_f32_e32 v72, v72
	v_add_f32_e32 v73, 1.0, v73
	v_rcp_f32_e32 v74, v73
	v_mul_f32_e32 v73, 0xbfb8aa3b, v69
	v_exp_f32_e32 v73, v73
	v_add_f32_e32 v72, 1.0, v72
	v_rcp_f32_e32 v72, v72
	v_add_f32_e32 v73, 1.0, v73
	v_rcp_f32_e32 v73, v73
	s_nop 0
	v_pk_mul_f32 v[68:69], v[68:69], v[72:73]
	v_mul_f32_e32 v72, 0xbfb8aa3b, v65
	v_exp_f32_e32 v72, v72
	s_nop 0
	v_add_f32_e32 v72, 1.0, v72
	v_rcp_f32_e32 v75, v72
	s_nop 0
	v_pk_mul_f32 v[72:73], v[64:65], v[74:75]
	v_mul_f32_e32 v65, 0xbfb8aa3b, v66
	v_exp_f32_e32 v65, v65
	v_mul_f32_e32 v64, 0xbfb8aa3b, v70
	v_exp_f32_e32 v64, v64
	v_add_f32_e32 v65, 1.0, v65
	v_rcp_f32_e32 v74, v65
	v_mul_f32_e32 v65, 0xbfb8aa3b, v71
	v_exp_f32_e32 v65, v65
	v_add_f32_e32 v64, 1.0, v64
	v_rcp_f32_e32 v64, v64
	v_add_f32_e32 v65, 1.0, v65
	v_rcp_f32_e32 v65, v65
	s_nop 0
	v_pk_mul_f32 v[70:71], v[70:71], v[64:65]
	v_mul_f32_e32 v64, 0xbfb8aa3b, v67
	v_exp_f32_e32 v64, v64
	v_cvt_pk_bf16_f32 v65, v70, v71
	v_add_f32_e32 v64, 1.0, v64
	v_rcp_f32_e32 v75, v64
	v_cvt_pk_bf16_f32 v64, v68, v69
	v_pk_mul_f32 v[74:75], v[66:67], v[74:75]
	v_cvt_pk_bf16_f32 v66, v72, v73
	v_cvt_pk_bf16_f32 v67, v74, v75
	global_store_dwordx4 v[76:77], v[64:67], off offset:256

; __device__ __forceinline__ float logsig_f(float x) { return fminf(x, 0.f) - __logf(1.f + __expf(-fabsf(x))); }
;     __device__ __forceinline__ void operator()(const f32x4 (&acc)[2][2][4][2], const pg8::Unit& u, int wr, int wc, int fr, int fq) const {
;     ...
;         if (pn == 14) {
;             if (wc == 0 && fq == 0) {
;                 const f32x4 fb0 = *(const f32x4*)fbias, fb1 = *(const f32x4*)(fbias + 4);
; #pragma unroll
;                 for (int ai = 0; ai < 2; ++ai)
; #pragma unroll
;                     for (int m = 0; m < 4; ++m) {
;                         const int row = row0 + ai * 128 + m * 16;
;                         const f32x4 sv = *(const f32x4*)(ssq + (size_t)row * 16), sv1 = *(const f32x4*)(ssq + (size_t)row * 16 + 4), sv2 = *(const f32x4*)(ssq + (size_t)row * 16 + 8), sv3 = *(const f32x4*)(ssq + (size_t)row * 16 + 12);
;                         const float st = ((sv[0] + sv[1]) + (sv[2] + sv[3])) + ((sv1[0] + sv1[1]) + (sv1[2] + sv1[3])) + ((sv2[0] + sv2[1]) + (sv2[2] + sv2[3])) + ((sv3[0] + sv3[1]) + (sv3[2] + sv3[3]));
;                         const float rs = __builtin_amdgcn_rsqf(st * (1.f / DM) + EPS);
;                         f32x4 a = acc[ai][0][m][0] * rs, b = acc[ai][0][m][1] * rs;
; #pragma unroll
;                         for (int i = 0; i < 4; ++i) { a[i] = logsig_f(a[i] + fb0[i]) * LOG2E; b[i] = logsig_f(b[i] + fb1[i]) * LOG2E; }
;                         *(f32x4*)(FF + (size_t)row * 8) = a; *(f32x4*)(FF + (size_t)row * 8 + 4) = b;
;                         asm volatile("" ::: "memory");
;                     }
;             }
.LBB0_420:
	s_and_saveexec_b64 s[10:11], s[38:39]
	s_cbranch_execz .LBB0_422
	v_ashrrev_i32_e32 v167, 31, v166
	v_lshlrev_b64 v[72:73], 6, v[166:167]
	v_lshl_add_u64 v[84:85], s[82:83], 0, v[72:73]
	global_load_dwordx4 v[64:67], v193, s[34:35] offset:16
	global_load_dwordx4 v[68:71], v193, s[34:35]
	flat_load_dwordx4 v[72:75], v[84:85]
	flat_load_dwordx4 v[76:79], v[84:85] offset:16
	flat_load_dwordx4 v[80:83], v[84:85] offset:32
	s_nop 0
	flat_load_dwordx4 v[84:87], v[84:85] offset:48
	s_mov_b32 s2, 0x3fb8aa3b
	s_waitcnt vmcnt(0) lgkmcnt(0)
	v_mov_b32_e32 v88, v73
	v_mov_b32_e32 v89, v74
	v_mov_b32_e32 v73, v75
	v_mov_b32_e32 v74, v77
	v_mov_b32_e32 v75, v78
	v_mov_b32_e32 v77, v79
	v_pk_add_f32 v[72:73], v[88:89], v[72:73]
	v_pk_add_f32 v[74:75], v[74:75], v[76:77]
	v_pk_add_f32 v[72:73], v[72:73], v[72:73] op_sel:[0,1] op_sel_hi:[1,0]
	v_pk_add_f32 v[74:75], v[74:75], v[74:75] op_sel:[0,1] op_sel_hi:[1,0]
	v_add_f32_e32 v76, v80, v81
	v_add_f32_e32 v78, v82, v83
	v_mov_b32_e32 v73, v84
	v_mov_b32_e32 v75, v85
	v_mov_b32_e32 v77, v86
	v_mov_b32_e32 v79, v87
	v_pk_add_f32 v[72:73], v[72:73], v[74:75]
	v_pk_add_f32 v[74:75], v[76:77], v[78:79]
	s_nop 0
	v_pk_add_f32 v[72:73], v[72:73], v[74:75]
	s_nop 0
	v_add_f32_e32 v72, v72, v73
	v_fmamk_f32 v72, v72, 0x3a800000, v212
	v_rsq_f32_e32 v72, v72
	s_nop 0
	v_pk_mul_f32 v[60:61], v[60:61], v[72:73] op_sel_hi:[1,0]
	v_pk_mul_f32 v[74:75], v[62:63], v[72:73] op_sel_hi:[1,0]
	v_pk_mul_f32 v[58:59], v[58:59], v[72:73] op_sel_hi:[1,0]
	v_pk_mul_f32 v[72:73], v[56:57], v[72:73] op_sel_hi:[1,0]
	v_add_f32_e32 v57, v68, v60
	v_min_f32_e32 v56, 0, v57
	v_mul_f32_e64 v57, |v57|, s57
	v_exp_f32_e32 v57, v57
	v_add_f32_e32 v61, v69, v61
	v_add_f32_e32 v73, v65, v73
	v_add_f32_e32 v57, 1.0, v57
	v_cmp_gt_f32_e32 vcc, s97, v57
	s_nop 1
	v_cndmask_b32_e64 v60, 0, 32, vcc
	v_ldexp_f32 v57, v57, v60
	v_log_f32_e32 v57, v57
	s_nop 0
	v_mul_f32_e32 v60, 0x3f317217, v57
	v_fma_f32 v60, v57, s52, -v60
	v_fmac_f32_e32 v60, 0x3377d1cf, v57
	v_fmac_f32_e32 v60, 0x3f317217, v57
	v_cmp_lt_f32_e64 s[8:9], |v57|, s53
	s_nop 1
	v_cndmask_b32_e64 v57, v57, v60, s[8:9]
	v_cndmask_b32_e32 v60, 0, v216, vcc
	v_sub_f32_e32 v62, v57, v60
	v_add_f32_e32 v57, v64, v72
	v_min_f32_e32 v60, 0, v57
	v_mul_f32_e64 v57, |v57|, s57
	v_exp_f32_e32 v57, v57
	s_nop 0
	v_add_f32_e32 v57, 1.0, v57
	v_cmp_gt_f32_e32 vcc, s97, v57
	s_nop 1
	v_cndmask_b32_e64 v63, 0, 32, vcc
	v_ldexp_f32 v57, v57, v63
	v_log_f32_e32 v57, v57
	s_nop 0
	v_mul_f32_e32 v63, 0x3f317217, v57
	v_fma_f32 v63, v57, s52, -v63
	v_fmac_f32_e32 v63, 0x3377d1cf, v57
	v_fmac_f32_e32 v63, 0x3f317217, v57
	v_cmp_lt_f32_e64 s[8:9], |v57|, s53
	s_nop 1
	v_cndmask_b32_e64 v57, v57, v63, s[8:9]
	v_cndmask_b32_e32 v63, 0, v216, vcc
	v_sub_f32_e32 v72, v57, v63
	v_min_f32_e32 v57, 0, v61
	v_mul_f32_e64 v61, |v61|, s57
	v_exp_f32_e32 v61, v61
	s_nop 0
	v_add_f32_e32 v61, 1.0, v61
	v_cmp_gt_f32_e32 vcc, s97, v61
	s_nop 1
	v_cndmask_b32_e64 v63, 0, 32, vcc
	v_ldexp_f32 v61, v61, v63
	v_log_f32_e32 v61, v61
	s_nop 0
	v_mul_f32_e32 v63, 0x3f317217, v61
	v_fma_f32 v63, v61, s52, -v63
	v_fmac_f32_e32 v63, 0x3377d1cf, v61
	v_fmac_f32_e32 v63, 0x3f317217, v61
	v_cmp_lt_f32_e64 s[8:9], |v61|, s53
	s_nop 1
	v_cndmask_b32_e64 v61, v61, v63, s[8:9]
	v_cndmask_b32_e32 v63, 0, v216, vcc
	v_sub_f32_e32 v63, v61, v63
	v_min_f32_e32 v61, 0, v73
	v_mul_f32_e64 v73, |v73|, s57
	v_exp_f32_e32 v73, v73
	v_pk_add_f32 v[56:57], v[56:57], v[62:63] neg_lo:[0,1] neg_hi:[0,1]
	v_add_f32_e32 v73, 1.0, v73
	v_cmp_gt_f32_e32 vcc, s97, v73
	s_nop 1
	v_cndmask_b32_e64 v76, 0, 32, vcc
	v_ldexp_f32 v73, v73, v76
	v_log_f32_e32 v73, v73
	s_nop 0
	v_mul_f32_e32 v76, 0x3f317217, v73
	v_fma_f32 v76, v73, s52, -v76
	v_fmac_f32_e32 v76, 0x3377d1cf, v73
	v_fmac_f32_e32 v76, 0x3f317217, v73
	v_cmp_lt_f32_e64 s[8:9], |v73|, s53
	s_nop 1
	v_cndmask_b32_e64 v73, v73, v76, s[8:9]
	v_cndmask_b32_e32 v76, 0, v216, vcc
	v_sub_f32_e32 v73, v73, v76
	v_add_f32_e32 v76, v70, v74
	v_min_f32_e32 v74, 0, v76
	v_mul_f32_e64 v76, |v76|, s57
	v_exp_f32_e32 v76, v76
	s_nop 0
	v_add_f32_e32 v76, 1.0, v76
	v_cmp_gt_f32_e32 vcc, s97, v76
	s_nop 1
	v_cndmask_b32_e64 v77, 0, 32, vcc
	v_ldexp_f32 v76, v76, v77
	v_log_f32_e32 v76, v76
	s_nop 0
	v_mul_f32_e32 v77, 0x3f317217, v76
	v_fma_f32 v77, v76, s52, -v77
	v_fmac_f32_e32 v77, 0x3377d1cf, v76
	v_fmac_f32_e32 v77, 0x3f317217, v76
	v_cmp_lt_f32_e64 s[8:9], |v76|, s53
	s_nop 1
	v_cndmask_b32_e64 v76, v76, v77, s[8:9]
	v_cndmask_b32_e32 v77, 0, v216, vcc
	v_sub_f32_e32 v76, v76, v77
	v_add_f32_e32 v77, v66, v58
	v_min_f32_e32 v58, 0, v77
	v_mul_f32_e64 v77, |v77|, s57
	v_exp_f32_e32 v77, v77
	s_nop 0
	v_add_f32_e32 v77, 1.0, v77
	v_cmp_gt_f32_e32 vcc, s97, v77
	s_nop 1
	v_cndmask_b32_e64 v78, 0, 32, vcc
	v_ldexp_f32 v77, v77, v78
	v_log_f32_e32 v77, v77
	s_nop 0
	v_mul_f32_e32 v78, 0x3f317217, v77
	v_fma_f32 v78, v77, s52, -v78
	v_fmac_f32_e32 v78, 0x3377d1cf, v77
	v_fmac_f32_e32 v78, 0x3f317217, v77
	v_cmp_lt_f32_e64 s[8:9], |v77|, s53
	s_nop 1
	v_cndmask_b32_e64 v77, v77, v78, s[8:9]
	v_cndmask_b32_e32 v78, 0, v216, vcc
	v_sub_f32_e32 v78, v77, v78
	v_add_f32_e32 v77, v71, v75
	v_min_f32_e32 v75, 0, v77
	v_mul_f32_e64 v77, |v77|, s57
	v_exp_f32_e32 v77, v77
	s_nop 0
	v_add_f32_e32 v77, 1.0, v77
	v_cmp_gt_f32_e32 vcc, s97, v77
	s_nop 1
	v_cndmask_b32_e64 v79, 0, 32, vcc
	v_ldexp_f32 v77, v77, v79
	v_log_f32_e32 v77, v77
	s_nop 0
	v_mul_f32_e32 v79, 0x3f317217, v77
	v_fma_f32 v79, v77, s52, -v79
	v_fmac_f32_e32 v79, 0x3377d1cf, v77
	v_fmac_f32_e32 v79, 0x3f317217, v77
	v_cmp_lt_f32_e64 s[8:9], |v77|, s53
	s_nop 1
	v_cndmask_b32_e64 v77, v77, v79, s[8:9]
	v_cndmask_b32_e32 v79, 0, v216, vcc
; __device__ __forceinline__ float logsig_f(float x) { return fminf(x, 0.f) - __logf(1.f + __expf(-fabsf(x))); }
;     __device__ __forceinline__ void operator()(const f32x4 (&acc)[2][2][4][2], const pg8::Unit& u, int wr, int wc, int fr, int fq) const {
;     ...
;                         const int row = row0 + ai * 128 + m * 16;
;                         const f32x4 sv = *(const f32x4*)(ssq + (size_t)row * 16), sv1 = *(const f32x4*)(ssq + (size_t)row * 16 + 4), sv2 = *(const f32x4*)(ssq + (size_t)row * 16 + 8), sv3 = *(const f32x4*)(ssq + (size_t)row * 16 + 12);
;                         const float st = ((sv[0] + sv[1]) + (sv[2] + sv[3])) + ((sv1[0] + sv1[1]) + (sv1[2] + sv1[3])) + ((sv2[0] + sv2[1]) + (sv2[2] + sv2[3])) + ((sv3[0] + sv3[1]) + (sv3[2] + sv3[3]));
;                         const float rs = __builtin_amdgcn_rsqf(st * (1.f / DM) + EPS);
;                         f32x4 a = acc[ai][0][m][0] * rs, b = acc[ai][0][m][1] * rs;
; #pragma unroll
;                         for (int i = 0; i < 4; ++i) { a[i] = logsig_f(a[i] + fb0[i]) * LOG2E; b[i] = logsig_f(b[i] + fb1[i]) * LOG2E; }
;                         *(f32x4*)(FF + (size_t)row * 8) = a; *(f32x4*)(FF + (size_t)row * 8 + 4) = b;
;                         asm volatile("" ::: "memory");
	v_sub_f32_e32 v77, v77, v79
	v_pk_add_f32 v[62:63], v[74:75], v[76:77] neg_lo:[0,1] neg_hi:[0,1]
	v_pk_mul_f32 v[74:75], v[56:57], s[2:3] op_sel_hi:[1,0]
	v_add_f32_e32 v56, v67, v59
	v_min_f32_e32 v59, 0, v56
	v_mul_f32_e64 v56, |v56|, s57
	v_exp_f32_e32 v56, v56
	v_pk_mul_f32 v[76:77], v[62:63], s[2:3] op_sel_hi:[1,0]
	v_add_f32_e32 v56, 1.0, v56
	v_cmp_gt_f32_e32 vcc, s97, v56
	s_nop 1
	v_cndmask_b32_e64 v57, 0, 32, vcc
	v_ldexp_f32 v56, v56, v57
	v_log_f32_e32 v56, v56
	s_nop 0
	v_mul_f32_e32 v57, 0x3f317217, v56
	v_fma_f32 v57, v56, s52, -v57
	v_fmac_f32_e32 v57, 0x3377d1cf, v56
	v_fmac_f32_e32 v57, 0x3f317217, v56
	v_cmp_lt_f32_e64 s[8:9], |v56|, s53
	s_nop 1
	v_cndmask_b32_e64 v56, v56, v57, s[8:9]
	v_cndmask_b32_e32 v57, 0, v216, vcc
	v_sub_f32_e32 v79, v56, v57
	v_pk_add_f32 v[56:57], v[60:61], v[72:73] neg_lo:[0,1] neg_hi:[0,1]
	v_lshlrev_b64 v[60:61], 5, v[166:167]
	v_pk_add_f32 v[58:59], v[58:59], v[78:79] neg_lo:[0,1] neg_hi:[0,1]
	v_pk_mul_f32 v[56:57], v[56:57], s[2:3] op_sel_hi:[1,0]
	v_lshl_add_u64 v[60:61], s[42:43], 0, v[60:61]
	v_pk_mul_f32 v[58:59], v[58:59], s[2:3] op_sel_hi:[1,0]
	global_store_dwordx4 v[60:61], v[74:77], off
	global_store_dwordx4 v[60:61], v[56:59], off offset:16
	s_nop 1
	v_or_b32_e32 v56, 16, v166
	v_ashrrev_i32_e32 v57, 31, v56
	v_lshlrev_b64 v[58:59], 6, v[56:57]
	v_lshl_add_u64 v[62:63], s[82:83], 0, v[58:59]
	flat_load_dwordx4 v[58:61], v[62:63]
	flat_load_dwordx4 v[72:75], v[62:63] offset:16
	flat_load_dwordx4 v[76:79], v[62:63] offset:32
	flat_load_dwordx4 v[80:83], v[62:63] offset:48
	s_waitcnt vmcnt(0) lgkmcnt(0)
	v_mov_b32_e32 v62, v59
	v_mov_b32_e32 v63, v60
	v_mov_b32_e32 v59, v61
	v_mov_b32_e32 v60, v73
	v_mov_b32_e32 v61, v74
	v_mov_b32_e32 v73, v75
	v_pk_add_f32 v[58:59], v[62:63], v[58:59]
	v_pk_add_f32 v[60:61], v[60:61], v[72:73]
	v_pk_add_f32 v[58:59], v[58:59], v[58:59] op_sel:[0,1] op_sel_hi:[1,0]
	v_pk_add_f32 v[60:61], v[60:61], v[60:61] op_sel:[0,1] op_sel_hi:[1,0]
	v_add_f32_e32 v62, v76, v77
	v_add_f32_e32 v72, v78, v79
	v_mov_b32_e32 v59, v80
	v_mov_b32_e32 v61, v81
	v_mov_b32_e32 v63, v82
	v_mov_b32_e32 v73, v83
	v_pk_add_f32 v[58:59], v[58:59], v[60:61]
	v_pk_add_f32 v[60:61], v[62:63], v[72:73]
	s_nop 0
	v_pk_add_f32 v[58:59], v[58:59], v[60:61]
	s_nop 0
	v_add_f32_e32 v58, v58, v59
	v_fmamk_f32 v58, v58, 0x3a800000, v212
	v_rsq_f32_e32 v60, v58
	s_nop 0
	v_pk_mul_f32 v[52:53], v[52:53], v[60:61] op_sel_hi:[1,0]
	v_pk_mul_f32 v[58:59], v[54:55], v[60:61] op_sel_hi:[1,0]
	v_add_f32_e32 v54, v68, v52
	v_min_f32_e32 v52, 0, v54
	v_mul_f32_e64 v54, |v54|, s57
	v_exp_f32_e32 v54, v54
	v_pk_mul_f32 v[48:49], v[48:49], v[60:61] op_sel_hi:[1,0]
	v_pk_mul_f32 v[50:51], v[50:51], v[60:61] op_sel_hi:[1,0]
	v_add_f32_e32 v54, 1.0, v54
	v_cmp_gt_f32_e32 vcc, s97, v54
	s_nop 1
	v_cndmask_b32_e64 v55, 0, 32, vcc
	v_ldexp_f32 v54, v54, v55
	v_log_f32_e32 v54, v54
	s_nop 0
	v_mul_f32_e32 v55, 0x3f317217, v54
	v_fma_f32 v55, v54, s52, -v55
	v_fmac_f32_e32 v55, 0x3377d1cf, v54
	v_fmac_f32_e32 v55, 0x3f317217, v54
	v_cmp_lt_f32_e64 s[8:9], |v54|, s53
	s_nop 1
	v_cndmask_b32_e64 v54, v54, v55, s[8:9]
	v_cndmask_b32_e32 v55, 0, v216, vcc
	v_sub_f32_e32 v60, v54, v55
	v_add_f32_e32 v54, v64, v48
	v_min_f32_e32 v48, 0, v54
	v_mul_f32_e64 v54, |v54|, s57
	v_exp_f32_e32 v54, v54
	s_nop 0
	v_add_f32_e32 v54, 1.0, v54
	v_cmp_gt_f32_e32 vcc, s97, v54
	s_nop 1
	v_cndmask_b32_e64 v55, 0, 32, vcc
	v_ldexp_f32 v54, v54, v55
	v_log_f32_e32 v54, v54
	s_nop 0
	v_mul_f32_e32 v55, 0x3f317217, v54
	v_fma_f32 v55, v54, s52, -v55
	v_fmac_f32_e32 v55, 0x3377d1cf, v54
	v_fmac_f32_e32 v55, 0x3f317217, v54
	v_cmp_lt_f32_e64 s[8:9], |v54|, s53
	s_nop 1
	v_cndmask_b32_e64 v54, v54, v55, s[8:9]
	v_cndmask_b32_e32 v55, 0, v216, vcc
	v_sub_f32_e32 v54, v54, v55
	v_add_f32_e32 v55, v69, v53
	v_min_f32_e32 v53, 0, v55
	v_mul_f32_e64 v55, |v55|, s57
	v_exp_f32_e32 v55, v55
	s_nop 0
	v_add_f32_e32 v55, 1.0, v55
	v_cmp_gt_f32_e32 vcc, s97, v55
	s_nop 1
	v_cndmask_b32_e64 v61, 0, 32, vcc
	v_ldexp_f32 v55, v55, v61
	v_log_f32_e32 v55, v55
	s_nop 0
	v_mul_f32_e32 v61, 0x3f317217, v55
	v_fma_f32 v61, v55, s52, -v61
	v_fmac_f32_e32 v61, 0x3377d1cf, v55
	v_fmac_f32_e32 v61, 0x3f317217, v55
	v_cmp_lt_f32_e64 s[8:9], |v55|, s53
	s_nop 1
	v_cndmask_b32_e64 v55, v55, v61, s[8:9]
	v_cndmask_b32_e32 v61, 0, v216, vcc
	v_sub_f32_e32 v61, v55, v61
	v_add_f32_e32 v55, v65, v49
	v_min_f32_e32 v49, 0, v55
	v_mul_f32_e64 v55, |v55|, s57
	v_exp_f32_e32 v55, v55
	v_pk_add_f32 v[52:53], v[52:53], v[60:61] neg_lo:[0,1] neg_hi:[0,1]
	v_add_f32_e32 v55, 1.0, v55
	v_cmp_gt_f32_e32 vcc, s97, v55
	s_nop 1
	v_cndmask_b32_e64 v62, 0, 32, vcc
	v_ldexp_f32 v55, v55, v62
	v_log_f32_e32 v55, v55
	s_nop 0
	v_mul_f32_e32 v62, 0x3f317217, v55
	v_fma_f32 v62, v55, s52, -v62
	v_fmac_f32_e32 v62, 0x3377d1cf, v55
	v_fmac_f32_e32 v62, 0x3f317217, v55
	v_cmp_lt_f32_e64 s[8:9], |v55|, s53
	s_nop 1
	v_cndmask_b32_e64 v55, v55, v62, s[8:9]
	v_cndmask_b32_e32 v62, 0, v216, vcc
	v_sub_f32_e32 v55, v55, v62
	v_add_f32_e32 v62, v70, v58
	v_min_f32_e32 v58, 0, v62
	v_mul_f32_e64 v62, |v62|, s57
	v_exp_f32_e32 v62, v62
	v_pk_add_f32 v[48:49], v[48:49], v[54:55] neg_lo:[0,1] neg_hi:[0,1]
	v_add_f32_e32 v62, 1.0, v62
	v_cmp_gt_f32_e32 vcc, s97, v62
	v_pk_mul_f32 v[48:49], v[48:49], s[2:3] op_sel_hi:[1,0]
	s_nop 0
	v_cndmask_b32_e64 v63, 0, 32, vcc
	v_ldexp_f32 v62, v62, v63
	v_log_f32_e32 v62, v62
	s_nop 0
	v_mul_f32_e32 v63, 0x3f317217, v62
	v_fma_f32 v63, v62, s52, -v63
	v_fmac_f32_e32 v63, 0x3377d1cf, v62
	v_fmac_f32_e32 v63, 0x3f317217, v62
	v_cmp_lt_f32_e64 s[8:9], |v62|, s53
	s_nop 1
	v_cndmask_b32_e64 v62, v62, v63, s[8:9]
	v_cndmask_b32_e32 v63, 0, v216, vcc
; __device__ __forceinline__ float logsig_f(float x) { return fminf(x, 0.f) - __logf(1.f + __expf(-fabsf(x))); }
;     __device__ __forceinline__ void operator()(const f32x4 (&acc)[2][2][4][2], const pg8::Unit& u, int wr, int wc, int fr, int fq) const {
;     ...
;                         const int row = row0 + ai * 128 + m * 16;
;                         const f32x4 sv = *(const f32x4*)(ssq + (size_t)row * 16), sv1 = *(const f32x4*)(ssq + (size_t)row * 16 + 4), sv2 = *(const f32x4*)(ssq + (size_t)row * 16 + 8), sv3 = *(const f32x4*)(ssq + (size_t)row * 16 + 12);
;                         const float st = ((sv[0] + sv[1]) + (sv[2] + sv[3])) + ((sv1[0] + sv1[1]) + (sv1[2] + sv1[3])) + ((sv2[0] + sv2[1]) + (sv2[2] + sv2[3])) + ((sv3[0] + sv3[1]) + (sv3[2] + sv3[3]));
;                         const float rs = __builtin_amdgcn_rsqf(st * (1.f / DM) + EPS);
;                         f32x4 a = acc[ai][0][m][0] * rs, b = acc[ai][0][m][1] * rs;
; #pragma unroll
;                         for (int i = 0; i < 4; ++i) { a[i] = logsig_f(a[i] + fb0[i]) * LOG2E; b[i] = logsig_f(b[i] + fb1[i]) * LOG2E; }
;                         *(f32x4*)(FF + (size_t)row * 8) = a; *(f32x4*)(FF + (size_t)row * 8 + 4) = b;
;                         asm volatile("" ::: "memory");
	v_sub_f32_e32 v62, v62, v63
	v_add_f32_e32 v63, v66, v50
	v_min_f32_e32 v50, 0, v63
	v_mul_f32_e64 v63, |v63|, s57
	v_exp_f32_e32 v63, v63
	s_nop 0
	v_add_f32_e32 v63, 1.0, v63
	v_cmp_gt_f32_e32 vcc, s97, v63
	s_nop 1
	v_cndmask_b32_e64 v72, 0, 32, vcc
	v_ldexp_f32 v63, v63, v72
	v_log_f32_e32 v63, v63
	s_nop 0
	v_mul_f32_e32 v72, 0x3f317217, v63
	v_fma_f32 v72, v63, s52, -v72
	v_fmac_f32_e32 v72, 0x3377d1cf, v63
	v_fmac_f32_e32 v72, 0x3f317217, v63
	v_cmp_lt_f32_e64 s[8:9], |v63|, s53
	s_nop 1
	v_cndmask_b32_e64 v63, v63, v72, s[8:9]
	v_cndmask_b32_e32 v72, 0, v216, vcc
	v_sub_f32_e32 v72, v63, v72
	v_add_f32_e32 v63, v71, v59
	v_min_f32_e32 v59, 0, v63
	v_mul_f32_e64 v63, |v63|, s57
	v_exp_f32_e32 v63, v63
	s_nop 0
	v_add_f32_e32 v63, 1.0, v63
	v_cmp_gt_f32_e32 vcc, s97, v63
	s_nop 1
	v_cndmask_b32_e64 v73, 0, 32, vcc
	v_ldexp_f32 v63, v63, v73
	v_log_f32_e32 v63, v63
	s_nop 0
	v_mul_f32_e32 v73, 0x3f317217, v63
	v_fma_f32 v73, v63, s52, -v73
	v_fmac_f32_e32 v73, 0x3377d1cf, v63
	v_fmac_f32_e32 v73, 0x3f317217, v63
	v_cmp_lt_f32_e64 s[8:9], |v63|, s53
	s_nop 1
	v_cndmask_b32_e64 v63, v63, v73, s[8:9]
	v_cndmask_b32_e32 v73, 0, v216, vcc
	v_sub_f32_e32 v63, v63, v73
	v_pk_add_f32 v[58:59], v[58:59], v[62:63] neg_lo:[0,1] neg_hi:[0,1]
	s_nop 0
	v_pk_mul_f32 v[60:61], v[58:59], s[2:3] op_sel_hi:[1,0]
	v_pk_mul_f32 v[58:59], v[52:53], s[2:3] op_sel_hi:[1,0]
	v_add_f32_e32 v52, v67, v51
	v_min_f32_e32 v51, 0, v52
	v_mul_f32_e64 v52, |v52|, s57
	v_exp_f32_e32 v52, v52
	s_nop 0
	v_add_f32_e32 v52, 1.0, v52
	v_cmp_gt_f32_e32 vcc, s97, v52
	s_nop 1
	v_cndmask_b32_e64 v53, 0, 32, vcc
	v_ldexp_f32 v52, v52, v53
	v_log_f32_e32 v52, v52
	s_nop 0
	v_mul_f32_e32 v53, 0x3f317217, v52
	v_fma_f32 v53, v52, s52, -v53
	v_fmac_f32_e32 v53, 0x3377d1cf, v52
	v_fmac_f32_e32 v53, 0x3f317217, v52
	v_cmp_lt_f32_e64 s[8:9], |v52|, s53
	s_nop 1
	v_cndmask_b32_e64 v52, v52, v53, s[8:9]
	v_cndmask_b32_e32 v53, 0, v216, vcc
	v_sub_f32_e32 v73, v52, v53
	v_lshlrev_b64 v[52:53], 5, v[56:57]
	v_pk_add_f32 v[50:51], v[50:51], v[72:73] neg_lo:[0,1] neg_hi:[0,1]
	v_lshl_add_u64 v[52:53], s[42:43], 0, v[52:53]
	v_pk_mul_f32 v[50:51], v[50:51], s[2:3] op_sel_hi:[1,0]
	global_store_dwordx4 v[52:53], v[58:61], off
	global_store_dwordx4 v[52:53], v[48:51], off offset:16
	s_nop 1
	v_or_b32_e32 v48, 32, v166
	v_ashrrev_i32_e32 v49, 31, v48
	v_lshlrev_b64 v[50:51], 6, v[48:49]
	v_lshl_add_u64 v[62:63], s[82:83], 0, v[50:51]
	flat_load_dwordx4 v[50:53], v[62:63]
	flat_load_dwordx4 v[54:57], v[62:63] offset:16
	flat_load_dwordx4 v[58:61], v[62:63] offset:32
	flat_load_dwordx4 v[72:75], v[62:63] offset:48
	s_waitcnt vmcnt(0) lgkmcnt(0)
	v_mov_b32_e32 v62, v51
	v_mov_b32_e32 v63, v52
	v_mov_b32_e32 v51, v53
	v_mov_b32_e32 v52, v55
	v_mov_b32_e32 v53, v56
	v_mov_b32_e32 v55, v57
	v_pk_add_f32 v[50:51], v[62:63], v[50:51]
	v_pk_add_f32 v[52:53], v[52:53], v[54:55]
	v_pk_add_f32 v[50:51], v[50:51], v[50:51] op_sel:[0,1] op_sel_hi:[1,0]
	v_pk_add_f32 v[52:53], v[52:53], v[52:53] op_sel:[0,1] op_sel_hi:[1,0]
	v_add_f32_e32 v54, v58, v59
	v_add_f32_e32 v56, v60, v61
	v_mov_b32_e32 v51, v72
	v_mov_b32_e32 v53, v73
	v_mov_b32_e32 v55, v74
	v_mov_b32_e32 v57, v75
	v_pk_add_f32 v[50:51], v[50:51], v[52:53]
	v_pk_add_f32 v[52:53], v[54:55], v[56:57]
	s_nop 0
	v_pk_add_f32 v[50:51], v[50:51], v[52:53]
	s_nop 0
	v_add_f32_e32 v50, v50, v51
	v_fmamk_f32 v50, v50, 0x3a800000, v212
	v_rsq_f32_e32 v52, v50
	s_nop 0
	v_pk_mul_f32 v[44:45], v[44:45], v[52:53] op_sel_hi:[1,0]
	v_pk_mul_f32 v[50:51], v[46:47], v[52:53] op_sel_hi:[1,0]
	v_add_f32_e32 v46, v68, v44
	v_min_f32_e32 v44, 0, v46
	v_mul_f32_e64 v46, |v46|, s57
	v_exp_f32_e32 v46, v46
	v_pk_mul_f32 v[40:41], v[40:41], v[52:53] op_sel_hi:[1,0]
	v_pk_mul_f32 v[42:43], v[42:43], v[52:53] op_sel_hi:[1,0]
	v_add_f32_e32 v46, 1.0, v46
	v_cmp_gt_f32_e32 vcc, s97, v46
	s_nop 1
	v_cndmask_b32_e64 v47, 0, 32, vcc
	v_ldexp_f32 v46, v46, v47
	v_log_f32_e32 v46, v46
	s_nop 0
	v_mul_f32_e32 v47, 0x3f317217, v46
	v_fma_f32 v47, v46, s52, -v47
	v_fmac_f32_e32 v47, 0x3377d1cf, v46
	v_fmac_f32_e32 v47, 0x3f317217, v46
	v_cmp_lt_f32_e64 s[8:9], |v46|, s53
	s_nop 1
	v_cndmask_b32_e64 v46, v46, v47, s[8:9]
	v_cndmask_b32_e32 v47, 0, v216, vcc
	v_sub_f32_e32 v52, v46, v47
	v_add_f32_e32 v46, v64, v40
	v_min_f32_e32 v40, 0, v46
	v_mul_f32_e64 v46, |v46|, s57
	v_exp_f32_e32 v46, v46
	s_nop 0
	v_add_f32_e32 v46, 1.0, v46
	v_cmp_gt_f32_e32 vcc, s97, v46
	s_nop 1
	v_cndmask_b32_e64 v47, 0, 32, vcc
	v_ldexp_f32 v46, v46, v47
	v_log_f32_e32 v46, v46
	s_nop 0
	v_mul_f32_e32 v47, 0x3f317217, v46
	v_fma_f32 v47, v46, s52, -v47
	v_fmac_f32_e32 v47, 0x3377d1cf, v46
	v_fmac_f32_e32 v47, 0x3f317217, v46
	v_cmp_lt_f32_e64 s[8:9], |v46|, s53
	s_nop 1
	v_cndmask_b32_e64 v46, v46, v47, s[8:9]
	v_cndmask_b32_e32 v47, 0, v216, vcc
	v_sub_f32_e32 v46, v46, v47
	v_add_f32_e32 v47, v69, v45
	v_min_f32_e32 v45, 0, v47
	v_mul_f32_e64 v47, |v47|, s57
	v_exp_f32_e32 v47, v47
	s_nop 0
	v_add_f32_e32 v47, 1.0, v47
	v_cmp_gt_f32_e32 vcc, s97, v47
	s_nop 1
	v_cndmask_b32_e64 v53, 0, 32, vcc
	v_ldexp_f32 v47, v47, v53
	v_log_f32_e32 v47, v47
	s_nop 0
	v_mul_f32_e32 v53, 0x3f317217, v47
	v_fma_f32 v53, v47, s52, -v53
	v_fmac_f32_e32 v53, 0x3377d1cf, v47
	v_fmac_f32_e32 v53, 0x3f317217, v47
	v_cmp_lt_f32_e64 s[8:9], |v47|, s53
	s_nop 1
	v_cndmask_b32_e64 v47, v47, v53, s[8:9]
	v_cndmask_b32_e32 v53, 0, v216, vcc
	v_sub_f32_e32 v53, v47, v53
	v_add_f32_e32 v47, v65, v41
	v_min_f32_e32 v41, 0, v47
	v_mul_f32_e64 v47, |v47|, s57
	v_exp_f32_e32 v47, v47
	v_pk_add_f32 v[44:45], v[44:45], v[52:53] neg_lo:[0,1] neg_hi:[0,1]
	v_add_f32_e32 v47, 1.0, v47
	v_cmp_gt_f32_e32 vcc, s97, v47
	s_nop 1
; __device__ __forceinline__ float logsig_f(float x) { return fminf(x, 0.f) - __logf(1.f + __expf(-fabsf(x))); }
;     __device__ __forceinline__ void operator()(const f32x4 (&acc)[2][2][4][2], const pg8::Unit& u, int wr, int wc, int fr, int fq) const {
;     ...
;                         const int row = row0 + ai * 128 + m * 16;
;                         const f32x4 sv = *(const f32x4*)(ssq + (size_t)row * 16), sv1 = *(const f32x4*)(ssq + (size_t)row * 16 + 4), sv2 = *(const f32x4*)(ssq + (size_t)row * 16 + 8), sv3 = *(const f32x4*)(ssq + (size_t)row * 16 + 12);
;                         const float st = ((sv[0] + sv[1]) + (sv[2] + sv[3])) + ((sv1[0] + sv1[1]) + (sv1[2] + sv1[3])) + ((sv2[0] + sv2[1]) + (sv2[2] + sv2[3])) + ((sv3[0] + sv3[1]) + (sv3[2] + sv3[3]));
;                         const float rs = __builtin_amdgcn_rsqf(st * (1.f / DM) + EPS);
;                         f32x4 a = acc[ai][0][m][0] * rs, b = acc[ai][0][m][1] * rs;
; #pragma unroll
;                         for (int i = 0; i < 4; ++i) { a[i] = logsig_f(a[i] + fb0[i]) * LOG2E; b[i] = logsig_f(b[i] + fb1[i]) * LOG2E; }
;                         *(f32x4*)(FF + (size_t)row * 8) = a; *(f32x4*)(FF + (size_t)row * 8 + 4) = b;
;                         asm volatile("" ::: "memory");
	v_cndmask_b32_e64 v54, 0, 32, vcc
	v_ldexp_f32 v47, v47, v54
	v_log_f32_e32 v47, v47
	s_nop 0
	v_mul_f32_e32 v54, 0x3f317217, v47
	v_fma_f32 v54, v47, s52, -v54
	v_fmac_f32_e32 v54, 0x3377d1cf, v47
	v_fmac_f32_e32 v54, 0x3f317217, v47
	v_cmp_lt_f32_e64 s[8:9], |v47|, s53
	s_nop 1
	v_cndmask_b32_e64 v47, v47, v54, s[8:9]
	v_cndmask_b32_e32 v54, 0, v216, vcc
	v_sub_f32_e32 v47, v47, v54
	v_add_f32_e32 v54, v70, v50
	v_min_f32_e32 v50, 0, v54
	v_mul_f32_e64 v54, |v54|, s57
	v_exp_f32_e32 v54, v54
	v_pk_add_f32 v[40:41], v[40:41], v[46:47] neg_lo:[0,1] neg_hi:[0,1]
	v_add_f32_e32 v54, 1.0, v54
	v_cmp_gt_f32_e32 vcc, s97, v54
	v_pk_mul_f32 v[40:41], v[40:41], s[2:3] op_sel_hi:[1,0]
	s_nop 0
	v_cndmask_b32_e64 v55, 0, 32, vcc
	v_ldexp_f32 v54, v54, v55
	v_log_f32_e32 v54, v54
	s_nop 0
	v_mul_f32_e32 v55, 0x3f317217, v54
	v_fma_f32 v55, v54, s52, -v55
	v_fmac_f32_e32 v55, 0x3377d1cf, v54
	v_fmac_f32_e32 v55, 0x3f317217, v54
	v_cmp_lt_f32_e64 s[8:9], |v54|, s53
	s_nop 1
	v_cndmask_b32_e64 v54, v54, v55, s[8:9]
	v_cndmask_b32_e32 v55, 0, v216, vcc
	v_sub_f32_e32 v54, v54, v55
	v_add_f32_e32 v55, v66, v42
	v_min_f32_e32 v42, 0, v55
	v_mul_f32_e64 v55, |v55|, s57
	v_exp_f32_e32 v55, v55
	s_nop 0
	v_add_f32_e32 v55, 1.0, v55
	v_cmp_gt_f32_e32 vcc, s97, v55
	s_nop 1
	v_cndmask_b32_e64 v56, 0, 32, vcc
	v_ldexp_f32 v55, v55, v56
	v_log_f32_e32 v55, v55
	s_nop 0
	v_mul_f32_e32 v56, 0x3f317217, v55
	v_fma_f32 v56, v55, s52, -v56
	v_fmac_f32_e32 v56, 0x3377d1cf, v55
	v_fmac_f32_e32 v56, 0x3f317217, v55
	v_cmp_lt_f32_e64 s[8:9], |v55|, s53
	s_nop 1
	v_cndmask_b32_e64 v55, v55, v56, s[8:9]
	v_cndmask_b32_e32 v56, 0, v216, vcc
	v_sub_f32_e32 v56, v55, v56
	v_add_f32_e32 v55, v71, v51
	v_min_f32_e32 v51, 0, v55
	v_mul_f32_e64 v55, |v55|, s57
	v_exp_f32_e32 v55, v55
	s_nop 0
	v_add_f32_e32 v55, 1.0, v55
	v_cmp_gt_f32_e32 vcc, s97, v55
	s_nop 1
	v_cndmask_b32_e64 v57, 0, 32, vcc
	v_ldexp_f32 v55, v55, v57
	v_log_f32_e32 v55, v55
	s_nop 0
	v_mul_f32_e32 v57, 0x3f317217, v55
	v_fma_f32 v57, v55, s52, -v57
	v_fmac_f32_e32 v57, 0x3377d1cf, v55
	v_fmac_f32_e32 v57, 0x3f317217, v55
	v_cmp_lt_f32_e64 s[8:9], |v55|, s53
	s_nop 1
	v_cndmask_b32_e64 v55, v55, v57, s[8:9]
	v_cndmask_b32_e32 v57, 0, v216, vcc
	v_sub_f32_e32 v55, v55, v57
	v_pk_add_f32 v[50:51], v[50:51], v[54:55] neg_lo:[0,1] neg_hi:[0,1]
	s_nop 0
	v_pk_mul_f32 v[52:53], v[50:51], s[2:3] op_sel_hi:[1,0]
	v_pk_mul_f32 v[50:51], v[44:45], s[2:3] op_sel_hi:[1,0]
	v_add_f32_e32 v44, v67, v43
	v_min_f32_e32 v43, 0, v44
	v_mul_f32_e64 v44, |v44|, s57
	v_exp_f32_e32 v44, v44
	s_nop 0
	v_add_f32_e32 v44, 1.0, v44
	v_cmp_gt_f32_e32 vcc, s97, v44
	s_nop 1
	v_cndmask_b32_e64 v45, 0, 32, vcc
	v_ldexp_f32 v44, v44, v45
	v_log_f32_e32 v44, v44
	s_nop 0
	v_mul_f32_e32 v45, 0x3f317217, v44
	v_fma_f32 v45, v44, s52, -v45
	v_fmac_f32_e32 v45, 0x3377d1cf, v44
	v_fmac_f32_e32 v45, 0x3f317217, v44
	v_cmp_lt_f32_e64 s[8:9], |v44|, s53
	s_nop 1
	v_cndmask_b32_e64 v44, v44, v45, s[8:9]
	v_cndmask_b32_e32 v45, 0, v216, vcc
	v_sub_f32_e32 v57, v44, v45
	v_lshlrev_b64 v[44:45], 5, v[48:49]
	v_pk_add_f32 v[42:43], v[42:43], v[56:57] neg_lo:[0,1] neg_hi:[0,1]
	v_lshl_add_u64 v[44:45], s[42:43], 0, v[44:45]
	v_pk_mul_f32 v[42:43], v[42:43], s[2:3] op_sel_hi:[1,0]
	global_store_dwordx4 v[44:45], v[50:53], off
	global_store_dwordx4 v[44:45], v[40:43], off offset:16
	s_nop 1
	v_or_b32_e32 v40, 48, v166
	v_ashrrev_i32_e32 v41, 31, v40
	v_lshlrev_b64 v[42:43], 6, v[40:41]
	v_lshl_add_u64 v[54:55], s[82:83], 0, v[42:43]
	flat_load_dwordx4 v[42:45], v[54:55]
	flat_load_dwordx4 v[46:49], v[54:55] offset:16
	flat_load_dwordx4 v[50:53], v[54:55] offset:32
	s_nop 0
	flat_load_dwordx4 v[54:57], v[54:55] offset:48
	s_waitcnt vmcnt(0) lgkmcnt(0)
	v_mov_b32_e32 v58, v43
	v_mov_b32_e32 v59, v44
	v_mov_b32_e32 v43, v45
	v_mov_b32_e32 v44, v47
	v_mov_b32_e32 v45, v48
	v_mov_b32_e32 v47, v49
	v_pk_add_f32 v[42:43], v[58:59], v[42:43]
	v_pk_add_f32 v[44:45], v[44:45], v[46:47]
	v_pk_add_f32 v[42:43], v[42:43], v[42:43] op_sel:[0,1] op_sel_hi:[1,0]
	v_pk_add_f32 v[44:45], v[44:45], v[44:45] op_sel:[0,1] op_sel_hi:[1,0]
	v_add_f32_e32 v46, v50, v51
	v_add_f32_e32 v48, v52, v53
	v_mov_b32_e32 v43, v54
	v_mov_b32_e32 v45, v55
	v_mov_b32_e32 v47, v56
	v_mov_b32_e32 v49, v57
	v_pk_add_f32 v[42:43], v[42:43], v[44:45]
	v_pk_add_f32 v[44:45], v[46:47], v[48:49]
	s_nop 0
	v_pk_add_f32 v[42:43], v[42:43], v[44:45]
	s_nop 0
	v_add_f32_e32 v42, v42, v43
	v_fmamk_f32 v42, v42, 0x3a800000, v212
	v_rsq_f32_e32 v44, v42
	s_nop 0
	v_pk_mul_f32 v[36:37], v[36:37], v[44:45] op_sel_hi:[1,0]
	v_pk_mul_f32 v[42:43], v[38:39], v[44:45] op_sel_hi:[1,0]
	v_add_f32_e32 v38, v68, v36
	v_min_f32_e32 v36, 0, v38
	v_mul_f32_e64 v38, |v38|, s57
	v_exp_f32_e32 v38, v38
	v_pk_mul_f32 v[32:33], v[32:33], v[44:45] op_sel_hi:[1,0]
	v_pk_mul_f32 v[34:35], v[34:35], v[44:45] op_sel_hi:[1,0]
	v_add_f32_e32 v38, 1.0, v38
	v_cmp_gt_f32_e32 vcc, s97, v38
	s_nop 1
	v_cndmask_b32_e64 v39, 0, 32, vcc
	v_ldexp_f32 v38, v38, v39
	v_log_f32_e32 v38, v38
	s_nop 0
	v_mul_f32_e32 v39, 0x3f317217, v38
	v_fma_f32 v39, v38, s52, -v39
	v_fmac_f32_e32 v39, 0x3377d1cf, v38
	v_fmac_f32_e32 v39, 0x3f317217, v38
	v_cmp_lt_f32_e64 s[8:9], |v38|, s53
	s_nop 1
	v_cndmask_b32_e64 v38, v38, v39, s[8:9]
	v_cndmask_b32_e32 v39, 0, v216, vcc
	v_sub_f32_e32 v44, v38, v39
	v_add_f32_e32 v38, v64, v32
	v_min_f32_e32 v32, 0, v38
	v_mul_f32_e64 v38, |v38|, s57
	v_exp_f32_e32 v38, v38
	s_nop 0
	v_add_f32_e32 v38, 1.0, v38
	v_cmp_gt_f32_e32 vcc, s97, v38
	s_nop 1
	v_cndmask_b32_e64 v39, 0, 32, vcc
	v_ldexp_f32 v38, v38, v39
	v_log_f32_e32 v38, v38
	s_nop 0
	v_mul_f32_e32 v39, 0x3f317217, v38
	v_fma_f32 v39, v38, s52, -v39
; __device__ __forceinline__ float logsig_f(float x) { return fminf(x, 0.f) - __logf(1.f + __expf(-fabsf(x))); }
;     __device__ __forceinline__ void operator()(const f32x4 (&acc)[2][2][4][2], const pg8::Unit& u, int wr, int wc, int fr, int fq) const {
;     ...
;                         const int row = row0 + ai * 128 + m * 16;
;                         const f32x4 sv = *(const f32x4*)(ssq + (size_t)row * 16), sv1 = *(const f32x4*)(ssq + (size_t)row * 16 + 4), sv2 = *(const f32x4*)(ssq + (size_t)row * 16 + 8), sv3 = *(const f32x4*)(ssq + (size_t)row * 16 + 12);
;                         const float st = ((sv[0] + sv[1]) + (sv[2] + sv[3])) + ((sv1[0] + sv1[1]) + (sv1[2] + sv1[3])) + ((sv2[0] + sv2[1]) + (sv2[2] + sv2[3])) + ((sv3[0] + sv3[1]) + (sv3[2] + sv3[3]));
;                         const float rs = __builtin_amdgcn_rsqf(st * (1.f / DM) + EPS);
;                         f32x4 a = acc[ai][0][m][0] * rs, b = acc[ai][0][m][1] * rs;
; #pragma unroll
;                         for (int i = 0; i < 4; ++i) { a[i] = logsig_f(a[i] + fb0[i]) * LOG2E; b[i] = logsig_f(b[i] + fb1[i]) * LOG2E; }
;                         *(f32x4*)(FF + (size_t)row * 8) = a; *(f32x4*)(FF + (size_t)row * 8 + 4) = b;
;                         asm volatile("" ::: "memory");
	v_fmac_f32_e32 v39, 0x3377d1cf, v38
	v_fmac_f32_e32 v39, 0x3f317217, v38
	v_cmp_lt_f32_e64 s[8:9], |v38|, s53
	s_nop 1
	v_cndmask_b32_e64 v38, v38, v39, s[8:9]
	v_cndmask_b32_e32 v39, 0, v216, vcc
	v_sub_f32_e32 v38, v38, v39
	v_add_f32_e32 v39, v69, v37
	v_min_f32_e32 v37, 0, v39
	v_mul_f32_e64 v39, |v39|, s57
	v_exp_f32_e32 v39, v39
	s_nop 0
	v_add_f32_e32 v39, 1.0, v39
	v_cmp_gt_f32_e32 vcc, s97, v39
	s_nop 1
	v_cndmask_b32_e64 v45, 0, 32, vcc
	v_ldexp_f32 v39, v39, v45
	v_log_f32_e32 v39, v39
	s_nop 0
	v_mul_f32_e32 v45, 0x3f317217, v39
	v_fma_f32 v45, v39, s52, -v45
	v_fmac_f32_e32 v45, 0x3377d1cf, v39
	v_fmac_f32_e32 v45, 0x3f317217, v39
	v_cmp_lt_f32_e64 s[8:9], |v39|, s53
	s_nop 1
	v_cndmask_b32_e64 v39, v39, v45, s[8:9]
	v_cndmask_b32_e32 v45, 0, v216, vcc
	v_sub_f32_e32 v45, v39, v45
	v_add_f32_e32 v39, v65, v33
	v_min_f32_e32 v33, 0, v39
	v_mul_f32_e64 v39, |v39|, s57
	v_exp_f32_e32 v39, v39
	v_pk_add_f32 v[36:37], v[36:37], v[44:45] neg_lo:[0,1] neg_hi:[0,1]
	v_add_f32_e32 v39, 1.0, v39
	v_cmp_gt_f32_e32 vcc, s97, v39
	s_nop 1
	v_cndmask_b32_e64 v46, 0, 32, vcc
	v_ldexp_f32 v39, v39, v46
	v_log_f32_e32 v39, v39
	s_nop 0
	v_mul_f32_e32 v46, 0x3f317217, v39
	v_fma_f32 v46, v39, s52, -v46
	v_fmac_f32_e32 v46, 0x3377d1cf, v39
	v_fmac_f32_e32 v46, 0x3f317217, v39
	v_cmp_lt_f32_e64 s[8:9], |v39|, s53
	s_nop 1
	v_cndmask_b32_e64 v39, v39, v46, s[8:9]
	v_cndmask_b32_e32 v46, 0, v216, vcc
	v_sub_f32_e32 v39, v39, v46
	v_add_f32_e32 v46, v70, v42
	v_min_f32_e32 v42, 0, v46
	v_mul_f32_e64 v46, |v46|, s57
	v_exp_f32_e32 v46, v46
	v_pk_add_f32 v[32:33], v[32:33], v[38:39] neg_lo:[0,1] neg_hi:[0,1]
	v_add_f32_e32 v46, 1.0, v46
	v_cmp_gt_f32_e32 vcc, s97, v46
	v_pk_mul_f32 v[32:33], v[32:33], s[2:3] op_sel_hi:[1,0]
	s_nop 0
	v_cndmask_b32_e64 v47, 0, 32, vcc
	v_ldexp_f32 v46, v46, v47
	v_log_f32_e32 v46, v46
	s_nop 0
	v_mul_f32_e32 v47, 0x3f317217, v46
	v_fma_f32 v47, v46, s52, -v47
	v_fmac_f32_e32 v47, 0x3377d1cf, v46
	v_fmac_f32_e32 v47, 0x3f317217, v46
	v_cmp_lt_f32_e64 s[8:9], |v46|, s53
	s_nop 1
	v_cndmask_b32_e64 v46, v46, v47, s[8:9]
	v_cndmask_b32_e32 v47, 0, v216, vcc
	v_sub_f32_e32 v46, v46, v47
	v_add_f32_e32 v47, v66, v34
	v_min_f32_e32 v34, 0, v47
	v_mul_f32_e64 v47, |v47|, s57
	v_exp_f32_e32 v47, v47
	s_nop 0
	v_add_f32_e32 v47, 1.0, v47
	v_cmp_gt_f32_e32 vcc, s97, v47
	s_nop 1
	v_cndmask_b32_e64 v48, 0, 32, vcc
	v_ldexp_f32 v47, v47, v48
	v_log_f32_e32 v47, v47
	s_nop 0
	v_mul_f32_e32 v48, 0x3f317217, v47
	v_fma_f32 v48, v47, s52, -v48
	v_fmac_f32_e32 v48, 0x3377d1cf, v47
	v_fmac_f32_e32 v48, 0x3f317217, v47
	v_cmp_lt_f32_e64 s[8:9], |v47|, s53
	s_nop 1
	v_cndmask_b32_e64 v47, v47, v48, s[8:9]
	v_cndmask_b32_e32 v48, 0, v216, vcc
	v_sub_f32_e32 v48, v47, v48
	v_add_f32_e32 v47, v71, v43
	v_min_f32_e32 v43, 0, v47
	v_mul_f32_e64 v47, |v47|, s57
	v_exp_f32_e32 v47, v47
	s_nop 0
	v_add_f32_e32 v47, 1.0, v47
	v_cmp_gt_f32_e32 vcc, s97, v47
	s_nop 1
	v_cndmask_b32_e64 v49, 0, 32, vcc
	v_ldexp_f32 v47, v47, v49
	v_log_f32_e32 v47, v47
	s_nop 0
	v_mul_f32_e32 v49, 0x3f317217, v47
	v_fma_f32 v49, v47, s52, -v49
	v_fmac_f32_e32 v49, 0x3377d1cf, v47
	v_fmac_f32_e32 v49, 0x3f317217, v47
	v_cmp_lt_f32_e64 s[8:9], |v47|, s53
	s_nop 1
	v_cndmask_b32_e64 v47, v47, v49, s[8:9]
	v_cndmask_b32_e32 v49, 0, v216, vcc
	v_sub_f32_e32 v47, v47, v49
	v_pk_add_f32 v[42:43], v[42:43], v[46:47] neg_lo:[0,1] neg_hi:[0,1]
	s_nop 0
	v_pk_mul_f32 v[44:45], v[42:43], s[2:3] op_sel_hi:[1,0]
	v_pk_mul_f32 v[42:43], v[36:37], s[2:3] op_sel_hi:[1,0]
	v_add_f32_e32 v36, v67, v35
	v_min_f32_e32 v35, 0, v36
	v_mul_f32_e64 v36, |v36|, s57
	v_exp_f32_e32 v36, v36
	s_nop 0
	v_add_f32_e32 v36, 1.0, v36
	v_cmp_gt_f32_e32 vcc, s97, v36
	s_nop 1
	v_cndmask_b32_e64 v37, 0, 32, vcc
	v_ldexp_f32 v36, v36, v37
	v_log_f32_e32 v36, v36
	s_nop 0
	v_mul_f32_e32 v37, 0x3f317217, v36
	v_fma_f32 v37, v36, s52, -v37
	v_fmac_f32_e32 v37, 0x3377d1cf, v36
	v_fmac_f32_e32 v37, 0x3f317217, v36
	v_cmp_lt_f32_e64 s[8:9], |v36|, s53
	s_nop 1
	v_cndmask_b32_e64 v36, v36, v37, s[8:9]
	v_cndmask_b32_e32 v37, 0, v216, vcc
	v_sub_f32_e32 v49, v36, v37
	v_lshlrev_b64 v[36:37], 5, v[40:41]
	v_pk_add_f32 v[34:35], v[34:35], v[48:49] neg_lo:[0,1] neg_hi:[0,1]
	v_lshl_add_u64 v[36:37], s[42:43], 0, v[36:37]
	v_pk_mul_f32 v[34:35], v[34:35], s[2:3] op_sel_hi:[1,0]
	global_store_dwordx4 v[36:37], v[42:45], off
	global_store_dwordx4 v[36:37], v[32:35], off offset:16
	s_nop 1
	v_add_u32_e32 v32, 0x80, v166
	v_ashrrev_i32_e32 v33, 31, v32
	v_lshlrev_b64 v[34:35], 6, v[32:33]
	v_lshl_add_u64 v[46:47], s[82:83], 0, v[34:35]
	flat_load_dwordx4 v[34:37], v[46:47]
	flat_load_dwordx4 v[38:41], v[46:47] offset:16
	flat_load_dwordx4 v[42:45], v[46:47] offset:32
	s_nop 0
	flat_load_dwordx4 v[46:49], v[46:47] offset:48
	s_waitcnt vmcnt(0) lgkmcnt(0)
; __device__ __forceinline__ float logsig_f(float x) { return fminf(x, 0.f) - __logf(1.f + __expf(-fabsf(x))); }
;     __device__ __forceinline__ void operator()(const f32x4 (&acc)[2][2][4][2], const pg8::Unit& u, int wr, int wc, int fr, int fq) const {
;     ...
;                         const int row = row0 + ai * 128 + m * 16;
;                         const f32x4 sv = *(const f32x4*)(ssq + (size_t)row * 16), sv1 = *(const f32x4*)(ssq + (size_t)row * 16 + 4), sv2 = *(const f32x4*)(ssq + (size_t)row * 16 + 8), sv3 = *(const f32x4*)(ssq + (size_t)row * 16 + 12);
;                         const float st = ((sv[0] + sv[1]) + (sv[2] + sv[3])) + ((sv1[0] + sv1[1]) + (sv1[2] + sv1[3])) + ((sv2[0] + sv2[1]) + (sv2[2] + sv2[3])) + ((sv3[0] + sv3[1]) + (sv3[2] + sv3[3]));
;                         const float rs = __builtin_amdgcn_rsqf(st * (1.f / DM) + EPS);
;                         f32x4 a = acc[ai][0][m][0] * rs, b = acc[ai][0][m][1] * rs;
; #pragma unroll
;                         for (int i = 0; i < 4; ++i) { a[i] = logsig_f(a[i] + fb0[i]) * LOG2E; b[i] = logsig_f(b[i] + fb1[i]) * LOG2E; }
;                         *(f32x4*)(FF + (size_t)row * 8) = a; *(f32x4*)(FF + (size_t)row * 8 + 4) = b;
;                         asm volatile("" ::: "memory");
	v_mov_b32_e32 v50, v35
	v_mov_b32_e32 v51, v36
	v_mov_b32_e32 v35, v37
	v_mov_b32_e32 v36, v39
	v_mov_b32_e32 v37, v40
	v_mov_b32_e32 v39, v41
	v_pk_add_f32 v[34:35], v[50:51], v[34:35]
	v_pk_add_f32 v[36:37], v[36:37], v[38:39]
	v_pk_add_f32 v[34:35], v[34:35], v[34:35] op_sel:[0,1] op_sel_hi:[1,0]
	v_pk_add_f32 v[36:37], v[36:37], v[36:37] op_sel:[0,1] op_sel_hi:[1,0]
	v_add_f32_e32 v38, v42, v43
	v_add_f32_e32 v40, v44, v45
	v_mov_b32_e32 v35, v46
	v_mov_b32_e32 v37, v47
	v_mov_b32_e32 v39, v48
	v_mov_b32_e32 v41, v49
	v_pk_add_f32 v[34:35], v[34:35], v[36:37]
	v_pk_add_f32 v[36:37], v[38:39], v[40:41]
	s_nop 0
	v_pk_add_f32 v[34:35], v[34:35], v[36:37]
	s_nop 0
	v_add_f32_e32 v34, v34, v35
	v_fmamk_f32 v34, v34, 0x3a800000, v212
	v_rsq_f32_e32 v36, v34
	s_nop 0
	v_pk_mul_f32 v[28:29], v[28:29], v[36:37] op_sel_hi:[1,0]
	v_pk_mul_f32 v[34:35], v[30:31], v[36:37] op_sel_hi:[1,0]
	v_add_f32_e32 v30, v68, v28
	v_min_f32_e32 v28, 0, v30
	v_mul_f32_e64 v30, |v30|, s57
	v_exp_f32_e32 v30, v30
	v_pk_mul_f32 v[24:25], v[24:25], v[36:37] op_sel_hi:[1,0]
	v_pk_mul_f32 v[26:27], v[26:27], v[36:37] op_sel_hi:[1,0]
	v_add_f32_e32 v30, 1.0, v30
	v_cmp_gt_f32_e32 vcc, s97, v30
	s_nop 1
	v_cndmask_b32_e64 v31, 0, 32, vcc
	v_ldexp_f32 v30, v30, v31
	v_log_f32_e32 v30, v30
	s_nop 0
	v_mul_f32_e32 v31, 0x3f317217, v30
	v_fma_f32 v31, v30, s52, -v31
	v_fmac_f32_e32 v31, 0x3377d1cf, v30
	v_fmac_f32_e32 v31, 0x3f317217, v30
	v_cmp_lt_f32_e64 s[8:9], |v30|, s53
	s_nop 1
	v_cndmask_b32_e64 v30, v30, v31, s[8:9]
	v_cndmask_b32_e32 v31, 0, v216, vcc
	v_sub_f32_e32 v36, v30, v31
	v_add_f32_e32 v30, v64, v24
	v_min_f32_e32 v24, 0, v30
	v_mul_f32_e64 v30, |v30|, s57
	v_exp_f32_e32 v30, v30
	s_nop 0
	v_add_f32_e32 v30, 1.0, v30
	v_cmp_gt_f32_e32 vcc, s97, v30
	s_nop 1
	v_cndmask_b32_e64 v31, 0, 32, vcc
	v_ldexp_f32 v30, v30, v31
	v_log_f32_e32 v30, v30
	s_nop 0
	v_mul_f32_e32 v31, 0x3f317217, v30
	v_fma_f32 v31, v30, s52, -v31
	v_fmac_f32_e32 v31, 0x3377d1cf, v30
	v_fmac_f32_e32 v31, 0x3f317217, v30
	v_cmp_lt_f32_e64 s[8:9], |v30|, s53
	s_nop 1
	v_cndmask_b32_e64 v30, v30, v31, s[8:9]
	v_cndmask_b32_e32 v31, 0, v216, vcc
	v_sub_f32_e32 v30, v30, v31
	v_add_f32_e32 v31, v69, v29
	v_min_f32_e32 v29, 0, v31
	v_mul_f32_e64 v31, |v31|, s57
	v_exp_f32_e32 v31, v31
	s_nop 0
	v_add_f32_e32 v31, 1.0, v31
	v_cmp_gt_f32_e32 vcc, s97, v31
	s_nop 1
	v_cndmask_b32_e64 v37, 0, 32, vcc
	v_ldexp_f32 v31, v31, v37
	v_log_f32_e32 v31, v31
	s_nop 0
	v_mul_f32_e32 v37, 0x3f317217, v31
	v_fma_f32 v37, v31, s52, -v37
	v_fmac_f32_e32 v37, 0x3377d1cf, v31
	v_fmac_f32_e32 v37, 0x3f317217, v31
	v_cmp_lt_f32_e64 s[8:9], |v31|, s53
	s_nop 1
	v_cndmask_b32_e64 v31, v31, v37, s[8:9]
	v_cndmask_b32_e32 v37, 0, v216, vcc
	v_sub_f32_e32 v37, v31, v37
	v_add_f32_e32 v31, v65, v25
	v_min_f32_e32 v25, 0, v31
	v_mul_f32_e64 v31, |v31|, s57
	v_exp_f32_e32 v31, v31
	v_pk_add_f32 v[28:29], v[28:29], v[36:37] neg_lo:[0,1] neg_hi:[0,1]
	v_add_f32_e32 v31, 1.0, v31
	v_cmp_gt_f32_e32 vcc, s97, v31
	s_nop 1
	v_cndmask_b32_e64 v38, 0, 32, vcc
	v_ldexp_f32 v31, v31, v38
	v_log_f32_e32 v31, v31
	s_nop 0
	v_mul_f32_e32 v38, 0x3f317217, v31
	v_fma_f32 v38, v31, s52, -v38
	v_fmac_f32_e32 v38, 0x3377d1cf, v31
	v_fmac_f32_e32 v38, 0x3f317217, v31
	v_cmp_lt_f32_e64 s[8:9], |v31|, s53
	s_nop 1
	v_cndmask_b32_e64 v31, v31, v38, s[8:9]
	v_cndmask_b32_e32 v38, 0, v216, vcc
	v_sub_f32_e32 v31, v31, v38
	v_add_f32_e32 v38, v70, v34
	v_min_f32_e32 v34, 0, v38
	v_mul_f32_e64 v38, |v38|, s57
	v_exp_f32_e32 v38, v38
	v_pk_add_f32 v[24:25], v[24:25], v[30:31] neg_lo:[0,1] neg_hi:[0,1]
	v_add_f32_e32 v38, 1.0, v38
	v_cmp_gt_f32_e32 vcc, s97, v38
	v_pk_mul_f32 v[24:25], v[24:25], s[2:3] op_sel_hi:[1,0]
	s_nop 0
	v_cndmask_b32_e64 v39, 0, 32, vcc
	v_ldexp_f32 v38, v38, v39
	v_log_f32_e32 v38, v38
	s_nop 0
	v_mul_f32_e32 v39, 0x3f317217, v38
	v_fma_f32 v39, v38, s52, -v39
	v_fmac_f32_e32 v39, 0x3377d1cf, v38
	v_fmac_f32_e32 v39, 0x3f317217, v38
	v_cmp_lt_f32_e64 s[8:9], |v38|, s53
	s_nop 1
	v_cndmask_b32_e64 v38, v38, v39, s[8:9]
	v_cndmask_b32_e32 v39, 0, v216, vcc
	v_sub_f32_e32 v38, v38, v39
	v_add_f32_e32 v39, v66, v26
	v_min_f32_e32 v26, 0, v39
	v_mul_f32_e64 v39, |v39|, s57
	v_exp_f32_e32 v39, v39
	s_nop 0
	v_add_f32_e32 v39, 1.0, v39
	v_cmp_gt_f32_e32 vcc, s97, v39
	s_nop 1
	v_cndmask_b32_e64 v40, 0, 32, vcc
	v_ldexp_f32 v39, v39, v40
	v_log_f32_e32 v39, v39
	s_nop 0
	v_mul_f32_e32 v40, 0x3f317217, v39
	v_fma_f32 v40, v39, s52, -v40
	v_fmac_f32_e32 v40, 0x3377d1cf, v39
	v_fmac_f32_e32 v40, 0x3f317217, v39
	v_cmp_lt_f32_e64 s[8:9], |v39|, s53
	s_nop 1
	v_cndmask_b32_e64 v39, v39, v40, s[8:9]
	v_cndmask_b32_e32 v40, 0, v216, vcc
	v_sub_f32_e32 v40, v39, v40
	v_add_f32_e32 v39, v71, v35
	v_min_f32_e32 v35, 0, v39
	v_mul_f32_e64 v39, |v39|, s57
	v_exp_f32_e32 v39, v39
	s_nop 0
	v_add_f32_e32 v39, 1.0, v39
	v_cmp_gt_f32_e32 vcc, s97, v39
	s_nop 1
	v_cndmask_b32_e64 v41, 0, 32, vcc
	v_ldexp_f32 v39, v39, v41
	v_log_f32_e32 v39, v39
	s_nop 0
	v_mul_f32_e32 v41, 0x3f317217, v39
	v_fma_f32 v41, v39, s52, -v41
	v_fmac_f32_e32 v41, 0x3377d1cf, v39
	v_fmac_f32_e32 v41, 0x3f317217, v39
	v_cmp_lt_f32_e64 s[8:9], |v39|, s53
	s_nop 1
	v_cndmask_b32_e64 v39, v39, v41, s[8:9]
	v_cndmask_b32_e32 v41, 0, v216, vcc
	v_sub_f32_e32 v39, v39, v41
	v_pk_add_f32 v[34:35], v[34:35], v[38:39] neg_lo:[0,1] neg_hi:[0,1]
	s_nop 0
	v_pk_mul_f32 v[36:37], v[34:35], s[2:3] op_sel_hi:[1,0]
	v_pk_mul_f32 v[34:35], v[28:29], s[2:3] op_sel_hi:[1,0]
	v_add_f32_e32 v28, v67, v27
	v_min_f32_e32 v27, 0, v28
	v_mul_f32_e64 v28, |v28|, s57
	v_exp_f32_e32 v28, v28
	s_nop 0
	v_add_f32_e32 v28, 1.0, v28
	v_cmp_gt_f32_e32 vcc, s97, v28
	s_nop 1
	v_cndmask_b32_e64 v29, 0, 32, vcc
	v_ldexp_f32 v28, v28, v29
	v_log_f32_e32 v28, v28
	s_nop 0
	v_mul_f32_e32 v29, 0x3f317217, v28
	v_fma_f32 v29, v28, s52, -v29
	v_fmac_f32_e32 v29, 0x3377d1cf, v28
	v_fmac_f32_e32 v29, 0x3f317217, v28
	v_cmp_lt_f32_e64 s[8:9], |v28|, s53
	s_nop 1
	v_cndmask_b32_e64 v28, v28, v29, s[8:9]
	v_cndmask_b32_e32 v29, 0, v216, vcc
	v_sub_f32_e32 v41, v28, v29
	v_lshlrev_b64 v[28:29], 5, v[32:33]
	v_pk_add_f32 v[26:27], v[26:27], v[40:41] neg_lo:[0,1] neg_hi:[0,1]
	v_lshl_add_u64 v[28:29], s[42:43], 0, v[28:29]
	v_pk_mul_f32 v[26:27], v[26:27], s[2:3] op_sel_hi:[1,0]
	global_store_dwordx4 v[28:29], v[34:37], off
	global_store_dwordx4 v[28:29], v[24:27], off offset:16
	s_nop 1
	v_add_u32_e32 v24, 0x90, v166
	v_ashrrev_i32_e32 v25, 31, v24
	v_lshlrev_b64 v[26:27], 6, v[24:25]
	v_lshl_add_u64 v[38:39], s[82:83], 0, v[26:27]
	flat_load_dwordx4 v[26:29], v[38:39]
	flat_load_dwordx4 v[30:33], v[38:39] offset:16
	flat_load_dwordx4 v[34:37], v[38:39] offset:32
	s_nop 0
	flat_load_dwordx4 v[38:41], v[38:39] offset:48
	s_waitcnt vmcnt(0) lgkmcnt(0)
; __device__ __forceinline__ float logsig_f(float x) { return fminf(x, 0.f) - __logf(1.f + __expf(-fabsf(x))); }
;     __device__ __forceinline__ void operator()(const f32x4 (&acc)[2][2][4][2], const pg8::Unit& u, int wr, int wc, int fr, int fq) const {
;     ...
;                         const int row = row0 + ai * 128 + m * 16;
;                         const f32x4 sv = *(const f32x4*)(ssq + (size_t)row * 16), sv1 = *(const f32x4*)(ssq + (size_t)row * 16 + 4), sv2 = *(const f32x4*)(ssq + (size_t)row * 16 + 8), sv3 = *(const f32x4*)(ssq + (size_t)row * 16 + 12);
;                         const float st = ((sv[0] + sv[1]) + (sv[2] + sv[3])) + ((sv1[0] + sv1[1]) + (sv1[2] + sv1[3])) + ((sv2[0] + sv2[1]) + (sv2[2] + sv2[3])) + ((sv3[0] + sv3[1]) + (sv3[2] + sv3[3]));
;                         const float rs = __builtin_amdgcn_rsqf(st * (1.f / DM) + EPS);
;                         f32x4 a = acc[ai][0][m][0] * rs, b = acc[ai][0][m][1] * rs;
; #pragma unroll
;                         for (int i = 0; i < 4; ++i) { a[i] = logsig_f(a[i] + fb0[i]) * LOG2E; b[i] = logsig_f(b[i] + fb1[i]) * LOG2E; }
;                         *(f32x4*)(FF + (size_t)row * 8) = a; *(f32x4*)(FF + (size_t)row * 8 + 4) = b;
;                         asm volatile("" ::: "memory");
	v_mov_b32_e32 v42, v27
	v_mov_b32_e32 v43, v28
	v_mov_b32_e32 v27, v29
	v_mov_b32_e32 v28, v31
	v_mov_b32_e32 v29, v32
	v_mov_b32_e32 v31, v33
	v_pk_add_f32 v[26:27], v[42:43], v[26:27]
	v_pk_add_f32 v[28:29], v[28:29], v[30:31]
	v_pk_add_f32 v[26:27], v[26:27], v[26:27] op_sel:[0,1] op_sel_hi:[1,0]
	v_pk_add_f32 v[28:29], v[28:29], v[28:29] op_sel:[0,1] op_sel_hi:[1,0]
	v_add_f32_e32 v30, v34, v35
	v_add_f32_e32 v32, v36, v37
	v_mov_b32_e32 v27, v38
	v_mov_b32_e32 v29, v39
	v_mov_b32_e32 v31, v40
	v_mov_b32_e32 v33, v41
	v_pk_add_f32 v[26:27], v[26:27], v[28:29]
	v_pk_add_f32 v[28:29], v[30:31], v[32:33]
	s_nop 0
	v_pk_add_f32 v[26:27], v[26:27], v[28:29]
	s_nop 0
	v_add_f32_e32 v26, v26, v27
	v_fmamk_f32 v26, v26, 0x3a800000, v212
	v_rsq_f32_e32 v28, v26
	s_nop 0
	v_pk_mul_f32 v[20:21], v[20:21], v[28:29] op_sel_hi:[1,0]
	v_pk_mul_f32 v[26:27], v[22:23], v[28:29] op_sel_hi:[1,0]
	v_add_f32_e32 v22, v68, v20
	v_min_f32_e32 v20, 0, v22
	v_mul_f32_e64 v22, |v22|, s57
	v_exp_f32_e32 v22, v22
	v_pk_mul_f32 v[16:17], v[16:17], v[28:29] op_sel_hi:[1,0]
	v_pk_mul_f32 v[18:19], v[18:19], v[28:29] op_sel_hi:[1,0]
	v_add_f32_e32 v22, 1.0, v22
	v_cmp_gt_f32_e32 vcc, s97, v22
	s_nop 1
	v_cndmask_b32_e64 v23, 0, 32, vcc
	v_ldexp_f32 v22, v22, v23
	v_log_f32_e32 v22, v22
	s_nop 0
	v_mul_f32_e32 v23, 0x3f317217, v22
	v_fma_f32 v23, v22, s52, -v23
	v_fmac_f32_e32 v23, 0x3377d1cf, v22
	v_fmac_f32_e32 v23, 0x3f317217, v22
	v_cmp_lt_f32_e64 s[8:9], |v22|, s53
	s_nop 1
	v_cndmask_b32_e64 v22, v22, v23, s[8:9]
	v_cndmask_b32_e32 v23, 0, v216, vcc
	v_sub_f32_e32 v28, v22, v23
	v_add_f32_e32 v22, v64, v16
	v_min_f32_e32 v16, 0, v22
	v_mul_f32_e64 v22, |v22|, s57
	v_exp_f32_e32 v22, v22
	s_nop 0
	v_add_f32_e32 v22, 1.0, v22
	v_cmp_gt_f32_e32 vcc, s97, v22
	s_nop 1
	v_cndmask_b32_e64 v23, 0, 32, vcc
	v_ldexp_f32 v22, v22, v23
	v_log_f32_e32 v22, v22
	s_nop 0
	v_mul_f32_e32 v23, 0x3f317217, v22
	v_fma_f32 v23, v22, s52, -v23
	v_fmac_f32_e32 v23, 0x3377d1cf, v22
	v_fmac_f32_e32 v23, 0x3f317217, v22
	v_cmp_lt_f32_e64 s[8:9], |v22|, s53
	s_nop 1
	v_cndmask_b32_e64 v22, v22, v23, s[8:9]
	v_cndmask_b32_e32 v23, 0, v216, vcc
	v_sub_f32_e32 v22, v22, v23
	v_add_f32_e32 v23, v69, v21
	v_min_f32_e32 v21, 0, v23
	v_mul_f32_e64 v23, |v23|, s57
	v_exp_f32_e32 v23, v23
	s_nop 0
	v_add_f32_e32 v23, 1.0, v23
	v_cmp_gt_f32_e32 vcc, s97, v23
	s_nop 1
	v_cndmask_b32_e64 v29, 0, 32, vcc
	v_ldexp_f32 v23, v23, v29
	v_log_f32_e32 v23, v23
	s_nop 0
	v_mul_f32_e32 v29, 0x3f317217, v23
	v_fma_f32 v29, v23, s52, -v29
	v_fmac_f32_e32 v29, 0x3377d1cf, v23
	v_fmac_f32_e32 v29, 0x3f317217, v23
	v_cmp_lt_f32_e64 s[8:9], |v23|, s53
	s_nop 1
	v_cndmask_b32_e64 v23, v23, v29, s[8:9]
	v_cndmask_b32_e32 v29, 0, v216, vcc
	v_sub_f32_e32 v29, v23, v29
	v_add_f32_e32 v23, v65, v17
	v_min_f32_e32 v17, 0, v23
	v_mul_f32_e64 v23, |v23|, s57
	v_exp_f32_e32 v23, v23
	v_pk_add_f32 v[20:21], v[20:21], v[28:29] neg_lo:[0,1] neg_hi:[0,1]
	v_add_f32_e32 v23, 1.0, v23
	v_cmp_gt_f32_e32 vcc, s97, v23
	s_nop 1
	v_cndmask_b32_e64 v30, 0, 32, vcc
	v_ldexp_f32 v23, v23, v30
	v_log_f32_e32 v23, v23
	s_nop 0
	v_mul_f32_e32 v30, 0x3f317217, v23
	v_fma_f32 v30, v23, s52, -v30
	v_fmac_f32_e32 v30, 0x3377d1cf, v23
	v_fmac_f32_e32 v30, 0x3f317217, v23
	v_cmp_lt_f32_e64 s[8:9], |v23|, s53
	s_nop 1
	v_cndmask_b32_e64 v23, v23, v30, s[8:9]
	v_cndmask_b32_e32 v30, 0, v216, vcc
	v_sub_f32_e32 v23, v23, v30
	v_add_f32_e32 v30, v70, v26
	v_min_f32_e32 v26, 0, v30
	v_mul_f32_e64 v30, |v30|, s57
	v_exp_f32_e32 v30, v30
	v_pk_add_f32 v[16:17], v[16:17], v[22:23] neg_lo:[0,1] neg_hi:[0,1]
	v_add_f32_e32 v30, 1.0, v30
	v_cmp_gt_f32_e32 vcc, s97, v30
	v_pk_mul_f32 v[16:17], v[16:17], s[2:3] op_sel_hi:[1,0]
	s_nop 0
	v_cndmask_b32_e64 v31, 0, 32, vcc
	v_ldexp_f32 v30, v30, v31
	v_log_f32_e32 v30, v30
	s_nop 0
	v_mul_f32_e32 v31, 0x3f317217, v30
	v_fma_f32 v31, v30, s52, -v31
	v_fmac_f32_e32 v31, 0x3377d1cf, v30
	v_fmac_f32_e32 v31, 0x3f317217, v30
	v_cmp_lt_f32_e64 s[8:9], |v30|, s53
	s_nop 1
	v_cndmask_b32_e64 v30, v30, v31, s[8:9]
	v_cndmask_b32_e32 v31, 0, v216, vcc
	v_sub_f32_e32 v30, v30, v31
	v_add_f32_e32 v31, v66, v18
	v_min_f32_e32 v18, 0, v31
	v_mul_f32_e64 v31, |v31|, s57
	v_exp_f32_e32 v31, v31
	s_nop 0
	v_add_f32_e32 v31, 1.0, v31
	v_cmp_gt_f32_e32 vcc, s97, v31
	s_nop 1
	v_cndmask_b32_e64 v32, 0, 32, vcc
	v_ldexp_f32 v31, v31, v32
	v_log_f32_e32 v31, v31
	s_nop 0
	v_mul_f32_e32 v32, 0x3f317217, v31
	v_fma_f32 v32, v31, s52, -v32
	v_fmac_f32_e32 v32, 0x3377d1cf, v31
	v_fmac_f32_e32 v32, 0x3f317217, v31
	v_cmp_lt_f32_e64 s[8:9], |v31|, s53
	s_nop 1
	v_cndmask_b32_e64 v31, v31, v32, s[8:9]
	v_cndmask_b32_e32 v32, 0, v216, vcc
	v_sub_f32_e32 v32, v31, v32
	v_add_f32_e32 v31, v71, v27
	v_min_f32_e32 v27, 0, v31
	v_mul_f32_e64 v31, |v31|, s57
	v_exp_f32_e32 v31, v31
	s_nop 0
	v_add_f32_e32 v31, 1.0, v31
	v_cmp_gt_f32_e32 vcc, s97, v31
	s_nop 1
	v_cndmask_b32_e64 v33, 0, 32, vcc
	v_ldexp_f32 v31, v31, v33
	v_log_f32_e32 v31, v31
	s_nop 0
	v_mul_f32_e32 v33, 0x3f317217, v31
	v_fma_f32 v33, v31, s52, -v33
	v_fmac_f32_e32 v33, 0x3377d1cf, v31
	v_fmac_f32_e32 v33, 0x3f317217, v31
	v_cmp_lt_f32_e64 s[8:9], |v31|, s53
	s_nop 1
	v_cndmask_b32_e64 v31, v31, v33, s[8:9]
	v_cndmask_b32_e32 v33, 0, v216, vcc
	v_sub_f32_e32 v31, v31, v33
	v_pk_add_f32 v[26:27], v[26:27], v[30:31] neg_lo:[0,1] neg_hi:[0,1]
	s_nop 0
	v_pk_mul_f32 v[28:29], v[26:27], s[2:3] op_sel_hi:[1,0]
	v_pk_mul_f32 v[26:27], v[20:21], s[2:3] op_sel_hi:[1,0]
	v_add_f32_e32 v20, v67, v19
	v_min_f32_e32 v19, 0, v20
	v_mul_f32_e64 v20, |v20|, s57
	v_exp_f32_e32 v20, v20
	s_nop 0
	v_add_f32_e32 v20, 1.0, v20
	v_cmp_gt_f32_e32 vcc, s97, v20
	s_nop 1
	v_cndmask_b32_e64 v21, 0, 32, vcc
	v_ldexp_f32 v20, v20, v21
	v_log_f32_e32 v20, v20
	s_nop 0
	v_mul_f32_e32 v21, 0x3f317217, v20
	v_fma_f32 v21, v20, s52, -v21
	v_fmac_f32_e32 v21, 0x3377d1cf, v20
	v_fmac_f32_e32 v21, 0x3f317217, v20
	v_cmp_lt_f32_e64 s[8:9], |v20|, s53
	s_nop 1
	v_cndmask_b32_e64 v20, v20, v21, s[8:9]
	v_cndmask_b32_e32 v21, 0, v216, vcc
	v_sub_f32_e32 v33, v20, v21
	v_lshlrev_b64 v[20:21], 5, v[24:25]
	v_pk_add_f32 v[18:19], v[18:19], v[32:33] neg_lo:[0,1] neg_hi:[0,1]
	v_lshl_add_u64 v[20:21], s[42:43], 0, v[20:21]
	v_pk_mul_f32 v[18:19], v[18:19], s[2:3] op_sel_hi:[1,0]
	global_store_dwordx4 v[20:21], v[26:29], off
	global_store_dwordx4 v[20:21], v[16:19], off offset:16
	s_nop 1
	v_add_u32_e32 v16, 0xa0, v166
	v_ashrrev_i32_e32 v17, 31, v16
	v_lshlrev_b64 v[18:19], 6, v[16:17]
	v_lshl_add_u64 v[30:31], s[82:83], 0, v[18:19]
	flat_load_dwordx4 v[18:21], v[30:31]
	flat_load_dwordx4 v[22:25], v[30:31] offset:16
	flat_load_dwordx4 v[26:29], v[30:31] offset:32
	s_nop 0
	flat_load_dwordx4 v[30:33], v[30:31] offset:48
	s_waitcnt vmcnt(0) lgkmcnt(0)
; __device__ __forceinline__ float logsig_f(float x) { return fminf(x, 0.f) - __logf(1.f + __expf(-fabsf(x))); }
;     __device__ __forceinline__ void operator()(const f32x4 (&acc)[2][2][4][2], const pg8::Unit& u, int wr, int wc, int fr, int fq) const {
;     ...
;                         const int row = row0 + ai * 128 + m * 16;
;                         const f32x4 sv = *(const f32x4*)(ssq + (size_t)row * 16), sv1 = *(const f32x4*)(ssq + (size_t)row * 16 + 4), sv2 = *(const f32x4*)(ssq + (size_t)row * 16 + 8), sv3 = *(const f32x4*)(ssq + (size_t)row * 16 + 12);
;                         const float st = ((sv[0] + sv[1]) + (sv[2] + sv[3])) + ((sv1[0] + sv1[1]) + (sv1[2] + sv1[3])) + ((sv2[0] + sv2[1]) + (sv2[2] + sv2[3])) + ((sv3[0] + sv3[1]) + (sv3[2] + sv3[3]));
;                         const float rs = __builtin_amdgcn_rsqf(st * (1.f / DM) + EPS);
;                         f32x4 a = acc[ai][0][m][0] * rs, b = acc[ai][0][m][1] * rs;
; #pragma unroll
;                         for (int i = 0; i < 4; ++i) { a[i] = logsig_f(a[i] + fb0[i]) * LOG2E; b[i] = logsig_f(b[i] + fb1[i]) * LOG2E; }
;                         *(f32x4*)(FF + (size_t)row * 8) = a; *(f32x4*)(FF + (size_t)row * 8 + 4) = b;
;                         asm volatile("" ::: "memory");
	v_mov_b32_e32 v34, v19
	v_mov_b32_e32 v35, v20
	v_mov_b32_e32 v19, v21
	v_mov_b32_e32 v20, v23
	v_mov_b32_e32 v21, v24
	v_mov_b32_e32 v23, v25
	v_pk_add_f32 v[18:19], v[34:35], v[18:19]
	v_pk_add_f32 v[20:21], v[20:21], v[22:23]
	v_pk_add_f32 v[18:19], v[18:19], v[18:19] op_sel:[0,1] op_sel_hi:[1,0]
	v_pk_add_f32 v[20:21], v[20:21], v[20:21] op_sel:[0,1] op_sel_hi:[1,0]
	v_add_f32_e32 v22, v26, v27
	v_add_f32_e32 v24, v28, v29
	v_mov_b32_e32 v19, v30
	v_mov_b32_e32 v21, v31
	v_mov_b32_e32 v23, v32
	v_mov_b32_e32 v25, v33
	v_pk_add_f32 v[18:19], v[18:19], v[20:21]
	v_pk_add_f32 v[20:21], v[22:23], v[24:25]
	s_nop 0
	v_pk_add_f32 v[18:19], v[18:19], v[20:21]
	s_nop 0
	v_add_f32_e32 v18, v18, v19
	v_fmamk_f32 v18, v18, 0x3a800000, v212
	v_rsq_f32_e32 v20, v18
	s_nop 0
	v_pk_mul_f32 v[12:13], v[12:13], v[20:21] op_sel_hi:[1,0]
	v_pk_mul_f32 v[18:19], v[14:15], v[20:21] op_sel_hi:[1,0]
	v_add_f32_e32 v14, v68, v12
	v_min_f32_e32 v12, 0, v14
	v_mul_f32_e64 v14, |v14|, s57
	v_exp_f32_e32 v14, v14
	v_pk_mul_f32 v[8:9], v[8:9], v[20:21] op_sel_hi:[1,0]
	v_pk_mul_f32 v[10:11], v[10:11], v[20:21] op_sel_hi:[1,0]
	v_add_f32_e32 v14, 1.0, v14
	v_cmp_gt_f32_e32 vcc, s97, v14
	s_nop 1
	v_cndmask_b32_e64 v15, 0, 32, vcc
	v_ldexp_f32 v14, v14, v15
	v_log_f32_e32 v14, v14
	s_nop 0
	v_mul_f32_e32 v15, 0x3f317217, v14
	v_fma_f32 v15, v14, s52, -v15
	v_fmac_f32_e32 v15, 0x3377d1cf, v14
	v_fmac_f32_e32 v15, 0x3f317217, v14
	v_cmp_lt_f32_e64 s[8:9], |v14|, s53
	s_nop 1
	v_cndmask_b32_e64 v14, v14, v15, s[8:9]
	v_cndmask_b32_e32 v15, 0, v216, vcc
	v_sub_f32_e32 v20, v14, v15
	v_add_f32_e32 v14, v64, v8
	v_min_f32_e32 v8, 0, v14
	v_mul_f32_e64 v14, |v14|, s57
	v_exp_f32_e32 v14, v14
	s_nop 0
	v_add_f32_e32 v14, 1.0, v14
	v_cmp_gt_f32_e32 vcc, s97, v14
	s_nop 1
	v_cndmask_b32_e64 v15, 0, 32, vcc
	v_ldexp_f32 v14, v14, v15
	v_log_f32_e32 v14, v14
	s_nop 0
	v_mul_f32_e32 v15, 0x3f317217, v14
	v_fma_f32 v15, v14, s52, -v15
	v_fmac_f32_e32 v15, 0x3377d1cf, v14
	v_fmac_f32_e32 v15, 0x3f317217, v14
	v_cmp_lt_f32_e64 s[8:9], |v14|, s53
	s_nop 1
	v_cndmask_b32_e64 v14, v14, v15, s[8:9]
	v_cndmask_b32_e32 v15, 0, v216, vcc
	v_sub_f32_e32 v14, v14, v15
	v_add_f32_e32 v15, v69, v13
	v_min_f32_e32 v13, 0, v15
	v_mul_f32_e64 v15, |v15|, s57
	v_exp_f32_e32 v15, v15
	s_nop 0
	v_add_f32_e32 v15, 1.0, v15
	v_cmp_gt_f32_e32 vcc, s97, v15
	s_nop 1
	v_cndmask_b32_e64 v21, 0, 32, vcc
	v_ldexp_f32 v15, v15, v21
	v_log_f32_e32 v15, v15
	s_nop 0
	v_mul_f32_e32 v21, 0x3f317217, v15
	v_fma_f32 v21, v15, s52, -v21
	v_fmac_f32_e32 v21, 0x3377d1cf, v15
	v_fmac_f32_e32 v21, 0x3f317217, v15
	v_cmp_lt_f32_e64 s[8:9], |v15|, s53
	s_nop 1
	v_cndmask_b32_e64 v15, v15, v21, s[8:9]
	v_cndmask_b32_e32 v21, 0, v216, vcc
	v_sub_f32_e32 v21, v15, v21
	v_add_f32_e32 v15, v65, v9
	v_min_f32_e32 v9, 0, v15
	v_mul_f32_e64 v15, |v15|, s57
	v_exp_f32_e32 v15, v15
	v_pk_add_f32 v[12:13], v[12:13], v[20:21] neg_lo:[0,1] neg_hi:[0,1]
	v_add_f32_e32 v15, 1.0, v15
	v_cmp_gt_f32_e32 vcc, s97, v15
	s_nop 1
	v_cndmask_b32_e64 v22, 0, 32, vcc
	v_ldexp_f32 v15, v15, v22
	v_log_f32_e32 v15, v15
	s_nop 0
	v_mul_f32_e32 v22, 0x3f317217, v15
	v_fma_f32 v22, v15, s52, -v22
	v_fmac_f32_e32 v22, 0x3377d1cf, v15
	v_fmac_f32_e32 v22, 0x3f317217, v15
	v_cmp_lt_f32_e64 s[8:9], |v15|, s53
	s_nop 1
	v_cndmask_b32_e64 v15, v15, v22, s[8:9]
	v_cndmask_b32_e32 v22, 0, v216, vcc
	v_sub_f32_e32 v15, v15, v22
	v_add_f32_e32 v22, v70, v18
	v_min_f32_e32 v18, 0, v22
	v_mul_f32_e64 v22, |v22|, s57
	v_exp_f32_e32 v22, v22
	v_pk_add_f32 v[8:9], v[8:9], v[14:15] neg_lo:[0,1] neg_hi:[0,1]
	v_add_f32_e32 v22, 1.0, v22
	v_cmp_gt_f32_e32 vcc, s97, v22
	v_pk_mul_f32 v[8:9], v[8:9], s[2:3] op_sel_hi:[1,0]
	s_nop 0
	v_cndmask_b32_e64 v23, 0, 32, vcc
	v_ldexp_f32 v22, v22, v23
	v_log_f32_e32 v22, v22
	s_nop 0
	v_mul_f32_e32 v23, 0x3f317217, v22
	v_fma_f32 v23, v22, s52, -v23
	v_fmac_f32_e32 v23, 0x3377d1cf, v22
	v_fmac_f32_e32 v23, 0x3f317217, v22
	v_cmp_lt_f32_e64 s[8:9], |v22|, s53
	s_nop 1
	v_cndmask_b32_e64 v22, v22, v23, s[8:9]
	v_cndmask_b32_e32 v23, 0, v216, vcc
	v_sub_f32_e32 v22, v22, v23
	v_add_f32_e32 v23, v66, v10
	v_min_f32_e32 v10, 0, v23
	v_mul_f32_e64 v23, |v23|, s57
	v_exp_f32_e32 v23, v23
	s_nop 0
	v_add_f32_e32 v23, 1.0, v23
	v_cmp_gt_f32_e32 vcc, s97, v23
	s_nop 1
	v_cndmask_b32_e64 v24, 0, 32, vcc
	v_ldexp_f32 v23, v23, v24
	v_log_f32_e32 v23, v23
	s_nop 0
	v_mul_f32_e32 v24, 0x3f317217, v23
	v_fma_f32 v24, v23, s52, -v24
	v_fmac_f32_e32 v24, 0x3377d1cf, v23
	v_fmac_f32_e32 v24, 0x3f317217, v23
	v_cmp_lt_f32_e64 s[8:9], |v23|, s53
	s_nop 1
	v_cndmask_b32_e64 v23, v23, v24, s[8:9]
	v_cndmask_b32_e32 v24, 0, v216, vcc
	v_sub_f32_e32 v24, v23, v24
	v_add_f32_e32 v23, v71, v19
	v_min_f32_e32 v19, 0, v23
	v_mul_f32_e64 v23, |v23|, s57
	v_exp_f32_e32 v23, v23
	s_nop 0
	v_add_f32_e32 v23, 1.0, v23
	v_cmp_gt_f32_e32 vcc, s97, v23
	s_nop 1
	v_cndmask_b32_e64 v25, 0, 32, vcc
	v_ldexp_f32 v23, v23, v25
	v_log_f32_e32 v23, v23
	s_nop 0
	v_mul_f32_e32 v25, 0x3f317217, v23
	v_fma_f32 v25, v23, s52, -v25
	v_fmac_f32_e32 v25, 0x3377d1cf, v23
	v_fmac_f32_e32 v25, 0x3f317217, v23
	v_cmp_lt_f32_e64 s[8:9], |v23|, s53
	s_nop 1
	v_cndmask_b32_e64 v23, v23, v25, s[8:9]
	v_cndmask_b32_e32 v25, 0, v216, vcc
	v_sub_f32_e32 v23, v23, v25
	v_pk_add_f32 v[18:19], v[18:19], v[22:23] neg_lo:[0,1] neg_hi:[0,1]
	s_nop 0
	v_pk_mul_f32 v[20:21], v[18:19], s[2:3] op_sel_hi:[1,0]
	v_pk_mul_f32 v[18:19], v[12:13], s[2:3] op_sel_hi:[1,0]
	v_add_f32_e32 v12, v67, v11
	v_min_f32_e32 v11, 0, v12
	v_mul_f32_e64 v12, |v12|, s57
	v_exp_f32_e32 v12, v12
	s_nop 0
	v_add_f32_e32 v12, 1.0, v12
	v_cmp_gt_f32_e32 vcc, s97, v12
	s_nop 1
	v_cndmask_b32_e64 v13, 0, 32, vcc
	v_ldexp_f32 v12, v12, v13
	v_log_f32_e32 v12, v12
	s_nop 0
	v_mul_f32_e32 v13, 0x3f317217, v12
	v_fma_f32 v13, v12, s52, -v13
	v_fmac_f32_e32 v13, 0x3377d1cf, v12
	v_fmac_f32_e32 v13, 0x3f317217, v12
	v_cmp_lt_f32_e64 s[8:9], |v12|, s53
	s_nop 1
	v_cndmask_b32_e64 v12, v12, v13, s[8:9]
	v_cndmask_b32_e32 v13, 0, v216, vcc
	v_sub_f32_e32 v25, v12, v13
	v_lshlrev_b64 v[12:13], 5, v[16:17]
	v_pk_add_f32 v[10:11], v[10:11], v[24:25] neg_lo:[0,1] neg_hi:[0,1]
	v_lshl_add_u64 v[12:13], s[42:43], 0, v[12:13]
	v_pk_mul_f32 v[10:11], v[10:11], s[2:3] op_sel_hi:[1,0]
	global_store_dwordx4 v[12:13], v[18:21], off
	global_store_dwordx4 v[12:13], v[8:11], off offset:16
	s_nop 1
	v_add_u32_e32 v8, 0xb0, v166
	v_ashrrev_i32_e32 v9, 31, v8
	v_lshlrev_b64 v[10:11], 6, v[8:9]
	v_lshl_add_u64 v[22:23], s[82:83], 0, v[10:11]
	flat_load_dwordx4 v[10:13], v[22:23]
	flat_load_dwordx4 v[14:17], v[22:23] offset:16
	flat_load_dwordx4 v[18:21], v[22:23] offset:32
	s_nop 0
	flat_load_dwordx4 v[22:25], v[22:23] offset:48
	s_waitcnt vmcnt(0) lgkmcnt(0)
; __device__ __forceinline__ float logsig_f(float x) { return fminf(x, 0.f) - __logf(1.f + __expf(-fabsf(x))); }
;     __device__ __forceinline__ void operator()(const f32x4 (&acc)[2][2][4][2], const pg8::Unit& u, int wr, int wc, int fr, int fq) const {
;     ...
;                         const int row = row0 + ai * 128 + m * 16;
;                         const f32x4 sv = *(const f32x4*)(ssq + (size_t)row * 16), sv1 = *(const f32x4*)(ssq + (size_t)row * 16 + 4), sv2 = *(const f32x4*)(ssq + (size_t)row * 16 + 8), sv3 = *(const f32x4*)(ssq + (size_t)row * 16 + 12);
;                         const float st = ((sv[0] + sv[1]) + (sv[2] + sv[3])) + ((sv1[0] + sv1[1]) + (sv1[2] + sv1[3])) + ((sv2[0] + sv2[1]) + (sv2[2] + sv2[3])) + ((sv3[0] + sv3[1]) + (sv3[2] + sv3[3]));
;                         const float rs = __builtin_amdgcn_rsqf(st * (1.f / DM) + EPS);
;                         f32x4 a = acc[ai][0][m][0] * rs, b = acc[ai][0][m][1] * rs;
; #pragma unroll
;                         for (int i = 0; i < 4; ++i) { a[i] = logsig_f(a[i] + fb0[i]) * LOG2E; b[i] = logsig_f(b[i] + fb1[i]) * LOG2E; }
;                         *(f32x4*)(FF + (size_t)row * 8) = a; *(f32x4*)(FF + (size_t)row * 8 + 4) = b;
;                         asm volatile("" ::: "memory");
	v_mov_b32_e32 v26, v11
	v_mov_b32_e32 v27, v12
	v_mov_b32_e32 v11, v13
	v_mov_b32_e32 v12, v15
	v_mov_b32_e32 v13, v16
	v_mov_b32_e32 v15, v17
	v_pk_add_f32 v[10:11], v[26:27], v[10:11]
	v_pk_add_f32 v[12:13], v[12:13], v[14:15]
	v_pk_add_f32 v[10:11], v[10:11], v[10:11] op_sel:[0,1] op_sel_hi:[1,0]
	v_pk_add_f32 v[12:13], v[12:13], v[12:13] op_sel:[0,1] op_sel_hi:[1,0]
	v_add_f32_e32 v14, v18, v19
	v_add_f32_e32 v16, v20, v21
	v_mov_b32_e32 v11, v22
	v_mov_b32_e32 v13, v23
	v_mov_b32_e32 v15, v24
	v_mov_b32_e32 v17, v25
	v_pk_add_f32 v[10:11], v[10:11], v[12:13]
	v_pk_add_f32 v[12:13], v[14:15], v[16:17]
	s_nop 0
	v_pk_add_f32 v[10:11], v[10:11], v[12:13]
	s_nop 0
	v_add_f32_e32 v10, v10, v11
	v_fmamk_f32 v10, v10, 0x3a800000, v212
	v_rsq_f32_e32 v12, v10
	s_nop 0
	v_pk_mul_f32 v[4:5], v[4:5], v[12:13] op_sel_hi:[1,0]
	v_pk_mul_f32 v[10:11], v[6:7], v[12:13] op_sel_hi:[1,0]
	v_add_f32_e32 v6, v68, v4
	v_min_f32_e32 v4, 0, v6
	v_mul_f32_e64 v6, |v6|, s57
	v_exp_f32_e32 v6, v6
	v_pk_mul_f32 v[0:1], v[0:1], v[12:13] op_sel_hi:[1,0]
	v_pk_mul_f32 v[2:3], v[2:3], v[12:13] op_sel_hi:[1,0]
	v_add_f32_e32 v6, 1.0, v6
	v_cmp_gt_f32_e32 vcc, s97, v6
	s_nop 1
	v_cndmask_b32_e64 v7, 0, 32, vcc
	v_ldexp_f32 v6, v6, v7
	v_log_f32_e32 v6, v6
	s_nop 0
	v_mul_f32_e32 v7, 0x3f317217, v6
	v_fma_f32 v7, v6, s52, -v7
	v_fmac_f32_e32 v7, 0x3377d1cf, v6
	v_fmac_f32_e32 v7, 0x3f317217, v6
	v_cmp_lt_f32_e64 s[8:9], |v6|, s53
	s_nop 1
	v_cndmask_b32_e64 v6, v6, v7, s[8:9]
	v_cndmask_b32_e32 v7, 0, v216, vcc
	v_sub_f32_e32 v12, v6, v7
	v_add_f32_e32 v6, v64, v0
	v_min_f32_e32 v0, 0, v6
	v_mul_f32_e64 v6, |v6|, s57
	v_exp_f32_e32 v6, v6
	s_nop 0
	v_add_f32_e32 v6, 1.0, v6
	v_cmp_gt_f32_e32 vcc, s97, v6
	s_nop 1
	v_cndmask_b32_e64 v7, 0, 32, vcc
	v_ldexp_f32 v6, v6, v7
	v_log_f32_e32 v6, v6
	s_nop 0
	v_mul_f32_e32 v7, 0x3f317217, v6
	v_fma_f32 v7, v6, s52, -v7
	v_fmac_f32_e32 v7, 0x3377d1cf, v6
	v_fmac_f32_e32 v7, 0x3f317217, v6
	v_cmp_lt_f32_e64 s[8:9], |v6|, s53
	s_nop 1
	v_cndmask_b32_e64 v6, v6, v7, s[8:9]
	v_cndmask_b32_e32 v7, 0, v216, vcc
	v_sub_f32_e32 v6, v6, v7
	v_add_f32_e32 v7, v69, v5
	v_min_f32_e32 v5, 0, v7
	v_mul_f32_e64 v7, |v7|, s57
	v_exp_f32_e32 v7, v7
	s_nop 0
	v_add_f32_e32 v7, 1.0, v7
	v_cmp_gt_f32_e32 vcc, s97, v7
	s_nop 1
	v_cndmask_b32_e64 v13, 0, 32, vcc
	v_ldexp_f32 v7, v7, v13
	v_log_f32_e32 v7, v7
	s_nop 0
	v_mul_f32_e32 v13, 0x3f317217, v7
	v_fma_f32 v13, v7, s52, -v13
	v_fmac_f32_e32 v13, 0x3377d1cf, v7
	v_fmac_f32_e32 v13, 0x3f317217, v7
	v_cmp_lt_f32_e64 s[8:9], |v7|, s53
	s_nop 1
	v_cndmask_b32_e64 v7, v7, v13, s[8:9]
	v_cndmask_b32_e32 v13, 0, v216, vcc
	v_sub_f32_e32 v13, v7, v13
	v_add_f32_e32 v7, v65, v1
	v_min_f32_e32 v1, 0, v7
	v_mul_f32_e64 v7, |v7|, s57
	v_exp_f32_e32 v7, v7
	v_pk_add_f32 v[4:5], v[4:5], v[12:13] neg_lo:[0,1] neg_hi:[0,1]
	v_add_f32_e32 v7, 1.0, v7
	v_cmp_gt_f32_e32 vcc, s97, v7
	s_nop 1
	v_cndmask_b32_e64 v14, 0, 32, vcc
	v_ldexp_f32 v7, v7, v14
	v_log_f32_e32 v7, v7
	s_nop 0
	v_mul_f32_e32 v14, 0x3f317217, v7
	v_fma_f32 v14, v7, s52, -v14
	v_fmac_f32_e32 v14, 0x3377d1cf, v7
	v_fmac_f32_e32 v14, 0x3f317217, v7
	v_cmp_lt_f32_e64 s[8:9], |v7|, s53
	s_nop 1
	v_cndmask_b32_e64 v7, v7, v14, s[8:9]
	v_cndmask_b32_e32 v14, 0, v216, vcc
	v_sub_f32_e32 v7, v7, v14
	v_add_f32_e32 v14, v70, v10
	v_min_f32_e32 v10, 0, v14
	v_mul_f32_e64 v14, |v14|, s57
	v_exp_f32_e32 v14, v14
	v_pk_add_f32 v[0:1], v[0:1], v[6:7] neg_lo:[0,1] neg_hi:[0,1]
	v_add_f32_e32 v14, 1.0, v14
	v_cmp_gt_f32_e32 vcc, s97, v14
	v_pk_mul_f32 v[0:1], v[0:1], s[2:3] op_sel_hi:[1,0]
	s_nop 0
	v_cndmask_b32_e64 v15, 0, 32, vcc
	v_ldexp_f32 v14, v14, v15
	v_log_f32_e32 v14, v14
	s_nop 0
	v_mul_f32_e32 v15, 0x3f317217, v14
	v_fma_f32 v15, v14, s52, -v15
	v_fmac_f32_e32 v15, 0x3377d1cf, v14
	v_fmac_f32_e32 v15, 0x3f317217, v14
	v_cmp_lt_f32_e64 s[8:9], |v14|, s53
	s_nop 1
	v_cndmask_b32_e64 v14, v14, v15, s[8:9]
	v_cndmask_b32_e32 v15, 0, v216, vcc
	v_sub_f32_e32 v14, v14, v15
	v_add_f32_e32 v15, v66, v2
	v_min_f32_e32 v2, 0, v15
	v_mul_f32_e64 v15, |v15|, s57
	v_exp_f32_e32 v15, v15
	s_nop 0
	v_add_f32_e32 v15, 1.0, v15
	v_cmp_gt_f32_e32 vcc, s97, v15
	s_nop 1
	v_cndmask_b32_e64 v16, 0, 32, vcc
	v_ldexp_f32 v15, v15, v16
	v_log_f32_e32 v15, v15
	s_nop 0
	v_mul_f32_e32 v16, 0x3f317217, v15
	v_fma_f32 v16, v15, s52, -v16
	v_fmac_f32_e32 v16, 0x3377d1cf, v15
	v_fmac_f32_e32 v16, 0x3f317217, v15
	v_cmp_lt_f32_e64 s[8:9], |v15|, s53
	s_nop 1
	v_cndmask_b32_e64 v15, v15, v16, s[8:9]
	v_cndmask_b32_e32 v16, 0, v216, vcc
	v_sub_f32_e32 v16, v15, v16
	v_add_f32_e32 v15, v71, v11
	v_min_f32_e32 v11, 0, v15
	v_mul_f32_e64 v15, |v15|, s57
	v_exp_f32_e32 v15, v15
	s_nop 0
	v_add_f32_e32 v15, 1.0, v15
	v_cmp_gt_f32_e32 vcc, s97, v15
	s_nop 1
	v_cndmask_b32_e64 v17, 0, 32, vcc
	v_ldexp_f32 v15, v15, v17
	v_log_f32_e32 v15, v15
	s_nop 0
	v_mul_f32_e32 v17, 0x3f317217, v15
	v_fma_f32 v17, v15, s52, -v17
	v_fmac_f32_e32 v17, 0x3377d1cf, v15
	v_fmac_f32_e32 v17, 0x3f317217, v15
	v_cmp_lt_f32_e64 s[8:9], |v15|, s53
	s_nop 1
	v_cndmask_b32_e64 v15, v15, v17, s[8:9]
	v_cndmask_b32_e32 v17, 0, v216, vcc
	v_sub_f32_e32 v15, v15, v17
	v_pk_add_f32 v[10:11], v[10:11], v[14:15] neg_lo:[0,1] neg_hi:[0,1]
	s_nop 0
	v_pk_mul_f32 v[12:13], v[10:11], s[2:3] op_sel_hi:[1,0]
	v_pk_mul_f32 v[10:11], v[4:5], s[2:3] op_sel_hi:[1,0]
	v_add_f32_e32 v4, v67, v3
	v_min_f32_e32 v3, 0, v4
	v_mul_f32_e64 v4, |v4|, s57
	v_exp_f32_e32 v4, v4
	s_nop 0
	v_add_f32_e32 v4, 1.0, v4
	v_cmp_gt_f32_e32 vcc, s97, v4
	s_nop 1
	v_cndmask_b32_e64 v5, 0, 32, vcc
	v_ldexp_f32 v4, v4, v5
	v_log_f32_e32 v4, v4
	s_nop 0
	v_mul_f32_e32 v5, 0x3f317217, v4
	v_fma_f32 v5, v4, s52, -v5
	v_fmac_f32_e32 v5, 0x3377d1cf, v4
	v_fmac_f32_e32 v5, 0x3f317217, v4
	v_cmp_lt_f32_e64 s[8:9], |v4|, s53
	s_nop 1
	v_cndmask_b32_e64 v4, v4, v5, s[8:9]
	v_cndmask_b32_e32 v5, 0, v216, vcc
	v_sub_f32_e32 v17, v4, v5
	v_lshlrev_b64 v[4:5], 5, v[8:9]
	v_pk_add_f32 v[2:3], v[2:3], v[16:17] neg_lo:[0,1] neg_hi:[0,1]
	v_lshl_add_u64 v[4:5], s[42:43], 0, v[4:5]
	v_pk_mul_f32 v[2:3], v[2:3], s[2:3] op_sel_hi:[1,0]
	global_store_dwordx4 v[4:5], v[10:13], off
	global_store_dwordx4 v[4:5], v[0:3], off offset:16
